# GEMM K-loops: LDS-DMA issue rebalanced across load segments (2/6/2/6 -> 2/4/4/6), vmcnt waits re-derived
# baseline (speedup 1.0000x reference)
; #define PG8_STAGE(bufoff, gbase, voff) do { _Pragma("unroll") for (int _i = 0; _i < 2; ++_i) \
;         __builtin_amdgcn_global_load_lds((const unsigned*)((const char*)(gbase) + (voff)[_i]), (PG8_LAS unsigned*)(lds + (bufoff) + ldsw + _i * 8192), 16, 0, 0); } while (0)
; #define PG8_LDA(dst, b, h) do { _Pragma("unroll") for (int m = 0; m < 4; ++m) _Pragma("unroll") for (int k = 0; k < 2; ++k) dst[m][k] = *(const PG8_LAS bf16x8*)(lds + PG8_SA(b, h) + aoff + m * 2048 + k * 1024); } while (0)
; #define PG8_LDB(dst, b, h) do { _Pragma("unroll") for (int n = 0; n < 2; ++n) _Pragma("unroll") for (int k = 0; k < 2; ++k) dst[n][k] = *(const PG8_LAS bf16x8*)(lds + PG8_SB(b, h) + boff + n * 2048 + k * 1024); } while (0)
; #define PG8_MMA(ai, bj, At, Bt) do { __builtin_amdgcn_s_setprio(1); _Pragma("unroll") for (int m = 0; m < 4; ++m) _Pragma("unroll") for (int n = 0; n < 2; ++n) _Pragma("unroll") for (int k = 0; k < 2; ++k) \
;         acc[ai][bj][m][n] = __builtin_amdgcn_mfma_f32_16x16x32_bf16(Bt[n][k], At[m][k], acc[ai][bj][m][n], 0, 0, 0); __builtin_amdgcn_s_setprio(0); } while (0)
; #define PG8_WAIT_V(n) asm volatile("s_waitcnt vmcnt(" #n ")" ::: "memory")
; #define PG8_BAR __builtin_amdgcn_s_barrier()
; template <class Epi, class Sched, bool ALIGN_EPI = false, bool SP2 = false>
; __device__ __forceinline__ void gemm_phase(PG8_LAS unsigned char* lds, const Gemm g, const Sched& S, const Epi& E, int wave_s_) {
;     ...
;         for (int t = 0; t < nt; t += 2) {
;             const bool last = (t == nt - 2);
;             const char* a1 = cA + (size_t)(t + 1) * kstep;
;             const char* a2 = last ? nA : cA + (size_t)(t + 2) * kstep; const char* b2 = last ? nB : cB + (size_t)(t + 2) * kstep;
;             const char* a3 = a2 + kstep; const char* b3 = b2 + kstep;
;             if (last && has_next) S.a_ready(nxt);
;             if constexpr (SP2) {
;             PG8_LDB(B0, 0, 0); PG8_LDB(B1, 0, 1); PG8_SCHED; PG8_LDA(At, 0, 0); PG8_STAGE(PG8_SA(1, 1), a1 + hstep, voffA);
;             PG8_WAIT_V(8); PG8_WAIT_L(0); PG8_BAR; PG8_MMA(0, 0, At, B0); PG8_MMA(0, 1, At, B1); PG8_BAR; PG8_SCHED;
;             PG8_LDA(At, 0, 1); PG8_STAGE(PG8_SB(0, 0), b2, voffB); PG8_STAGE(PG8_SB(0, 1), b2 + hstep, voffB); PG8_STAGE(PG8_SA(0, 0), a2, voffA);
;             PG8_WAIT_V(8); PG8_WAIT_L(0); PG8_BAR; PG8_MMA(1, 0, At, B0); PG8_MMA(1, 1, At, B1); PG8_BAR; PG8_SCHED;
.LBB0_206:
	s_add_u32 s17, s22, 0x100
	s_addc_u32 s48, s23, 0
	s_add_u32 s22, s24, 0x40080
	v_mov_b32_e32 v0, 0
	s_addc_u32 s23, s25, 0
	s_mov_b32 s49, -2
	s_add_u32 s24, s22, 0xfffc0080
	s_addc_u32 s25, s23, -1
	s_add_i32 s50, 0, 0x10000
	s_cmp_eq_u32 s49, 12
	s_cselect_b32 s27, s9, s25
	s_cselect_b32 s26, s8, s24
	s_cselect_b32 s25, s19, s48
	s_cselect_b32 s24, s18, s17
	s_add_i32 s52, 0, 0x14000
	v_add_u32_e32 v152, s50, v138
	v_add_u32_e32 v168, s52, v138
	ds_read_b128 v[140:143], v152
	ds_read_b128 v[144:147], v152 offset:1024
	ds_read_b128 v[148:151], v152 offset:2048
	ds_read_b128 v[152:155], v152 offset:3072
	ds_read_b128 v[156:159], v168
	ds_read_b128 v[160:163], v168 offset:1024
	ds_read_b128 v[164:167], v168 offset:2048
	ds_read_b128 v[168:171], v168 offset:3072
	v_lshl_add_u64 v[214:215], s[22:23], 0, v[136:137]
	s_add_i32 m0, s35, 0xc000
	ds_read_b128 v[172:175], v139
	ds_read_b128 v[176:179], v139 offset:1024
	ds_read_b128 v[180:183], v139 offset:2048
	ds_read_b128 v[184:187], v139 offset:3072
	ds_read_b128 v[188:191], v139 offset:4096
	ds_read_b128 v[192:195], v139 offset:5120
	ds_read_b128 v[206:209], v139 offset:6144
	ds_read_b128 v[210:213], v139 offset:7168
	global_load_lds_dwordx4 v[214:215], off
	v_lshl_add_u64 v[214:215], s[22:23], 0, v[134:135]
	s_add_i32 m0, s35, 0xe000
	s_nop 0
	global_load_lds_dwordx4 v[214:215], off
	s_waitcnt vmcnt(8)
	s_waitcnt lgkmcnt(0)
	s_barrier
	s_setprio 1
	s_waitcnt lgkmcnt(0)
	v_mfma_f32_16x16x32_bf16 v[124:127], v[140:143], v[172:175], 0
	v_mfma_f32_16x16x32_bf16 v[116:119], v[148:151], v[172:175], 0
	v_mfma_f32_16x16x32_bf16 v[108:111], v[140:143], v[180:183], 0
	v_mfma_f32_16x16x32_bf16 v[100:103], v[148:151], v[180:183], 0
	v_mfma_f32_16x16x32_bf16 v[92:95], v[140:143], v[188:191], 0
	v_mfma_f32_16x16x32_bf16 v[84:87], v[148:151], v[188:191], 0
	v_mfma_f32_16x16x32_bf16 v[76:79], v[140:143], v[206:209], 0
	v_mfma_f32_16x16x32_bf16 v[68:71], v[148:151], v[206:209], 0
	v_mfma_f32_16x16x32_bf16 v[124:127], v[144:147], v[176:179], v[124:127]
	v_mfma_f32_16x16x32_bf16 v[116:119], v[152:155], v[176:179], v[116:119]
	v_mfma_f32_16x16x32_bf16 v[108:111], v[144:147], v[184:187], v[108:111]
	v_mfma_f32_16x16x32_bf16 v[100:103], v[152:155], v[184:187], v[100:103]
	v_mfma_f32_16x16x32_bf16 v[92:95], v[144:147], v[192:195], v[92:95]
	v_mfma_f32_16x16x32_bf16 v[84:87], v[152:155], v[192:195], v[84:87]
	v_mfma_f32_16x16x32_bf16 v[76:79], v[144:147], v[210:213], v[76:79]
	v_mfma_f32_16x16x32_bf16 v[68:71], v[152:155], v[210:213], v[68:71]
	s_setprio 0
	s_setprio 1
	v_mfma_f32_16x16x32_bf16 v[120:123], v[156:159], v[172:175], 0
	v_mfma_f32_16x16x32_bf16 v[112:115], v[164:167], v[172:175], 0
	v_mfma_f32_16x16x32_bf16 v[104:107], v[156:159], v[180:183], 0
	v_mfma_f32_16x16x32_bf16 v[96:99], v[164:167], v[180:183], 0
	v_mfma_f32_16x16x32_bf16 v[88:91], v[156:159], v[188:191], 0
	v_mfma_f32_16x16x32_bf16 v[80:83], v[164:167], v[188:191], 0
	v_mfma_f32_16x16x32_bf16 v[72:75], v[156:159], v[206:209], 0
	v_mfma_f32_16x16x32_bf16 v[64:67], v[164:167], v[206:209], 0
	v_mfma_f32_16x16x32_bf16 v[120:123], v[160:163], v[176:179], v[120:123]
	v_mfma_f32_16x16x32_bf16 v[112:115], v[168:171], v[176:179], v[112:115]
	v_mfma_f32_16x16x32_bf16 v[104:107], v[160:163], v[184:187], v[104:107]
	v_mfma_f32_16x16x32_bf16 v[96:99], v[168:171], v[184:187], v[96:99]
	v_mfma_f32_16x16x32_bf16 v[88:91], v[160:163], v[192:195], v[88:91]
	v_mfma_f32_16x16x32_bf16 v[80:83], v[168:171], v[192:195], v[80:83]
	v_mfma_f32_16x16x32_bf16 v[72:75], v[160:163], v[210:213], v[72:75]
	v_mfma_f32_16x16x32_bf16 v[64:67], v[168:171], v[210:213], v[64:67]
	s_setprio 0
	s_barrier
	s_add_i32 s50, s50, s34
	v_lshl_add_u64 v[214:215], s[24:25], 0, v[196:197]
	s_mov_b32 m0, s50
	ds_read_b128 v[172:175], v139 offset:16384
	ds_read_b128 v[176:179], v139 offset:17408
	ds_read_b128 v[180:183], v139 offset:18432
	ds_read_b128 v[184:187], v139 offset:19456
	ds_read_b128 v[188:191], v139 offset:20480
	ds_read_b128 v[192:195], v139 offset:21504
	ds_read_b128 v[206:209], v139 offset:22528
	ds_read_b128 v[210:213], v139 offset:23552
	global_load_lds_dwordx4 v[214:215], off
	s_add_i32 m0, s50, 0x2000
	s_add_u32 s50, s24, 0x40000
	v_lshl_add_u64 v[216:217], s[24:25], 0, v[132:133]
	s_addc_u32 s51, s25, 0
	s_add_i32 s52, s52, s34
	global_load_lds_dwordx4 v[216:217], off
	v_lshl_add_u64 v[218:219], s[50:51], 0, v[196:197]
	s_mov_b32 m0, s52
	v_lshl_add_u64 v[220:221], s[26:27], 0, v[130:131]
	global_load_lds_dwordx4 v[218:219], off
	v_lshl_add_u64 v[218:219], s[50:51], 0, v[132:133]
	s_add_i32 m0, s52, 0x2000
	s_nop 0
	global_load_lds_dwordx4 v[218:219], off
	v_lshl_add_u64 v[218:219], s[26:27], 0, v[128:129]
	s_waitcnt vmcnt(6)
	s_waitcnt lgkmcnt(0)
	s_barrier
; #define PG8_STAGE(bufoff, gbase, voff) do { _Pragma("unroll") for (int _i = 0; _i < 2; ++_i) \
;         __builtin_amdgcn_global_load_lds((const unsigned*)((const char*)(gbase) + (voff)[_i]), (PG8_LAS unsigned*)(lds + (bufoff) + ldsw + _i * 8192), 16, 0, 0); } while (0)
; #define PG8_LDA(dst, b, h) do { _Pragma("unroll") for (int m = 0; m < 4; ++m) _Pragma("unroll") for (int k = 0; k < 2; ++k) dst[m][k] = *(const PG8_LAS bf16x8*)(lds + PG8_SA(b, h) + aoff + m * 2048 + k * 1024); } while (0)
; #define PG8_LDB(dst, b, h) do { _Pragma("unroll") for (int n = 0; n < 2; ++n) _Pragma("unroll") for (int k = 0; k < 2; ++k) dst[n][k] = *(const PG8_LAS bf16x8*)(lds + PG8_SB(b, h) + boff + n * 2048 + k * 1024); } while (0)
; #define PG8_MMA(ai, bj, At, Bt) do { __builtin_amdgcn_s_setprio(1); _Pragma("unroll") for (int m = 0; m < 4; ++m) _Pragma("unroll") for (int n = 0; n < 2; ++n) _Pragma("unroll") for (int k = 0; k < 2; ++k) \
;         acc[ai][bj][m][n] = __builtin_amdgcn_mfma_f32_16x16x32_bf16(Bt[n][k], At[m][k], acc[ai][bj][m][n], 0, 0, 0); __builtin_amdgcn_s_setprio(0); } while (0)
; #define PG8_WAIT_V(n) asm volatile("s_waitcnt vmcnt(" #n ")" ::: "memory")
; #define PG8_WAIT_L(n) asm volatile("s_waitcnt lgkmcnt(" #n ")" ::: "memory")
; #define PG8_BAR __builtin_amdgcn_s_barrier()
; #define PG8_SCHED __builtin_amdgcn_sched_barrier(0)
; template <class Epi, class Sched, bool ALIGN_EPI = false, bool SP2 = false>
; __device__ __forceinline__ void gemm_phase(PG8_LAS unsigned char* lds, const Gemm g, const Sched& S, const Epi& E, int wave_s_) {
;     ...
;             PG8_WAIT_V(8); PG8_WAIT_L(0); PG8_BAR; PG8_MMA(1, 0, At, B0); PG8_MMA(1, 1, At, B1); PG8_BAR; PG8_SCHED;
;             PG8_LDB(B0, 1, 0); PG8_LDB(B1, 1, 1); PG8_SCHED; PG8_LDA(At, 1, 0); PG8_STAGE(PG8_SA(0, 1), a2 + hstep, voffA);
;             PG8_WAIT_V(8); PG8_WAIT_L(0); PG8_BAR; PG8_MMA(0, 0, At, B0); PG8_MMA(0, 1, At, B1); PG8_BAR; PG8_SCHED;
	s_setprio 1
	s_waitcnt lgkmcnt(0)
	v_mfma_f32_16x16x32_bf16 v[60:63], v[140:143], v[172:175], 0
	v_mfma_f32_16x16x32_bf16 v[52:55], v[148:151], v[172:175], 0
	v_mfma_f32_16x16x32_bf16 v[44:47], v[140:143], v[180:183], 0
	v_mfma_f32_16x16x32_bf16 v[36:39], v[148:151], v[180:183], 0
	v_mfma_f32_16x16x32_bf16 v[28:31], v[140:143], v[188:191], 0
	v_mfma_f32_16x16x32_bf16 v[20:23], v[148:151], v[188:191], 0
	v_mfma_f32_16x16x32_bf16 v[12:15], v[140:143], v[206:209], 0
	v_mfma_f32_16x16x32_bf16 v[4:7], v[148:151], v[206:209], 0
	v_mfma_f32_16x16x32_bf16 v[60:63], v[144:147], v[176:179], v[60:63]
	v_mfma_f32_16x16x32_bf16 v[52:55], v[152:155], v[176:179], v[52:55]
	v_mfma_f32_16x16x32_bf16 v[44:47], v[144:147], v[184:187], v[44:47]
	v_mfma_f32_16x16x32_bf16 v[36:39], v[152:155], v[184:187], v[36:39]
	v_mfma_f32_16x16x32_bf16 v[28:31], v[144:147], v[192:195], v[28:31]
	v_mfma_f32_16x16x32_bf16 v[20:23], v[152:155], v[192:195], v[20:23]
	v_mfma_f32_16x16x32_bf16 v[12:15], v[144:147], v[210:213], v[12:15]
	v_mfma_f32_16x16x32_bf16 v[4:7], v[152:155], v[210:213], v[4:7]
	s_setprio 0
	s_setprio 1
	v_mfma_f32_16x16x32_bf16 v[56:59], v[156:159], v[172:175], 0
	v_mfma_f32_16x16x32_bf16 v[48:51], v[164:167], v[172:175], 0
	v_mfma_f32_16x16x32_bf16 v[40:43], v[156:159], v[180:183], 0
	v_mfma_f32_16x16x32_bf16 v[32:35], v[164:167], v[180:183], 0
	v_mfma_f32_16x16x32_bf16 v[24:27], v[156:159], v[188:191], 0
	v_mfma_f32_16x16x32_bf16 v[16:19], v[164:167], v[188:191], 0
	v_mfma_f32_16x16x32_bf16 v[8:11], v[156:159], v[206:209], 0
	v_mfma_f32_16x16x32_bf16 v[0:3], v[164:167], v[206:209], 0
	v_mfma_f32_16x16x32_bf16 v[56:59], v[160:163], v[176:179], v[56:59]
	v_mfma_f32_16x16x32_bf16 v[48:51], v[168:171], v[176:179], v[48:51]
	v_mfma_f32_16x16x32_bf16 v[40:43], v[160:163], v[184:187], v[40:43]
	v_mfma_f32_16x16x32_bf16 v[32:35], v[168:171], v[184:187], v[32:35]
	v_mfma_f32_16x16x32_bf16 v[24:27], v[160:163], v[192:195], v[24:27]
	v_mfma_f32_16x16x32_bf16 v[16:19], v[168:171], v[192:195], v[16:19]
	v_mfma_f32_16x16x32_bf16 v[8:11], v[160:163], v[210:213], v[8:11]
	v_mfma_f32_16x16x32_bf16 v[0:3], v[168:171], v[210:213], v[0:3]
	s_setprio 0
	s_barrier
	s_add_i32 s50, 0, 0x18000
	s_add_i32 s51, 0, 0x1c000
	v_add_u32_e32 v152, s50, v138
	v_add_u32_e32 v168, s51, v138
	ds_read_b128 v[140:143], v152
	ds_read_b128 v[144:147], v152 offset:1024
	ds_read_b128 v[148:151], v152 offset:2048
	ds_read_b128 v[152:155], v152 offset:3072
	ds_read_b128 v[156:159], v168
	ds_read_b128 v[160:163], v168 offset:1024
	ds_read_b128 v[164:167], v168 offset:2048
	ds_read_b128 v[168:171], v168 offset:3072
	s_add_u32 s26, s26, 0x40000
	s_addc_u32 s27, s27, 0
	s_mov_b32 m0, s37
	v_lshl_add_u64 v[222:223], s[26:27], 0, v[128:129]
	ds_read_b128 v[172:175], v139 offset:32768
	ds_read_b128 v[176:179], v139 offset:33792
	ds_read_b128 v[180:183], v139 offset:34816
	ds_read_b128 v[184:187], v139 offset:35840
	ds_read_b128 v[188:191], v139 offset:36864
	ds_read_b128 v[192:195], v139 offset:37888
	ds_read_b128 v[206:209], v139 offset:38912
	ds_read_b128 v[210:213], v139 offset:39936
	global_load_lds_dwordx4 v[222:223], off
	v_lshl_add_u64 v[222:223], s[26:27], 0, v[130:131]
	s_mov_b32 m0, s38
	s_nop 0
	global_load_lds_dwordx4 v[222:223], off
	s_mov_b32 m0, s35
	s_nop 0
	global_load_lds_dwordx4 v[218:219], off
	s_mov_b32 m0, s36
	s_nop 0
	global_load_lds_dwordx4 v[220:221], off
	s_waitcnt vmcnt(8)
	s_waitcnt lgkmcnt(0)
	s_barrier
	s_setprio 1
	s_waitcnt lgkmcnt(0)
	v_mfma_f32_16x16x32_bf16 v[124:127], v[140:143], v[172:175], v[124:127]
	v_mfma_f32_16x16x32_bf16 v[116:119], v[148:151], v[172:175], v[116:119]
	v_mfma_f32_16x16x32_bf16 v[108:111], v[140:143], v[180:183], v[108:111]
	v_mfma_f32_16x16x32_bf16 v[100:103], v[148:151], v[180:183], v[100:103]
	v_mfma_f32_16x16x32_bf16 v[92:95], v[140:143], v[188:191], v[92:95]
	v_mfma_f32_16x16x32_bf16 v[84:87], v[148:151], v[188:191], v[84:87]
	v_mfma_f32_16x16x32_bf16 v[76:79], v[140:143], v[206:209], v[76:79]
	v_mfma_f32_16x16x32_bf16 v[68:71], v[148:151], v[206:209], v[68:71]
	v_mfma_f32_16x16x32_bf16 v[124:127], v[144:147], v[176:179], v[124:127]
	v_mfma_f32_16x16x32_bf16 v[116:119], v[152:155], v[176:179], v[116:119]
	v_mfma_f32_16x16x32_bf16 v[108:111], v[144:147], v[184:187], v[108:111]
	v_mfma_f32_16x16x32_bf16 v[100:103], v[152:155], v[184:187], v[100:103]
	v_mfma_f32_16x16x32_bf16 v[92:95], v[144:147], v[192:195], v[92:95]
	v_mfma_f32_16x16x32_bf16 v[84:87], v[152:155], v[192:195], v[84:87]
	v_mfma_f32_16x16x32_bf16 v[76:79], v[144:147], v[210:213], v[76:79]
	v_mfma_f32_16x16x32_bf16 v[68:71], v[152:155], v[210:213], v[68:71]
	s_setprio 0
	s_setprio 1
	v_mfma_f32_16x16x32_bf16 v[120:123], v[156:159], v[172:175], v[120:123]
	v_mfma_f32_16x16x32_bf16 v[112:115], v[164:167], v[172:175], v[112:115]
	v_mfma_f32_16x16x32_bf16 v[104:107], v[156:159], v[180:183], v[104:107]
	v_mfma_f32_16x16x32_bf16 v[96:99], v[164:167], v[180:183], v[96:99]
	v_mfma_f32_16x16x32_bf16 v[88:91], v[156:159], v[188:191], v[88:91]
	v_mfma_f32_16x16x32_bf16 v[80:83], v[164:167], v[188:191], v[80:83]
	v_mfma_f32_16x16x32_bf16 v[72:75], v[156:159], v[206:209], v[72:75]
	v_mfma_f32_16x16x32_bf16 v[64:67], v[164:167], v[206:209], v[64:67]
	v_mfma_f32_16x16x32_bf16 v[120:123], v[160:163], v[176:179], v[120:123]
	v_mfma_f32_16x16x32_bf16 v[112:115], v[168:171], v[176:179], v[112:115]
	v_mfma_f32_16x16x32_bf16 v[104:107], v[160:163], v[184:187], v[104:107]
	v_mfma_f32_16x16x32_bf16 v[96:99], v[168:171], v[184:187], v[96:99]
	v_mfma_f32_16x16x32_bf16 v[88:91], v[160:163], v[192:195], v[88:91]
	v_mfma_f32_16x16x32_bf16 v[80:83], v[168:171], v[192:195], v[80:83]
	v_mfma_f32_16x16x32_bf16 v[72:75], v[160:163], v[210:213], v[72:75]
	v_mfma_f32_16x16x32_bf16 v[64:67], v[168:171], v[210:213], v[64:67]
	s_setprio 0
	s_barrier
; #define PG8_STAGE(bufoff, gbase, voff) do { _Pragma("unroll") for (int _i = 0; _i < 2; ++_i) \
;         __builtin_amdgcn_global_load_lds((const unsigned*)((const char*)(gbase) + (voff)[_i]), (PG8_LAS unsigned*)(lds + (bufoff) + ldsw + _i * 8192), 16, 0, 0); } while (0)
; #define PG8_LDA(dst, b, h) do { _Pragma("unroll") for (int m = 0; m < 4; ++m) _Pragma("unroll") for (int k = 0; k < 2; ++k) dst[m][k] = *(const PG8_LAS bf16x8*)(lds + PG8_SA(b, h) + aoff + m * 2048 + k * 1024); } while (0)
; #define PG8_WAIT_V(n) asm volatile("s_waitcnt vmcnt(" #n ")" ::: "memory")
; #define PG8_WAIT_L(n) asm volatile("s_waitcnt lgkmcnt(" #n ")" ::: "memory")
; #define PG8_BAR __builtin_amdgcn_s_barrier()
; template <class Epi, class Sched, bool ALIGN_EPI = false, bool SP2 = false>
; __device__ __forceinline__ void gemm_phase(PG8_LAS unsigned char* lds, const Gemm g, const Sched& S, const Epi& E, int wave_s_) {
;     ...
;         for (int t = 0; t < nt; t += 2) {
;             const bool last = (t == nt - 2);
;             const char* a1 = cA + (size_t)(t + 1) * kstep;
;             const char* a2 = last ? nA : cA + (size_t)(t + 2) * kstep; const char* b2 = last ? nB : cB + (size_t)(t + 2) * kstep;
;             const char* a3 = a2 + kstep; const char* b3 = b2 + kstep;
;             if (last && has_next) S.a_ready(nxt);
;             if constexpr (SP2) {
;             PG8_LDB(B0, 0, 0); PG8_LDB(B1, 0, 1); PG8_SCHED; PG8_LDA(At, 0, 0); PG8_STAGE(PG8_SA(1, 1), a1 + hstep, voffA);
;             PG8_WAIT_V(8); PG8_WAIT_L(0); PG8_BAR; PG8_MMA(0, 0, At, B0); PG8_MMA(0, 1, At, B1); PG8_BAR; PG8_SCHED;
;             PG8_LDA(At, 0, 1); PG8_STAGE(PG8_SB(0, 0), b2, voffB); PG8_STAGE(PG8_SB(0, 1), b2 + hstep, voffB); PG8_STAGE(PG8_SA(0, 0), a2, voffA);
;             PG8_WAIT_V(8); PG8_WAIT_L(0); PG8_BAR; PG8_MMA(1, 0, At, B0); PG8_MMA(1, 1, At, B1); PG8_BAR; PG8_SCHED;
;             PG8_LDB(B0, 1, 0); PG8_LDB(B1, 1, 1); PG8_SCHED; PG8_LDA(At, 1, 0); PG8_STAGE(PG8_SA(0, 1), a2 + hstep, voffA);
;             PG8_WAIT_V(8); PG8_WAIT_L(0); PG8_BAR; PG8_MMA(0, 0, At, B0); PG8_MMA(0, 1, At, B1); PG8_BAR; PG8_SCHED;
;             PG8_LDA(At, 1, 1); PG8_STAGE(PG8_SB(1, 0), b3, voffB); PG8_STAGE(PG8_SB(1, 1), b3 + hstep, voffB); PG8_STAGE(PG8_SA(1, 0), a3, voffA);
;             PG8_WAIT_V(8); PG8_WAIT_L(0); PG8_BAR; PG8_MMA(1, 0, At, B0); PG8_MMA(1, 1, At, B1); PG8_BAR; PG8_SCHED;
	s_add_i32 s26, s50, s34
	v_lshl_add_u64 v[214:215], v[214:215], 0, s[76:77]
	s_mov_b32 m0, s26
	ds_read_b128 v[172:175], v139 offset:49152
	ds_read_b128 v[176:179], v139 offset:50176
	ds_read_b128 v[180:183], v139 offset:51200
	ds_read_b128 v[184:187], v139 offset:52224
	ds_read_b128 v[188:191], v139 offset:53248
	ds_read_b128 v[192:195], v139 offset:54272
	ds_read_b128 v[206:209], v139 offset:55296
	ds_read_b128 v[210:213], v139 offset:56320
	global_load_lds_dwordx4 v[214:215], off
	s_add_i32 m0, s26, 0x2000
	s_add_u32 s24, s24, 0x40080
	v_lshl_add_u64 v[214:215], v[216:217], 0, s[76:77]
	s_addc_u32 s25, s25, 0
	s_add_i32 s26, s51, s34
	global_load_lds_dwordx4 v[214:215], off
	v_lshl_add_u64 v[214:215], s[24:25], 0, v[196:197]
	s_mov_b32 m0, s26
	s_nop 0
	global_load_lds_dwordx4 v[214:215], off
	v_lshl_add_u64 v[214:215], s[24:25], 0, v[132:133]
	s_add_i32 m0, s26, 0x2000
	s_nop 0
	global_load_lds_dwordx4 v[214:215], off
	v_lshl_add_u64 v[214:215], v[218:219], 0, s[76:77]
	s_mov_b32 m0, s41
	s_nop 0
	global_load_lds_dwordx4 v[214:215], off
	v_lshl_add_u64 v[214:215], v[220:221], 0, s[76:77]
	s_mov_b32 m0, s42
	s_nop 0
	global_load_lds_dwordx4 v[214:215], off
	s_waitcnt vmcnt(6)
	s_waitcnt lgkmcnt(0)
	s_barrier
	s_setprio 1
	s_waitcnt lgkmcnt(0)
	v_mfma_f32_16x16x32_bf16 v[60:63], v[140:143], v[172:175], v[60:63]
	v_mfma_f32_16x16x32_bf16 v[52:55], v[148:151], v[172:175], v[52:55]
	v_mfma_f32_16x16x32_bf16 v[44:47], v[140:143], v[180:183], v[44:47]
	v_mfma_f32_16x16x32_bf16 v[36:39], v[148:151], v[180:183], v[36:39]
	v_mfma_f32_16x16x32_bf16 v[28:31], v[140:143], v[188:191], v[28:31]
	v_mfma_f32_16x16x32_bf16 v[20:23], v[148:151], v[188:191], v[20:23]
	v_mfma_f32_16x16x32_bf16 v[12:15], v[140:143], v[206:209], v[12:15]
	v_mfma_f32_16x16x32_bf16 v[4:7], v[148:151], v[206:209], v[4:7]
	v_mfma_f32_16x16x32_bf16 v[60:63], v[144:147], v[176:179], v[60:63]
	v_mfma_f32_16x16x32_bf16 v[52:55], v[152:155], v[176:179], v[52:55]
	v_mfma_f32_16x16x32_bf16 v[44:47], v[144:147], v[184:187], v[44:47]
	v_mfma_f32_16x16x32_bf16 v[36:39], v[152:155], v[184:187], v[36:39]
	v_mfma_f32_16x16x32_bf16 v[28:31], v[144:147], v[192:195], v[28:31]
	v_mfma_f32_16x16x32_bf16 v[20:23], v[152:155], v[192:195], v[20:23]
	v_mfma_f32_16x16x32_bf16 v[12:15], v[144:147], v[210:213], v[12:15]
	v_mfma_f32_16x16x32_bf16 v[4:7], v[152:155], v[210:213], v[4:7]
	s_setprio 0
	s_setprio 1
	v_mfma_f32_16x16x32_bf16 v[56:59], v[156:159], v[172:175], v[56:59]
	v_mfma_f32_16x16x32_bf16 v[48:51], v[164:167], v[172:175], v[48:51]
	v_mfma_f32_16x16x32_bf16 v[40:43], v[156:159], v[180:183], v[40:43]
	v_mfma_f32_16x16x32_bf16 v[32:35], v[164:167], v[180:183], v[32:35]
	v_mfma_f32_16x16x32_bf16 v[24:27], v[156:159], v[188:191], v[24:27]
	v_mfma_f32_16x16x32_bf16 v[16:19], v[164:167], v[188:191], v[16:19]
	v_mfma_f32_16x16x32_bf16 v[8:11], v[156:159], v[206:209], v[8:11]
	v_mfma_f32_16x16x32_bf16 v[0:3], v[164:167], v[206:209], v[0:3]
	v_mfma_f32_16x16x32_bf16 v[56:59], v[160:163], v[176:179], v[56:59]
	v_mfma_f32_16x16x32_bf16 v[48:51], v[168:171], v[176:179], v[48:51]
	v_mfma_f32_16x16x32_bf16 v[40:43], v[160:163], v[184:187], v[40:43]
	v_mfma_f32_16x16x32_bf16 v[32:35], v[168:171], v[184:187], v[32:35]
	v_mfma_f32_16x16x32_bf16 v[24:27], v[160:163], v[192:195], v[24:27]
	v_mfma_f32_16x16x32_bf16 v[16:19], v[168:171], v[192:195], v[16:19]
	v_mfma_f32_16x16x32_bf16 v[8:11], v[160:163], v[210:213], v[8:11]
	v_mfma_f32_16x16x32_bf16 v[0:3], v[168:171], v[210:213], v[0:3]
	s_setprio 0
	s_barrier
	s_add_i32 s49, s49, 2
	s_add_u32 s17, s17, 0x100
	s_addc_u32 s48, s48, 0
	s_add_u32 s22, s22, 0x100
	s_addc_u32 s23, s23, 0
	s_cmp_gt_u32 s49, 13
	s_cbranch_scc0 .LBB0_207
	s_branch .Lpeel_exit_0
.LBB0_207:
	s_add_u32 s24, s22, 0xfffc0080
	s_addc_u32 s25, s23, -1
	s_add_i32 s50, 0, 0x10000
	s_cmp_eq_u32 s49, 12
	s_cselect_b32 s27, s9, s25
	s_cselect_b32 s26, s8, s24
	s_cselect_b32 s25, s19, s48
	s_cselect_b32 s24, s18, s17
	s_add_i32 s52, 0, 0x14000
	v_add_u32_e32 v152, s50, v138
	v_add_u32_e32 v168, s52, v138
	ds_read_b128 v[140:143], v152
	ds_read_b128 v[144:147], v152 offset:1024
	ds_read_b128 v[148:151], v152 offset:2048
	ds_read_b128 v[152:155], v152 offset:3072
	ds_read_b128 v[156:159], v168
	ds_read_b128 v[160:163], v168 offset:1024
	ds_read_b128 v[164:167], v168 offset:2048
	ds_read_b128 v[168:171], v168 offset:3072
	v_lshl_add_u64 v[214:215], s[22:23], 0, v[136:137]
	s_add_i32 m0, s35, 0xc000
	ds_read_b128 v[172:175], v139
	ds_read_b128 v[176:179], v139 offset:1024
	ds_read_b128 v[180:183], v139 offset:2048
	ds_read_b128 v[184:187], v139 offset:3072
	ds_read_b128 v[188:191], v139 offset:4096
	ds_read_b128 v[192:195], v139 offset:5120
	ds_read_b128 v[206:209], v139 offset:6144
	ds_read_b128 v[210:213], v139 offset:7168
	global_load_lds_dwordx4 v[214:215], off
	v_lshl_add_u64 v[214:215], s[22:23], 0, v[134:135]
	s_add_i32 m0, s35, 0xe000
	s_nop 0
	global_load_lds_dwordx4 v[214:215], off
	s_waitcnt vmcnt(8)
	s_waitcnt lgkmcnt(0)
	s_barrier
; #define PG8_STAGE(bufoff, gbase, voff) do { _Pragma("unroll") for (int _i = 0; _i < 2; ++_i) \
;         __builtin_amdgcn_global_load_lds((const unsigned*)((const char*)(gbase) + (voff)[_i]), (PG8_LAS unsigned*)(lds + (bufoff) + ldsw + _i * 8192), 16, 0, 0); } while (0)
; #define PG8_LDA(dst, b, h) do { _Pragma("unroll") for (int m = 0; m < 4; ++m) _Pragma("unroll") for (int k = 0; k < 2; ++k) dst[m][k] = *(const PG8_LAS bf16x8*)(lds + PG8_SA(b, h) + aoff + m * 2048 + k * 1024); } while (0)
; #define PG8_MMA(ai, bj, At, Bt) do { __builtin_amdgcn_s_setprio(1); _Pragma("unroll") for (int m = 0; m < 4; ++m) _Pragma("unroll") for (int n = 0; n < 2; ++n) _Pragma("unroll") for (int k = 0; k < 2; ++k) \
;         acc[ai][bj][m][n] = __builtin_amdgcn_mfma_f32_16x16x32_bf16(Bt[n][k], At[m][k], acc[ai][bj][m][n], 0, 0, 0); __builtin_amdgcn_s_setprio(0); } while (0)
; #define PG8_WAIT_V(n) asm volatile("s_waitcnt vmcnt(" #n ")" ::: "memory")
; #define PG8_WAIT_L(n) asm volatile("s_waitcnt lgkmcnt(" #n ")" ::: "memory")
; #define PG8_BAR __builtin_amdgcn_s_barrier()
; #define PG8_SCHED __builtin_amdgcn_sched_barrier(0)
; template <class Epi, class Sched, bool ALIGN_EPI = false, bool SP2 = false>
; __device__ __forceinline__ void gemm_phase(PG8_LAS unsigned char* lds, const Gemm g, const Sched& S, const Epi& E, int wave_s_) {
;     ...
;             PG8_WAIT_V(8); PG8_WAIT_L(0); PG8_BAR; PG8_MMA(0, 0, At, B0); PG8_MMA(0, 1, At, B1); PG8_BAR; PG8_SCHED;
;             PG8_LDA(At, 0, 1); PG8_STAGE(PG8_SB(0, 0), b2, voffB); PG8_STAGE(PG8_SB(0, 1), b2 + hstep, voffB); PG8_STAGE(PG8_SA(0, 0), a2, voffA);
;             PG8_WAIT_V(8); PG8_WAIT_L(0); PG8_BAR; PG8_MMA(1, 0, At, B0); PG8_MMA(1, 1, At, B1); PG8_BAR; PG8_SCHED;
	s_setprio 1
	s_waitcnt lgkmcnt(0)
	v_mfma_f32_16x16x32_bf16 v[124:127], v[140:143], v[172:175], v[124:127]
	v_mfma_f32_16x16x32_bf16 v[116:119], v[148:151], v[172:175], v[116:119]
	v_mfma_f32_16x16x32_bf16 v[108:111], v[140:143], v[180:183], v[108:111]
	v_mfma_f32_16x16x32_bf16 v[100:103], v[148:151], v[180:183], v[100:103]
	v_mfma_f32_16x16x32_bf16 v[92:95], v[140:143], v[188:191], v[92:95]
	v_mfma_f32_16x16x32_bf16 v[84:87], v[148:151], v[188:191], v[84:87]
	v_mfma_f32_16x16x32_bf16 v[76:79], v[140:143], v[206:209], v[76:79]
	v_mfma_f32_16x16x32_bf16 v[68:71], v[148:151], v[206:209], v[68:71]
	v_mfma_f32_16x16x32_bf16 v[124:127], v[144:147], v[176:179], v[124:127]
	v_mfma_f32_16x16x32_bf16 v[116:119], v[152:155], v[176:179], v[116:119]
	v_mfma_f32_16x16x32_bf16 v[108:111], v[144:147], v[184:187], v[108:111]
	v_mfma_f32_16x16x32_bf16 v[100:103], v[152:155], v[184:187], v[100:103]
	v_mfma_f32_16x16x32_bf16 v[92:95], v[144:147], v[192:195], v[92:95]
	v_mfma_f32_16x16x32_bf16 v[84:87], v[152:155], v[192:195], v[84:87]
	v_mfma_f32_16x16x32_bf16 v[76:79], v[144:147], v[210:213], v[76:79]
	v_mfma_f32_16x16x32_bf16 v[68:71], v[152:155], v[210:213], v[68:71]
	s_setprio 0
	s_setprio 1
	v_mfma_f32_16x16x32_bf16 v[120:123], v[156:159], v[172:175], v[120:123]
	v_mfma_f32_16x16x32_bf16 v[112:115], v[164:167], v[172:175], v[112:115]
	v_mfma_f32_16x16x32_bf16 v[104:107], v[156:159], v[180:183], v[104:107]
	v_mfma_f32_16x16x32_bf16 v[96:99], v[164:167], v[180:183], v[96:99]
	v_mfma_f32_16x16x32_bf16 v[88:91], v[156:159], v[188:191], v[88:91]
	v_mfma_f32_16x16x32_bf16 v[80:83], v[164:167], v[188:191], v[80:83]
	v_mfma_f32_16x16x32_bf16 v[72:75], v[156:159], v[206:209], v[72:75]
	v_mfma_f32_16x16x32_bf16 v[64:67], v[164:167], v[206:209], v[64:67]
	v_mfma_f32_16x16x32_bf16 v[120:123], v[160:163], v[176:179], v[120:123]
	v_mfma_f32_16x16x32_bf16 v[112:115], v[168:171], v[176:179], v[112:115]
	v_mfma_f32_16x16x32_bf16 v[104:107], v[160:163], v[184:187], v[104:107]
	v_mfma_f32_16x16x32_bf16 v[96:99], v[168:171], v[184:187], v[96:99]
	v_mfma_f32_16x16x32_bf16 v[88:91], v[160:163], v[192:195], v[88:91]
	v_mfma_f32_16x16x32_bf16 v[80:83], v[168:171], v[192:195], v[80:83]
	v_mfma_f32_16x16x32_bf16 v[72:75], v[160:163], v[210:213], v[72:75]
	v_mfma_f32_16x16x32_bf16 v[64:67], v[168:171], v[210:213], v[64:67]
	s_setprio 0
	s_barrier
	s_add_i32 s50, s50, s34
	v_lshl_add_u64 v[214:215], s[24:25], 0, v[196:197]
	s_mov_b32 m0, s50
	ds_read_b128 v[172:175], v139 offset:16384
	ds_read_b128 v[176:179], v139 offset:17408
	ds_read_b128 v[180:183], v139 offset:18432
	ds_read_b128 v[184:187], v139 offset:19456
	ds_read_b128 v[188:191], v139 offset:20480
	ds_read_b128 v[192:195], v139 offset:21504
	ds_read_b128 v[206:209], v139 offset:22528
	ds_read_b128 v[210:213], v139 offset:23552
	global_load_lds_dwordx4 v[214:215], off
	s_add_i32 m0, s50, 0x2000
	s_add_u32 s50, s24, 0x40000
	v_lshl_add_u64 v[216:217], s[24:25], 0, v[132:133]
	s_addc_u32 s51, s25, 0
	s_add_i32 s52, s52, s34
	global_load_lds_dwordx4 v[216:217], off
	v_lshl_add_u64 v[218:219], s[50:51], 0, v[196:197]
	s_mov_b32 m0, s52
	v_lshl_add_u64 v[220:221], s[26:27], 0, v[130:131]
	global_load_lds_dwordx4 v[218:219], off
	v_lshl_add_u64 v[218:219], s[50:51], 0, v[132:133]
	s_add_i32 m0, s52, 0x2000
	s_nop 0
	global_load_lds_dwordx4 v[218:219], off
	v_lshl_add_u64 v[218:219], s[26:27], 0, v[128:129]
	s_waitcnt vmcnt(6)
	s_waitcnt lgkmcnt(0)
	s_barrier
	s_setprio 1
	s_waitcnt lgkmcnt(0)
	v_mfma_f32_16x16x32_bf16 v[60:63], v[140:143], v[172:175], v[60:63]
	v_mfma_f32_16x16x32_bf16 v[52:55], v[148:151], v[172:175], v[52:55]
	v_mfma_f32_16x16x32_bf16 v[44:47], v[140:143], v[180:183], v[44:47]
	v_mfma_f32_16x16x32_bf16 v[36:39], v[148:151], v[180:183], v[36:39]
	v_mfma_f32_16x16x32_bf16 v[28:31], v[140:143], v[188:191], v[28:31]
	v_mfma_f32_16x16x32_bf16 v[20:23], v[148:151], v[188:191], v[20:23]
	v_mfma_f32_16x16x32_bf16 v[12:15], v[140:143], v[206:209], v[12:15]
	v_mfma_f32_16x16x32_bf16 v[4:7], v[148:151], v[206:209], v[4:7]
	v_mfma_f32_16x16x32_bf16 v[60:63], v[144:147], v[176:179], v[60:63]
	v_mfma_f32_16x16x32_bf16 v[52:55], v[152:155], v[176:179], v[52:55]
	v_mfma_f32_16x16x32_bf16 v[44:47], v[144:147], v[184:187], v[44:47]
	v_mfma_f32_16x16x32_bf16 v[36:39], v[152:155], v[184:187], v[36:39]
	v_mfma_f32_16x16x32_bf16 v[28:31], v[144:147], v[192:195], v[28:31]
	v_mfma_f32_16x16x32_bf16 v[20:23], v[152:155], v[192:195], v[20:23]
	v_mfma_f32_16x16x32_bf16 v[12:15], v[144:147], v[210:213], v[12:15]
	v_mfma_f32_16x16x32_bf16 v[4:7], v[152:155], v[210:213], v[4:7]
	s_setprio 0
	s_setprio 1
	v_mfma_f32_16x16x32_bf16 v[56:59], v[156:159], v[172:175], v[56:59]
	v_mfma_f32_16x16x32_bf16 v[48:51], v[164:167], v[172:175], v[48:51]
	v_mfma_f32_16x16x32_bf16 v[40:43], v[156:159], v[180:183], v[40:43]
	v_mfma_f32_16x16x32_bf16 v[32:35], v[164:167], v[180:183], v[32:35]
	v_mfma_f32_16x16x32_bf16 v[24:27], v[156:159], v[188:191], v[24:27]
	v_mfma_f32_16x16x32_bf16 v[16:19], v[164:167], v[188:191], v[16:19]
	v_mfma_f32_16x16x32_bf16 v[8:11], v[156:159], v[206:209], v[8:11]
	v_mfma_f32_16x16x32_bf16 v[0:3], v[164:167], v[206:209], v[0:3]
	v_mfma_f32_16x16x32_bf16 v[56:59], v[160:163], v[176:179], v[56:59]
	v_mfma_f32_16x16x32_bf16 v[48:51], v[168:171], v[176:179], v[48:51]
	v_mfma_f32_16x16x32_bf16 v[40:43], v[160:163], v[184:187], v[40:43]
	v_mfma_f32_16x16x32_bf16 v[32:35], v[168:171], v[184:187], v[32:35]
	v_mfma_f32_16x16x32_bf16 v[24:27], v[160:163], v[192:195], v[24:27]
	v_mfma_f32_16x16x32_bf16 v[16:19], v[168:171], v[192:195], v[16:19]
	v_mfma_f32_16x16x32_bf16 v[8:11], v[160:163], v[210:213], v[8:11]
	v_mfma_f32_16x16x32_bf16 v[0:3], v[168:171], v[210:213], v[0:3]
	s_setprio 0
	s_barrier
; #define PG8_STAGE(bufoff, gbase, voff) do { _Pragma("unroll") for (int _i = 0; _i < 2; ++_i) \
;         __builtin_amdgcn_global_load_lds((const unsigned*)((const char*)(gbase) + (voff)[_i]), (PG8_LAS unsigned*)(lds + (bufoff) + ldsw + _i * 8192), 16, 0, 0); } while (0)
; #define PG8_LDA(dst, b, h) do { _Pragma("unroll") for (int m = 0; m < 4; ++m) _Pragma("unroll") for (int k = 0; k < 2; ++k) dst[m][k] = *(const PG8_LAS bf16x8*)(lds + PG8_SA(b, h) + aoff + m * 2048 + k * 1024); } while (0)
; #define PG8_LDB(dst, b, h) do { _Pragma("unroll") for (int n = 0; n < 2; ++n) _Pragma("unroll") for (int k = 0; k < 2; ++k) dst[n][k] = *(const PG8_LAS bf16x8*)(lds + PG8_SB(b, h) + boff + n * 2048 + k * 1024); } while (0)
; #define PG8_MMA(ai, bj, At, Bt) do { __builtin_amdgcn_s_setprio(1); _Pragma("unroll") for (int m = 0; m < 4; ++m) _Pragma("unroll") for (int n = 0; n < 2; ++n) _Pragma("unroll") for (int k = 0; k < 2; ++k) \
;         acc[ai][bj][m][n] = __builtin_amdgcn_mfma_f32_16x16x32_bf16(Bt[n][k], At[m][k], acc[ai][bj][m][n], 0, 0, 0); __builtin_amdgcn_s_setprio(0); } while (0)
; #define PG8_WAIT_V(n) asm volatile("s_waitcnt vmcnt(" #n ")" ::: "memory")
; #define PG8_WAIT_L(n) asm volatile("s_waitcnt lgkmcnt(" #n ")" ::: "memory")
; #define PG8_BAR __builtin_amdgcn_s_barrier()
; #define PG8_SCHED __builtin_amdgcn_sched_barrier(0)
; template <class Epi, class Sched, bool ALIGN_EPI = false, bool SP2 = false>
; __device__ __forceinline__ void gemm_phase(PG8_LAS unsigned char* lds, const Gemm g, const Sched& S, const Epi& E, int wave_s_) {
;     ...
;             PG8_LDB(B0, 1, 0); PG8_LDB(B1, 1, 1); PG8_SCHED; PG8_LDA(At, 1, 0); PG8_STAGE(PG8_SA(0, 1), a2 + hstep, voffA);
;             PG8_WAIT_V(8); PG8_WAIT_L(0); PG8_BAR; PG8_MMA(0, 0, At, B0); PG8_MMA(0, 1, At, B1); PG8_BAR; PG8_SCHED;
	s_add_i32 s50, 0, 0x18000
	s_add_i32 s51, 0, 0x1c000
	v_add_u32_e32 v152, s50, v138
	v_add_u32_e32 v168, s51, v138
	ds_read_b128 v[140:143], v152
	ds_read_b128 v[144:147], v152 offset:1024
	ds_read_b128 v[148:151], v152 offset:2048
	ds_read_b128 v[152:155], v152 offset:3072
	ds_read_b128 v[156:159], v168
	ds_read_b128 v[160:163], v168 offset:1024
	ds_read_b128 v[164:167], v168 offset:2048
	ds_read_b128 v[168:171], v168 offset:3072
	s_add_u32 s26, s26, 0x40000
	s_addc_u32 s27, s27, 0
	s_mov_b32 m0, s37
	v_lshl_add_u64 v[222:223], s[26:27], 0, v[128:129]
	ds_read_b128 v[172:175], v139 offset:32768
	ds_read_b128 v[176:179], v139 offset:33792
	ds_read_b128 v[180:183], v139 offset:34816
	ds_read_b128 v[184:187], v139 offset:35840
	ds_read_b128 v[188:191], v139 offset:36864
	ds_read_b128 v[192:195], v139 offset:37888
	ds_read_b128 v[206:209], v139 offset:38912
	ds_read_b128 v[210:213], v139 offset:39936
	global_load_lds_dwordx4 v[222:223], off
	v_lshl_add_u64 v[222:223], s[26:27], 0, v[130:131]
	s_mov_b32 m0, s38
	s_nop 0
	global_load_lds_dwordx4 v[222:223], off
	s_mov_b32 m0, s35
	s_nop 0
	global_load_lds_dwordx4 v[218:219], off
	s_mov_b32 m0, s36
	s_nop 0
	global_load_lds_dwordx4 v[220:221], off
	s_waitcnt vmcnt(8)
	s_waitcnt lgkmcnt(0)
	s_barrier
	s_setprio 1
	s_waitcnt lgkmcnt(0)
	v_mfma_f32_16x16x32_bf16 v[124:127], v[140:143], v[172:175], v[124:127]
	v_mfma_f32_16x16x32_bf16 v[116:119], v[148:151], v[172:175], v[116:119]
	v_mfma_f32_16x16x32_bf16 v[108:111], v[140:143], v[180:183], v[108:111]
	v_mfma_f32_16x16x32_bf16 v[100:103], v[148:151], v[180:183], v[100:103]
	v_mfma_f32_16x16x32_bf16 v[92:95], v[140:143], v[188:191], v[92:95]
	v_mfma_f32_16x16x32_bf16 v[84:87], v[148:151], v[188:191], v[84:87]
	v_mfma_f32_16x16x32_bf16 v[76:79], v[140:143], v[206:209], v[76:79]
	v_mfma_f32_16x16x32_bf16 v[68:71], v[148:151], v[206:209], v[68:71]
	v_mfma_f32_16x16x32_bf16 v[124:127], v[144:147], v[176:179], v[124:127]
	v_mfma_f32_16x16x32_bf16 v[116:119], v[152:155], v[176:179], v[116:119]
	v_mfma_f32_16x16x32_bf16 v[108:111], v[144:147], v[184:187], v[108:111]
	v_mfma_f32_16x16x32_bf16 v[100:103], v[152:155], v[184:187], v[100:103]
	v_mfma_f32_16x16x32_bf16 v[92:95], v[144:147], v[192:195], v[92:95]
	v_mfma_f32_16x16x32_bf16 v[84:87], v[152:155], v[192:195], v[84:87]
	v_mfma_f32_16x16x32_bf16 v[76:79], v[144:147], v[210:213], v[76:79]
	v_mfma_f32_16x16x32_bf16 v[68:71], v[152:155], v[210:213], v[68:71]
	s_setprio 0
	s_setprio 1
	v_mfma_f32_16x16x32_bf16 v[120:123], v[156:159], v[172:175], v[120:123]
	v_mfma_f32_16x16x32_bf16 v[112:115], v[164:167], v[172:175], v[112:115]
	v_mfma_f32_16x16x32_bf16 v[104:107], v[156:159], v[180:183], v[104:107]
	v_mfma_f32_16x16x32_bf16 v[96:99], v[164:167], v[180:183], v[96:99]
	v_mfma_f32_16x16x32_bf16 v[88:91], v[156:159], v[188:191], v[88:91]
	v_mfma_f32_16x16x32_bf16 v[80:83], v[164:167], v[188:191], v[80:83]
	v_mfma_f32_16x16x32_bf16 v[72:75], v[156:159], v[206:209], v[72:75]
	v_mfma_f32_16x16x32_bf16 v[64:67], v[164:167], v[206:209], v[64:67]
	v_mfma_f32_16x16x32_bf16 v[120:123], v[160:163], v[176:179], v[120:123]
	v_mfma_f32_16x16x32_bf16 v[112:115], v[168:171], v[176:179], v[112:115]
	v_mfma_f32_16x16x32_bf16 v[104:107], v[160:163], v[184:187], v[104:107]
	v_mfma_f32_16x16x32_bf16 v[96:99], v[168:171], v[184:187], v[96:99]
	v_mfma_f32_16x16x32_bf16 v[88:91], v[160:163], v[192:195], v[88:91]
	v_mfma_f32_16x16x32_bf16 v[80:83], v[168:171], v[192:195], v[80:83]
	v_mfma_f32_16x16x32_bf16 v[72:75], v[160:163], v[210:213], v[72:75]
	v_mfma_f32_16x16x32_bf16 v[64:67], v[168:171], v[210:213], v[64:67]
	s_setprio 0
	s_barrier
; #define PG8_STAGE(bufoff, gbase, voff) do { _Pragma("unroll") for (int _i = 0; _i < 2; ++_i) \
;         __builtin_amdgcn_global_load_lds((const unsigned*)((const char*)(gbase) + (voff)[_i]), (PG8_LAS unsigned*)(lds + (bufoff) + ldsw + _i * 8192), 16, 0, 0); } while (0)
; #define PG8_LDA(dst, b, h) do { _Pragma("unroll") for (int m = 0; m < 4; ++m) _Pragma("unroll") for (int k = 0; k < 2; ++k) dst[m][k] = *(const PG8_LAS bf16x8*)(lds + PG8_SA(b, h) + aoff + m * 2048 + k * 1024); } while (0)
; #define PG8_WAIT_V(n) asm volatile("s_waitcnt vmcnt(" #n ")" ::: "memory")
; #define PG8_WAIT_L(n) asm volatile("s_waitcnt lgkmcnt(" #n ")" ::: "memory")
; #define PG8_BAR __builtin_amdgcn_s_barrier()
; template <class Epi, class Sched, bool ALIGN_EPI = false, bool SP2 = false>
; __device__ __forceinline__ void gemm_phase(PG8_LAS unsigned char* lds, const Gemm g, const Sched& S, const Epi& E, int wave_s_) {
;     ...
;         for (int t = 0; t < nt; t += 2) {
;             const bool last = (t == nt - 2);
;             const char* a1 = cA + (size_t)(t + 1) * kstep;
;             const char* a2 = last ? nA : cA + (size_t)(t + 2) * kstep; const char* b2 = last ? nB : cB + (size_t)(t + 2) * kstep;
;             const char* a3 = a2 + kstep; const char* b3 = b2 + kstep;
;             if (last && has_next) S.a_ready(nxt);
;             if constexpr (SP2) {
;             PG8_LDB(B0, 0, 0); PG8_LDB(B1, 0, 1); PG8_SCHED; PG8_LDA(At, 0, 0); PG8_STAGE(PG8_SA(1, 1), a1 + hstep, voffA);
;             PG8_WAIT_V(8); PG8_WAIT_L(0); PG8_BAR; PG8_MMA(0, 0, At, B0); PG8_MMA(0, 1, At, B1); PG8_BAR; PG8_SCHED;
;             PG8_LDA(At, 0, 1); PG8_STAGE(PG8_SB(0, 0), b2, voffB); PG8_STAGE(PG8_SB(0, 1), b2 + hstep, voffB); PG8_STAGE(PG8_SA(0, 0), a2, voffA);
;             PG8_WAIT_V(8); PG8_WAIT_L(0); PG8_BAR; PG8_MMA(1, 0, At, B0); PG8_MMA(1, 1, At, B1); PG8_BAR; PG8_SCHED;
;             PG8_LDB(B0, 1, 0); PG8_LDB(B1, 1, 1); PG8_SCHED; PG8_LDA(At, 1, 0); PG8_STAGE(PG8_SA(0, 1), a2 + hstep, voffA);
;             PG8_WAIT_V(8); PG8_WAIT_L(0); PG8_BAR; PG8_MMA(0, 0, At, B0); PG8_MMA(0, 1, At, B1); PG8_BAR; PG8_SCHED;
;             PG8_LDA(At, 1, 1); PG8_STAGE(PG8_SB(1, 0), b3, voffB); PG8_STAGE(PG8_SB(1, 1), b3 + hstep, voffB); PG8_STAGE(PG8_SA(1, 0), a3, voffA);
;             PG8_WAIT_V(8); PG8_WAIT_L(0); PG8_BAR; PG8_MMA(1, 0, At, B0); PG8_MMA(1, 1, At, B1); PG8_BAR; PG8_SCHED;
	s_add_i32 s26, s50, s34
	v_lshl_add_u64 v[214:215], v[214:215], 0, s[76:77]
	s_mov_b32 m0, s26
	ds_read_b128 v[172:175], v139 offset:49152
	ds_read_b128 v[176:179], v139 offset:50176
	ds_read_b128 v[180:183], v139 offset:51200
	ds_read_b128 v[184:187], v139 offset:52224
	ds_read_b128 v[188:191], v139 offset:53248
	ds_read_b128 v[192:195], v139 offset:54272
	ds_read_b128 v[206:209], v139 offset:55296
	ds_read_b128 v[210:213], v139 offset:56320
	global_load_lds_dwordx4 v[214:215], off
	s_add_i32 m0, s26, 0x2000
	s_add_u32 s24, s24, 0x40080
	v_lshl_add_u64 v[214:215], v[216:217], 0, s[76:77]
	s_addc_u32 s25, s25, 0
	s_add_i32 s26, s51, s34
	global_load_lds_dwordx4 v[214:215], off
	v_lshl_add_u64 v[214:215], s[24:25], 0, v[196:197]
	s_mov_b32 m0, s26
	s_nop 0
	global_load_lds_dwordx4 v[214:215], off
	v_lshl_add_u64 v[214:215], s[24:25], 0, v[132:133]
	s_add_i32 m0, s26, 0x2000
	s_nop 0
	global_load_lds_dwordx4 v[214:215], off
	v_lshl_add_u64 v[214:215], v[218:219], 0, s[76:77]
	s_mov_b32 m0, s41
	s_nop 0
	global_load_lds_dwordx4 v[214:215], off
	v_lshl_add_u64 v[214:215], v[220:221], 0, s[76:77]
	s_mov_b32 m0, s42
	s_nop 0
	global_load_lds_dwordx4 v[214:215], off
	s_waitcnt vmcnt(6)
	s_waitcnt lgkmcnt(0)
	s_barrier
	s_setprio 1
	s_waitcnt lgkmcnt(0)
	v_mfma_f32_16x16x32_bf16 v[60:63], v[140:143], v[172:175], v[60:63]
	v_mfma_f32_16x16x32_bf16 v[52:55], v[148:151], v[172:175], v[52:55]
	v_mfma_f32_16x16x32_bf16 v[44:47], v[140:143], v[180:183], v[44:47]
	v_mfma_f32_16x16x32_bf16 v[36:39], v[148:151], v[180:183], v[36:39]
	v_mfma_f32_16x16x32_bf16 v[28:31], v[140:143], v[188:191], v[28:31]
	v_mfma_f32_16x16x32_bf16 v[20:23], v[148:151], v[188:191], v[20:23]
	v_mfma_f32_16x16x32_bf16 v[12:15], v[140:143], v[206:209], v[12:15]
	v_mfma_f32_16x16x32_bf16 v[4:7], v[148:151], v[206:209], v[4:7]
	v_mfma_f32_16x16x32_bf16 v[60:63], v[144:147], v[176:179], v[60:63]
	v_mfma_f32_16x16x32_bf16 v[52:55], v[152:155], v[176:179], v[52:55]
	v_mfma_f32_16x16x32_bf16 v[44:47], v[144:147], v[184:187], v[44:47]
	v_mfma_f32_16x16x32_bf16 v[36:39], v[152:155], v[184:187], v[36:39]
	v_mfma_f32_16x16x32_bf16 v[28:31], v[144:147], v[192:195], v[28:31]
	v_mfma_f32_16x16x32_bf16 v[20:23], v[152:155], v[192:195], v[20:23]
	v_mfma_f32_16x16x32_bf16 v[12:15], v[144:147], v[210:213], v[12:15]
	v_mfma_f32_16x16x32_bf16 v[4:7], v[152:155], v[210:213], v[4:7]
	s_setprio 0
	s_setprio 1
	v_mfma_f32_16x16x32_bf16 v[56:59], v[156:159], v[172:175], v[56:59]
	v_mfma_f32_16x16x32_bf16 v[48:51], v[164:167], v[172:175], v[48:51]
	v_mfma_f32_16x16x32_bf16 v[40:43], v[156:159], v[180:183], v[40:43]
	v_mfma_f32_16x16x32_bf16 v[32:35], v[164:167], v[180:183], v[32:35]
	v_mfma_f32_16x16x32_bf16 v[24:27], v[156:159], v[188:191], v[24:27]
	v_mfma_f32_16x16x32_bf16 v[16:19], v[164:167], v[188:191], v[16:19]
	v_mfma_f32_16x16x32_bf16 v[8:11], v[156:159], v[206:209], v[8:11]
	v_mfma_f32_16x16x32_bf16 v[0:3], v[164:167], v[206:209], v[0:3]
	v_mfma_f32_16x16x32_bf16 v[56:59], v[160:163], v[176:179], v[56:59]
	v_mfma_f32_16x16x32_bf16 v[48:51], v[168:171], v[176:179], v[48:51]
	v_mfma_f32_16x16x32_bf16 v[40:43], v[160:163], v[184:187], v[40:43]
	v_mfma_f32_16x16x32_bf16 v[32:35], v[168:171], v[184:187], v[32:35]
	v_mfma_f32_16x16x32_bf16 v[24:27], v[160:163], v[192:195], v[24:27]
	v_mfma_f32_16x16x32_bf16 v[16:19], v[168:171], v[192:195], v[16:19]
	v_mfma_f32_16x16x32_bf16 v[8:11], v[160:163], v[210:213], v[8:11]
	v_mfma_f32_16x16x32_bf16 v[0:3], v[168:171], v[210:213], v[0:3]
	s_setprio 0
	s_barrier
	s_add_i32 s49, s49, 2
	s_add_u32 s17, s17, 0x100
	s_addc_u32 s48, s48, 0
	s_add_u32 s22, s22, 0x100
	s_addc_u32 s23, s23, 0
	s_cmp_gt_u32 s49, 13
	s_cbranch_scc0 .LBB0_207

; #define PG8_STAGE(bufoff, gbase, voff) do { _Pragma("unroll") for (int _i = 0; _i < 2; ++_i) \
;         __builtin_amdgcn_global_load_lds((const unsigned*)((const char*)(gbase) + (voff)[_i]), (PG8_LAS unsigned*)(lds + (bufoff) + ldsw + _i * 8192), 16, 0, 0); } while (0)
; #define PG8_LDA(dst, b, h) do { _Pragma("unroll") for (int m = 0; m < 4; ++m) _Pragma("unroll") for (int k = 0; k < 2; ++k) dst[m][k] = *(const PG8_LAS bf16x8*)(lds + PG8_SA(b, h) + aoff + m * 2048 + k * 1024); } while (0)
; #define PG8_LDB(dst, b, h) do { _Pragma("unroll") for (int n = 0; n < 2; ++n) _Pragma("unroll") for (int k = 0; k < 2; ++k) dst[n][k] = *(const PG8_LAS bf16x8*)(lds + PG8_SB(b, h) + boff + n * 2048 + k * 1024); } while (0)
; #define PG8_MMA(ai, bj, At, Bt) do { __builtin_amdgcn_s_setprio(1); _Pragma("unroll") for (int m = 0; m < 4; ++m) _Pragma("unroll") for (int n = 0; n < 2; ++n) _Pragma("unroll") for (int k = 0; k < 2; ++k) \
;         acc[ai][bj][m][n] = __builtin_amdgcn_mfma_f32_16x16x32_bf16(Bt[n][k], At[m][k], acc[ai][bj][m][n], 0, 0, 0); __builtin_amdgcn_s_setprio(0); } while (0)
; #define PG8_WAIT_V(n) asm volatile("s_waitcnt vmcnt(" #n ")" ::: "memory")
; #define PG8_BAR __builtin_amdgcn_s_barrier()
; template <class Epi, class Sched, bool ALIGN_EPI = false, bool SP2 = false>
; __device__ __forceinline__ void gemm_phase(PG8_LAS unsigned char* lds, const Gemm g, const Sched& S, const Epi& E, int wave_s_) {
;     ...
;         for (int t = 0; t < nt; t += 2) {
;             const bool last = (t == nt - 2);
;             const char* a1 = cA + (size_t)(t + 1) * kstep;
;             const char* a2 = last ? nA : cA + (size_t)(t + 2) * kstep; const char* b2 = last ? nB : cB + (size_t)(t + 2) * kstep;
;             const char* a3 = a2 + kstep; const char* b3 = b2 + kstep;
;             if (last && has_next) S.a_ready(nxt);
;             if constexpr (SP2) {
;             PG8_LDB(B0, 0, 0); PG8_LDB(B1, 0, 1); PG8_SCHED; PG8_LDA(At, 0, 0); PG8_STAGE(PG8_SA(1, 1), a1 + hstep, voffA);
;             PG8_WAIT_V(8); PG8_WAIT_L(0); PG8_BAR; PG8_MMA(0, 0, At, B0); PG8_MMA(0, 1, At, B1); PG8_BAR; PG8_SCHED;
;             PG8_LDA(At, 0, 1); PG8_STAGE(PG8_SB(0, 0), b2, voffB); PG8_STAGE(PG8_SB(0, 1), b2 + hstep, voffB); PG8_STAGE(PG8_SA(0, 0), a2, voffA);
;             PG8_WAIT_V(8); PG8_WAIT_L(0); PG8_BAR; PG8_MMA(1, 0, At, B0); PG8_MMA(1, 1, At, B1); PG8_BAR; PG8_SCHED;
.LBB0_297:
	s_cmpk_gt_u32 s57, 0xfff
	s_cselect_b64 s[30:31], -1, 0
	s_cmpk_lt_u32 s57, 0x1000
	s_cselect_b64 s[8:9], -1, 0
	s_and_b64 s[34:35], s[8:9], exec
	s_cselect_b32 s59, 44, 4
	s_add_i32 s60, s59, -2
	s_add_u32 s61, s12, 0x100
	v_mov_b32_e32 v0, 0
	s_addc_u32 s62, s13, 0
	s_mov_b32 s34, 0
	s_add_i32 s63, s34, 2
	s_add_u32 s12, s10, 0x100
	s_addc_u32 s13, s11, 0
	s_add_i32 s64, 0, 0x10000
	s_cmp_eq_u32 s60, s34
	s_cselect_b32 s37, s27, s13
	s_cselect_b32 s36, s26, s12
	s_cselect_b32 s35, s29, s62
	s_cselect_b32 s34, s28, s61
	s_add_i32 s65, 0, 0x14000
	v_add_u32_e32 v80, s64, v226
	v_add_u32_e32 v100, s65, v226
	ds_read_b128 v[64:67], v80
	ds_read_b128 v[68:71], v80 offset:1024
	ds_read_b128 v[76:79], v80 offset:2048
	ds_read_b128 v[80:83], v80 offset:3072
	ds_read_b128 v[88:91], v100
	ds_read_b128 v[92:95], v100 offset:1024
	ds_read_b128 v[96:99], v100 offset:2048
	ds_read_b128 v[100:103], v100 offset:3072
	v_lshl_add_u64 v[208:209], s[10:11], 0, v[206:207]
	s_add_i32 m0, s42, 0xc000
	ds_read_b128 v[160:163], v227
	ds_read_b128 v[164:167], v227 offset:1024
	ds_read_b128 v[168:171], v227 offset:2048
	ds_read_b128 v[172:175], v227 offset:3072
	ds_read_b128 v[176:179], v227 offset:4096
	ds_read_b128 v[180:183], v227 offset:5120
	ds_read_b128 v[184:187], v227 offset:6144
	ds_read_b128 v[188:191], v227 offset:7168
	global_load_lds_dwordx4 v[208:209], off
	v_lshl_add_u64 v[208:209], s[10:11], 0, v[194:195]
	s_add_i32 m0, s42, 0xe000
	s_nop 0
	global_load_lds_dwordx4 v[208:209], off
	s_waitcnt vmcnt(8)
	s_waitcnt lgkmcnt(0)
	s_barrier
	s_setprio 1
	s_waitcnt lgkmcnt(0)
	v_mfma_f32_16x16x32_bf16 v[156:159], v[64:67], v[160:163], 0
	v_mfma_f32_16x16x32_bf16 v[152:155], v[76:79], v[160:163], 0
	v_mfma_f32_16x16x32_bf16 v[144:147], v[64:67], v[168:171], 0
	v_mfma_f32_16x16x32_bf16 v[136:139], v[76:79], v[168:171], 0
	v_mfma_f32_16x16x32_bf16 v[124:127], v[64:67], v[176:179], 0
	v_mfma_f32_16x16x32_bf16 v[120:123], v[76:79], v[176:179], 0
	v_mfma_f32_16x16x32_bf16 v[112:115], v[64:67], v[184:187], 0
	v_mfma_f32_16x16x32_bf16 v[104:107], v[76:79], v[184:187], 0
	v_mfma_f32_16x16x32_bf16 v[156:159], v[68:71], v[164:167], v[156:159]
	v_mfma_f32_16x16x32_bf16 v[152:155], v[80:83], v[164:167], v[152:155]
	v_mfma_f32_16x16x32_bf16 v[144:147], v[68:71], v[172:175], v[144:147]
	v_mfma_f32_16x16x32_bf16 v[136:139], v[80:83], v[172:175], v[136:139]
	v_mfma_f32_16x16x32_bf16 v[124:127], v[68:71], v[180:183], v[124:127]
	v_mfma_f32_16x16x32_bf16 v[120:123], v[80:83], v[180:183], v[120:123]
	v_mfma_f32_16x16x32_bf16 v[112:115], v[68:71], v[188:191], v[112:115]
	v_mfma_f32_16x16x32_bf16 v[104:107], v[80:83], v[188:191], v[104:107]
	s_setprio 0
	s_setprio 1
	v_mfma_f32_16x16x32_bf16 v[148:151], v[88:91], v[160:163], 0
	v_mfma_f32_16x16x32_bf16 v[140:143], v[96:99], v[160:163], 0
	v_mfma_f32_16x16x32_bf16 v[132:135], v[88:91], v[168:171], 0
	v_mfma_f32_16x16x32_bf16 v[128:131], v[96:99], v[168:171], 0
	v_mfma_f32_16x16x32_bf16 v[116:119], v[88:91], v[176:179], 0
	v_mfma_f32_16x16x32_bf16 v[108:111], v[96:99], v[176:179], 0
	v_mfma_f32_16x16x32_bf16 v[84:87], v[88:91], v[184:187], 0
	v_mfma_f32_16x16x32_bf16 v[72:75], v[96:99], v[184:187], 0
	v_mfma_f32_16x16x32_bf16 v[148:151], v[92:95], v[164:167], v[148:151]
	v_mfma_f32_16x16x32_bf16 v[140:143], v[100:103], v[164:167], v[140:143]
	v_mfma_f32_16x16x32_bf16 v[132:135], v[92:95], v[172:175], v[132:135]
	v_mfma_f32_16x16x32_bf16 v[128:131], v[100:103], v[172:175], v[128:131]
	v_mfma_f32_16x16x32_bf16 v[116:119], v[92:95], v[180:183], v[116:119]
	v_mfma_f32_16x16x32_bf16 v[108:111], v[100:103], v[180:183], v[108:111]
	v_mfma_f32_16x16x32_bf16 v[84:87], v[92:95], v[188:191], v[84:87]
	v_mfma_f32_16x16x32_bf16 v[72:75], v[100:103], v[188:191], v[72:75]
	s_setprio 0
	s_barrier
	s_add_i32 s10, s64, s41
	v_lshl_add_u64 v[208:209], s[34:35], 0, v[196:197]
	s_mov_b32 m0, s10
	ds_read_b128 v[160:163], v227 offset:16384
	ds_read_b128 v[164:167], v227 offset:17408
	ds_read_b128 v[168:171], v227 offset:18432
	ds_read_b128 v[172:175], v227 offset:19456
	ds_read_b128 v[176:179], v227 offset:20480
	ds_read_b128 v[180:183], v227 offset:21504
	ds_read_b128 v[184:187], v227 offset:22528
	ds_read_b128 v[188:191], v227 offset:23552
	global_load_lds_dwordx4 v[208:209], off
	s_add_i32 m0, s10, 0x2000
	s_add_u32 s10, s34, 0xb0000
	v_lshl_add_u64 v[210:211], s[34:35], 0, v[192:193]
	s_addc_u32 s11, s35, 0
	s_add_i32 s64, s65, s41
	global_load_lds_dwordx4 v[210:211], off
	v_lshl_add_u64 v[212:213], s[10:11], 0, v[196:197]
	s_mov_b32 m0, s64
	v_lshl_add_u64 v[214:215], s[36:37], 0, v[192:193]
	global_load_lds_dwordx4 v[212:213], off
	v_lshl_add_u64 v[212:213], s[10:11], 0, v[192:193]
	s_add_i32 m0, s64, 0x2000
	s_nop 0
	global_load_lds_dwordx4 v[212:213], off
	v_lshl_add_u64 v[212:213], s[36:37], 0, v[196:197]
	s_waitcnt vmcnt(6)
	s_waitcnt lgkmcnt(0)
	s_barrier
; #define PG8_STAGE(bufoff, gbase, voff) do { _Pragma("unroll") for (int _i = 0; _i < 2; ++_i) \
;         __builtin_amdgcn_global_load_lds((const unsigned*)((const char*)(gbase) + (voff)[_i]), (PG8_LAS unsigned*)(lds + (bufoff) + ldsw + _i * 8192), 16, 0, 0); } while (0)
; #define PG8_LDA(dst, b, h) do { _Pragma("unroll") for (int m = 0; m < 4; ++m) _Pragma("unroll") for (int k = 0; k < 2; ++k) dst[m][k] = *(const PG8_LAS bf16x8*)(lds + PG8_SA(b, h) + aoff + m * 2048 + k * 1024); } while (0)
; #define PG8_LDB(dst, b, h) do { _Pragma("unroll") for (int n = 0; n < 2; ++n) _Pragma("unroll") for (int k = 0; k < 2; ++k) dst[n][k] = *(const PG8_LAS bf16x8*)(lds + PG8_SB(b, h) + boff + n * 2048 + k * 1024); } while (0)
; #define PG8_MMA(ai, bj, At, Bt) do { __builtin_amdgcn_s_setprio(1); _Pragma("unroll") for (int m = 0; m < 4; ++m) _Pragma("unroll") for (int n = 0; n < 2; ++n) _Pragma("unroll") for (int k = 0; k < 2; ++k) \
;         acc[ai][bj][m][n] = __builtin_amdgcn_mfma_f32_16x16x32_bf16(Bt[n][k], At[m][k], acc[ai][bj][m][n], 0, 0, 0); __builtin_amdgcn_s_setprio(0); } while (0)
; #define PG8_WAIT_V(n) asm volatile("s_waitcnt vmcnt(" #n ")" ::: "memory")
; #define PG8_WAIT_L(n) asm volatile("s_waitcnt lgkmcnt(" #n ")" ::: "memory")
; #define PG8_BAR __builtin_amdgcn_s_barrier()
; #define PG8_SCHED __builtin_amdgcn_sched_barrier(0)
; template <class Epi, class Sched, bool ALIGN_EPI = false, bool SP2 = false>
; __device__ __forceinline__ void gemm_phase(PG8_LAS unsigned char* lds, const Gemm g, const Sched& S, const Epi& E, int wave_s_) {
;     ...
;             PG8_WAIT_V(8); PG8_WAIT_L(0); PG8_BAR; PG8_MMA(1, 0, At, B0); PG8_MMA(1, 1, At, B1); PG8_BAR; PG8_SCHED;
;             PG8_LDB(B0, 1, 0); PG8_LDB(B1, 1, 1); PG8_SCHED; PG8_LDA(At, 1, 0); PG8_STAGE(PG8_SA(0, 1), a2 + hstep, voffA);
;             PG8_WAIT_V(8); PG8_WAIT_L(0); PG8_BAR; PG8_MMA(0, 0, At, B0); PG8_MMA(0, 1, At, B1); PG8_BAR; PG8_SCHED;
	s_setprio 1
	s_waitcnt lgkmcnt(0)
	v_mfma_f32_16x16x32_bf16 v[60:63], v[64:67], v[160:163], 0
	v_mfma_f32_16x16x32_bf16 v[56:59], v[76:79], v[160:163], 0
	v_mfma_f32_16x16x32_bf16 v[48:51], v[64:67], v[168:171], 0
	v_mfma_f32_16x16x32_bf16 v[40:43], v[76:79], v[168:171], 0
	v_mfma_f32_16x16x32_bf16 v[28:31], v[64:67], v[176:179], 0
	v_mfma_f32_16x16x32_bf16 v[24:27], v[76:79], v[176:179], 0
	v_mfma_f32_16x16x32_bf16 v[16:19], v[64:67], v[184:187], 0
	v_mfma_f32_16x16x32_bf16 v[8:11], v[76:79], v[184:187], 0
	v_mfma_f32_16x16x32_bf16 v[60:63], v[68:71], v[164:167], v[60:63]
	v_mfma_f32_16x16x32_bf16 v[56:59], v[80:83], v[164:167], v[56:59]
	v_mfma_f32_16x16x32_bf16 v[48:51], v[68:71], v[172:175], v[48:51]
	v_mfma_f32_16x16x32_bf16 v[40:43], v[80:83], v[172:175], v[40:43]
	v_mfma_f32_16x16x32_bf16 v[28:31], v[68:71], v[180:183], v[28:31]
	v_mfma_f32_16x16x32_bf16 v[24:27], v[80:83], v[180:183], v[24:27]
	v_mfma_f32_16x16x32_bf16 v[16:19], v[68:71], v[188:191], v[16:19]
	v_mfma_f32_16x16x32_bf16 v[8:11], v[80:83], v[188:191], v[8:11]
	s_setprio 0
	s_setprio 1
	v_mfma_f32_16x16x32_bf16 v[52:55], v[88:91], v[160:163], 0
	v_mfma_f32_16x16x32_bf16 v[44:47], v[96:99], v[160:163], 0
	v_mfma_f32_16x16x32_bf16 v[36:39], v[88:91], v[168:171], 0
	v_mfma_f32_16x16x32_bf16 v[32:35], v[96:99], v[168:171], 0
	v_mfma_f32_16x16x32_bf16 v[20:23], v[88:91], v[176:179], 0
	v_mfma_f32_16x16x32_bf16 v[12:15], v[96:99], v[176:179], 0
	v_mfma_f32_16x16x32_bf16 v[4:7], v[88:91], v[184:187], 0
	v_mfma_f32_16x16x32_bf16 v[0:3], v[96:99], v[184:187], 0
	v_mfma_f32_16x16x32_bf16 v[52:55], v[92:95], v[164:167], v[52:55]
	v_mfma_f32_16x16x32_bf16 v[44:47], v[100:103], v[164:167], v[44:47]
	v_mfma_f32_16x16x32_bf16 v[36:39], v[92:95], v[172:175], v[36:39]
	v_mfma_f32_16x16x32_bf16 v[32:35], v[100:103], v[172:175], v[32:35]
	v_mfma_f32_16x16x32_bf16 v[20:23], v[92:95], v[180:183], v[20:23]
	v_mfma_f32_16x16x32_bf16 v[12:15], v[100:103], v[180:183], v[12:15]
	v_mfma_f32_16x16x32_bf16 v[4:7], v[92:95], v[188:191], v[4:7]
	v_mfma_f32_16x16x32_bf16 v[0:3], v[100:103], v[188:191], v[0:3]
	s_setprio 0
	s_barrier
	s_add_i32 s64, 0, 0x18000
	s_add_i32 s65, 0, 0x1c000
	v_add_u32_e32 v80, s64, v226
	v_add_u32_e32 v100, s65, v226
	ds_read_b128 v[64:67], v80
	ds_read_b128 v[68:71], v80 offset:1024
	ds_read_b128 v[76:79], v80 offset:2048
	ds_read_b128 v[80:83], v80 offset:3072
	ds_read_b128 v[88:91], v100
	ds_read_b128 v[92:95], v100 offset:1024
	ds_read_b128 v[96:99], v100 offset:2048
	ds_read_b128 v[100:103], v100 offset:3072
	s_add_u32 s10, s36, 0xb0000
	s_addc_u32 s11, s37, 0
	s_mov_b32 m0, s44
	v_lshl_add_u64 v[216:217], s[10:11], 0, v[196:197]
	ds_read_b128 v[160:163], v227 offset:32768
	ds_read_b128 v[164:167], v227 offset:33792
	ds_read_b128 v[168:171], v227 offset:34816
	ds_read_b128 v[172:175], v227 offset:35840
	ds_read_b128 v[176:179], v227 offset:36864
	ds_read_b128 v[180:183], v227 offset:37888
	ds_read_b128 v[184:187], v227 offset:38912
	ds_read_b128 v[188:191], v227 offset:39936
	global_load_lds_dwordx4 v[216:217], off
	v_lshl_add_u64 v[216:217], s[10:11], 0, v[192:193]
	s_mov_b32 m0, s45
	s_nop 0
	global_load_lds_dwordx4 v[216:217], off
	s_mov_b32 m0, s42
	s_nop 0
	global_load_lds_dwordx4 v[212:213], off
	s_mov_b32 m0, s43
	s_nop 0
	global_load_lds_dwordx4 v[214:215], off
	s_waitcnt vmcnt(8)
	s_waitcnt lgkmcnt(0)
	s_barrier
	s_setprio 1
	s_waitcnt lgkmcnt(0)
	v_mfma_f32_16x16x32_bf16 v[156:159], v[64:67], v[160:163], v[156:159]
	v_mfma_f32_16x16x32_bf16 v[152:155], v[76:79], v[160:163], v[152:155]
	v_mfma_f32_16x16x32_bf16 v[144:147], v[64:67], v[168:171], v[144:147]
	v_mfma_f32_16x16x32_bf16 v[136:139], v[76:79], v[168:171], v[136:139]
	v_mfma_f32_16x16x32_bf16 v[124:127], v[64:67], v[176:179], v[124:127]
	v_mfma_f32_16x16x32_bf16 v[120:123], v[76:79], v[176:179], v[120:123]
	v_mfma_f32_16x16x32_bf16 v[112:115], v[64:67], v[184:187], v[112:115]
	v_mfma_f32_16x16x32_bf16 v[104:107], v[76:79], v[184:187], v[104:107]
	v_mfma_f32_16x16x32_bf16 v[156:159], v[68:71], v[164:167], v[156:159]
	v_mfma_f32_16x16x32_bf16 v[152:155], v[80:83], v[164:167], v[152:155]
	v_mfma_f32_16x16x32_bf16 v[144:147], v[68:71], v[172:175], v[144:147]
	v_mfma_f32_16x16x32_bf16 v[136:139], v[80:83], v[172:175], v[136:139]
	v_mfma_f32_16x16x32_bf16 v[124:127], v[68:71], v[180:183], v[124:127]
	v_mfma_f32_16x16x32_bf16 v[120:123], v[80:83], v[180:183], v[120:123]
	v_mfma_f32_16x16x32_bf16 v[112:115], v[68:71], v[188:191], v[112:115]
	v_mfma_f32_16x16x32_bf16 v[104:107], v[80:83], v[188:191], v[104:107]
	s_setprio 0
	s_setprio 1
	v_mfma_f32_16x16x32_bf16 v[148:151], v[88:91], v[160:163], v[148:151]
	v_mfma_f32_16x16x32_bf16 v[140:143], v[96:99], v[160:163], v[140:143]
	v_mfma_f32_16x16x32_bf16 v[132:135], v[88:91], v[168:171], v[132:135]
	v_mfma_f32_16x16x32_bf16 v[128:131], v[96:99], v[168:171], v[128:131]
	v_mfma_f32_16x16x32_bf16 v[116:119], v[88:91], v[176:179], v[116:119]
	v_mfma_f32_16x16x32_bf16 v[108:111], v[96:99], v[176:179], v[108:111]
	v_mfma_f32_16x16x32_bf16 v[84:87], v[88:91], v[184:187], v[84:87]
	v_mfma_f32_16x16x32_bf16 v[72:75], v[96:99], v[184:187], v[72:75]
	v_mfma_f32_16x16x32_bf16 v[148:151], v[92:95], v[164:167], v[148:151]
	v_mfma_f32_16x16x32_bf16 v[140:143], v[100:103], v[164:167], v[140:143]
	v_mfma_f32_16x16x32_bf16 v[132:135], v[92:95], v[172:175], v[132:135]
	v_mfma_f32_16x16x32_bf16 v[128:131], v[100:103], v[172:175], v[128:131]
	v_mfma_f32_16x16x32_bf16 v[116:119], v[92:95], v[180:183], v[116:119]
	v_mfma_f32_16x16x32_bf16 v[108:111], v[100:103], v[180:183], v[108:111]
	v_mfma_f32_16x16x32_bf16 v[84:87], v[92:95], v[188:191], v[84:87]
	v_mfma_f32_16x16x32_bf16 v[72:75], v[100:103], v[188:191], v[72:75]
	s_setprio 0
	s_barrier
; #define PG8_STAGE(bufoff, gbase, voff) do { _Pragma("unroll") for (int _i = 0; _i < 2; ++_i) \
;         __builtin_amdgcn_global_load_lds((const unsigned*)((const char*)(gbase) + (voff)[_i]), (PG8_LAS unsigned*)(lds + (bufoff) + ldsw + _i * 8192), 16, 0, 0); } while (0)
; #define PG8_LDA(dst, b, h) do { _Pragma("unroll") for (int m = 0; m < 4; ++m) _Pragma("unroll") for (int k = 0; k < 2; ++k) dst[m][k] = *(const PG8_LAS bf16x8*)(lds + PG8_SA(b, h) + aoff + m * 2048 + k * 1024); } while (0)
; #define PG8_WAIT_V(n) asm volatile("s_waitcnt vmcnt(" #n ")" ::: "memory")
; #define PG8_WAIT_L(n) asm volatile("s_waitcnt lgkmcnt(" #n ")" ::: "memory")
; #define PG8_BAR __builtin_amdgcn_s_barrier()
; template <class Epi, class Sched, bool ALIGN_EPI = false, bool SP2 = false>
; __device__ __forceinline__ void gemm_phase(PG8_LAS unsigned char* lds, const Gemm g, const Sched& S, const Epi& E, int wave_s_) {
;     ...
;         for (int t = 0; t < nt; t += 2) {
;             const bool last = (t == nt - 2);
;             const char* a1 = cA + (size_t)(t + 1) * kstep;
;             const char* a2 = last ? nA : cA + (size_t)(t + 2) * kstep; const char* b2 = last ? nB : cB + (size_t)(t + 2) * kstep;
;             const char* a3 = a2 + kstep; const char* b3 = b2 + kstep;
;             if (last && has_next) S.a_ready(nxt);
;             if constexpr (SP2) {
;             PG8_LDB(B0, 0, 0); PG8_LDB(B1, 0, 1); PG8_SCHED; PG8_LDA(At, 0, 0); PG8_STAGE(PG8_SA(1, 1), a1 + hstep, voffA);
;             PG8_WAIT_V(8); PG8_WAIT_L(0); PG8_BAR; PG8_MMA(0, 0, At, B0); PG8_MMA(0, 1, At, B1); PG8_BAR; PG8_SCHED;
;             PG8_LDA(At, 0, 1); PG8_STAGE(PG8_SB(0, 0), b2, voffB); PG8_STAGE(PG8_SB(0, 1), b2 + hstep, voffB); PG8_STAGE(PG8_SA(0, 0), a2, voffA);
;             PG8_WAIT_V(8); PG8_WAIT_L(0); PG8_BAR; PG8_MMA(1, 0, At, B0); PG8_MMA(1, 1, At, B1); PG8_BAR; PG8_SCHED;
;             PG8_LDB(B0, 1, 0); PG8_LDB(B1, 1, 1); PG8_SCHED; PG8_LDA(At, 1, 0); PG8_STAGE(PG8_SA(0, 1), a2 + hstep, voffA);
;             PG8_WAIT_V(8); PG8_WAIT_L(0); PG8_BAR; PG8_MMA(0, 0, At, B0); PG8_MMA(0, 1, At, B1); PG8_BAR; PG8_SCHED;
;             PG8_LDA(At, 1, 1); PG8_STAGE(PG8_SB(1, 0), b3, voffB); PG8_STAGE(PG8_SB(1, 1), b3 + hstep, voffB); PG8_STAGE(PG8_SA(1, 0), a3, voffA);
;             PG8_WAIT_V(8); PG8_WAIT_L(0); PG8_BAR; PG8_MMA(1, 0, At, B0); PG8_MMA(1, 1, At, B1); PG8_BAR; PG8_SCHED;
	s_add_i32 s10, s64, s41
	v_lshl_add_u64 v[208:209], v[208:209], 0, s[76:77]
	s_mov_b32 m0, s10
	ds_read_b128 v[160:163], v227 offset:49152
	ds_read_b128 v[164:167], v227 offset:50176
	ds_read_b128 v[168:171], v227 offset:51200
	ds_read_b128 v[172:175], v227 offset:52224
	ds_read_b128 v[176:179], v227 offset:53248
	ds_read_b128 v[180:183], v227 offset:54272
	ds_read_b128 v[184:187], v227 offset:55296
	ds_read_b128 v[188:191], v227 offset:56320
	global_load_lds_dwordx4 v[208:209], off
	s_add_i32 m0, s10, 0x2000
	s_add_u32 s10, s34, 0xb0080
	v_lshl_add_u64 v[208:209], v[210:211], 0, s[76:77]
	s_addc_u32 s11, s35, 0
	s_add_i32 s34, s65, s41
	global_load_lds_dwordx4 v[208:209], off
	v_lshl_add_u64 v[208:209], s[10:11], 0, v[196:197]
	s_mov_b32 m0, s34
	s_nop 0
	global_load_lds_dwordx4 v[208:209], off
	v_lshl_add_u64 v[208:209], s[10:11], 0, v[192:193]
	s_add_i32 m0, s34, 0x2000
	s_nop 0
	global_load_lds_dwordx4 v[208:209], off
	v_lshl_add_u64 v[208:209], v[212:213], 0, s[76:77]
	s_mov_b32 m0, s48
	s_nop 0
	global_load_lds_dwordx4 v[208:209], off
	v_lshl_add_u64 v[208:209], v[214:215], 0, s[76:77]
	s_mov_b32 m0, s49
	s_nop 0
	global_load_lds_dwordx4 v[208:209], off
	s_waitcnt vmcnt(6)
	s_waitcnt lgkmcnt(0)
	s_barrier
	s_setprio 1
	s_waitcnt lgkmcnt(0)
	v_mfma_f32_16x16x32_bf16 v[60:63], v[64:67], v[160:163], v[60:63]
	v_mfma_f32_16x16x32_bf16 v[56:59], v[76:79], v[160:163], v[56:59]
	v_mfma_f32_16x16x32_bf16 v[48:51], v[64:67], v[168:171], v[48:51]
	v_mfma_f32_16x16x32_bf16 v[40:43], v[76:79], v[168:171], v[40:43]
	v_mfma_f32_16x16x32_bf16 v[28:31], v[64:67], v[176:179], v[28:31]
	v_mfma_f32_16x16x32_bf16 v[24:27], v[76:79], v[176:179], v[24:27]
	v_mfma_f32_16x16x32_bf16 v[16:19], v[64:67], v[184:187], v[16:19]
	v_mfma_f32_16x16x32_bf16 v[8:11], v[76:79], v[184:187], v[8:11]
	v_mfma_f32_16x16x32_bf16 v[60:63], v[68:71], v[164:167], v[60:63]
	v_mfma_f32_16x16x32_bf16 v[56:59], v[80:83], v[164:167], v[56:59]
	v_mfma_f32_16x16x32_bf16 v[48:51], v[68:71], v[172:175], v[48:51]
	v_mfma_f32_16x16x32_bf16 v[40:43], v[80:83], v[172:175], v[40:43]
	v_mfma_f32_16x16x32_bf16 v[28:31], v[68:71], v[180:183], v[28:31]
	v_mfma_f32_16x16x32_bf16 v[24:27], v[80:83], v[180:183], v[24:27]
	v_mfma_f32_16x16x32_bf16 v[16:19], v[68:71], v[188:191], v[16:19]
	v_mfma_f32_16x16x32_bf16 v[8:11], v[80:83], v[188:191], v[8:11]
	s_setprio 0
	s_setprio 1
	v_mfma_f32_16x16x32_bf16 v[52:55], v[88:91], v[160:163], v[52:55]
	v_mfma_f32_16x16x32_bf16 v[44:47], v[96:99], v[160:163], v[44:47]
	v_mfma_f32_16x16x32_bf16 v[36:39], v[88:91], v[168:171], v[36:39]
	v_mfma_f32_16x16x32_bf16 v[32:35], v[96:99], v[168:171], v[32:35]
	v_mfma_f32_16x16x32_bf16 v[20:23], v[88:91], v[176:179], v[20:23]
	v_mfma_f32_16x16x32_bf16 v[12:15], v[96:99], v[176:179], v[12:15]
	v_mfma_f32_16x16x32_bf16 v[4:7], v[88:91], v[184:187], v[4:7]
	v_mfma_f32_16x16x32_bf16 v[0:3], v[96:99], v[184:187], v[0:3]
	v_mfma_f32_16x16x32_bf16 v[52:55], v[92:95], v[164:167], v[52:55]
	v_mfma_f32_16x16x32_bf16 v[44:47], v[100:103], v[164:167], v[44:47]
	v_mfma_f32_16x16x32_bf16 v[36:39], v[92:95], v[172:175], v[36:39]
	v_mfma_f32_16x16x32_bf16 v[32:35], v[100:103], v[172:175], v[32:35]
	v_mfma_f32_16x16x32_bf16 v[20:23], v[92:95], v[180:183], v[20:23]
	v_mfma_f32_16x16x32_bf16 v[12:15], v[100:103], v[180:183], v[12:15]
	v_mfma_f32_16x16x32_bf16 v[4:7], v[92:95], v[188:191], v[4:7]
	v_mfma_f32_16x16x32_bf16 v[0:3], v[100:103], v[188:191], v[0:3]
	s_setprio 0
	s_barrier
	s_add_u32 s61, s61, 0x100
	s_addc_u32 s62, s62, 0
	s_cmp_ge_u32 s63, s59
	s_mov_b64 s[10:11], s[12:13]
	s_mov_b32 s34, s63
	s_cbranch_scc0 .LBB0_298
	s_branch .Lpeel_exit_1
.LBB0_298:
	s_add_i32 s63, s34, 2
	s_add_u32 s12, s10, 0x100
	s_addc_u32 s13, s11, 0
	s_add_i32 s64, 0, 0x10000
	s_cmp_eq_u32 s60, s34
	s_cselect_b32 s37, s27, s13
	s_cselect_b32 s36, s26, s12
	s_cselect_b32 s35, s29, s62
	s_cselect_b32 s34, s28, s61
	s_add_i32 s65, 0, 0x14000
	v_add_u32_e32 v80, s64, v226
	v_add_u32_e32 v100, s65, v226
	ds_read_b128 v[64:67], v80
	ds_read_b128 v[68:71], v80 offset:1024
	ds_read_b128 v[76:79], v80 offset:2048
	ds_read_b128 v[80:83], v80 offset:3072
	ds_read_b128 v[88:91], v100
	ds_read_b128 v[92:95], v100 offset:1024
	ds_read_b128 v[96:99], v100 offset:2048
	ds_read_b128 v[100:103], v100 offset:3072
	v_lshl_add_u64 v[208:209], s[10:11], 0, v[206:207]
	s_add_i32 m0, s42, 0xc000
	ds_read_b128 v[160:163], v227
	ds_read_b128 v[164:167], v227 offset:1024
	ds_read_b128 v[168:171], v227 offset:2048
	ds_read_b128 v[172:175], v227 offset:3072
	ds_read_b128 v[176:179], v227 offset:4096
	ds_read_b128 v[180:183], v227 offset:5120
	ds_read_b128 v[184:187], v227 offset:6144
	ds_read_b128 v[188:191], v227 offset:7168
	global_load_lds_dwordx4 v[208:209], off
	v_lshl_add_u64 v[208:209], s[10:11], 0, v[194:195]
	s_add_i32 m0, s42, 0xe000
	s_nop 0
	global_load_lds_dwordx4 v[208:209], off
	s_waitcnt vmcnt(8)
	s_waitcnt lgkmcnt(0)
	s_barrier
; #define PG8_STAGE(bufoff, gbase, voff) do { _Pragma("unroll") for (int _i = 0; _i < 2; ++_i) \
;         __builtin_amdgcn_global_load_lds((const unsigned*)((const char*)(gbase) + (voff)[_i]), (PG8_LAS unsigned*)(lds + (bufoff) + ldsw + _i * 8192), 16, 0, 0); } while (0)
; #define PG8_LDA(dst, b, h) do { _Pragma("unroll") for (int m = 0; m < 4; ++m) _Pragma("unroll") for (int k = 0; k < 2; ++k) dst[m][k] = *(const PG8_LAS bf16x8*)(lds + PG8_SA(b, h) + aoff + m * 2048 + k * 1024); } while (0)
; #define PG8_MMA(ai, bj, At, Bt) do { __builtin_amdgcn_s_setprio(1); _Pragma("unroll") for (int m = 0; m < 4; ++m) _Pragma("unroll") for (int n = 0; n < 2; ++n) _Pragma("unroll") for (int k = 0; k < 2; ++k) \
;         acc[ai][bj][m][n] = __builtin_amdgcn_mfma_f32_16x16x32_bf16(Bt[n][k], At[m][k], acc[ai][bj][m][n], 0, 0, 0); __builtin_amdgcn_s_setprio(0); } while (0)
; #define PG8_WAIT_V(n) asm volatile("s_waitcnt vmcnt(" #n ")" ::: "memory")
; #define PG8_WAIT_L(n) asm volatile("s_waitcnt lgkmcnt(" #n ")" ::: "memory")
; #define PG8_BAR __builtin_amdgcn_s_barrier()
; #define PG8_SCHED __builtin_amdgcn_sched_barrier(0)
; template <class Epi, class Sched, bool ALIGN_EPI = false, bool SP2 = false>
; __device__ __forceinline__ void gemm_phase(PG8_LAS unsigned char* lds, const Gemm g, const Sched& S, const Epi& E, int wave_s_) {
;     ...
;             PG8_WAIT_V(8); PG8_WAIT_L(0); PG8_BAR; PG8_MMA(0, 0, At, B0); PG8_MMA(0, 1, At, B1); PG8_BAR; PG8_SCHED;
;             PG8_LDA(At, 0, 1); PG8_STAGE(PG8_SB(0, 0), b2, voffB); PG8_STAGE(PG8_SB(0, 1), b2 + hstep, voffB); PG8_STAGE(PG8_SA(0, 0), a2, voffA);
;             PG8_WAIT_V(8); PG8_WAIT_L(0); PG8_BAR; PG8_MMA(1, 0, At, B0); PG8_MMA(1, 1, At, B1); PG8_BAR; PG8_SCHED;
	s_setprio 1
	s_waitcnt lgkmcnt(0)
	v_mfma_f32_16x16x32_bf16 v[156:159], v[64:67], v[160:163], v[156:159]
	v_mfma_f32_16x16x32_bf16 v[152:155], v[76:79], v[160:163], v[152:155]
	v_mfma_f32_16x16x32_bf16 v[144:147], v[64:67], v[168:171], v[144:147]
	v_mfma_f32_16x16x32_bf16 v[136:139], v[76:79], v[168:171], v[136:139]
	v_mfma_f32_16x16x32_bf16 v[124:127], v[64:67], v[176:179], v[124:127]
	v_mfma_f32_16x16x32_bf16 v[120:123], v[76:79], v[176:179], v[120:123]
	v_mfma_f32_16x16x32_bf16 v[112:115], v[64:67], v[184:187], v[112:115]
	v_mfma_f32_16x16x32_bf16 v[104:107], v[76:79], v[184:187], v[104:107]
	v_mfma_f32_16x16x32_bf16 v[156:159], v[68:71], v[164:167], v[156:159]
	v_mfma_f32_16x16x32_bf16 v[152:155], v[80:83], v[164:167], v[152:155]
	v_mfma_f32_16x16x32_bf16 v[144:147], v[68:71], v[172:175], v[144:147]
	v_mfma_f32_16x16x32_bf16 v[136:139], v[80:83], v[172:175], v[136:139]
	v_mfma_f32_16x16x32_bf16 v[124:127], v[68:71], v[180:183], v[124:127]
	v_mfma_f32_16x16x32_bf16 v[120:123], v[80:83], v[180:183], v[120:123]
	v_mfma_f32_16x16x32_bf16 v[112:115], v[68:71], v[188:191], v[112:115]
	v_mfma_f32_16x16x32_bf16 v[104:107], v[80:83], v[188:191], v[104:107]
	s_setprio 0
	s_setprio 1
	v_mfma_f32_16x16x32_bf16 v[148:151], v[88:91], v[160:163], v[148:151]
	v_mfma_f32_16x16x32_bf16 v[140:143], v[96:99], v[160:163], v[140:143]
	v_mfma_f32_16x16x32_bf16 v[132:135], v[88:91], v[168:171], v[132:135]
	v_mfma_f32_16x16x32_bf16 v[128:131], v[96:99], v[168:171], v[128:131]
	v_mfma_f32_16x16x32_bf16 v[116:119], v[88:91], v[176:179], v[116:119]
	v_mfma_f32_16x16x32_bf16 v[108:111], v[96:99], v[176:179], v[108:111]
	v_mfma_f32_16x16x32_bf16 v[84:87], v[88:91], v[184:187], v[84:87]
	v_mfma_f32_16x16x32_bf16 v[72:75], v[96:99], v[184:187], v[72:75]
	v_mfma_f32_16x16x32_bf16 v[148:151], v[92:95], v[164:167], v[148:151]
	v_mfma_f32_16x16x32_bf16 v[140:143], v[100:103], v[164:167], v[140:143]
	v_mfma_f32_16x16x32_bf16 v[132:135], v[92:95], v[172:175], v[132:135]
	v_mfma_f32_16x16x32_bf16 v[128:131], v[100:103], v[172:175], v[128:131]
	v_mfma_f32_16x16x32_bf16 v[116:119], v[92:95], v[180:183], v[116:119]
	v_mfma_f32_16x16x32_bf16 v[108:111], v[100:103], v[180:183], v[108:111]
	v_mfma_f32_16x16x32_bf16 v[84:87], v[92:95], v[188:191], v[84:87]
	v_mfma_f32_16x16x32_bf16 v[72:75], v[100:103], v[188:191], v[72:75]
	s_setprio 0
	s_barrier
	s_add_i32 s10, s64, s41
	v_lshl_add_u64 v[208:209], s[34:35], 0, v[196:197]
	s_mov_b32 m0, s10
	ds_read_b128 v[160:163], v227 offset:16384
	ds_read_b128 v[164:167], v227 offset:17408
	ds_read_b128 v[168:171], v227 offset:18432
	ds_read_b128 v[172:175], v227 offset:19456
	ds_read_b128 v[176:179], v227 offset:20480
	ds_read_b128 v[180:183], v227 offset:21504
	ds_read_b128 v[184:187], v227 offset:22528
	ds_read_b128 v[188:191], v227 offset:23552
	global_load_lds_dwordx4 v[208:209], off
	s_add_i32 m0, s10, 0x2000
	s_add_u32 s10, s34, 0xb0000
	v_lshl_add_u64 v[210:211], s[34:35], 0, v[192:193]
	s_addc_u32 s11, s35, 0
	s_add_i32 s64, s65, s41
	global_load_lds_dwordx4 v[210:211], off
	v_lshl_add_u64 v[212:213], s[10:11], 0, v[196:197]
	s_mov_b32 m0, s64
	v_lshl_add_u64 v[214:215], s[36:37], 0, v[192:193]
	global_load_lds_dwordx4 v[212:213], off
	v_lshl_add_u64 v[212:213], s[10:11], 0, v[192:193]
	s_add_i32 m0, s64, 0x2000
	s_nop 0
	global_load_lds_dwordx4 v[212:213], off
	v_lshl_add_u64 v[212:213], s[36:37], 0, v[196:197]
	s_waitcnt vmcnt(6)
	s_waitcnt lgkmcnt(0)
	s_barrier
	s_setprio 1
	s_waitcnt lgkmcnt(0)
	v_mfma_f32_16x16x32_bf16 v[60:63], v[64:67], v[160:163], v[60:63]
	v_mfma_f32_16x16x32_bf16 v[56:59], v[76:79], v[160:163], v[56:59]
	v_mfma_f32_16x16x32_bf16 v[48:51], v[64:67], v[168:171], v[48:51]
	v_mfma_f32_16x16x32_bf16 v[40:43], v[76:79], v[168:171], v[40:43]
	v_mfma_f32_16x16x32_bf16 v[28:31], v[64:67], v[176:179], v[28:31]
	v_mfma_f32_16x16x32_bf16 v[24:27], v[76:79], v[176:179], v[24:27]
	v_mfma_f32_16x16x32_bf16 v[16:19], v[64:67], v[184:187], v[16:19]
	v_mfma_f32_16x16x32_bf16 v[8:11], v[76:79], v[184:187], v[8:11]
	v_mfma_f32_16x16x32_bf16 v[60:63], v[68:71], v[164:167], v[60:63]
	v_mfma_f32_16x16x32_bf16 v[56:59], v[80:83], v[164:167], v[56:59]
	v_mfma_f32_16x16x32_bf16 v[48:51], v[68:71], v[172:175], v[48:51]
	v_mfma_f32_16x16x32_bf16 v[40:43], v[80:83], v[172:175], v[40:43]
	v_mfma_f32_16x16x32_bf16 v[28:31], v[68:71], v[180:183], v[28:31]
	v_mfma_f32_16x16x32_bf16 v[24:27], v[80:83], v[180:183], v[24:27]
	v_mfma_f32_16x16x32_bf16 v[16:19], v[68:71], v[188:191], v[16:19]
	v_mfma_f32_16x16x32_bf16 v[8:11], v[80:83], v[188:191], v[8:11]
	s_setprio 0
	s_setprio 1
	v_mfma_f32_16x16x32_bf16 v[52:55], v[88:91], v[160:163], v[52:55]
	v_mfma_f32_16x16x32_bf16 v[44:47], v[96:99], v[160:163], v[44:47]
	v_mfma_f32_16x16x32_bf16 v[36:39], v[88:91], v[168:171], v[36:39]
	v_mfma_f32_16x16x32_bf16 v[32:35], v[96:99], v[168:171], v[32:35]
	v_mfma_f32_16x16x32_bf16 v[20:23], v[88:91], v[176:179], v[20:23]
	v_mfma_f32_16x16x32_bf16 v[12:15], v[96:99], v[176:179], v[12:15]
	v_mfma_f32_16x16x32_bf16 v[4:7], v[88:91], v[184:187], v[4:7]
	v_mfma_f32_16x16x32_bf16 v[0:3], v[96:99], v[184:187], v[0:3]
	v_mfma_f32_16x16x32_bf16 v[52:55], v[92:95], v[164:167], v[52:55]
	v_mfma_f32_16x16x32_bf16 v[44:47], v[100:103], v[164:167], v[44:47]
	v_mfma_f32_16x16x32_bf16 v[36:39], v[92:95], v[172:175], v[36:39]
	v_mfma_f32_16x16x32_bf16 v[32:35], v[100:103], v[172:175], v[32:35]
	v_mfma_f32_16x16x32_bf16 v[20:23], v[92:95], v[180:183], v[20:23]
	v_mfma_f32_16x16x32_bf16 v[12:15], v[100:103], v[180:183], v[12:15]
	v_mfma_f32_16x16x32_bf16 v[4:7], v[92:95], v[188:191], v[4:7]
	v_mfma_f32_16x16x32_bf16 v[0:3], v[100:103], v[188:191], v[0:3]
	s_setprio 0
	s_barrier
; #define PG8_STAGE(bufoff, gbase, voff) do { _Pragma("unroll") for (int _i = 0; _i < 2; ++_i) \
;         __builtin_amdgcn_global_load_lds((const unsigned*)((const char*)(gbase) + (voff)[_i]), (PG8_LAS unsigned*)(lds + (bufoff) + ldsw + _i * 8192), 16, 0, 0); } while (0)
; #define PG8_LDA(dst, b, h) do { _Pragma("unroll") for (int m = 0; m < 4; ++m) _Pragma("unroll") for (int k = 0; k < 2; ++k) dst[m][k] = *(const PG8_LAS bf16x8*)(lds + PG8_SA(b, h) + aoff + m * 2048 + k * 1024); } while (0)
; #define PG8_LDB(dst, b, h) do { _Pragma("unroll") for (int n = 0; n < 2; ++n) _Pragma("unroll") for (int k = 0; k < 2; ++k) dst[n][k] = *(const PG8_LAS bf16x8*)(lds + PG8_SB(b, h) + boff + n * 2048 + k * 1024); } while (0)
; #define PG8_MMA(ai, bj, At, Bt) do { __builtin_amdgcn_s_setprio(1); _Pragma("unroll") for (int m = 0; m < 4; ++m) _Pragma("unroll") for (int n = 0; n < 2; ++n) _Pragma("unroll") for (int k = 0; k < 2; ++k) \
;         acc[ai][bj][m][n] = __builtin_amdgcn_mfma_f32_16x16x32_bf16(Bt[n][k], At[m][k], acc[ai][bj][m][n], 0, 0, 0); __builtin_amdgcn_s_setprio(0); } while (0)
; #define PG8_WAIT_V(n) asm volatile("s_waitcnt vmcnt(" #n ")" ::: "memory")
; #define PG8_WAIT_L(n) asm volatile("s_waitcnt lgkmcnt(" #n ")" ::: "memory")
; #define PG8_BAR __builtin_amdgcn_s_barrier()
; #define PG8_SCHED __builtin_amdgcn_sched_barrier(0)
; template <class Epi, class Sched, bool ALIGN_EPI = false, bool SP2 = false>
; __device__ __forceinline__ void gemm_phase(PG8_LAS unsigned char* lds, const Gemm g, const Sched& S, const Epi& E, int wave_s_) {
;     ...
;             PG8_LDB(B0, 1, 0); PG8_LDB(B1, 1, 1); PG8_SCHED; PG8_LDA(At, 1, 0); PG8_STAGE(PG8_SA(0, 1), a2 + hstep, voffA);
;             PG8_WAIT_V(8); PG8_WAIT_L(0); PG8_BAR; PG8_MMA(0, 0, At, B0); PG8_MMA(0, 1, At, B1); PG8_BAR; PG8_SCHED;
	s_add_i32 s64, 0, 0x18000
	s_add_i32 s65, 0, 0x1c000
	v_add_u32_e32 v80, s64, v226
	v_add_u32_e32 v100, s65, v226
	ds_read_b128 v[64:67], v80
	ds_read_b128 v[68:71], v80 offset:1024
	ds_read_b128 v[76:79], v80 offset:2048
	ds_read_b128 v[80:83], v80 offset:3072
	ds_read_b128 v[88:91], v100
	ds_read_b128 v[92:95], v100 offset:1024
	ds_read_b128 v[96:99], v100 offset:2048
	ds_read_b128 v[100:103], v100 offset:3072
	s_add_u32 s10, s36, 0xb0000
	s_addc_u32 s11, s37, 0
	s_mov_b32 m0, s44
	v_lshl_add_u64 v[216:217], s[10:11], 0, v[196:197]
	ds_read_b128 v[160:163], v227 offset:32768
	ds_read_b128 v[164:167], v227 offset:33792
	ds_read_b128 v[168:171], v227 offset:34816
	ds_read_b128 v[172:175], v227 offset:35840
	ds_read_b128 v[176:179], v227 offset:36864
	ds_read_b128 v[180:183], v227 offset:37888
	ds_read_b128 v[184:187], v227 offset:38912
	ds_read_b128 v[188:191], v227 offset:39936
	global_load_lds_dwordx4 v[216:217], off
	v_lshl_add_u64 v[216:217], s[10:11], 0, v[192:193]
	s_mov_b32 m0, s45
	s_nop 0
	global_load_lds_dwordx4 v[216:217], off
	s_mov_b32 m0, s42
	s_nop 0
	global_load_lds_dwordx4 v[212:213], off
	s_mov_b32 m0, s43
	s_nop 0
	global_load_lds_dwordx4 v[214:215], off
	s_waitcnt vmcnt(8)
	s_waitcnt lgkmcnt(0)
	s_barrier
	s_setprio 1
	s_waitcnt lgkmcnt(0)
	v_mfma_f32_16x16x32_bf16 v[156:159], v[64:67], v[160:163], v[156:159]
	v_mfma_f32_16x16x32_bf16 v[152:155], v[76:79], v[160:163], v[152:155]
	v_mfma_f32_16x16x32_bf16 v[144:147], v[64:67], v[168:171], v[144:147]
	v_mfma_f32_16x16x32_bf16 v[136:139], v[76:79], v[168:171], v[136:139]
	v_mfma_f32_16x16x32_bf16 v[124:127], v[64:67], v[176:179], v[124:127]
	v_mfma_f32_16x16x32_bf16 v[120:123], v[76:79], v[176:179], v[120:123]
	v_mfma_f32_16x16x32_bf16 v[112:115], v[64:67], v[184:187], v[112:115]
	v_mfma_f32_16x16x32_bf16 v[104:107], v[76:79], v[184:187], v[104:107]
	v_mfma_f32_16x16x32_bf16 v[156:159], v[68:71], v[164:167], v[156:159]
	v_mfma_f32_16x16x32_bf16 v[152:155], v[80:83], v[164:167], v[152:155]
	v_mfma_f32_16x16x32_bf16 v[144:147], v[68:71], v[172:175], v[144:147]
	v_mfma_f32_16x16x32_bf16 v[136:139], v[80:83], v[172:175], v[136:139]
	v_mfma_f32_16x16x32_bf16 v[124:127], v[68:71], v[180:183], v[124:127]
	v_mfma_f32_16x16x32_bf16 v[120:123], v[80:83], v[180:183], v[120:123]
	v_mfma_f32_16x16x32_bf16 v[112:115], v[68:71], v[188:191], v[112:115]
	v_mfma_f32_16x16x32_bf16 v[104:107], v[80:83], v[188:191], v[104:107]
	s_setprio 0
	s_setprio 1
	v_mfma_f32_16x16x32_bf16 v[148:151], v[88:91], v[160:163], v[148:151]
	v_mfma_f32_16x16x32_bf16 v[140:143], v[96:99], v[160:163], v[140:143]
	v_mfma_f32_16x16x32_bf16 v[132:135], v[88:91], v[168:171], v[132:135]
	v_mfma_f32_16x16x32_bf16 v[128:131], v[96:99], v[168:171], v[128:131]
	v_mfma_f32_16x16x32_bf16 v[116:119], v[88:91], v[176:179], v[116:119]
	v_mfma_f32_16x16x32_bf16 v[108:111], v[96:99], v[176:179], v[108:111]
	v_mfma_f32_16x16x32_bf16 v[84:87], v[88:91], v[184:187], v[84:87]
	v_mfma_f32_16x16x32_bf16 v[72:75], v[96:99], v[184:187], v[72:75]
	v_mfma_f32_16x16x32_bf16 v[148:151], v[92:95], v[164:167], v[148:151]
	v_mfma_f32_16x16x32_bf16 v[140:143], v[100:103], v[164:167], v[140:143]
	v_mfma_f32_16x16x32_bf16 v[132:135], v[92:95], v[172:175], v[132:135]
	v_mfma_f32_16x16x32_bf16 v[128:131], v[100:103], v[172:175], v[128:131]
	v_mfma_f32_16x16x32_bf16 v[116:119], v[92:95], v[180:183], v[116:119]
	v_mfma_f32_16x16x32_bf16 v[108:111], v[100:103], v[180:183], v[108:111]
	v_mfma_f32_16x16x32_bf16 v[84:87], v[92:95], v[188:191], v[84:87]
	v_mfma_f32_16x16x32_bf16 v[72:75], v[100:103], v[188:191], v[72:75]
	s_setprio 0
	s_barrier
; #define PG8_STAGE(bufoff, gbase, voff) do { _Pragma("unroll") for (int _i = 0; _i < 2; ++_i) \
;         __builtin_amdgcn_global_load_lds((const unsigned*)((const char*)(gbase) + (voff)[_i]), (PG8_LAS unsigned*)(lds + (bufoff) + ldsw + _i * 8192), 16, 0, 0); } while (0)
; #define PG8_LDA(dst, b, h) do { _Pragma("unroll") for (int m = 0; m < 4; ++m) _Pragma("unroll") for (int k = 0; k < 2; ++k) dst[m][k] = *(const PG8_LAS bf16x8*)(lds + PG8_SA(b, h) + aoff + m * 2048 + k * 1024); } while (0)
; #define PG8_MMA(ai, bj, At, Bt) do { __builtin_amdgcn_s_setprio(1); _Pragma("unroll") for (int m = 0; m < 4; ++m) _Pragma("unroll") for (int n = 0; n < 2; ++n) _Pragma("unroll") for (int k = 0; k < 2; ++k) \
;         acc[ai][bj][m][n] = __builtin_amdgcn_mfma_f32_16x16x32_bf16(Bt[n][k], At[m][k], acc[ai][bj][m][n], 0, 0, 0); __builtin_amdgcn_s_setprio(0); } while (0)
; #define PG8_WAIT_V(n) asm volatile("s_waitcnt vmcnt(" #n ")" ::: "memory")
; #define PG8_WAIT_L(n) asm volatile("s_waitcnt lgkmcnt(" #n ")" ::: "memory")
; #define PG8_BAR __builtin_amdgcn_s_barrier()
; #define PG8_SCHED __builtin_amdgcn_sched_barrier(0)
; template <class Epi, class Sched, bool ALIGN_EPI = false, bool SP2 = false>
; __device__ __forceinline__ void gemm_phase(PG8_LAS unsigned char* lds, const Gemm g, const Sched& S, const Epi& E, int wave_s_) {
;     ...
;             PG8_LDA(At, 1, 1); PG8_STAGE(PG8_SB(1, 0), b3, voffB); PG8_STAGE(PG8_SB(1, 1), b3 + hstep, voffB); PG8_STAGE(PG8_SA(1, 0), a3, voffA);
;             PG8_WAIT_V(8); PG8_WAIT_L(0); PG8_BAR; PG8_MMA(1, 0, At, B0); PG8_MMA(1, 1, At, B1); PG8_BAR; PG8_SCHED;
	s_add_i32 s10, s64, s41
	v_lshl_add_u64 v[208:209], v[208:209], 0, s[76:77]
	s_mov_b32 m0, s10
	ds_read_b128 v[160:163], v227 offset:49152
	ds_read_b128 v[164:167], v227 offset:50176
	ds_read_b128 v[168:171], v227 offset:51200
	ds_read_b128 v[172:175], v227 offset:52224
	ds_read_b128 v[176:179], v227 offset:53248
	ds_read_b128 v[180:183], v227 offset:54272
	ds_read_b128 v[184:187], v227 offset:55296
	ds_read_b128 v[188:191], v227 offset:56320
	global_load_lds_dwordx4 v[208:209], off
	s_add_i32 m0, s10, 0x2000
	s_add_u32 s10, s34, 0xb0080
	v_lshl_add_u64 v[208:209], v[210:211], 0, s[76:77]
	s_addc_u32 s11, s35, 0
	s_add_i32 s34, s65, s41
	global_load_lds_dwordx4 v[208:209], off
	v_lshl_add_u64 v[208:209], s[10:11], 0, v[196:197]
	s_mov_b32 m0, s34
	s_nop 0
	global_load_lds_dwordx4 v[208:209], off
	v_lshl_add_u64 v[208:209], s[10:11], 0, v[192:193]
	s_add_i32 m0, s34, 0x2000
	s_nop 0
	global_load_lds_dwordx4 v[208:209], off
	v_lshl_add_u64 v[208:209], v[212:213], 0, s[76:77]
	s_mov_b32 m0, s48
	s_nop 0
	global_load_lds_dwordx4 v[208:209], off
	v_lshl_add_u64 v[208:209], v[214:215], 0, s[76:77]
	s_mov_b32 m0, s49
	s_nop 0
	global_load_lds_dwordx4 v[208:209], off
	s_waitcnt vmcnt(6)
	s_waitcnt lgkmcnt(0)
	s_barrier
	s_setprio 1
	s_waitcnt lgkmcnt(0)
	v_mfma_f32_16x16x32_bf16 v[60:63], v[64:67], v[160:163], v[60:63]
	v_mfma_f32_16x16x32_bf16 v[56:59], v[76:79], v[160:163], v[56:59]
	v_mfma_f32_16x16x32_bf16 v[48:51], v[64:67], v[168:171], v[48:51]
	v_mfma_f32_16x16x32_bf16 v[40:43], v[76:79], v[168:171], v[40:43]
	v_mfma_f32_16x16x32_bf16 v[28:31], v[64:67], v[176:179], v[28:31]
	v_mfma_f32_16x16x32_bf16 v[24:27], v[76:79], v[176:179], v[24:27]
	v_mfma_f32_16x16x32_bf16 v[16:19], v[64:67], v[184:187], v[16:19]
	v_mfma_f32_16x16x32_bf16 v[8:11], v[76:79], v[184:187], v[8:11]
	v_mfma_f32_16x16x32_bf16 v[60:63], v[68:71], v[164:167], v[60:63]
	v_mfma_f32_16x16x32_bf16 v[56:59], v[80:83], v[164:167], v[56:59]
	v_mfma_f32_16x16x32_bf16 v[48:51], v[68:71], v[172:175], v[48:51]
	v_mfma_f32_16x16x32_bf16 v[40:43], v[80:83], v[172:175], v[40:43]
	v_mfma_f32_16x16x32_bf16 v[28:31], v[68:71], v[180:183], v[28:31]
	v_mfma_f32_16x16x32_bf16 v[24:27], v[80:83], v[180:183], v[24:27]
	v_mfma_f32_16x16x32_bf16 v[16:19], v[68:71], v[188:191], v[16:19]
	v_mfma_f32_16x16x32_bf16 v[8:11], v[80:83], v[188:191], v[8:11]
	s_setprio 0
	s_setprio 1
	v_mfma_f32_16x16x32_bf16 v[52:55], v[88:91], v[160:163], v[52:55]
	v_mfma_f32_16x16x32_bf16 v[44:47], v[96:99], v[160:163], v[44:47]
	v_mfma_f32_16x16x32_bf16 v[36:39], v[88:91], v[168:171], v[36:39]
	v_mfma_f32_16x16x32_bf16 v[32:35], v[96:99], v[168:171], v[32:35]
	v_mfma_f32_16x16x32_bf16 v[20:23], v[88:91], v[176:179], v[20:23]
	v_mfma_f32_16x16x32_bf16 v[12:15], v[96:99], v[176:179], v[12:15]
	v_mfma_f32_16x16x32_bf16 v[4:7], v[88:91], v[184:187], v[4:7]
	v_mfma_f32_16x16x32_bf16 v[0:3], v[96:99], v[184:187], v[0:3]
	v_mfma_f32_16x16x32_bf16 v[52:55], v[92:95], v[164:167], v[52:55]
	v_mfma_f32_16x16x32_bf16 v[44:47], v[100:103], v[164:167], v[44:47]
	v_mfma_f32_16x16x32_bf16 v[36:39], v[92:95], v[172:175], v[36:39]
	v_mfma_f32_16x16x32_bf16 v[32:35], v[100:103], v[172:175], v[32:35]
	v_mfma_f32_16x16x32_bf16 v[20:23], v[92:95], v[180:183], v[20:23]
	v_mfma_f32_16x16x32_bf16 v[12:15], v[100:103], v[180:183], v[12:15]
	v_mfma_f32_16x16x32_bf16 v[4:7], v[92:95], v[188:191], v[4:7]
	v_mfma_f32_16x16x32_bf16 v[0:3], v[100:103], v[188:191], v[0:3]
	s_setprio 0
	s_barrier
	s_add_u32 s61, s61, 0x100
	s_addc_u32 s62, s62, 0
	s_cmp_ge_u32 s63, s59
	s_mov_b64 s[10:11], s[12:13]
	s_mov_b32 s34, s63
	s_cbranch_scc0 .LBB0_298

;     __device__ __forceinline__ int nt_of(const Unit& u) const { return (u.pm >> 12) ? ktper : kt; }
; #define PG8_STAGE(bufoff, gbase, voff) do { _Pragma("unroll") for (int _i = 0; _i < 2; ++_i) \
;         __builtin_amdgcn_global_load_lds((const unsigned*)((const char*)(gbase) + (voff)[_i]), (PG8_LAS unsigned*)(lds + (bufoff) + ldsw + _i * 8192), 16, 0, 0); } while (0)
; #define PG8_LDA(dst, b, h) do { _Pragma("unroll") for (int m = 0; m < 4; ++m) _Pragma("unroll") for (int k = 0; k < 2; ++k) dst[m][k] = *(const PG8_LAS bf16x8*)(lds + PG8_SA(b, h) + aoff + m * 2048 + k * 1024); } while (0)
; #define PG8_LDB(dst, b, h) do { _Pragma("unroll") for (int n = 0; n < 2; ++n) _Pragma("unroll") for (int k = 0; k < 2; ++k) dst[n][k] = *(const PG8_LAS bf16x8*)(lds + PG8_SB(b, h) + boff + n * 2048 + k * 1024); } while (0)
; #define PG8_BAR __builtin_amdgcn_s_barrier()
; template <class Epi, class Sched, bool ALIGN_EPI = false, bool SP2 = false>
; __device__ __forceinline__ void gemm_phase(PG8_LAS unsigned char* lds, const Gemm g, const Sched& S, const Epi& E, int wave_s_) {
;     ...
;     for (;;) {
;         const bool has_next = S.next(ui + 1, nxt);
;         const char* nA = has_next ? (const char*)g.A + (size_t)(nxt.pm & 4095) * tstep + (size_t)S.k0_of(nxt) * kstep : cA; const char* nB = has_next ? (const char*)g.Bt + (size_t)nxt.pn * tstep + (size_t)S.k0_of(nxt) * kstep : cB;
;         const int nt = S.nt_of(cur);
;         for (int t = 0; t < nt; t += 2) {
;             const bool last = (t == nt - 2);
;             const char* a1 = cA + (size_t)(t + 1) * kstep;
;             const char* a2 = last ? nA : cA + (size_t)(t + 2) * kstep; const char* b2 = last ? nB : cB + (size_t)(t + 2) * kstep;
;             const char* a3 = a2 + kstep; const char* b3 = b2 + kstep;
;             if (last && has_next) S.a_ready(nxt);
;             if constexpr (SP2) {
;             PG8_LDB(B0, 0, 0); PG8_LDB(B1, 0, 1); PG8_SCHED; PG8_LDA(At, 0, 0); PG8_STAGE(PG8_SA(1, 1), a1 + hstep, voffA);
;             PG8_WAIT_V(8); PG8_WAIT_L(0); PG8_BAR; PG8_MMA(0, 0, At, B0); PG8_MMA(0, 1, At, B1); PG8_BAR; PG8_SCHED;
;             PG8_LDA(At, 0, 1); PG8_STAGE(PG8_SB(0, 0), b2, voffB); PG8_STAGE(PG8_SB(0, 1), b2 + hstep, voffB); PG8_STAGE(PG8_SA(0, 0), a2, voffA);
;             PG8_WAIT_V(8); PG8_WAIT_L(0); PG8_BAR; PG8_MMA(1, 0, At, B0); PG8_MMA(1, 1, At, B1); PG8_BAR; PG8_SCHED;
.LBB0_561:
	s_add_u32 s6, s12, 0x40080
	s_addc_u32 s7, s13, 0
	s_add_u32 s9, s10, 0x100
	v_mov_b32_e32 v0, 0
	s_addc_u32 s14, s11, 0
	s_mov_b32 s15, -2
	s_add_u32 s10, s6, 0xfffc0080
	s_addc_u32 s11, s7, -1
	s_add_i32 s16, 0, 0x10000
	s_cmp_eq_u32 s15, 12
	s_cselect_b32 s13, s61, s11
	s_cselect_b32 s12, s60, s10
	s_cselect_b32 s11, s63, s14
	s_cselect_b32 s10, s62, s9
	s_add_i32 s18, 0, 0x14000
	v_add_u32_e32 v154, s16, v152
	v_add_u32_e32 v170, s18, v152
	ds_read_b128 v[128:131], v154
	ds_read_b128 v[144:147], v154 offset:1024
	ds_read_b128 v[148:151], v154 offset:2048
	ds_read_b128 v[154:157], v154 offset:3072
	ds_read_b128 v[158:161], v170
	ds_read_b128 v[162:165], v170 offset:1024
	ds_read_b128 v[166:169], v170 offset:2048
	ds_read_b128 v[170:173], v170 offset:3072
	v_lshl_add_u64 v[194:195], s[6:7], 0, v[140:141]
	s_add_i32 m0, s93, 0xc000
	ds_read_b128 v[174:177], v153
	ds_read_b128 v[178:181], v153 offset:1024
	ds_read_b128 v[182:185], v153 offset:2048
	ds_read_b128 v[186:189], v153 offset:3072
	ds_read_b128 v[190:193], v153 offset:4096
	ds_read_b128 v[206:209], v153 offset:5120
	ds_read_b128 v[210:213], v153 offset:6144
	ds_read_b128 v[214:217], v153 offset:7168
	global_load_lds_dwordx4 v[194:195], off
	v_lshl_add_u64 v[194:195], s[6:7], 0, v[142:143]
	s_add_i32 m0, s93, 0xe000
	s_nop 0
	global_load_lds_dwordx4 v[194:195], off
	s_waitcnt vmcnt(8)
	s_waitcnt lgkmcnt(0)
	s_barrier
	s_setprio 1
	s_waitcnt lgkmcnt(0)
	v_mfma_f32_16x16x32_bf16 v[124:127], v[128:131], v[174:177], 0
	v_mfma_f32_16x16x32_bf16 v[120:123], v[148:151], v[174:177], 0
	v_mfma_f32_16x16x32_bf16 v[116:119], v[128:131], v[182:185], 0
	v_mfma_f32_16x16x32_bf16 v[112:115], v[148:151], v[182:185], 0
	v_mfma_f32_16x16x32_bf16 v[108:111], v[128:131], v[190:193], 0
	v_mfma_f32_16x16x32_bf16 v[104:107], v[148:151], v[190:193], 0
	v_mfma_f32_16x16x32_bf16 v[100:103], v[128:131], v[210:213], 0
	v_mfma_f32_16x16x32_bf16 v[96:99], v[148:151], v[210:213], 0
	v_mfma_f32_16x16x32_bf16 v[124:127], v[144:147], v[178:181], v[124:127]
	v_mfma_f32_16x16x32_bf16 v[120:123], v[154:157], v[178:181], v[120:123]
	v_mfma_f32_16x16x32_bf16 v[116:119], v[144:147], v[186:189], v[116:119]
	v_mfma_f32_16x16x32_bf16 v[112:115], v[154:157], v[186:189], v[112:115]
	v_mfma_f32_16x16x32_bf16 v[108:111], v[144:147], v[206:209], v[108:111]
	v_mfma_f32_16x16x32_bf16 v[104:107], v[154:157], v[206:209], v[104:107]
	v_mfma_f32_16x16x32_bf16 v[100:103], v[144:147], v[214:217], v[100:103]
	v_mfma_f32_16x16x32_bf16 v[96:99], v[154:157], v[214:217], v[96:99]
	s_setprio 0
	s_setprio 1
	v_mfma_f32_16x16x32_bf16 v[60:63], v[158:161], v[174:177], 0
	v_mfma_f32_16x16x32_bf16 v[56:59], v[166:169], v[174:177], 0
	v_mfma_f32_16x16x32_bf16 v[52:55], v[158:161], v[182:185], 0
	v_mfma_f32_16x16x32_bf16 v[48:51], v[166:169], v[182:185], 0
	v_mfma_f32_16x16x32_bf16 v[44:47], v[158:161], v[190:193], 0
	v_mfma_f32_16x16x32_bf16 v[40:43], v[166:169], v[190:193], 0
	v_mfma_f32_16x16x32_bf16 v[36:39], v[158:161], v[210:213], 0
	v_mfma_f32_16x16x32_bf16 v[32:35], v[166:169], v[210:213], 0
	v_mfma_f32_16x16x32_bf16 v[60:63], v[162:165], v[178:181], v[60:63]
	v_mfma_f32_16x16x32_bf16 v[56:59], v[170:173], v[178:181], v[56:59]
	v_mfma_f32_16x16x32_bf16 v[52:55], v[162:165], v[186:189], v[52:55]
	v_mfma_f32_16x16x32_bf16 v[48:51], v[170:173], v[186:189], v[48:51]
	v_mfma_f32_16x16x32_bf16 v[44:47], v[162:165], v[206:209], v[44:47]
	v_mfma_f32_16x16x32_bf16 v[40:43], v[170:173], v[206:209], v[40:43]
	v_mfma_f32_16x16x32_bf16 v[36:39], v[162:165], v[214:217], v[36:39]
	v_mfma_f32_16x16x32_bf16 v[32:35], v[170:173], v[214:217], v[32:35]
	s_setprio 0
	s_barrier
	s_add_i32 s16, s16, s92
	v_lshl_add_u64 v[194:195], s[10:11], 0, v[134:135]
	s_mov_b32 m0, s16
	ds_read_b128 v[174:177], v153 offset:16384
	ds_read_b128 v[178:181], v153 offset:17408
	ds_read_b128 v[182:185], v153 offset:18432
	ds_read_b128 v[186:189], v153 offset:19456
	ds_read_b128 v[190:193], v153 offset:20480
	ds_read_b128 v[206:209], v153 offset:21504
	ds_read_b128 v[210:213], v153 offset:22528
	ds_read_b128 v[214:217], v153 offset:23552
	global_load_lds_dwordx4 v[194:195], off
	s_add_i32 m0, s16, 0x2000
	s_add_u32 s16, s10, 0x40000
	v_lshl_add_u64 v[218:219], s[10:11], 0, v[138:139]
	s_addc_u32 s17, s11, 0
	s_add_i32 s18, s18, s92
	global_load_lds_dwordx4 v[218:219], off
	v_lshl_add_u64 v[220:221], s[16:17], 0, v[134:135]
	s_mov_b32 m0, s18
	v_lshl_add_u64 v[222:223], s[12:13], 0, v[136:137]
	global_load_lds_dwordx4 v[220:221], off
	v_lshl_add_u64 v[220:221], s[16:17], 0, v[138:139]
	s_add_i32 m0, s18, 0x2000
	s_nop 0
	global_load_lds_dwordx4 v[220:221], off
	v_lshl_add_u64 v[220:221], s[12:13], 0, v[132:133]
	s_waitcnt vmcnt(6)
	s_waitcnt lgkmcnt(0)
	s_barrier
; #define PG8_STAGE(bufoff, gbase, voff) do { _Pragma("unroll") for (int _i = 0; _i < 2; ++_i) \
;         __builtin_amdgcn_global_load_lds((const unsigned*)((const char*)(gbase) + (voff)[_i]), (PG8_LAS unsigned*)(lds + (bufoff) + ldsw + _i * 8192), 16, 0, 0); } while (0)
; #define PG8_LDA(dst, b, h) do { _Pragma("unroll") for (int m = 0; m < 4; ++m) _Pragma("unroll") for (int k = 0; k < 2; ++k) dst[m][k] = *(const PG8_LAS bf16x8*)(lds + PG8_SA(b, h) + aoff + m * 2048 + k * 1024); } while (0)
; #define PG8_LDB(dst, b, h) do { _Pragma("unroll") for (int n = 0; n < 2; ++n) _Pragma("unroll") for (int k = 0; k < 2; ++k) dst[n][k] = *(const PG8_LAS bf16x8*)(lds + PG8_SB(b, h) + boff + n * 2048 + k * 1024); } while (0)
; #define PG8_MMA(ai, bj, At, Bt) do { __builtin_amdgcn_s_setprio(1); _Pragma("unroll") for (int m = 0; m < 4; ++m) _Pragma("unroll") for (int n = 0; n < 2; ++n) _Pragma("unroll") for (int k = 0; k < 2; ++k) \
;         acc[ai][bj][m][n] = __builtin_amdgcn_mfma_f32_16x16x32_bf16(Bt[n][k], At[m][k], acc[ai][bj][m][n], 0, 0, 0); __builtin_amdgcn_s_setprio(0); } while (0)
; #define PG8_WAIT_V(n) asm volatile("s_waitcnt vmcnt(" #n ")" ::: "memory")
; #define PG8_WAIT_L(n) asm volatile("s_waitcnt lgkmcnt(" #n ")" ::: "memory")
; #define PG8_BAR __builtin_amdgcn_s_barrier()
; #define PG8_SCHED __builtin_amdgcn_sched_barrier(0)
; template <class Epi, class Sched, bool ALIGN_EPI = false, bool SP2 = false>
; __device__ __forceinline__ void gemm_phase(PG8_LAS unsigned char* lds, const Gemm g, const Sched& S, const Epi& E, int wave_s_) {
;     ...
;             PG8_WAIT_V(8); PG8_WAIT_L(0); PG8_BAR; PG8_MMA(1, 0, At, B0); PG8_MMA(1, 1, At, B1); PG8_BAR; PG8_SCHED;
;             PG8_LDB(B0, 1, 0); PG8_LDB(B1, 1, 1); PG8_SCHED; PG8_LDA(At, 1, 0); PG8_STAGE(PG8_SA(0, 1), a2 + hstep, voffA);
;             PG8_WAIT_V(8); PG8_WAIT_L(0); PG8_BAR; PG8_MMA(0, 0, At, B0); PG8_MMA(0, 1, At, B1); PG8_BAR; PG8_SCHED;
	s_setprio 1
	s_waitcnt lgkmcnt(0)
	v_mfma_f32_16x16x32_bf16 v[92:95], v[128:131], v[174:177], 0
	v_mfma_f32_16x16x32_bf16 v[88:91], v[148:151], v[174:177], 0
	v_mfma_f32_16x16x32_bf16 v[84:87], v[128:131], v[182:185], 0
	v_mfma_f32_16x16x32_bf16 v[80:83], v[148:151], v[182:185], 0
	v_mfma_f32_16x16x32_bf16 v[76:79], v[128:131], v[190:193], 0
	v_mfma_f32_16x16x32_bf16 v[72:75], v[148:151], v[190:193], 0
	v_mfma_f32_16x16x32_bf16 v[68:71], v[128:131], v[210:213], 0
	v_mfma_f32_16x16x32_bf16 v[64:67], v[148:151], v[210:213], 0
	v_mfma_f32_16x16x32_bf16 v[92:95], v[144:147], v[178:181], v[92:95]
	v_mfma_f32_16x16x32_bf16 v[88:91], v[154:157], v[178:181], v[88:91]
	v_mfma_f32_16x16x32_bf16 v[84:87], v[144:147], v[186:189], v[84:87]
	v_mfma_f32_16x16x32_bf16 v[80:83], v[154:157], v[186:189], v[80:83]
	v_mfma_f32_16x16x32_bf16 v[76:79], v[144:147], v[206:209], v[76:79]
	v_mfma_f32_16x16x32_bf16 v[72:75], v[154:157], v[206:209], v[72:75]
	v_mfma_f32_16x16x32_bf16 v[68:71], v[144:147], v[214:217], v[68:71]
	v_mfma_f32_16x16x32_bf16 v[64:67], v[154:157], v[214:217], v[64:67]
	s_setprio 0
	s_setprio 1
	v_mfma_f32_16x16x32_bf16 v[28:31], v[158:161], v[174:177], 0
	v_mfma_f32_16x16x32_bf16 v[24:27], v[166:169], v[174:177], 0
	v_mfma_f32_16x16x32_bf16 v[20:23], v[158:161], v[182:185], 0
	v_mfma_f32_16x16x32_bf16 v[16:19], v[166:169], v[182:185], 0
	v_mfma_f32_16x16x32_bf16 v[12:15], v[158:161], v[190:193], 0
	v_mfma_f32_16x16x32_bf16 v[8:11], v[166:169], v[190:193], 0
	v_mfma_f32_16x16x32_bf16 v[4:7], v[158:161], v[210:213], 0
	v_mfma_f32_16x16x32_bf16 v[0:3], v[166:169], v[210:213], 0
	v_mfma_f32_16x16x32_bf16 v[28:31], v[162:165], v[178:181], v[28:31]
	v_mfma_f32_16x16x32_bf16 v[24:27], v[170:173], v[178:181], v[24:27]
	v_mfma_f32_16x16x32_bf16 v[20:23], v[162:165], v[186:189], v[20:23]
	v_mfma_f32_16x16x32_bf16 v[16:19], v[170:173], v[186:189], v[16:19]
	v_mfma_f32_16x16x32_bf16 v[12:15], v[162:165], v[206:209], v[12:15]
	v_mfma_f32_16x16x32_bf16 v[8:11], v[170:173], v[206:209], v[8:11]
	v_mfma_f32_16x16x32_bf16 v[4:7], v[162:165], v[214:217], v[4:7]
	v_mfma_f32_16x16x32_bf16 v[0:3], v[170:173], v[214:217], v[0:3]
	s_setprio 0
	s_barrier
	s_add_i32 s16, 0, 0x18000
	s_add_i32 s17, 0, 0x1c000
	v_add_u32_e32 v154, s16, v152
	v_add_u32_e32 v170, s17, v152
	ds_read_b128 v[128:131], v154
	ds_read_b128 v[144:147], v154 offset:1024
	ds_read_b128 v[148:151], v154 offset:2048
	ds_read_b128 v[154:157], v154 offset:3072
	ds_read_b128 v[158:161], v170
	ds_read_b128 v[162:165], v170 offset:1024
	ds_read_b128 v[166:169], v170 offset:2048
	ds_read_b128 v[170:173], v170 offset:3072
	s_add_u32 s12, s12, 0x40000
	s_addc_u32 s13, s13, 0
	s_mov_b32 m0, s95
	v_lshl_add_u64 v[224:225], s[12:13], 0, v[132:133]
	ds_read_b128 v[174:177], v153 offset:32768
	ds_read_b128 v[178:181], v153 offset:33792
	ds_read_b128 v[182:185], v153 offset:34816
	ds_read_b128 v[186:189], v153 offset:35840
	ds_read_b128 v[190:193], v153 offset:36864
	ds_read_b128 v[206:209], v153 offset:37888
	ds_read_b128 v[210:213], v153 offset:38912
	ds_read_b128 v[214:217], v153 offset:39936
	global_load_lds_dwordx4 v[224:225], off
	v_lshl_add_u64 v[224:225], s[12:13], 0, v[136:137]
	s_mov_b32 m0, s96
	s_nop 0
	global_load_lds_dwordx4 v[224:225], off
	s_mov_b32 m0, s93
	s_nop 0
	global_load_lds_dwordx4 v[220:221], off
	s_mov_b32 m0, s94
	s_nop 0
	global_load_lds_dwordx4 v[222:223], off
	s_waitcnt vmcnt(8)
	s_waitcnt lgkmcnt(0)
	s_barrier
	s_setprio 1
	s_waitcnt lgkmcnt(0)
	v_mfma_f32_16x16x32_bf16 v[124:127], v[128:131], v[174:177], v[124:127]
	v_mfma_f32_16x16x32_bf16 v[120:123], v[148:151], v[174:177], v[120:123]
	v_mfma_f32_16x16x32_bf16 v[116:119], v[128:131], v[182:185], v[116:119]
	v_mfma_f32_16x16x32_bf16 v[112:115], v[148:151], v[182:185], v[112:115]
	v_mfma_f32_16x16x32_bf16 v[108:111], v[128:131], v[190:193], v[108:111]
	v_mfma_f32_16x16x32_bf16 v[104:107], v[148:151], v[190:193], v[104:107]
	v_mfma_f32_16x16x32_bf16 v[100:103], v[128:131], v[210:213], v[100:103]
	v_mfma_f32_16x16x32_bf16 v[96:99], v[148:151], v[210:213], v[96:99]
	v_mfma_f32_16x16x32_bf16 v[124:127], v[144:147], v[178:181], v[124:127]
	v_mfma_f32_16x16x32_bf16 v[120:123], v[154:157], v[178:181], v[120:123]
	v_mfma_f32_16x16x32_bf16 v[116:119], v[144:147], v[186:189], v[116:119]
	v_mfma_f32_16x16x32_bf16 v[112:115], v[154:157], v[186:189], v[112:115]
	v_mfma_f32_16x16x32_bf16 v[108:111], v[144:147], v[206:209], v[108:111]
	v_mfma_f32_16x16x32_bf16 v[104:107], v[154:157], v[206:209], v[104:107]
	v_mfma_f32_16x16x32_bf16 v[100:103], v[144:147], v[214:217], v[100:103]
	v_mfma_f32_16x16x32_bf16 v[96:99], v[154:157], v[214:217], v[96:99]
	s_setprio 0
	s_setprio 1
	v_mfma_f32_16x16x32_bf16 v[60:63], v[158:161], v[174:177], v[60:63]
	v_mfma_f32_16x16x32_bf16 v[56:59], v[166:169], v[174:177], v[56:59]
	v_mfma_f32_16x16x32_bf16 v[52:55], v[158:161], v[182:185], v[52:55]
	v_mfma_f32_16x16x32_bf16 v[48:51], v[166:169], v[182:185], v[48:51]
	v_mfma_f32_16x16x32_bf16 v[44:47], v[158:161], v[190:193], v[44:47]
	v_mfma_f32_16x16x32_bf16 v[40:43], v[166:169], v[190:193], v[40:43]
	v_mfma_f32_16x16x32_bf16 v[36:39], v[158:161], v[210:213], v[36:39]
	v_mfma_f32_16x16x32_bf16 v[32:35], v[166:169], v[210:213], v[32:35]
	v_mfma_f32_16x16x32_bf16 v[60:63], v[162:165], v[178:181], v[60:63]
	v_mfma_f32_16x16x32_bf16 v[56:59], v[170:173], v[178:181], v[56:59]
	v_mfma_f32_16x16x32_bf16 v[52:55], v[162:165], v[186:189], v[52:55]
	v_mfma_f32_16x16x32_bf16 v[48:51], v[170:173], v[186:189], v[48:51]
	v_mfma_f32_16x16x32_bf16 v[44:47], v[162:165], v[206:209], v[44:47]
	v_mfma_f32_16x16x32_bf16 v[40:43], v[170:173], v[206:209], v[40:43]
	v_mfma_f32_16x16x32_bf16 v[36:39], v[162:165], v[214:217], v[36:39]
	v_mfma_f32_16x16x32_bf16 v[32:35], v[170:173], v[214:217], v[32:35]
	s_setprio 0
	s_barrier
; #define PG8_STAGE(bufoff, gbase, voff) do { _Pragma("unroll") for (int _i = 0; _i < 2; ++_i) \
;         __builtin_amdgcn_global_load_lds((const unsigned*)((const char*)(gbase) + (voff)[_i]), (PG8_LAS unsigned*)(lds + (bufoff) + ldsw + _i * 8192), 16, 0, 0); } while (0)
; #define PG8_LDA(dst, b, h) do { _Pragma("unroll") for (int m = 0; m < 4; ++m) _Pragma("unroll") for (int k = 0; k < 2; ++k) dst[m][k] = *(const PG8_LAS bf16x8*)(lds + PG8_SA(b, h) + aoff + m * 2048 + k * 1024); } while (0)
; #define PG8_LDB(dst, b, h) do { _Pragma("unroll") for (int n = 0; n < 2; ++n) _Pragma("unroll") for (int k = 0; k < 2; ++k) dst[n][k] = *(const PG8_LAS bf16x8*)(lds + PG8_SB(b, h) + boff + n * 2048 + k * 1024); } while (0)
; #define PG8_MMA(ai, bj, At, Bt) do { __builtin_amdgcn_s_setprio(1); _Pragma("unroll") for (int m = 0; m < 4; ++m) _Pragma("unroll") for (int n = 0; n < 2; ++n) _Pragma("unroll") for (int k = 0; k < 2; ++k) \
;         acc[ai][bj][m][n] = __builtin_amdgcn_mfma_f32_16x16x32_bf16(Bt[n][k], At[m][k], acc[ai][bj][m][n], 0, 0, 0); __builtin_amdgcn_s_setprio(0); } while (0)
; #define PG8_WAIT_V(n) asm volatile("s_waitcnt vmcnt(" #n ")" ::: "memory")
; #define PG8_BAR __builtin_amdgcn_s_barrier()
; template <class Epi, class Sched, bool ALIGN_EPI = false, bool SP2 = false>
; __device__ __forceinline__ void gemm_phase(PG8_LAS unsigned char* lds, const Gemm g, const Sched& S, const Epi& E, int wave_s_) {
;     ...
;         for (int t = 0; t < nt; t += 2) {
;             const bool last = (t == nt - 2);
;             const char* a1 = cA + (size_t)(t + 1) * kstep;
;             const char* a2 = last ? nA : cA + (size_t)(t + 2) * kstep; const char* b2 = last ? nB : cB + (size_t)(t + 2) * kstep;
;             const char* a3 = a2 + kstep; const char* b3 = b2 + kstep;
;             if (last && has_next) S.a_ready(nxt);
;             if constexpr (SP2) {
;             PG8_LDB(B0, 0, 0); PG8_LDB(B1, 0, 1); PG8_SCHED; PG8_LDA(At, 0, 0); PG8_STAGE(PG8_SA(1, 1), a1 + hstep, voffA);
;             PG8_WAIT_V(8); PG8_WAIT_L(0); PG8_BAR; PG8_MMA(0, 0, At, B0); PG8_MMA(0, 1, At, B1); PG8_BAR; PG8_SCHED;
;     ...
;             PG8_LDA(At, 1, 1); PG8_STAGE(PG8_SB(1, 0), b3, voffB); PG8_STAGE(PG8_SB(1, 1), b3 + hstep, voffB); PG8_STAGE(PG8_SA(1, 0), a3, voffA);
;             PG8_WAIT_V(8); PG8_WAIT_L(0); PG8_BAR; PG8_MMA(1, 0, At, B0); PG8_MMA(1, 1, At, B1); PG8_BAR; PG8_SCHED;
	s_add_i32 s12, s16, s92
	v_lshl_add_u64 v[194:195], v[194:195], 0, s[76:77]
	s_mov_b32 m0, s12
	ds_read_b128 v[174:177], v153 offset:49152
	ds_read_b128 v[178:181], v153 offset:50176
	ds_read_b128 v[182:185], v153 offset:51200
	ds_read_b128 v[186:189], v153 offset:52224
	ds_read_b128 v[190:193], v153 offset:53248
	ds_read_b128 v[206:209], v153 offset:54272
	ds_read_b128 v[210:213], v153 offset:55296
	ds_read_b128 v[214:217], v153 offset:56320
	global_load_lds_dwordx4 v[194:195], off
	s_add_i32 m0, s12, 0x2000
	s_add_u32 s10, s10, 0x40080
	v_lshl_add_u64 v[194:195], v[218:219], 0, s[76:77]
	s_addc_u32 s11, s11, 0
	s_add_i32 s12, s17, s92
	global_load_lds_dwordx4 v[194:195], off
	v_lshl_add_u64 v[194:195], s[10:11], 0, v[134:135]
	s_mov_b32 m0, s12
	s_nop 0
	global_load_lds_dwordx4 v[194:195], off
	v_lshl_add_u64 v[194:195], s[10:11], 0, v[138:139]
	s_add_i32 m0, s12, 0x2000
	s_nop 0
	global_load_lds_dwordx4 v[194:195], off
	v_lshl_add_u64 v[194:195], v[220:221], 0, s[76:77]
	s_mov_b32 m0, s48
	s_nop 0
	global_load_lds_dwordx4 v[194:195], off
	v_lshl_add_u64 v[194:195], v[222:223], 0, s[76:77]
	s_mov_b32 m0, s49
	s_nop 0
	global_load_lds_dwordx4 v[194:195], off
	s_waitcnt vmcnt(6)
	s_waitcnt lgkmcnt(0)
	s_barrier
	s_setprio 1
	s_waitcnt lgkmcnt(0)
	v_mfma_f32_16x16x32_bf16 v[92:95], v[128:131], v[174:177], v[92:95]
	v_mfma_f32_16x16x32_bf16 v[88:91], v[148:151], v[174:177], v[88:91]
	v_mfma_f32_16x16x32_bf16 v[84:87], v[128:131], v[182:185], v[84:87]
	v_mfma_f32_16x16x32_bf16 v[80:83], v[148:151], v[182:185], v[80:83]
	v_mfma_f32_16x16x32_bf16 v[76:79], v[128:131], v[190:193], v[76:79]
	v_mfma_f32_16x16x32_bf16 v[72:75], v[148:151], v[190:193], v[72:75]
	v_mfma_f32_16x16x32_bf16 v[68:71], v[128:131], v[210:213], v[68:71]
	v_mfma_f32_16x16x32_bf16 v[64:67], v[148:151], v[210:213], v[64:67]
	v_mfma_f32_16x16x32_bf16 v[92:95], v[144:147], v[178:181], v[92:95]
	v_mfma_f32_16x16x32_bf16 v[88:91], v[154:157], v[178:181], v[88:91]
	v_mfma_f32_16x16x32_bf16 v[84:87], v[144:147], v[186:189], v[84:87]
	v_mfma_f32_16x16x32_bf16 v[80:83], v[154:157], v[186:189], v[80:83]
	v_mfma_f32_16x16x32_bf16 v[76:79], v[144:147], v[206:209], v[76:79]
	v_mfma_f32_16x16x32_bf16 v[72:75], v[154:157], v[206:209], v[72:75]
	v_mfma_f32_16x16x32_bf16 v[68:71], v[144:147], v[214:217], v[68:71]
	v_mfma_f32_16x16x32_bf16 v[64:67], v[154:157], v[214:217], v[64:67]
	s_setprio 0
	s_setprio 1
	v_mfma_f32_16x16x32_bf16 v[28:31], v[158:161], v[174:177], v[28:31]
	v_mfma_f32_16x16x32_bf16 v[24:27], v[166:169], v[174:177], v[24:27]
	v_mfma_f32_16x16x32_bf16 v[20:23], v[158:161], v[182:185], v[20:23]
	v_mfma_f32_16x16x32_bf16 v[16:19], v[166:169], v[182:185], v[16:19]
	v_mfma_f32_16x16x32_bf16 v[12:15], v[158:161], v[190:193], v[12:15]
	v_mfma_f32_16x16x32_bf16 v[8:11], v[166:169], v[190:193], v[8:11]
	v_mfma_f32_16x16x32_bf16 v[4:7], v[158:161], v[210:213], v[4:7]
	v_mfma_f32_16x16x32_bf16 v[0:3], v[166:169], v[210:213], v[0:3]
	v_mfma_f32_16x16x32_bf16 v[28:31], v[162:165], v[178:181], v[28:31]
	v_mfma_f32_16x16x32_bf16 v[24:27], v[170:173], v[178:181], v[24:27]
	v_mfma_f32_16x16x32_bf16 v[20:23], v[162:165], v[186:189], v[20:23]
	v_mfma_f32_16x16x32_bf16 v[16:19], v[170:173], v[186:189], v[16:19]
	v_mfma_f32_16x16x32_bf16 v[12:15], v[162:165], v[206:209], v[12:15]
	v_mfma_f32_16x16x32_bf16 v[8:11], v[170:173], v[206:209], v[8:11]
	v_mfma_f32_16x16x32_bf16 v[4:7], v[162:165], v[214:217], v[4:7]
	v_mfma_f32_16x16x32_bf16 v[0:3], v[170:173], v[214:217], v[0:3]
	s_setprio 0
	s_barrier
	s_add_i32 s15, s15, 2
	s_add_u32 s6, s6, 0x100
	s_addc_u32 s7, s7, 0
	s_add_u32 s9, s9, 0x100
	s_addc_u32 s14, s14, 0
	s_cmp_gt_u32 s15, 13
	s_cbranch_scc0 .LBB0_562
	s_branch .Lpeel_exit_2
.LBB0_562:
	s_add_u32 s10, s6, 0xfffc0080
	s_addc_u32 s11, s7, -1
	s_add_i32 s16, 0, 0x10000
	s_cmp_eq_u32 s15, 12
	s_cselect_b32 s13, s61, s11
	s_cselect_b32 s12, s60, s10
	s_cselect_b32 s11, s63, s14
	s_cselect_b32 s10, s62, s9
	s_add_i32 s18, 0, 0x14000
	v_add_u32_e32 v154, s16, v152
	v_add_u32_e32 v170, s18, v152
	ds_read_b128 v[128:131], v154
	ds_read_b128 v[144:147], v154 offset:1024
	ds_read_b128 v[148:151], v154 offset:2048
	ds_read_b128 v[154:157], v154 offset:3072
	ds_read_b128 v[158:161], v170
	ds_read_b128 v[162:165], v170 offset:1024
	ds_read_b128 v[166:169], v170 offset:2048
	ds_read_b128 v[170:173], v170 offset:3072
	v_lshl_add_u64 v[194:195], s[6:7], 0, v[140:141]
	s_add_i32 m0, s93, 0xc000
	ds_read_b128 v[174:177], v153
	ds_read_b128 v[178:181], v153 offset:1024
	ds_read_b128 v[182:185], v153 offset:2048
	ds_read_b128 v[186:189], v153 offset:3072
	ds_read_b128 v[190:193], v153 offset:4096
	ds_read_b128 v[206:209], v153 offset:5120
	ds_read_b128 v[210:213], v153 offset:6144
	ds_read_b128 v[214:217], v153 offset:7168
	global_load_lds_dwordx4 v[194:195], off
	v_lshl_add_u64 v[194:195], s[6:7], 0, v[142:143]
	s_add_i32 m0, s93, 0xe000
	s_nop 0
	global_load_lds_dwordx4 v[194:195], off
	s_waitcnt vmcnt(8)
	s_waitcnt lgkmcnt(0)
	s_barrier
; #define PG8_STAGE(bufoff, gbase, voff) do { _Pragma("unroll") for (int _i = 0; _i < 2; ++_i) \
;         __builtin_amdgcn_global_load_lds((const unsigned*)((const char*)(gbase) + (voff)[_i]), (PG8_LAS unsigned*)(lds + (bufoff) + ldsw + _i * 8192), 16, 0, 0); } while (0)
; #define PG8_LDA(dst, b, h) do { _Pragma("unroll") for (int m = 0; m < 4; ++m) _Pragma("unroll") for (int k = 0; k < 2; ++k) dst[m][k] = *(const PG8_LAS bf16x8*)(lds + PG8_SA(b, h) + aoff + m * 2048 + k * 1024); } while (0)
; #define PG8_MMA(ai, bj, At, Bt) do { __builtin_amdgcn_s_setprio(1); _Pragma("unroll") for (int m = 0; m < 4; ++m) _Pragma("unroll") for (int n = 0; n < 2; ++n) _Pragma("unroll") for (int k = 0; k < 2; ++k) \
;         acc[ai][bj][m][n] = __builtin_amdgcn_mfma_f32_16x16x32_bf16(Bt[n][k], At[m][k], acc[ai][bj][m][n], 0, 0, 0); __builtin_amdgcn_s_setprio(0); } while (0)
; #define PG8_WAIT_V(n) asm volatile("s_waitcnt vmcnt(" #n ")" ::: "memory")
; #define PG8_WAIT_L(n) asm volatile("s_waitcnt lgkmcnt(" #n ")" ::: "memory")
; #define PG8_BAR __builtin_amdgcn_s_barrier()
; #define PG8_SCHED __builtin_amdgcn_sched_barrier(0)
; template <class Epi, class Sched, bool ALIGN_EPI = false, bool SP2 = false>
; __device__ __forceinline__ void gemm_phase(PG8_LAS unsigned char* lds, const Gemm g, const Sched& S, const Epi& E, int wave_s_) {
;     ...
;             PG8_WAIT_V(8); PG8_WAIT_L(0); PG8_BAR; PG8_MMA(0, 0, At, B0); PG8_MMA(0, 1, At, B1); PG8_BAR; PG8_SCHED;
;             PG8_LDA(At, 0, 1); PG8_STAGE(PG8_SB(0, 0), b2, voffB); PG8_STAGE(PG8_SB(0, 1), b2 + hstep, voffB); PG8_STAGE(PG8_SA(0, 0), a2, voffA);
;             PG8_WAIT_V(8); PG8_WAIT_L(0); PG8_BAR; PG8_MMA(1, 0, At, B0); PG8_MMA(1, 1, At, B1); PG8_BAR; PG8_SCHED;
	s_setprio 1
	s_waitcnt lgkmcnt(0)
	v_mfma_f32_16x16x32_bf16 v[124:127], v[128:131], v[174:177], v[124:127]
	v_mfma_f32_16x16x32_bf16 v[120:123], v[148:151], v[174:177], v[120:123]
	v_mfma_f32_16x16x32_bf16 v[116:119], v[128:131], v[182:185], v[116:119]
	v_mfma_f32_16x16x32_bf16 v[112:115], v[148:151], v[182:185], v[112:115]
	v_mfma_f32_16x16x32_bf16 v[108:111], v[128:131], v[190:193], v[108:111]
	v_mfma_f32_16x16x32_bf16 v[104:107], v[148:151], v[190:193], v[104:107]
	v_mfma_f32_16x16x32_bf16 v[100:103], v[128:131], v[210:213], v[100:103]
	v_mfma_f32_16x16x32_bf16 v[96:99], v[148:151], v[210:213], v[96:99]
	v_mfma_f32_16x16x32_bf16 v[124:127], v[144:147], v[178:181], v[124:127]
	v_mfma_f32_16x16x32_bf16 v[120:123], v[154:157], v[178:181], v[120:123]
	v_mfma_f32_16x16x32_bf16 v[116:119], v[144:147], v[186:189], v[116:119]
	v_mfma_f32_16x16x32_bf16 v[112:115], v[154:157], v[186:189], v[112:115]
	v_mfma_f32_16x16x32_bf16 v[108:111], v[144:147], v[206:209], v[108:111]
	v_mfma_f32_16x16x32_bf16 v[104:107], v[154:157], v[206:209], v[104:107]
	v_mfma_f32_16x16x32_bf16 v[100:103], v[144:147], v[214:217], v[100:103]
	v_mfma_f32_16x16x32_bf16 v[96:99], v[154:157], v[214:217], v[96:99]
	s_setprio 0
	s_setprio 1
	v_mfma_f32_16x16x32_bf16 v[60:63], v[158:161], v[174:177], v[60:63]
	v_mfma_f32_16x16x32_bf16 v[56:59], v[166:169], v[174:177], v[56:59]
	v_mfma_f32_16x16x32_bf16 v[52:55], v[158:161], v[182:185], v[52:55]
	v_mfma_f32_16x16x32_bf16 v[48:51], v[166:169], v[182:185], v[48:51]
	v_mfma_f32_16x16x32_bf16 v[44:47], v[158:161], v[190:193], v[44:47]
	v_mfma_f32_16x16x32_bf16 v[40:43], v[166:169], v[190:193], v[40:43]
	v_mfma_f32_16x16x32_bf16 v[36:39], v[158:161], v[210:213], v[36:39]
	v_mfma_f32_16x16x32_bf16 v[32:35], v[166:169], v[210:213], v[32:35]
	v_mfma_f32_16x16x32_bf16 v[60:63], v[162:165], v[178:181], v[60:63]
	v_mfma_f32_16x16x32_bf16 v[56:59], v[170:173], v[178:181], v[56:59]
	v_mfma_f32_16x16x32_bf16 v[52:55], v[162:165], v[186:189], v[52:55]
	v_mfma_f32_16x16x32_bf16 v[48:51], v[170:173], v[186:189], v[48:51]
	v_mfma_f32_16x16x32_bf16 v[44:47], v[162:165], v[206:209], v[44:47]
	v_mfma_f32_16x16x32_bf16 v[40:43], v[170:173], v[206:209], v[40:43]
	v_mfma_f32_16x16x32_bf16 v[36:39], v[162:165], v[214:217], v[36:39]
	v_mfma_f32_16x16x32_bf16 v[32:35], v[170:173], v[214:217], v[32:35]
	s_setprio 0
	s_barrier
	s_add_i32 s16, s16, s92
	v_lshl_add_u64 v[194:195], s[10:11], 0, v[134:135]
	s_mov_b32 m0, s16
	ds_read_b128 v[174:177], v153 offset:16384
	ds_read_b128 v[178:181], v153 offset:17408
	ds_read_b128 v[182:185], v153 offset:18432
	ds_read_b128 v[186:189], v153 offset:19456
	ds_read_b128 v[190:193], v153 offset:20480
	ds_read_b128 v[206:209], v153 offset:21504
	ds_read_b128 v[210:213], v153 offset:22528
	ds_read_b128 v[214:217], v153 offset:23552
	global_load_lds_dwordx4 v[194:195], off
	s_add_i32 m0, s16, 0x2000
	s_add_u32 s16, s10, 0x40000
	v_lshl_add_u64 v[218:219], s[10:11], 0, v[138:139]
	s_addc_u32 s17, s11, 0
	s_add_i32 s18, s18, s92
	global_load_lds_dwordx4 v[218:219], off
	v_lshl_add_u64 v[220:221], s[16:17], 0, v[134:135]
	s_mov_b32 m0, s18
	v_lshl_add_u64 v[222:223], s[12:13], 0, v[136:137]
	global_load_lds_dwordx4 v[220:221], off
	v_lshl_add_u64 v[220:221], s[16:17], 0, v[138:139]
	s_add_i32 m0, s18, 0x2000
	s_nop 0
	global_load_lds_dwordx4 v[220:221], off
	v_lshl_add_u64 v[220:221], s[12:13], 0, v[132:133]
	s_waitcnt vmcnt(6)
	s_waitcnt lgkmcnt(0)
	s_barrier
	s_setprio 1
	s_waitcnt lgkmcnt(0)
	v_mfma_f32_16x16x32_bf16 v[92:95], v[128:131], v[174:177], v[92:95]
	v_mfma_f32_16x16x32_bf16 v[88:91], v[148:151], v[174:177], v[88:91]
	v_mfma_f32_16x16x32_bf16 v[84:87], v[128:131], v[182:185], v[84:87]
	v_mfma_f32_16x16x32_bf16 v[80:83], v[148:151], v[182:185], v[80:83]
	v_mfma_f32_16x16x32_bf16 v[76:79], v[128:131], v[190:193], v[76:79]
	v_mfma_f32_16x16x32_bf16 v[72:75], v[148:151], v[190:193], v[72:75]
	v_mfma_f32_16x16x32_bf16 v[68:71], v[128:131], v[210:213], v[68:71]
	v_mfma_f32_16x16x32_bf16 v[64:67], v[148:151], v[210:213], v[64:67]
	v_mfma_f32_16x16x32_bf16 v[92:95], v[144:147], v[178:181], v[92:95]
	v_mfma_f32_16x16x32_bf16 v[88:91], v[154:157], v[178:181], v[88:91]
	v_mfma_f32_16x16x32_bf16 v[84:87], v[144:147], v[186:189], v[84:87]
	v_mfma_f32_16x16x32_bf16 v[80:83], v[154:157], v[186:189], v[80:83]
	v_mfma_f32_16x16x32_bf16 v[76:79], v[144:147], v[206:209], v[76:79]
	v_mfma_f32_16x16x32_bf16 v[72:75], v[154:157], v[206:209], v[72:75]
	v_mfma_f32_16x16x32_bf16 v[68:71], v[144:147], v[214:217], v[68:71]
	v_mfma_f32_16x16x32_bf16 v[64:67], v[154:157], v[214:217], v[64:67]
	s_setprio 0
	s_setprio 1
	v_mfma_f32_16x16x32_bf16 v[28:31], v[158:161], v[174:177], v[28:31]
	v_mfma_f32_16x16x32_bf16 v[24:27], v[166:169], v[174:177], v[24:27]
	v_mfma_f32_16x16x32_bf16 v[20:23], v[158:161], v[182:185], v[20:23]
	v_mfma_f32_16x16x32_bf16 v[16:19], v[166:169], v[182:185], v[16:19]
	v_mfma_f32_16x16x32_bf16 v[12:15], v[158:161], v[190:193], v[12:15]
	v_mfma_f32_16x16x32_bf16 v[8:11], v[166:169], v[190:193], v[8:11]
	v_mfma_f32_16x16x32_bf16 v[4:7], v[158:161], v[210:213], v[4:7]
	v_mfma_f32_16x16x32_bf16 v[0:3], v[166:169], v[210:213], v[0:3]
	v_mfma_f32_16x16x32_bf16 v[28:31], v[162:165], v[178:181], v[28:31]
	v_mfma_f32_16x16x32_bf16 v[24:27], v[170:173], v[178:181], v[24:27]
	v_mfma_f32_16x16x32_bf16 v[20:23], v[162:165], v[186:189], v[20:23]
	v_mfma_f32_16x16x32_bf16 v[16:19], v[170:173], v[186:189], v[16:19]
	v_mfma_f32_16x16x32_bf16 v[12:15], v[162:165], v[206:209], v[12:15]
	v_mfma_f32_16x16x32_bf16 v[8:11], v[170:173], v[206:209], v[8:11]
	v_mfma_f32_16x16x32_bf16 v[4:7], v[162:165], v[214:217], v[4:7]
	v_mfma_f32_16x16x32_bf16 v[0:3], v[170:173], v[214:217], v[0:3]
	s_setprio 0
	s_barrier
; #define PG8_STAGE(bufoff, gbase, voff) do { _Pragma("unroll") for (int _i = 0; _i < 2; ++_i) \
;         __builtin_amdgcn_global_load_lds((const unsigned*)((const char*)(gbase) + (voff)[_i]), (PG8_LAS unsigned*)(lds + (bufoff) + ldsw + _i * 8192), 16, 0, 0); } while (0)
; #define PG8_LDA(dst, b, h) do { _Pragma("unroll") for (int m = 0; m < 4; ++m) _Pragma("unroll") for (int k = 0; k < 2; ++k) dst[m][k] = *(const PG8_LAS bf16x8*)(lds + PG8_SA(b, h) + aoff + m * 2048 + k * 1024); } while (0)
; #define PG8_LDB(dst, b, h) do { _Pragma("unroll") for (int n = 0; n < 2; ++n) _Pragma("unroll") for (int k = 0; k < 2; ++k) dst[n][k] = *(const PG8_LAS bf16x8*)(lds + PG8_SB(b, h) + boff + n * 2048 + k * 1024); } while (0)
; #define PG8_MMA(ai, bj, At, Bt) do { __builtin_amdgcn_s_setprio(1); _Pragma("unroll") for (int m = 0; m < 4; ++m) _Pragma("unroll") for (int n = 0; n < 2; ++n) _Pragma("unroll") for (int k = 0; k < 2; ++k) \
;         acc[ai][bj][m][n] = __builtin_amdgcn_mfma_f32_16x16x32_bf16(Bt[n][k], At[m][k], acc[ai][bj][m][n], 0, 0, 0); __builtin_amdgcn_s_setprio(0); } while (0)
; #define PG8_WAIT_V(n) asm volatile("s_waitcnt vmcnt(" #n ")" ::: "memory")
; #define PG8_WAIT_L(n) asm volatile("s_waitcnt lgkmcnt(" #n ")" ::: "memory")
; #define PG8_BAR __builtin_amdgcn_s_barrier()
; #define PG8_SCHED __builtin_amdgcn_sched_barrier(0)
; template <class Epi, class Sched, bool ALIGN_EPI = false, bool SP2 = false>
; __device__ __forceinline__ void gemm_phase(PG8_LAS unsigned char* lds, const Gemm g, const Sched& S, const Epi& E, int wave_s_) {
;     ...
;             PG8_LDB(B0, 1, 0); PG8_LDB(B1, 1, 1); PG8_SCHED; PG8_LDA(At, 1, 0); PG8_STAGE(PG8_SA(0, 1), a2 + hstep, voffA);
;             PG8_WAIT_V(8); PG8_WAIT_L(0); PG8_BAR; PG8_MMA(0, 0, At, B0); PG8_MMA(0, 1, At, B1); PG8_BAR; PG8_SCHED;
	s_add_i32 s16, 0, 0x18000
	s_add_i32 s17, 0, 0x1c000
	v_add_u32_e32 v154, s16, v152
	v_add_u32_e32 v170, s17, v152
	ds_read_b128 v[128:131], v154
	ds_read_b128 v[144:147], v154 offset:1024
	ds_read_b128 v[148:151], v154 offset:2048
	ds_read_b128 v[154:157], v154 offset:3072
	ds_read_b128 v[158:161], v170
	ds_read_b128 v[162:165], v170 offset:1024
	ds_read_b128 v[166:169], v170 offset:2048
	ds_read_b128 v[170:173], v170 offset:3072
	s_add_u32 s12, s12, 0x40000
	s_addc_u32 s13, s13, 0
	s_mov_b32 m0, s95
	v_lshl_add_u64 v[224:225], s[12:13], 0, v[132:133]
	ds_read_b128 v[174:177], v153 offset:32768
	ds_read_b128 v[178:181], v153 offset:33792
	ds_read_b128 v[182:185], v153 offset:34816
	ds_read_b128 v[186:189], v153 offset:35840
	ds_read_b128 v[190:193], v153 offset:36864
	ds_read_b128 v[206:209], v153 offset:37888
	ds_read_b128 v[210:213], v153 offset:38912
	ds_read_b128 v[214:217], v153 offset:39936
	global_load_lds_dwordx4 v[224:225], off
	v_lshl_add_u64 v[224:225], s[12:13], 0, v[136:137]
	s_mov_b32 m0, s96
	s_nop 0
	global_load_lds_dwordx4 v[224:225], off
	s_mov_b32 m0, s93
	s_nop 0
	global_load_lds_dwordx4 v[220:221], off
	s_mov_b32 m0, s94
	s_nop 0
	global_load_lds_dwordx4 v[222:223], off
	s_waitcnt vmcnt(8)
	s_waitcnt lgkmcnt(0)
	s_barrier
	s_setprio 1
	s_waitcnt lgkmcnt(0)
	v_mfma_f32_16x16x32_bf16 v[124:127], v[128:131], v[174:177], v[124:127]
	v_mfma_f32_16x16x32_bf16 v[120:123], v[148:151], v[174:177], v[120:123]
	v_mfma_f32_16x16x32_bf16 v[116:119], v[128:131], v[182:185], v[116:119]
	v_mfma_f32_16x16x32_bf16 v[112:115], v[148:151], v[182:185], v[112:115]
	v_mfma_f32_16x16x32_bf16 v[108:111], v[128:131], v[190:193], v[108:111]
	v_mfma_f32_16x16x32_bf16 v[104:107], v[148:151], v[190:193], v[104:107]
	v_mfma_f32_16x16x32_bf16 v[100:103], v[128:131], v[210:213], v[100:103]
	v_mfma_f32_16x16x32_bf16 v[96:99], v[148:151], v[210:213], v[96:99]
	v_mfma_f32_16x16x32_bf16 v[124:127], v[144:147], v[178:181], v[124:127]
	v_mfma_f32_16x16x32_bf16 v[120:123], v[154:157], v[178:181], v[120:123]
	v_mfma_f32_16x16x32_bf16 v[116:119], v[144:147], v[186:189], v[116:119]
	v_mfma_f32_16x16x32_bf16 v[112:115], v[154:157], v[186:189], v[112:115]
	v_mfma_f32_16x16x32_bf16 v[108:111], v[144:147], v[206:209], v[108:111]
	v_mfma_f32_16x16x32_bf16 v[104:107], v[154:157], v[206:209], v[104:107]
	v_mfma_f32_16x16x32_bf16 v[100:103], v[144:147], v[214:217], v[100:103]
	v_mfma_f32_16x16x32_bf16 v[96:99], v[154:157], v[214:217], v[96:99]
	s_setprio 0
	s_setprio 1
	v_mfma_f32_16x16x32_bf16 v[60:63], v[158:161], v[174:177], v[60:63]
	v_mfma_f32_16x16x32_bf16 v[56:59], v[166:169], v[174:177], v[56:59]
	v_mfma_f32_16x16x32_bf16 v[52:55], v[158:161], v[182:185], v[52:55]
	v_mfma_f32_16x16x32_bf16 v[48:51], v[166:169], v[182:185], v[48:51]
	v_mfma_f32_16x16x32_bf16 v[44:47], v[158:161], v[190:193], v[44:47]
	v_mfma_f32_16x16x32_bf16 v[40:43], v[166:169], v[190:193], v[40:43]
	v_mfma_f32_16x16x32_bf16 v[36:39], v[158:161], v[210:213], v[36:39]
	v_mfma_f32_16x16x32_bf16 v[32:35], v[166:169], v[210:213], v[32:35]
	v_mfma_f32_16x16x32_bf16 v[60:63], v[162:165], v[178:181], v[60:63]
	v_mfma_f32_16x16x32_bf16 v[56:59], v[170:173], v[178:181], v[56:59]
	v_mfma_f32_16x16x32_bf16 v[52:55], v[162:165], v[186:189], v[52:55]
	v_mfma_f32_16x16x32_bf16 v[48:51], v[170:173], v[186:189], v[48:51]
	v_mfma_f32_16x16x32_bf16 v[44:47], v[162:165], v[206:209], v[44:47]
	v_mfma_f32_16x16x32_bf16 v[40:43], v[170:173], v[206:209], v[40:43]
	v_mfma_f32_16x16x32_bf16 v[36:39], v[162:165], v[214:217], v[36:39]
	v_mfma_f32_16x16x32_bf16 v[32:35], v[170:173], v[214:217], v[32:35]
	s_setprio 0
	s_barrier
; #define PG8_STAGE(bufoff, gbase, voff) do { _Pragma("unroll") for (int _i = 0; _i < 2; ++_i) \
;         __builtin_amdgcn_global_load_lds((const unsigned*)((const char*)(gbase) + (voff)[_i]), (PG8_LAS unsigned*)(lds + (bufoff) + ldsw + _i * 8192), 16, 0, 0); } while (0)
; #define PG8_LDA(dst, b, h) do { _Pragma("unroll") for (int m = 0; m < 4; ++m) _Pragma("unroll") for (int k = 0; k < 2; ++k) dst[m][k] = *(const PG8_LAS bf16x8*)(lds + PG8_SA(b, h) + aoff + m * 2048 + k * 1024); } while (0)
; #define PG8_MMA(ai, bj, At, Bt) do { __builtin_amdgcn_s_setprio(1); _Pragma("unroll") for (int m = 0; m < 4; ++m) _Pragma("unroll") for (int n = 0; n < 2; ++n) _Pragma("unroll") for (int k = 0; k < 2; ++k) \
;         acc[ai][bj][m][n] = __builtin_amdgcn_mfma_f32_16x16x32_bf16(Bt[n][k], At[m][k], acc[ai][bj][m][n], 0, 0, 0); __builtin_amdgcn_s_setprio(0); } while (0)
; #define PG8_WAIT_V(n) asm volatile("s_waitcnt vmcnt(" #n ")" ::: "memory")
; #define PG8_WAIT_L(n) asm volatile("s_waitcnt lgkmcnt(" #n ")" ::: "memory")
; #define PG8_BAR __builtin_amdgcn_s_barrier()
; #define PG8_SCHED __builtin_amdgcn_sched_barrier(0)
; template <class Epi, class Sched, bool ALIGN_EPI = false, bool SP2 = false>
; __device__ __forceinline__ void gemm_phase(PG8_LAS unsigned char* lds, const Gemm g, const Sched& S, const Epi& E, int wave_s_) {
;     ...
;             PG8_LDA(At, 1, 1); PG8_STAGE(PG8_SB(1, 0), b3, voffB); PG8_STAGE(PG8_SB(1, 1), b3 + hstep, voffB); PG8_STAGE(PG8_SA(1, 0), a3, voffA);
;             PG8_WAIT_V(8); PG8_WAIT_L(0); PG8_BAR; PG8_MMA(1, 0, At, B0); PG8_MMA(1, 1, At, B1); PG8_BAR; PG8_SCHED;
	s_add_i32 s12, s16, s92
	v_lshl_add_u64 v[194:195], v[194:195], 0, s[76:77]
	s_mov_b32 m0, s12
	ds_read_b128 v[174:177], v153 offset:49152
	ds_read_b128 v[178:181], v153 offset:50176
	ds_read_b128 v[182:185], v153 offset:51200
	ds_read_b128 v[186:189], v153 offset:52224
	ds_read_b128 v[190:193], v153 offset:53248
	ds_read_b128 v[206:209], v153 offset:54272
	ds_read_b128 v[210:213], v153 offset:55296
	ds_read_b128 v[214:217], v153 offset:56320
	global_load_lds_dwordx4 v[194:195], off
	s_add_i32 m0, s12, 0x2000
	s_add_u32 s10, s10, 0x40080
	v_lshl_add_u64 v[194:195], v[218:219], 0, s[76:77]
	s_addc_u32 s11, s11, 0
	s_add_i32 s12, s17, s92
	global_load_lds_dwordx4 v[194:195], off
	v_lshl_add_u64 v[194:195], s[10:11], 0, v[134:135]
	s_mov_b32 m0, s12
	s_nop 0
	global_load_lds_dwordx4 v[194:195], off
	v_lshl_add_u64 v[194:195], s[10:11], 0, v[138:139]
	s_add_i32 m0, s12, 0x2000
	s_nop 0
	global_load_lds_dwordx4 v[194:195], off
	v_lshl_add_u64 v[194:195], v[220:221], 0, s[76:77]
	s_mov_b32 m0, s48
	s_nop 0
	global_load_lds_dwordx4 v[194:195], off
	v_lshl_add_u64 v[194:195], v[222:223], 0, s[76:77]
	s_mov_b32 m0, s49
	s_nop 0
	global_load_lds_dwordx4 v[194:195], off
	s_waitcnt vmcnt(6)
	s_waitcnt lgkmcnt(0)
	s_barrier
	s_setprio 1
	s_waitcnt lgkmcnt(0)
	v_mfma_f32_16x16x32_bf16 v[92:95], v[128:131], v[174:177], v[92:95]
	v_mfma_f32_16x16x32_bf16 v[88:91], v[148:151], v[174:177], v[88:91]
	v_mfma_f32_16x16x32_bf16 v[84:87], v[128:131], v[182:185], v[84:87]
	v_mfma_f32_16x16x32_bf16 v[80:83], v[148:151], v[182:185], v[80:83]
	v_mfma_f32_16x16x32_bf16 v[76:79], v[128:131], v[190:193], v[76:79]
	v_mfma_f32_16x16x32_bf16 v[72:75], v[148:151], v[190:193], v[72:75]
	v_mfma_f32_16x16x32_bf16 v[68:71], v[128:131], v[210:213], v[68:71]
	v_mfma_f32_16x16x32_bf16 v[64:67], v[148:151], v[210:213], v[64:67]
	v_mfma_f32_16x16x32_bf16 v[92:95], v[144:147], v[178:181], v[92:95]
	v_mfma_f32_16x16x32_bf16 v[88:91], v[154:157], v[178:181], v[88:91]
	v_mfma_f32_16x16x32_bf16 v[84:87], v[144:147], v[186:189], v[84:87]
	v_mfma_f32_16x16x32_bf16 v[80:83], v[154:157], v[186:189], v[80:83]
	v_mfma_f32_16x16x32_bf16 v[76:79], v[144:147], v[206:209], v[76:79]
	v_mfma_f32_16x16x32_bf16 v[72:75], v[154:157], v[206:209], v[72:75]
	v_mfma_f32_16x16x32_bf16 v[68:71], v[144:147], v[214:217], v[68:71]
	v_mfma_f32_16x16x32_bf16 v[64:67], v[154:157], v[214:217], v[64:67]
	s_setprio 0
	s_setprio 1
	v_mfma_f32_16x16x32_bf16 v[28:31], v[158:161], v[174:177], v[28:31]
	v_mfma_f32_16x16x32_bf16 v[24:27], v[166:169], v[174:177], v[24:27]
	v_mfma_f32_16x16x32_bf16 v[20:23], v[158:161], v[182:185], v[20:23]
	v_mfma_f32_16x16x32_bf16 v[16:19], v[166:169], v[182:185], v[16:19]
	v_mfma_f32_16x16x32_bf16 v[12:15], v[158:161], v[190:193], v[12:15]
	v_mfma_f32_16x16x32_bf16 v[8:11], v[166:169], v[190:193], v[8:11]
	v_mfma_f32_16x16x32_bf16 v[4:7], v[158:161], v[210:213], v[4:7]
	v_mfma_f32_16x16x32_bf16 v[0:3], v[166:169], v[210:213], v[0:3]
	v_mfma_f32_16x16x32_bf16 v[28:31], v[162:165], v[178:181], v[28:31]
	v_mfma_f32_16x16x32_bf16 v[24:27], v[170:173], v[178:181], v[24:27]
	v_mfma_f32_16x16x32_bf16 v[20:23], v[162:165], v[186:189], v[20:23]
	v_mfma_f32_16x16x32_bf16 v[16:19], v[170:173], v[186:189], v[16:19]
	v_mfma_f32_16x16x32_bf16 v[12:15], v[162:165], v[206:209], v[12:15]
	v_mfma_f32_16x16x32_bf16 v[8:11], v[170:173], v[206:209], v[8:11]
	v_mfma_f32_16x16x32_bf16 v[4:7], v[162:165], v[214:217], v[4:7]
	v_mfma_f32_16x16x32_bf16 v[0:3], v[170:173], v[214:217], v[0:3]
	s_setprio 0
	s_barrier
	s_add_i32 s15, s15, 2
	s_add_u32 s6, s6, 0x100
	s_addc_u32 s7, s7, 0
	s_add_u32 s9, s9, 0x100
	s_addc_u32 s14, s14, 0
	s_cmp_gt_u32 s15, 13
	s_cbranch_scc0 .LBB0_562

;     __device__ __forceinline__ int nt_of(const Unit& u) const { return (u.pm >> 12) ? ktper : kt; }
; #define PG8_STAGE(bufoff, gbase, voff) do { _Pragma("unroll") for (int _i = 0; _i < 2; ++_i) \
;         __builtin_amdgcn_global_load_lds((const unsigned*)((const char*)(gbase) + (voff)[_i]), (PG8_LAS unsigned*)(lds + (bufoff) + ldsw + _i * 8192), 16, 0, 0); } while (0)
; #define PG8_LDA(dst, b, h) do { _Pragma("unroll") for (int m = 0; m < 4; ++m) _Pragma("unroll") for (int k = 0; k < 2; ++k) dst[m][k] = *(const PG8_LAS bf16x8*)(lds + PG8_SA(b, h) + aoff + m * 2048 + k * 1024); } while (0)
; #define PG8_LDB(dst, b, h) do { _Pragma("unroll") for (int n = 0; n < 2; ++n) _Pragma("unroll") for (int k = 0; k < 2; ++k) dst[n][k] = *(const PG8_LAS bf16x8*)(lds + PG8_SB(b, h) + boff + n * 2048 + k * 1024); } while (0)
; #define PG8_BAR __builtin_amdgcn_s_barrier()
; template <class Epi, class Sched, bool ALIGN_EPI = false, bool SP2 = false>
; __device__ __forceinline__ void gemm_phase(PG8_LAS unsigned char* lds, const Gemm g, const Sched& S, const Epi& E, int wave_s_) {
;     ...
;     for (;;) {
;         const bool has_next = S.next(ui + 1, nxt);
;         const char* nA = has_next ? (const char*)g.A + (size_t)(nxt.pm & 4095) * tstep + (size_t)S.k0_of(nxt) * kstep : cA; const char* nB = has_next ? (const char*)g.Bt + (size_t)nxt.pn * tstep + (size_t)S.k0_of(nxt) * kstep : cB;
;         const int nt = S.nt_of(cur);
;         for (int t = 0; t < nt; t += 2) {
;             const bool last = (t == nt - 2);
;             const char* a1 = cA + (size_t)(t + 1) * kstep;
;             const char* a2 = last ? nA : cA + (size_t)(t + 2) * kstep; const char* b2 = last ? nB : cB + (size_t)(t + 2) * kstep;
;             const char* a3 = a2 + kstep; const char* b3 = b2 + kstep;
;             if (last && has_next) S.a_ready(nxt);
;             if constexpr (SP2) {
;             PG8_LDB(B0, 0, 0); PG8_LDB(B1, 0, 1); PG8_SCHED; PG8_LDA(At, 0, 0); PG8_STAGE(PG8_SA(1, 1), a1 + hstep, voffA);
;             PG8_WAIT_V(8); PG8_WAIT_L(0); PG8_BAR; PG8_MMA(0, 0, At, B0); PG8_MMA(0, 1, At, B1); PG8_BAR; PG8_SCHED;
;             PG8_LDA(At, 0, 1); PG8_STAGE(PG8_SB(0, 0), b2, voffB); PG8_STAGE(PG8_SB(0, 1), b2 + hstep, voffB); PG8_STAGE(PG8_SA(0, 0), a2, voffA);
;             PG8_WAIT_V(8); PG8_WAIT_L(0); PG8_BAR; PG8_MMA(1, 0, At, B0); PG8_MMA(1, 1, At, B1); PG8_BAR; PG8_SCHED;
.LBB0_1184:
	s_add_u32 s18, s18, 0x40080
	s_addc_u32 s19, s19, 0
	s_add_u32 s15, s20, 0x100
	v_mov_b32_e32 v0, 0
	s_addc_u32 s44, s21, 0
	s_mov_b32 s45, -2
	s_add_u32 s20, s18, 0xfffc0080
	s_addc_u32 s21, s19, -1
	s_add_i32 s46, 0, 0x10000
	s_cmp_eq_u32 s45, 12
	s_cselect_b32 s23, s7, s21
	s_cselect_b32 s22, s6, s20
	s_cselect_b32 s21, s17, s44
	s_cselect_b32 s20, s16, s15
	s_add_i32 s48, 0, 0x14000
	v_add_u32_e32 v148, s46, v134
	v_add_u32_e32 v164, s48, v134
	ds_read_b128 v[136:139], v148
	ds_read_b128 v[140:143], v148 offset:1024
	ds_read_b128 v[144:147], v148 offset:2048
	ds_read_b128 v[148:151], v148 offset:3072
	ds_read_b128 v[152:155], v164
	ds_read_b128 v[156:159], v164 offset:1024
	ds_read_b128 v[160:163], v164 offset:2048
	ds_read_b128 v[164:167], v164 offset:3072
	v_lshl_add_u64 v[210:211], s[18:19], 0, v[130:131]
	s_add_i32 m0, s30, 0xc000
	ds_read_b128 v[168:171], v135
	ds_read_b128 v[172:175], v135 offset:1024
	ds_read_b128 v[176:179], v135 offset:2048
	ds_read_b128 v[180:183], v135 offset:3072
	ds_read_b128 v[184:187], v135 offset:4096
	ds_read_b128 v[188:191], v135 offset:5120
	ds_read_b128 v[192:195], v135 offset:6144
	ds_read_b128 v[206:209], v135 offset:7168
	global_load_lds_dwordx4 v[210:211], off
	v_lshl_add_u64 v[210:211], s[18:19], 0, v[132:133]
	s_add_i32 m0, s30, 0xe000
	s_nop 0
	global_load_lds_dwordx4 v[210:211], off
	s_waitcnt vmcnt(8)
	s_waitcnt lgkmcnt(0)
	s_barrier
	s_setprio 1
	s_waitcnt lgkmcnt(0)
	v_mfma_f32_16x16x32_bf16 v[124:127], v[136:139], v[168:171], 0
	v_mfma_f32_16x16x32_bf16 v[120:123], v[144:147], v[168:171], 0
	v_mfma_f32_16x16x32_bf16 v[116:119], v[136:139], v[176:179], 0
	v_mfma_f32_16x16x32_bf16 v[112:115], v[144:147], v[176:179], 0
	v_mfma_f32_16x16x32_bf16 v[108:111], v[136:139], v[184:187], 0
	v_mfma_f32_16x16x32_bf16 v[100:103], v[144:147], v[184:187], 0
	v_mfma_f32_16x16x32_bf16 v[92:95], v[136:139], v[192:195], 0
	v_mfma_f32_16x16x32_bf16 v[84:87], v[144:147], v[192:195], 0
	v_mfma_f32_16x16x32_bf16 v[124:127], v[140:143], v[172:175], v[124:127]
	v_mfma_f32_16x16x32_bf16 v[120:123], v[148:151], v[172:175], v[120:123]
	v_mfma_f32_16x16x32_bf16 v[116:119], v[140:143], v[180:183], v[116:119]
	v_mfma_f32_16x16x32_bf16 v[112:115], v[148:151], v[180:183], v[112:115]
	v_mfma_f32_16x16x32_bf16 v[108:111], v[140:143], v[188:191], v[108:111]
	v_mfma_f32_16x16x32_bf16 v[100:103], v[148:151], v[188:191], v[100:103]
	v_mfma_f32_16x16x32_bf16 v[92:95], v[140:143], v[206:209], v[92:95]
	v_mfma_f32_16x16x32_bf16 v[84:87], v[148:151], v[206:209], v[84:87]
	s_setprio 0
	s_setprio 1
	v_mfma_f32_16x16x32_bf16 v[104:107], v[152:155], v[168:171], 0
	v_mfma_f32_16x16x32_bf16 v[96:99], v[160:163], v[168:171], 0
	v_mfma_f32_16x16x32_bf16 v[88:91], v[152:155], v[176:179], 0
	v_mfma_f32_16x16x32_bf16 v[80:83], v[160:163], v[176:179], 0
	v_mfma_f32_16x16x32_bf16 v[76:79], v[152:155], v[184:187], 0
	v_mfma_f32_16x16x32_bf16 v[72:75], v[160:163], v[184:187], 0
	v_mfma_f32_16x16x32_bf16 v[68:71], v[152:155], v[192:195], 0
	v_mfma_f32_16x16x32_bf16 v[64:67], v[160:163], v[192:195], 0
	v_mfma_f32_16x16x32_bf16 v[104:107], v[156:159], v[172:175], v[104:107]
	v_mfma_f32_16x16x32_bf16 v[96:99], v[164:167], v[172:175], v[96:99]
	v_mfma_f32_16x16x32_bf16 v[88:91], v[156:159], v[180:183], v[88:91]
	v_mfma_f32_16x16x32_bf16 v[80:83], v[164:167], v[180:183], v[80:83]
	v_mfma_f32_16x16x32_bf16 v[76:79], v[156:159], v[188:191], v[76:79]
	v_mfma_f32_16x16x32_bf16 v[72:75], v[164:167], v[188:191], v[72:75]
	v_mfma_f32_16x16x32_bf16 v[68:71], v[156:159], v[206:209], v[68:71]
	v_mfma_f32_16x16x32_bf16 v[64:67], v[164:167], v[206:209], v[64:67]
	s_setprio 0
	s_barrier
	s_add_i32 s46, s46, s29
	v_lshl_add_u64 v[210:211], s[20:21], 0, v[196:197]
	s_mov_b32 m0, s46
	ds_read_b128 v[168:171], v135 offset:16384
	ds_read_b128 v[172:175], v135 offset:17408
	ds_read_b128 v[176:179], v135 offset:18432
	ds_read_b128 v[180:183], v135 offset:19456
	ds_read_b128 v[184:187], v135 offset:20480
	ds_read_b128 v[188:191], v135 offset:21504
	ds_read_b128 v[192:195], v135 offset:22528
	ds_read_b128 v[206:209], v135 offset:23552
	global_load_lds_dwordx4 v[210:211], off
	s_add_i32 m0, s46, 0x2000
	s_add_u32 s46, s20, 0x40000
	v_lshl_add_u64 v[212:213], s[20:21], 0, v[128:129]
	s_addc_u32 s47, s21, 0
	s_add_i32 s48, s48, s29
	global_load_lds_dwordx4 v[212:213], off
	v_lshl_add_u64 v[214:215], s[46:47], 0, v[196:197]
	s_mov_b32 m0, s48
	v_lshl_add_u64 v[216:217], s[22:23], 0, v[128:129]
	global_load_lds_dwordx4 v[214:215], off
	v_lshl_add_u64 v[214:215], s[46:47], 0, v[128:129]
	s_add_i32 m0, s48, 0x2000
	s_nop 0
	global_load_lds_dwordx4 v[214:215], off
	v_lshl_add_u64 v[214:215], s[22:23], 0, v[196:197]
	s_waitcnt vmcnt(6)
	s_waitcnt lgkmcnt(0)
	s_barrier
; #define PG8_STAGE(bufoff, gbase, voff) do { _Pragma("unroll") for (int _i = 0; _i < 2; ++_i) \
;         __builtin_amdgcn_global_load_lds((const unsigned*)((const char*)(gbase) + (voff)[_i]), (PG8_LAS unsigned*)(lds + (bufoff) + ldsw + _i * 8192), 16, 0, 0); } while (0)
; #define PG8_LDA(dst, b, h) do { _Pragma("unroll") for (int m = 0; m < 4; ++m) _Pragma("unroll") for (int k = 0; k < 2; ++k) dst[m][k] = *(const PG8_LAS bf16x8*)(lds + PG8_SA(b, h) + aoff + m * 2048 + k * 1024); } while (0)
; #define PG8_LDB(dst, b, h) do { _Pragma("unroll") for (int n = 0; n < 2; ++n) _Pragma("unroll") for (int k = 0; k < 2; ++k) dst[n][k] = *(const PG8_LAS bf16x8*)(lds + PG8_SB(b, h) + boff + n * 2048 + k * 1024); } while (0)
; #define PG8_MMA(ai, bj, At, Bt) do { __builtin_amdgcn_s_setprio(1); _Pragma("unroll") for (int m = 0; m < 4; ++m) _Pragma("unroll") for (int n = 0; n < 2; ++n) _Pragma("unroll") for (int k = 0; k < 2; ++k) \
;         acc[ai][bj][m][n] = __builtin_amdgcn_mfma_f32_16x16x32_bf16(Bt[n][k], At[m][k], acc[ai][bj][m][n], 0, 0, 0); __builtin_amdgcn_s_setprio(0); } while (0)
; #define PG8_WAIT_V(n) asm volatile("s_waitcnt vmcnt(" #n ")" ::: "memory")
; #define PG8_WAIT_L(n) asm volatile("s_waitcnt lgkmcnt(" #n ")" ::: "memory")
; #define PG8_BAR __builtin_amdgcn_s_barrier()
; #define PG8_SCHED __builtin_amdgcn_sched_barrier(0)
; template <class Epi, class Sched, bool ALIGN_EPI = false, bool SP2 = false>
; __device__ __forceinline__ void gemm_phase(PG8_LAS unsigned char* lds, const Gemm g, const Sched& S, const Epi& E, int wave_s_) {
;     ...
;             PG8_WAIT_V(8); PG8_WAIT_L(0); PG8_BAR; PG8_MMA(1, 0, At, B0); PG8_MMA(1, 1, At, B1); PG8_BAR; PG8_SCHED;
;             PG8_LDB(B0, 1, 0); PG8_LDB(B1, 1, 1); PG8_SCHED; PG8_LDA(At, 1, 0); PG8_STAGE(PG8_SA(0, 1), a2 + hstep, voffA);
;             PG8_WAIT_V(8); PG8_WAIT_L(0); PG8_BAR; PG8_MMA(0, 0, At, B0); PG8_MMA(0, 1, At, B1); PG8_BAR; PG8_SCHED;
	s_setprio 1
	s_waitcnt lgkmcnt(0)
	v_mfma_f32_16x16x32_bf16 v[60:63], v[136:139], v[168:171], 0
	v_mfma_f32_16x16x32_bf16 v[56:59], v[144:147], v[168:171], 0
	v_mfma_f32_16x16x32_bf16 v[52:55], v[136:139], v[176:179], 0
	v_mfma_f32_16x16x32_bf16 v[48:51], v[144:147], v[176:179], 0
	v_mfma_f32_16x16x32_bf16 v[44:47], v[136:139], v[184:187], 0
	v_mfma_f32_16x16x32_bf16 v[36:39], v[144:147], v[184:187], 0
	v_mfma_f32_16x16x32_bf16 v[28:31], v[136:139], v[192:195], 0
	v_mfma_f32_16x16x32_bf16 v[20:23], v[144:147], v[192:195], 0
	v_mfma_f32_16x16x32_bf16 v[60:63], v[140:143], v[172:175], v[60:63]
	v_mfma_f32_16x16x32_bf16 v[56:59], v[148:151], v[172:175], v[56:59]
	v_mfma_f32_16x16x32_bf16 v[52:55], v[140:143], v[180:183], v[52:55]
	v_mfma_f32_16x16x32_bf16 v[48:51], v[148:151], v[180:183], v[48:51]
	v_mfma_f32_16x16x32_bf16 v[44:47], v[140:143], v[188:191], v[44:47]
	v_mfma_f32_16x16x32_bf16 v[36:39], v[148:151], v[188:191], v[36:39]
	v_mfma_f32_16x16x32_bf16 v[28:31], v[140:143], v[206:209], v[28:31]
	v_mfma_f32_16x16x32_bf16 v[20:23], v[148:151], v[206:209], v[20:23]
	s_setprio 0
	s_setprio 1
	v_mfma_f32_16x16x32_bf16 v[40:43], v[152:155], v[168:171], 0
	v_mfma_f32_16x16x32_bf16 v[32:35], v[160:163], v[168:171], 0
	v_mfma_f32_16x16x32_bf16 v[24:27], v[152:155], v[176:179], 0
	v_mfma_f32_16x16x32_bf16 v[16:19], v[160:163], v[176:179], 0
	v_mfma_f32_16x16x32_bf16 v[12:15], v[152:155], v[184:187], 0
	v_mfma_f32_16x16x32_bf16 v[8:11], v[160:163], v[184:187], 0
	v_mfma_f32_16x16x32_bf16 v[4:7], v[152:155], v[192:195], 0
	v_mfma_f32_16x16x32_bf16 v[0:3], v[160:163], v[192:195], 0
	v_mfma_f32_16x16x32_bf16 v[40:43], v[156:159], v[172:175], v[40:43]
	v_mfma_f32_16x16x32_bf16 v[32:35], v[164:167], v[172:175], v[32:35]
	v_mfma_f32_16x16x32_bf16 v[24:27], v[156:159], v[180:183], v[24:27]
	v_mfma_f32_16x16x32_bf16 v[16:19], v[164:167], v[180:183], v[16:19]
	v_mfma_f32_16x16x32_bf16 v[12:15], v[156:159], v[188:191], v[12:15]
	v_mfma_f32_16x16x32_bf16 v[8:11], v[164:167], v[188:191], v[8:11]
	v_mfma_f32_16x16x32_bf16 v[4:7], v[156:159], v[206:209], v[4:7]
	v_mfma_f32_16x16x32_bf16 v[0:3], v[164:167], v[206:209], v[0:3]
	s_setprio 0
	s_barrier
	s_add_i32 s46, 0, 0x18000
	s_add_i32 s47, 0, 0x1c000
	v_add_u32_e32 v148, s46, v134
	v_add_u32_e32 v164, s47, v134
	ds_read_b128 v[136:139], v148
	ds_read_b128 v[140:143], v148 offset:1024
	ds_read_b128 v[144:147], v148 offset:2048
	ds_read_b128 v[148:151], v148 offset:3072
	ds_read_b128 v[152:155], v164
	ds_read_b128 v[156:159], v164 offset:1024
	ds_read_b128 v[160:163], v164 offset:2048
	ds_read_b128 v[164:167], v164 offset:3072
	s_add_u32 s22, s22, 0x40000
	s_addc_u32 s23, s23, 0
	s_mov_b32 m0, s33
	v_lshl_add_u64 v[218:219], s[22:23], 0, v[196:197]
	ds_read_b128 v[168:171], v135 offset:32768
	ds_read_b128 v[172:175], v135 offset:33792
	ds_read_b128 v[176:179], v135 offset:34816
	ds_read_b128 v[180:183], v135 offset:35840
	ds_read_b128 v[184:187], v135 offset:36864
	ds_read_b128 v[188:191], v135 offset:37888
	ds_read_b128 v[192:195], v135 offset:38912
	ds_read_b128 v[206:209], v135 offset:39936
	global_load_lds_dwordx4 v[218:219], off
	v_lshl_add_u64 v[218:219], s[22:23], 0, v[128:129]
	s_mov_b32 m0, s34
	s_nop 0
	global_load_lds_dwordx4 v[218:219], off
	s_mov_b32 m0, s30
	s_nop 0
	global_load_lds_dwordx4 v[214:215], off
	s_mov_b32 m0, s31
	s_nop 0
	global_load_lds_dwordx4 v[216:217], off
	s_waitcnt vmcnt(8)
	s_waitcnt lgkmcnt(0)
	s_barrier
	s_setprio 1
	s_waitcnt lgkmcnt(0)
	v_mfma_f32_16x16x32_bf16 v[124:127], v[136:139], v[168:171], v[124:127]
	v_mfma_f32_16x16x32_bf16 v[120:123], v[144:147], v[168:171], v[120:123]
	v_mfma_f32_16x16x32_bf16 v[116:119], v[136:139], v[176:179], v[116:119]
	v_mfma_f32_16x16x32_bf16 v[112:115], v[144:147], v[176:179], v[112:115]
	v_mfma_f32_16x16x32_bf16 v[108:111], v[136:139], v[184:187], v[108:111]
	v_mfma_f32_16x16x32_bf16 v[100:103], v[144:147], v[184:187], v[100:103]
	v_mfma_f32_16x16x32_bf16 v[92:95], v[136:139], v[192:195], v[92:95]
	v_mfma_f32_16x16x32_bf16 v[84:87], v[144:147], v[192:195], v[84:87]
	v_mfma_f32_16x16x32_bf16 v[124:127], v[140:143], v[172:175], v[124:127]
	v_mfma_f32_16x16x32_bf16 v[120:123], v[148:151], v[172:175], v[120:123]
	v_mfma_f32_16x16x32_bf16 v[116:119], v[140:143], v[180:183], v[116:119]
	v_mfma_f32_16x16x32_bf16 v[112:115], v[148:151], v[180:183], v[112:115]
	v_mfma_f32_16x16x32_bf16 v[108:111], v[140:143], v[188:191], v[108:111]
	v_mfma_f32_16x16x32_bf16 v[100:103], v[148:151], v[188:191], v[100:103]
	v_mfma_f32_16x16x32_bf16 v[92:95], v[140:143], v[206:209], v[92:95]
	v_mfma_f32_16x16x32_bf16 v[84:87], v[148:151], v[206:209], v[84:87]
	s_setprio 0
	s_setprio 1
	v_mfma_f32_16x16x32_bf16 v[104:107], v[152:155], v[168:171], v[104:107]
	v_mfma_f32_16x16x32_bf16 v[96:99], v[160:163], v[168:171], v[96:99]
	v_mfma_f32_16x16x32_bf16 v[88:91], v[152:155], v[176:179], v[88:91]
	v_mfma_f32_16x16x32_bf16 v[80:83], v[160:163], v[176:179], v[80:83]
	v_mfma_f32_16x16x32_bf16 v[76:79], v[152:155], v[184:187], v[76:79]
	v_mfma_f32_16x16x32_bf16 v[72:75], v[160:163], v[184:187], v[72:75]
	v_mfma_f32_16x16x32_bf16 v[68:71], v[152:155], v[192:195], v[68:71]
	v_mfma_f32_16x16x32_bf16 v[64:67], v[160:163], v[192:195], v[64:67]
	v_mfma_f32_16x16x32_bf16 v[104:107], v[156:159], v[172:175], v[104:107]
	v_mfma_f32_16x16x32_bf16 v[96:99], v[164:167], v[172:175], v[96:99]
	v_mfma_f32_16x16x32_bf16 v[88:91], v[156:159], v[180:183], v[88:91]
	v_mfma_f32_16x16x32_bf16 v[80:83], v[164:167], v[180:183], v[80:83]
	v_mfma_f32_16x16x32_bf16 v[76:79], v[156:159], v[188:191], v[76:79]
	v_mfma_f32_16x16x32_bf16 v[72:75], v[164:167], v[188:191], v[72:75]
	v_mfma_f32_16x16x32_bf16 v[68:71], v[156:159], v[206:209], v[68:71]
	v_mfma_f32_16x16x32_bf16 v[64:67], v[164:167], v[206:209], v[64:67]
	s_setprio 0
	s_barrier
; #define PG8_STAGE(bufoff, gbase, voff) do { _Pragma("unroll") for (int _i = 0; _i < 2; ++_i) \
;         __builtin_amdgcn_global_load_lds((const unsigned*)((const char*)(gbase) + (voff)[_i]), (PG8_LAS unsigned*)(lds + (bufoff) + ldsw + _i * 8192), 16, 0, 0); } while (0)
; #define PG8_LDA(dst, b, h) do { _Pragma("unroll") for (int m = 0; m < 4; ++m) _Pragma("unroll") for (int k = 0; k < 2; ++k) dst[m][k] = *(const PG8_LAS bf16x8*)(lds + PG8_SA(b, h) + aoff + m * 2048 + k * 1024); } while (0)
; #define PG8_LDB(dst, b, h) do { _Pragma("unroll") for (int n = 0; n < 2; ++n) _Pragma("unroll") for (int k = 0; k < 2; ++k) dst[n][k] = *(const PG8_LAS bf16x8*)(lds + PG8_SB(b, h) + boff + n * 2048 + k * 1024); } while (0)
; #define PG8_MMA(ai, bj, At, Bt) do { __builtin_amdgcn_s_setprio(1); _Pragma("unroll") for (int m = 0; m < 4; ++m) _Pragma("unroll") for (int n = 0; n < 2; ++n) _Pragma("unroll") for (int k = 0; k < 2; ++k) \
;         acc[ai][bj][m][n] = __builtin_amdgcn_mfma_f32_16x16x32_bf16(Bt[n][k], At[m][k], acc[ai][bj][m][n], 0, 0, 0); __builtin_amdgcn_s_setprio(0); } while (0)
; #define PG8_WAIT_V(n) asm volatile("s_waitcnt vmcnt(" #n ")" ::: "memory")
; #define PG8_BAR __builtin_amdgcn_s_barrier()
; template <class Epi, class Sched, bool ALIGN_EPI = false, bool SP2 = false>
; __device__ __forceinline__ void gemm_phase(PG8_LAS unsigned char* lds, const Gemm g, const Sched& S, const Epi& E, int wave_s_) {
;     ...
;         for (int t = 0; t < nt; t += 2) {
;             const bool last = (t == nt - 2);
;             const char* a1 = cA + (size_t)(t + 1) * kstep;
;             const char* a2 = last ? nA : cA + (size_t)(t + 2) * kstep; const char* b2 = last ? nB : cB + (size_t)(t + 2) * kstep;
;             const char* a3 = a2 + kstep; const char* b3 = b2 + kstep;
;             if (last && has_next) S.a_ready(nxt);
;             if constexpr (SP2) {
;             PG8_LDB(B0, 0, 0); PG8_LDB(B1, 0, 1); PG8_SCHED; PG8_LDA(At, 0, 0); PG8_STAGE(PG8_SA(1, 1), a1 + hstep, voffA);
;             PG8_WAIT_V(8); PG8_WAIT_L(0); PG8_BAR; PG8_MMA(0, 0, At, B0); PG8_MMA(0, 1, At, B1); PG8_BAR; PG8_SCHED;
;     ...
;             PG8_LDA(At, 1, 1); PG8_STAGE(PG8_SB(1, 0), b3, voffB); PG8_STAGE(PG8_SB(1, 1), b3 + hstep, voffB); PG8_STAGE(PG8_SA(1, 0), a3, voffA);
;             PG8_WAIT_V(8); PG8_WAIT_L(0); PG8_BAR; PG8_MMA(1, 0, At, B0); PG8_MMA(1, 1, At, B1); PG8_BAR; PG8_SCHED;
	s_add_i32 s22, s46, s29
	v_lshl_add_u64 v[210:211], v[210:211], 0, s[76:77]
	s_mov_b32 m0, s22
	ds_read_b128 v[168:171], v135 offset:49152
	ds_read_b128 v[172:175], v135 offset:50176
	ds_read_b128 v[176:179], v135 offset:51200
	ds_read_b128 v[180:183], v135 offset:52224
	ds_read_b128 v[184:187], v135 offset:53248
	ds_read_b128 v[188:191], v135 offset:54272
	ds_read_b128 v[192:195], v135 offset:55296
	ds_read_b128 v[206:209], v135 offset:56320
	global_load_lds_dwordx4 v[210:211], off
	s_add_i32 m0, s22, 0x2000
	s_add_u32 s20, s20, 0x40080
	v_lshl_add_u64 v[210:211], v[212:213], 0, s[76:77]
	s_addc_u32 s21, s21, 0
	s_add_i32 s22, s47, s29
	global_load_lds_dwordx4 v[210:211], off
	v_lshl_add_u64 v[210:211], s[20:21], 0, v[196:197]
	s_mov_b32 m0, s22
	s_nop 0
	global_load_lds_dwordx4 v[210:211], off
	v_lshl_add_u64 v[210:211], s[20:21], 0, v[128:129]
	s_add_i32 m0, s22, 0x2000
	s_nop 0
	global_load_lds_dwordx4 v[210:211], off
	v_lshl_add_u64 v[210:211], v[214:215], 0, s[76:77]
	s_mov_b32 m0, s38
	s_nop 0
	global_load_lds_dwordx4 v[210:211], off
	v_lshl_add_u64 v[210:211], v[216:217], 0, s[76:77]
	s_mov_b32 m0, s39
	s_nop 0
	global_load_lds_dwordx4 v[210:211], off
	s_waitcnt vmcnt(6)
	s_waitcnt lgkmcnt(0)
	s_barrier
	s_setprio 1
	s_waitcnt lgkmcnt(0)
	v_mfma_f32_16x16x32_bf16 v[60:63], v[136:139], v[168:171], v[60:63]
	v_mfma_f32_16x16x32_bf16 v[56:59], v[144:147], v[168:171], v[56:59]
	v_mfma_f32_16x16x32_bf16 v[52:55], v[136:139], v[176:179], v[52:55]
	v_mfma_f32_16x16x32_bf16 v[48:51], v[144:147], v[176:179], v[48:51]
	v_mfma_f32_16x16x32_bf16 v[44:47], v[136:139], v[184:187], v[44:47]
	v_mfma_f32_16x16x32_bf16 v[36:39], v[144:147], v[184:187], v[36:39]
	v_mfma_f32_16x16x32_bf16 v[28:31], v[136:139], v[192:195], v[28:31]
	v_mfma_f32_16x16x32_bf16 v[20:23], v[144:147], v[192:195], v[20:23]
	v_mfma_f32_16x16x32_bf16 v[60:63], v[140:143], v[172:175], v[60:63]
	v_mfma_f32_16x16x32_bf16 v[56:59], v[148:151], v[172:175], v[56:59]
	v_mfma_f32_16x16x32_bf16 v[52:55], v[140:143], v[180:183], v[52:55]
	v_mfma_f32_16x16x32_bf16 v[48:51], v[148:151], v[180:183], v[48:51]
	v_mfma_f32_16x16x32_bf16 v[44:47], v[140:143], v[188:191], v[44:47]
	v_mfma_f32_16x16x32_bf16 v[36:39], v[148:151], v[188:191], v[36:39]
	v_mfma_f32_16x16x32_bf16 v[28:31], v[140:143], v[206:209], v[28:31]
	v_mfma_f32_16x16x32_bf16 v[20:23], v[148:151], v[206:209], v[20:23]
	s_setprio 0
	s_setprio 1
	v_mfma_f32_16x16x32_bf16 v[40:43], v[152:155], v[168:171], v[40:43]
	v_mfma_f32_16x16x32_bf16 v[32:35], v[160:163], v[168:171], v[32:35]
	v_mfma_f32_16x16x32_bf16 v[24:27], v[152:155], v[176:179], v[24:27]
	v_mfma_f32_16x16x32_bf16 v[16:19], v[160:163], v[176:179], v[16:19]
	v_mfma_f32_16x16x32_bf16 v[12:15], v[152:155], v[184:187], v[12:15]
	v_mfma_f32_16x16x32_bf16 v[8:11], v[160:163], v[184:187], v[8:11]
	v_mfma_f32_16x16x32_bf16 v[4:7], v[152:155], v[192:195], v[4:7]
	v_mfma_f32_16x16x32_bf16 v[0:3], v[160:163], v[192:195], v[0:3]
	v_mfma_f32_16x16x32_bf16 v[40:43], v[156:159], v[172:175], v[40:43]
	v_mfma_f32_16x16x32_bf16 v[32:35], v[164:167], v[172:175], v[32:35]
	v_mfma_f32_16x16x32_bf16 v[24:27], v[156:159], v[180:183], v[24:27]
	v_mfma_f32_16x16x32_bf16 v[16:19], v[164:167], v[180:183], v[16:19]
	v_mfma_f32_16x16x32_bf16 v[12:15], v[156:159], v[188:191], v[12:15]
	v_mfma_f32_16x16x32_bf16 v[8:11], v[164:167], v[188:191], v[8:11]
	v_mfma_f32_16x16x32_bf16 v[4:7], v[156:159], v[206:209], v[4:7]
	v_mfma_f32_16x16x32_bf16 v[0:3], v[164:167], v[206:209], v[0:3]
	s_setprio 0
	s_barrier
	s_add_i32 s45, s45, 2
	s_add_u32 s18, s18, 0x100
	s_addc_u32 s19, s19, 0
	s_add_u32 s15, s15, 0x100
	s_addc_u32 s44, s44, 0
	s_cmp_gt_u32 s45, 13
	s_cbranch_scc0 .LBB0_1185
	s_branch .Lpeel_exit_3
.LBB0_1185:
	s_add_u32 s20, s18, 0xfffc0080
	s_addc_u32 s21, s19, -1
	s_add_i32 s46, 0, 0x10000
	s_cmp_eq_u32 s45, 12
	s_cselect_b32 s23, s7, s21
	s_cselect_b32 s22, s6, s20
	s_cselect_b32 s21, s17, s44
	s_cselect_b32 s20, s16, s15
	s_add_i32 s48, 0, 0x14000
	v_add_u32_e32 v148, s46, v134
	v_add_u32_e32 v164, s48, v134
	ds_read_b128 v[136:139], v148
	ds_read_b128 v[140:143], v148 offset:1024
	ds_read_b128 v[144:147], v148 offset:2048
	ds_read_b128 v[148:151], v148 offset:3072
	ds_read_b128 v[152:155], v164
	ds_read_b128 v[156:159], v164 offset:1024
	ds_read_b128 v[160:163], v164 offset:2048
	ds_read_b128 v[164:167], v164 offset:3072
	v_lshl_add_u64 v[210:211], s[18:19], 0, v[130:131]
	s_add_i32 m0, s30, 0xc000
	ds_read_b128 v[168:171], v135
	ds_read_b128 v[172:175], v135 offset:1024
	ds_read_b128 v[176:179], v135 offset:2048
	ds_read_b128 v[180:183], v135 offset:3072
	ds_read_b128 v[184:187], v135 offset:4096
	ds_read_b128 v[188:191], v135 offset:5120
	ds_read_b128 v[192:195], v135 offset:6144
	ds_read_b128 v[206:209], v135 offset:7168
	global_load_lds_dwordx4 v[210:211], off
	v_lshl_add_u64 v[210:211], s[18:19], 0, v[132:133]
	s_add_i32 m0, s30, 0xe000
	s_nop 0
	global_load_lds_dwordx4 v[210:211], off
	s_waitcnt vmcnt(8)
	s_waitcnt lgkmcnt(0)
	s_barrier
; #define PG8_STAGE(bufoff, gbase, voff) do { _Pragma("unroll") for (int _i = 0; _i < 2; ++_i) \
;         __builtin_amdgcn_global_load_lds((const unsigned*)((const char*)(gbase) + (voff)[_i]), (PG8_LAS unsigned*)(lds + (bufoff) + ldsw + _i * 8192), 16, 0, 0); } while (0)
; #define PG8_LDA(dst, b, h) do { _Pragma("unroll") for (int m = 0; m < 4; ++m) _Pragma("unroll") for (int k = 0; k < 2; ++k) dst[m][k] = *(const PG8_LAS bf16x8*)(lds + PG8_SA(b, h) + aoff + m * 2048 + k * 1024); } while (0)
; #define PG8_MMA(ai, bj, At, Bt) do { __builtin_amdgcn_s_setprio(1); _Pragma("unroll") for (int m = 0; m < 4; ++m) _Pragma("unroll") for (int n = 0; n < 2; ++n) _Pragma("unroll") for (int k = 0; k < 2; ++k) \
;         acc[ai][bj][m][n] = __builtin_amdgcn_mfma_f32_16x16x32_bf16(Bt[n][k], At[m][k], acc[ai][bj][m][n], 0, 0, 0); __builtin_amdgcn_s_setprio(0); } while (0)
; #define PG8_WAIT_V(n) asm volatile("s_waitcnt vmcnt(" #n ")" ::: "memory")
; #define PG8_WAIT_L(n) asm volatile("s_waitcnt lgkmcnt(" #n ")" ::: "memory")
; #define PG8_BAR __builtin_amdgcn_s_barrier()
; #define PG8_SCHED __builtin_amdgcn_sched_barrier(0)
; template <class Epi, class Sched, bool ALIGN_EPI = false, bool SP2 = false>
; __device__ __forceinline__ void gemm_phase(PG8_LAS unsigned char* lds, const Gemm g, const Sched& S, const Epi& E, int wave_s_) {
;     ...
;             PG8_WAIT_V(8); PG8_WAIT_L(0); PG8_BAR; PG8_MMA(0, 0, At, B0); PG8_MMA(0, 1, At, B1); PG8_BAR; PG8_SCHED;
;             PG8_LDA(At, 0, 1); PG8_STAGE(PG8_SB(0, 0), b2, voffB); PG8_STAGE(PG8_SB(0, 1), b2 + hstep, voffB); PG8_STAGE(PG8_SA(0, 0), a2, voffA);
;             PG8_WAIT_V(8); PG8_WAIT_L(0); PG8_BAR; PG8_MMA(1, 0, At, B0); PG8_MMA(1, 1, At, B1); PG8_BAR; PG8_SCHED;
	s_setprio 1
	s_waitcnt lgkmcnt(0)
	v_mfma_f32_16x16x32_bf16 v[124:127], v[136:139], v[168:171], v[124:127]
	v_mfma_f32_16x16x32_bf16 v[120:123], v[144:147], v[168:171], v[120:123]
	v_mfma_f32_16x16x32_bf16 v[116:119], v[136:139], v[176:179], v[116:119]
	v_mfma_f32_16x16x32_bf16 v[112:115], v[144:147], v[176:179], v[112:115]
	v_mfma_f32_16x16x32_bf16 v[108:111], v[136:139], v[184:187], v[108:111]
	v_mfma_f32_16x16x32_bf16 v[100:103], v[144:147], v[184:187], v[100:103]
	v_mfma_f32_16x16x32_bf16 v[92:95], v[136:139], v[192:195], v[92:95]
	v_mfma_f32_16x16x32_bf16 v[84:87], v[144:147], v[192:195], v[84:87]
	v_mfma_f32_16x16x32_bf16 v[124:127], v[140:143], v[172:175], v[124:127]
	v_mfma_f32_16x16x32_bf16 v[120:123], v[148:151], v[172:175], v[120:123]
	v_mfma_f32_16x16x32_bf16 v[116:119], v[140:143], v[180:183], v[116:119]
	v_mfma_f32_16x16x32_bf16 v[112:115], v[148:151], v[180:183], v[112:115]
	v_mfma_f32_16x16x32_bf16 v[108:111], v[140:143], v[188:191], v[108:111]
	v_mfma_f32_16x16x32_bf16 v[100:103], v[148:151], v[188:191], v[100:103]
	v_mfma_f32_16x16x32_bf16 v[92:95], v[140:143], v[206:209], v[92:95]
	v_mfma_f32_16x16x32_bf16 v[84:87], v[148:151], v[206:209], v[84:87]
	s_setprio 0
	s_setprio 1
	v_mfma_f32_16x16x32_bf16 v[104:107], v[152:155], v[168:171], v[104:107]
	v_mfma_f32_16x16x32_bf16 v[96:99], v[160:163], v[168:171], v[96:99]
	v_mfma_f32_16x16x32_bf16 v[88:91], v[152:155], v[176:179], v[88:91]
	v_mfma_f32_16x16x32_bf16 v[80:83], v[160:163], v[176:179], v[80:83]
	v_mfma_f32_16x16x32_bf16 v[76:79], v[152:155], v[184:187], v[76:79]
	v_mfma_f32_16x16x32_bf16 v[72:75], v[160:163], v[184:187], v[72:75]
	v_mfma_f32_16x16x32_bf16 v[68:71], v[152:155], v[192:195], v[68:71]
	v_mfma_f32_16x16x32_bf16 v[64:67], v[160:163], v[192:195], v[64:67]
	v_mfma_f32_16x16x32_bf16 v[104:107], v[156:159], v[172:175], v[104:107]
	v_mfma_f32_16x16x32_bf16 v[96:99], v[164:167], v[172:175], v[96:99]
	v_mfma_f32_16x16x32_bf16 v[88:91], v[156:159], v[180:183], v[88:91]
	v_mfma_f32_16x16x32_bf16 v[80:83], v[164:167], v[180:183], v[80:83]
	v_mfma_f32_16x16x32_bf16 v[76:79], v[156:159], v[188:191], v[76:79]
	v_mfma_f32_16x16x32_bf16 v[72:75], v[164:167], v[188:191], v[72:75]
	v_mfma_f32_16x16x32_bf16 v[68:71], v[156:159], v[206:209], v[68:71]
	v_mfma_f32_16x16x32_bf16 v[64:67], v[164:167], v[206:209], v[64:67]
	s_setprio 0
	s_barrier
	s_add_i32 s46, s46, s29
	v_lshl_add_u64 v[210:211], s[20:21], 0, v[196:197]
	s_mov_b32 m0, s46
	ds_read_b128 v[168:171], v135 offset:16384
	ds_read_b128 v[172:175], v135 offset:17408
	ds_read_b128 v[176:179], v135 offset:18432
	ds_read_b128 v[180:183], v135 offset:19456
	ds_read_b128 v[184:187], v135 offset:20480
	ds_read_b128 v[188:191], v135 offset:21504
	ds_read_b128 v[192:195], v135 offset:22528
	ds_read_b128 v[206:209], v135 offset:23552
	global_load_lds_dwordx4 v[210:211], off
	s_add_i32 m0, s46, 0x2000
	s_add_u32 s46, s20, 0x40000
	v_lshl_add_u64 v[212:213], s[20:21], 0, v[128:129]
	s_addc_u32 s47, s21, 0
	s_add_i32 s48, s48, s29
	global_load_lds_dwordx4 v[212:213], off
	v_lshl_add_u64 v[214:215], s[46:47], 0, v[196:197]
	s_mov_b32 m0, s48
	v_lshl_add_u64 v[216:217], s[22:23], 0, v[128:129]
	global_load_lds_dwordx4 v[214:215], off
	v_lshl_add_u64 v[214:215], s[46:47], 0, v[128:129]
	s_add_i32 m0, s48, 0x2000
	s_nop 0
	global_load_lds_dwordx4 v[214:215], off
	v_lshl_add_u64 v[214:215], s[22:23], 0, v[196:197]
	s_waitcnt vmcnt(6)
	s_waitcnt lgkmcnt(0)
	s_barrier
	s_setprio 1
	s_waitcnt lgkmcnt(0)
	v_mfma_f32_16x16x32_bf16 v[60:63], v[136:139], v[168:171], v[60:63]
	v_mfma_f32_16x16x32_bf16 v[56:59], v[144:147], v[168:171], v[56:59]
	v_mfma_f32_16x16x32_bf16 v[52:55], v[136:139], v[176:179], v[52:55]
	v_mfma_f32_16x16x32_bf16 v[48:51], v[144:147], v[176:179], v[48:51]
	v_mfma_f32_16x16x32_bf16 v[44:47], v[136:139], v[184:187], v[44:47]
	v_mfma_f32_16x16x32_bf16 v[36:39], v[144:147], v[184:187], v[36:39]
	v_mfma_f32_16x16x32_bf16 v[28:31], v[136:139], v[192:195], v[28:31]
	v_mfma_f32_16x16x32_bf16 v[20:23], v[144:147], v[192:195], v[20:23]
	v_mfma_f32_16x16x32_bf16 v[60:63], v[140:143], v[172:175], v[60:63]
	v_mfma_f32_16x16x32_bf16 v[56:59], v[148:151], v[172:175], v[56:59]
	v_mfma_f32_16x16x32_bf16 v[52:55], v[140:143], v[180:183], v[52:55]
	v_mfma_f32_16x16x32_bf16 v[48:51], v[148:151], v[180:183], v[48:51]
	v_mfma_f32_16x16x32_bf16 v[44:47], v[140:143], v[188:191], v[44:47]
	v_mfma_f32_16x16x32_bf16 v[36:39], v[148:151], v[188:191], v[36:39]
	v_mfma_f32_16x16x32_bf16 v[28:31], v[140:143], v[206:209], v[28:31]
	v_mfma_f32_16x16x32_bf16 v[20:23], v[148:151], v[206:209], v[20:23]
	s_setprio 0
	s_setprio 1
	v_mfma_f32_16x16x32_bf16 v[40:43], v[152:155], v[168:171], v[40:43]
	v_mfma_f32_16x16x32_bf16 v[32:35], v[160:163], v[168:171], v[32:35]
	v_mfma_f32_16x16x32_bf16 v[24:27], v[152:155], v[176:179], v[24:27]
	v_mfma_f32_16x16x32_bf16 v[16:19], v[160:163], v[176:179], v[16:19]
	v_mfma_f32_16x16x32_bf16 v[12:15], v[152:155], v[184:187], v[12:15]
	v_mfma_f32_16x16x32_bf16 v[8:11], v[160:163], v[184:187], v[8:11]
	v_mfma_f32_16x16x32_bf16 v[4:7], v[152:155], v[192:195], v[4:7]
	v_mfma_f32_16x16x32_bf16 v[0:3], v[160:163], v[192:195], v[0:3]
	v_mfma_f32_16x16x32_bf16 v[40:43], v[156:159], v[172:175], v[40:43]
	v_mfma_f32_16x16x32_bf16 v[32:35], v[164:167], v[172:175], v[32:35]
	v_mfma_f32_16x16x32_bf16 v[24:27], v[156:159], v[180:183], v[24:27]
	v_mfma_f32_16x16x32_bf16 v[16:19], v[164:167], v[180:183], v[16:19]
	v_mfma_f32_16x16x32_bf16 v[12:15], v[156:159], v[188:191], v[12:15]
	v_mfma_f32_16x16x32_bf16 v[8:11], v[164:167], v[188:191], v[8:11]
	v_mfma_f32_16x16x32_bf16 v[4:7], v[156:159], v[206:209], v[4:7]
	v_mfma_f32_16x16x32_bf16 v[0:3], v[164:167], v[206:209], v[0:3]
	s_setprio 0
	s_barrier
; #define PG8_STAGE(bufoff, gbase, voff) do { _Pragma("unroll") for (int _i = 0; _i < 2; ++_i) \
;         __builtin_amdgcn_global_load_lds((const unsigned*)((const char*)(gbase) + (voff)[_i]), (PG8_LAS unsigned*)(lds + (bufoff) + ldsw + _i * 8192), 16, 0, 0); } while (0)
; #define PG8_LDA(dst, b, h) do { _Pragma("unroll") for (int m = 0; m < 4; ++m) _Pragma("unroll") for (int k = 0; k < 2; ++k) dst[m][k] = *(const PG8_LAS bf16x8*)(lds + PG8_SA(b, h) + aoff + m * 2048 + k * 1024); } while (0)
; #define PG8_LDB(dst, b, h) do { _Pragma("unroll") for (int n = 0; n < 2; ++n) _Pragma("unroll") for (int k = 0; k < 2; ++k) dst[n][k] = *(const PG8_LAS bf16x8*)(lds + PG8_SB(b, h) + boff + n * 2048 + k * 1024); } while (0)
; #define PG8_MMA(ai, bj, At, Bt) do { __builtin_amdgcn_s_setprio(1); _Pragma("unroll") for (int m = 0; m < 4; ++m) _Pragma("unroll") for (int n = 0; n < 2; ++n) _Pragma("unroll") for (int k = 0; k < 2; ++k) \
;         acc[ai][bj][m][n] = __builtin_amdgcn_mfma_f32_16x16x32_bf16(Bt[n][k], At[m][k], acc[ai][bj][m][n], 0, 0, 0); __builtin_amdgcn_s_setprio(0); } while (0)
; #define PG8_WAIT_V(n) asm volatile("s_waitcnt vmcnt(" #n ")" ::: "memory")
; #define PG8_WAIT_L(n) asm volatile("s_waitcnt lgkmcnt(" #n ")" ::: "memory")
; #define PG8_BAR __builtin_amdgcn_s_barrier()
; #define PG8_SCHED __builtin_amdgcn_sched_barrier(0)
; template <class Epi, class Sched, bool ALIGN_EPI = false, bool SP2 = false>
; __device__ __forceinline__ void gemm_phase(PG8_LAS unsigned char* lds, const Gemm g, const Sched& S, const Epi& E, int wave_s_) {
;     ...
;             PG8_LDB(B0, 1, 0); PG8_LDB(B1, 1, 1); PG8_SCHED; PG8_LDA(At, 1, 0); PG8_STAGE(PG8_SA(0, 1), a2 + hstep, voffA);
;             PG8_WAIT_V(8); PG8_WAIT_L(0); PG8_BAR; PG8_MMA(0, 0, At, B0); PG8_MMA(0, 1, At, B1); PG8_BAR; PG8_SCHED;
	s_add_i32 s46, 0, 0x18000
	s_add_i32 s47, 0, 0x1c000
	v_add_u32_e32 v148, s46, v134
	v_add_u32_e32 v164, s47, v134
	ds_read_b128 v[136:139], v148
	ds_read_b128 v[140:143], v148 offset:1024
	ds_read_b128 v[144:147], v148 offset:2048
	ds_read_b128 v[148:151], v148 offset:3072
	ds_read_b128 v[152:155], v164
	ds_read_b128 v[156:159], v164 offset:1024
	ds_read_b128 v[160:163], v164 offset:2048
	ds_read_b128 v[164:167], v164 offset:3072
	s_add_u32 s22, s22, 0x40000
	s_addc_u32 s23, s23, 0
	s_mov_b32 m0, s33
	v_lshl_add_u64 v[218:219], s[22:23], 0, v[196:197]
	ds_read_b128 v[168:171], v135 offset:32768
	ds_read_b128 v[172:175], v135 offset:33792
	ds_read_b128 v[176:179], v135 offset:34816
	ds_read_b128 v[180:183], v135 offset:35840
	ds_read_b128 v[184:187], v135 offset:36864
	ds_read_b128 v[188:191], v135 offset:37888
	ds_read_b128 v[192:195], v135 offset:38912
	ds_read_b128 v[206:209], v135 offset:39936
	global_load_lds_dwordx4 v[218:219], off
	v_lshl_add_u64 v[218:219], s[22:23], 0, v[128:129]
	s_mov_b32 m0, s34
	s_nop 0
	global_load_lds_dwordx4 v[218:219], off
	s_mov_b32 m0, s30
	s_nop 0
	global_load_lds_dwordx4 v[214:215], off
	s_mov_b32 m0, s31
	s_nop 0
	global_load_lds_dwordx4 v[216:217], off
	s_waitcnt vmcnt(8)
	s_waitcnt lgkmcnt(0)
	s_barrier
	s_setprio 1
	s_waitcnt lgkmcnt(0)
	v_mfma_f32_16x16x32_bf16 v[124:127], v[136:139], v[168:171], v[124:127]
	v_mfma_f32_16x16x32_bf16 v[120:123], v[144:147], v[168:171], v[120:123]
	v_mfma_f32_16x16x32_bf16 v[116:119], v[136:139], v[176:179], v[116:119]
	v_mfma_f32_16x16x32_bf16 v[112:115], v[144:147], v[176:179], v[112:115]
	v_mfma_f32_16x16x32_bf16 v[108:111], v[136:139], v[184:187], v[108:111]
	v_mfma_f32_16x16x32_bf16 v[100:103], v[144:147], v[184:187], v[100:103]
	v_mfma_f32_16x16x32_bf16 v[92:95], v[136:139], v[192:195], v[92:95]
	v_mfma_f32_16x16x32_bf16 v[84:87], v[144:147], v[192:195], v[84:87]
	v_mfma_f32_16x16x32_bf16 v[124:127], v[140:143], v[172:175], v[124:127]
	v_mfma_f32_16x16x32_bf16 v[120:123], v[148:151], v[172:175], v[120:123]
	v_mfma_f32_16x16x32_bf16 v[116:119], v[140:143], v[180:183], v[116:119]
	v_mfma_f32_16x16x32_bf16 v[112:115], v[148:151], v[180:183], v[112:115]
	v_mfma_f32_16x16x32_bf16 v[108:111], v[140:143], v[188:191], v[108:111]
	v_mfma_f32_16x16x32_bf16 v[100:103], v[148:151], v[188:191], v[100:103]
	v_mfma_f32_16x16x32_bf16 v[92:95], v[140:143], v[206:209], v[92:95]
	v_mfma_f32_16x16x32_bf16 v[84:87], v[148:151], v[206:209], v[84:87]
	s_setprio 0
	s_setprio 1
	v_mfma_f32_16x16x32_bf16 v[104:107], v[152:155], v[168:171], v[104:107]
	v_mfma_f32_16x16x32_bf16 v[96:99], v[160:163], v[168:171], v[96:99]
	v_mfma_f32_16x16x32_bf16 v[88:91], v[152:155], v[176:179], v[88:91]
	v_mfma_f32_16x16x32_bf16 v[80:83], v[160:163], v[176:179], v[80:83]
	v_mfma_f32_16x16x32_bf16 v[76:79], v[152:155], v[184:187], v[76:79]
	v_mfma_f32_16x16x32_bf16 v[72:75], v[160:163], v[184:187], v[72:75]
	v_mfma_f32_16x16x32_bf16 v[68:71], v[152:155], v[192:195], v[68:71]
	v_mfma_f32_16x16x32_bf16 v[64:67], v[160:163], v[192:195], v[64:67]
	v_mfma_f32_16x16x32_bf16 v[104:107], v[156:159], v[172:175], v[104:107]
	v_mfma_f32_16x16x32_bf16 v[96:99], v[164:167], v[172:175], v[96:99]
	v_mfma_f32_16x16x32_bf16 v[88:91], v[156:159], v[180:183], v[88:91]
	v_mfma_f32_16x16x32_bf16 v[80:83], v[164:167], v[180:183], v[80:83]
	v_mfma_f32_16x16x32_bf16 v[76:79], v[156:159], v[188:191], v[76:79]
	v_mfma_f32_16x16x32_bf16 v[72:75], v[164:167], v[188:191], v[72:75]
	v_mfma_f32_16x16x32_bf16 v[68:71], v[156:159], v[206:209], v[68:71]
	v_mfma_f32_16x16x32_bf16 v[64:67], v[164:167], v[206:209], v[64:67]
	s_setprio 0
	s_barrier
; #define PG8_STAGE(bufoff, gbase, voff) do { _Pragma("unroll") for (int _i = 0; _i < 2; ++_i) \
;         __builtin_amdgcn_global_load_lds((const unsigned*)((const char*)(gbase) + (voff)[_i]), (PG8_LAS unsigned*)(lds + (bufoff) + ldsw + _i * 8192), 16, 0, 0); } while (0)
; #define PG8_LDA(dst, b, h) do { _Pragma("unroll") for (int m = 0; m < 4; ++m) _Pragma("unroll") for (int k = 0; k < 2; ++k) dst[m][k] = *(const PG8_LAS bf16x8*)(lds + PG8_SA(b, h) + aoff + m * 2048 + k * 1024); } while (0)
; #define PG8_MMA(ai, bj, At, Bt) do { __builtin_amdgcn_s_setprio(1); _Pragma("unroll") for (int m = 0; m < 4; ++m) _Pragma("unroll") for (int n = 0; n < 2; ++n) _Pragma("unroll") for (int k = 0; k < 2; ++k) \
;         acc[ai][bj][m][n] = __builtin_amdgcn_mfma_f32_16x16x32_bf16(Bt[n][k], At[m][k], acc[ai][bj][m][n], 0, 0, 0); __builtin_amdgcn_s_setprio(0); } while (0)
; #define PG8_WAIT_V(n) asm volatile("s_waitcnt vmcnt(" #n ")" ::: "memory")
; #define PG8_WAIT_L(n) asm volatile("s_waitcnt lgkmcnt(" #n ")" ::: "memory")
; #define PG8_BAR __builtin_amdgcn_s_barrier()
; #define PG8_SCHED __builtin_amdgcn_sched_barrier(0)
; template <class Epi, class Sched, bool ALIGN_EPI = false, bool SP2 = false>
; __device__ __forceinline__ void gemm_phase(PG8_LAS unsigned char* lds, const Gemm g, const Sched& S, const Epi& E, int wave_s_) {
;     ...
;             PG8_LDA(At, 1, 1); PG8_STAGE(PG8_SB(1, 0), b3, voffB); PG8_STAGE(PG8_SB(1, 1), b3 + hstep, voffB); PG8_STAGE(PG8_SA(1, 0), a3, voffA);
;             PG8_WAIT_V(8); PG8_WAIT_L(0); PG8_BAR; PG8_MMA(1, 0, At, B0); PG8_MMA(1, 1, At, B1); PG8_BAR; PG8_SCHED;
	s_add_i32 s22, s46, s29
	v_lshl_add_u64 v[210:211], v[210:211], 0, s[76:77]
	s_mov_b32 m0, s22
	ds_read_b128 v[168:171], v135 offset:49152
	ds_read_b128 v[172:175], v135 offset:50176
	ds_read_b128 v[176:179], v135 offset:51200
	ds_read_b128 v[180:183], v135 offset:52224
	ds_read_b128 v[184:187], v135 offset:53248
	ds_read_b128 v[188:191], v135 offset:54272
	ds_read_b128 v[192:195], v135 offset:55296
	ds_read_b128 v[206:209], v135 offset:56320
	global_load_lds_dwordx4 v[210:211], off
	s_add_i32 m0, s22, 0x2000
	s_add_u32 s20, s20, 0x40080
	v_lshl_add_u64 v[210:211], v[212:213], 0, s[76:77]
	s_addc_u32 s21, s21, 0
	s_add_i32 s22, s47, s29
	global_load_lds_dwordx4 v[210:211], off
	v_lshl_add_u64 v[210:211], s[20:21], 0, v[196:197]
	s_mov_b32 m0, s22
	s_nop 0
	global_load_lds_dwordx4 v[210:211], off
	v_lshl_add_u64 v[210:211], s[20:21], 0, v[128:129]
	s_add_i32 m0, s22, 0x2000
	s_nop 0
	global_load_lds_dwordx4 v[210:211], off
	v_lshl_add_u64 v[210:211], v[214:215], 0, s[76:77]
	s_mov_b32 m0, s38
	s_nop 0
	global_load_lds_dwordx4 v[210:211], off
	v_lshl_add_u64 v[210:211], v[216:217], 0, s[76:77]
	s_mov_b32 m0, s39
	s_nop 0
	global_load_lds_dwordx4 v[210:211], off
	s_waitcnt vmcnt(6)
	s_waitcnt lgkmcnt(0)
	s_barrier
	s_setprio 1
	s_waitcnt lgkmcnt(0)
	v_mfma_f32_16x16x32_bf16 v[60:63], v[136:139], v[168:171], v[60:63]
	v_mfma_f32_16x16x32_bf16 v[56:59], v[144:147], v[168:171], v[56:59]
	v_mfma_f32_16x16x32_bf16 v[52:55], v[136:139], v[176:179], v[52:55]
	v_mfma_f32_16x16x32_bf16 v[48:51], v[144:147], v[176:179], v[48:51]
	v_mfma_f32_16x16x32_bf16 v[44:47], v[136:139], v[184:187], v[44:47]
	v_mfma_f32_16x16x32_bf16 v[36:39], v[144:147], v[184:187], v[36:39]
	v_mfma_f32_16x16x32_bf16 v[28:31], v[136:139], v[192:195], v[28:31]
	v_mfma_f32_16x16x32_bf16 v[20:23], v[144:147], v[192:195], v[20:23]
	v_mfma_f32_16x16x32_bf16 v[60:63], v[140:143], v[172:175], v[60:63]
	v_mfma_f32_16x16x32_bf16 v[56:59], v[148:151], v[172:175], v[56:59]
	v_mfma_f32_16x16x32_bf16 v[52:55], v[140:143], v[180:183], v[52:55]
	v_mfma_f32_16x16x32_bf16 v[48:51], v[148:151], v[180:183], v[48:51]
	v_mfma_f32_16x16x32_bf16 v[44:47], v[140:143], v[188:191], v[44:47]
	v_mfma_f32_16x16x32_bf16 v[36:39], v[148:151], v[188:191], v[36:39]
	v_mfma_f32_16x16x32_bf16 v[28:31], v[140:143], v[206:209], v[28:31]
	v_mfma_f32_16x16x32_bf16 v[20:23], v[148:151], v[206:209], v[20:23]
	s_setprio 0
	s_setprio 1
	v_mfma_f32_16x16x32_bf16 v[40:43], v[152:155], v[168:171], v[40:43]
	v_mfma_f32_16x16x32_bf16 v[32:35], v[160:163], v[168:171], v[32:35]
	v_mfma_f32_16x16x32_bf16 v[24:27], v[152:155], v[176:179], v[24:27]
	v_mfma_f32_16x16x32_bf16 v[16:19], v[160:163], v[176:179], v[16:19]
	v_mfma_f32_16x16x32_bf16 v[12:15], v[152:155], v[184:187], v[12:15]
	v_mfma_f32_16x16x32_bf16 v[8:11], v[160:163], v[184:187], v[8:11]
	v_mfma_f32_16x16x32_bf16 v[4:7], v[152:155], v[192:195], v[4:7]
	v_mfma_f32_16x16x32_bf16 v[0:3], v[160:163], v[192:195], v[0:3]
	v_mfma_f32_16x16x32_bf16 v[40:43], v[156:159], v[172:175], v[40:43]
	v_mfma_f32_16x16x32_bf16 v[32:35], v[164:167], v[172:175], v[32:35]
	v_mfma_f32_16x16x32_bf16 v[24:27], v[156:159], v[180:183], v[24:27]
	v_mfma_f32_16x16x32_bf16 v[16:19], v[164:167], v[180:183], v[16:19]
	v_mfma_f32_16x16x32_bf16 v[12:15], v[156:159], v[188:191], v[12:15]
	v_mfma_f32_16x16x32_bf16 v[8:11], v[164:167], v[188:191], v[8:11]
	v_mfma_f32_16x16x32_bf16 v[4:7], v[156:159], v[206:209], v[4:7]
	v_mfma_f32_16x16x32_bf16 v[0:3], v[164:167], v[206:209], v[0:3]
	s_setprio 0
	s_barrier
	s_add_i32 s45, s45, 2
	s_add_u32 s18, s18, 0x100
	s_addc_u32 s19, s19, 0
	s_add_u32 s15, s15, 0x100
	s_addc_u32 s44, s44, 0
	s_cmp_gt_u32 s45, 13
	s_cbranch_scc0 .LBB0_1185

;     __device__ __forceinline__ int nt_of(const Unit& u) const { return (u.pm >> 12) ? ktper : kt; }
; #define PG8_STAGE(bufoff, gbase, voff) do { _Pragma("unroll") for (int _i = 0; _i < 2; ++_i) \
;         __builtin_amdgcn_global_load_lds((const unsigned*)((const char*)(gbase) + (voff)[_i]), (PG8_LAS unsigned*)(lds + (bufoff) + ldsw + _i * 8192), 16, 0, 0); } while (0)
; #define PG8_LDA(dst, b, h) do { _Pragma("unroll") for (int m = 0; m < 4; ++m) _Pragma("unroll") for (int k = 0; k < 2; ++k) dst[m][k] = *(const PG8_LAS bf16x8*)(lds + PG8_SA(b, h) + aoff + m * 2048 + k * 1024); } while (0)
; #define PG8_LDB(dst, b, h) do { _Pragma("unroll") for (int n = 0; n < 2; ++n) _Pragma("unroll") for (int k = 0; k < 2; ++k) dst[n][k] = *(const PG8_LAS bf16x8*)(lds + PG8_SB(b, h) + boff + n * 2048 + k * 1024); } while (0)
; #define PG8_BAR __builtin_amdgcn_s_barrier()
; template <class Epi, class Sched, bool ALIGN_EPI = false, bool SP2 = false>
; __device__ __forceinline__ void gemm_phase(PG8_LAS unsigned char* lds, const Gemm g, const Sched& S, const Epi& E, int wave_s_) {
;     ...
;     for (;;) {
;         const bool has_next = S.next(ui + 1, nxt);
;         const char* nA = has_next ? (const char*)g.A + (size_t)(nxt.pm & 4095) * tstep + (size_t)S.k0_of(nxt) * kstep : cA; const char* nB = has_next ? (const char*)g.Bt + (size_t)nxt.pn * tstep + (size_t)S.k0_of(nxt) * kstep : cB;
;         const int nt = S.nt_of(cur);
;         for (int t = 0; t < nt; t += 2) {
;             const bool last = (t == nt - 2);
;             const char* a1 = cA + (size_t)(t + 1) * kstep;
;             const char* a2 = last ? nA : cA + (size_t)(t + 2) * kstep; const char* b2 = last ? nB : cB + (size_t)(t + 2) * kstep;
;             const char* a3 = a2 + kstep; const char* b3 = b2 + kstep;
;             if (last && has_next) S.a_ready(nxt);
;             if constexpr (SP2) {
;             PG8_LDB(B0, 0, 0); PG8_LDB(B1, 0, 1); PG8_SCHED; PG8_LDA(At, 0, 0); PG8_STAGE(PG8_SA(1, 1), a1 + hstep, voffA);
;             PG8_WAIT_V(8); PG8_WAIT_L(0); PG8_BAR; PG8_MMA(0, 0, At, B0); PG8_MMA(0, 1, At, B1); PG8_BAR; PG8_SCHED;
;             PG8_LDA(At, 0, 1); PG8_STAGE(PG8_SB(0, 0), b2, voffB); PG8_STAGE(PG8_SB(0, 1), b2 + hstep, voffB); PG8_STAGE(PG8_SA(0, 0), a2, voffA);
;             PG8_WAIT_V(8); PG8_WAIT_L(0); PG8_BAR; PG8_MMA(1, 0, At, B0); PG8_MMA(1, 1, At, B1); PG8_BAR; PG8_SCHED;
.LBB0_1337:
	s_add_u32 s45, s18, 0x100
	v_mov_b32_e32 v0, 0
	s_addc_u32 s46, s19, 0
	s_mov_b32 s47, -2
	s_add_u32 s18, s16, 0x100
	s_addc_u32 s19, s17, 0
	s_add_i32 s48, 0, 0x10000
	s_cmp_eq_u32 s47, 2
	s_cselect_b32 s23, s7, s19
	s_cselect_b32 s22, s6, s18
	s_cselect_b32 s21, s15, s46
	s_cselect_b32 s20, s14, s45
	s_add_i32 s49, 0, 0x14000
	v_add_u32_e32 v152, s48, v142
	v_add_u32_e32 v168, s49, v142
	ds_read_b128 v[138:141], v152
	ds_read_b128 v[144:147], v152 offset:1024
	ds_read_b128 v[148:151], v152 offset:2048
	ds_read_b128 v[152:155], v152 offset:3072
	ds_read_b128 v[156:159], v168
	ds_read_b128 v[160:163], v168 offset:1024
	ds_read_b128 v[164:167], v168 offset:2048
	ds_read_b128 v[168:171], v168 offset:3072
	v_lshl_add_u64 v[214:215], s[16:17], 0, v[134:135]
	s_add_i32 m0, s30, 0xc000
	ds_read_b128 v[172:175], v143
	ds_read_b128 v[176:179], v143 offset:1024
	ds_read_b128 v[180:183], v143 offset:2048
	ds_read_b128 v[184:187], v143 offset:3072
	ds_read_b128 v[188:191], v143 offset:4096
	ds_read_b128 v[192:195], v143 offset:5120
	ds_read_b128 v[206:209], v143 offset:6144
	ds_read_b128 v[210:213], v143 offset:7168
	global_load_lds_dwordx4 v[214:215], off
	v_lshl_add_u64 v[214:215], s[16:17], 0, v[136:137]
	s_add_i32 m0, s30, 0xe000
	s_nop 0
	global_load_lds_dwordx4 v[214:215], off
	s_waitcnt vmcnt(8)
	s_waitcnt lgkmcnt(0)
	s_barrier
	s_setprio 1
	s_waitcnt lgkmcnt(0)
	v_mfma_f32_16x16x32_bf16 v[124:127], v[138:141], v[172:175], 0
	v_mfma_f32_16x16x32_bf16 v[120:123], v[148:151], v[172:175], 0
	v_mfma_f32_16x16x32_bf16 v[116:119], v[138:141], v[180:183], 0
	v_mfma_f32_16x16x32_bf16 v[108:111], v[148:151], v[180:183], 0
	v_mfma_f32_16x16x32_bf16 v[100:103], v[138:141], v[188:191], 0
	v_mfma_f32_16x16x32_bf16 v[92:95], v[148:151], v[188:191], 0
	v_mfma_f32_16x16x32_bf16 v[84:87], v[138:141], v[206:209], 0
	v_mfma_f32_16x16x32_bf16 v[76:79], v[148:151], v[206:209], 0
	v_mfma_f32_16x16x32_bf16 v[124:127], v[144:147], v[176:179], v[124:127]
	v_mfma_f32_16x16x32_bf16 v[120:123], v[152:155], v[176:179], v[120:123]
	v_mfma_f32_16x16x32_bf16 v[116:119], v[144:147], v[184:187], v[116:119]
	v_mfma_f32_16x16x32_bf16 v[108:111], v[152:155], v[184:187], v[108:111]
	v_mfma_f32_16x16x32_bf16 v[100:103], v[144:147], v[192:195], v[100:103]
	v_mfma_f32_16x16x32_bf16 v[92:95], v[152:155], v[192:195], v[92:95]
	v_mfma_f32_16x16x32_bf16 v[84:87], v[144:147], v[210:213], v[84:87]
	v_mfma_f32_16x16x32_bf16 v[76:79], v[152:155], v[210:213], v[76:79]
	s_setprio 0
	s_setprio 1
	v_mfma_f32_16x16x32_bf16 v[112:115], v[156:159], v[172:175], 0
	v_mfma_f32_16x16x32_bf16 v[104:107], v[164:167], v[172:175], 0
	v_mfma_f32_16x16x32_bf16 v[96:99], v[156:159], v[180:183], 0
	v_mfma_f32_16x16x32_bf16 v[88:91], v[164:167], v[180:183], 0
	v_mfma_f32_16x16x32_bf16 v[80:83], v[156:159], v[188:191], 0
	v_mfma_f32_16x16x32_bf16 v[72:75], v[164:167], v[188:191], 0
	v_mfma_f32_16x16x32_bf16 v[68:71], v[156:159], v[206:209], 0
	v_mfma_f32_16x16x32_bf16 v[64:67], v[164:167], v[206:209], 0
	v_mfma_f32_16x16x32_bf16 v[112:115], v[160:163], v[176:179], v[112:115]
	v_mfma_f32_16x16x32_bf16 v[104:107], v[168:171], v[176:179], v[104:107]
	v_mfma_f32_16x16x32_bf16 v[96:99], v[160:163], v[184:187], v[96:99]
	v_mfma_f32_16x16x32_bf16 v[88:91], v[168:171], v[184:187], v[88:91]
	v_mfma_f32_16x16x32_bf16 v[80:83], v[160:163], v[192:195], v[80:83]
	v_mfma_f32_16x16x32_bf16 v[72:75], v[168:171], v[192:195], v[72:75]
	v_mfma_f32_16x16x32_bf16 v[68:71], v[160:163], v[210:213], v[68:71]
	v_mfma_f32_16x16x32_bf16 v[64:67], v[168:171], v[210:213], v[64:67]
	s_setprio 0
	s_barrier
	s_add_i32 s16, s48, s29
	v_lshl_add_u64 v[214:215], s[20:21], 0, v[196:197]
	s_mov_b32 m0, s16
	ds_read_b128 v[172:175], v143 offset:16384
	ds_read_b128 v[176:179], v143 offset:17408
	ds_read_b128 v[180:183], v143 offset:18432
	ds_read_b128 v[184:187], v143 offset:19456
	ds_read_b128 v[188:191], v143 offset:20480
	ds_read_b128 v[192:195], v143 offset:21504
	ds_read_b128 v[206:209], v143 offset:22528
	ds_read_b128 v[210:213], v143 offset:23552
	global_load_lds_dwordx4 v[214:215], off
	s_add_i32 m0, s16, 0x2000
	s_add_u32 s16, s20, 0x18000
	v_lshl_add_u64 v[216:217], s[20:21], 0, v[132:133]
	s_addc_u32 s17, s21, 0
	s_add_i32 s48, s49, s29
	global_load_lds_dwordx4 v[216:217], off
	v_lshl_add_u64 v[218:219], s[16:17], 0, v[196:197]
	s_mov_b32 m0, s48
	v_lshl_add_u64 v[220:221], s[22:23], 0, v[130:131]
	global_load_lds_dwordx4 v[218:219], off
	v_lshl_add_u64 v[218:219], s[16:17], 0, v[132:133]
	s_add_i32 m0, s48, 0x2000
	s_nop 0
	global_load_lds_dwordx4 v[218:219], off
	v_lshl_add_u64 v[218:219], s[22:23], 0, v[128:129]
	s_waitcnt vmcnt(6)
	s_waitcnt lgkmcnt(0)
	s_barrier
; #define PG8_STAGE(bufoff, gbase, voff) do { _Pragma("unroll") for (int _i = 0; _i < 2; ++_i) \
;         __builtin_amdgcn_global_load_lds((const unsigned*)((const char*)(gbase) + (voff)[_i]), (PG8_LAS unsigned*)(lds + (bufoff) + ldsw + _i * 8192), 16, 0, 0); } while (0)
; #define PG8_LDA(dst, b, h) do { _Pragma("unroll") for (int m = 0; m < 4; ++m) _Pragma("unroll") for (int k = 0; k < 2; ++k) dst[m][k] = *(const PG8_LAS bf16x8*)(lds + PG8_SA(b, h) + aoff + m * 2048 + k * 1024); } while (0)
; #define PG8_LDB(dst, b, h) do { _Pragma("unroll") for (int n = 0; n < 2; ++n) _Pragma("unroll") for (int k = 0; k < 2; ++k) dst[n][k] = *(const PG8_LAS bf16x8*)(lds + PG8_SB(b, h) + boff + n * 2048 + k * 1024); } while (0)
; #define PG8_MMA(ai, bj, At, Bt) do { __builtin_amdgcn_s_setprio(1); _Pragma("unroll") for (int m = 0; m < 4; ++m) _Pragma("unroll") for (int n = 0; n < 2; ++n) _Pragma("unroll") for (int k = 0; k < 2; ++k) \
;         acc[ai][bj][m][n] = __builtin_amdgcn_mfma_f32_16x16x32_bf16(Bt[n][k], At[m][k], acc[ai][bj][m][n], 0, 0, 0); __builtin_amdgcn_s_setprio(0); } while (0)
; #define PG8_WAIT_V(n) asm volatile("s_waitcnt vmcnt(" #n ")" ::: "memory")
; #define PG8_WAIT_L(n) asm volatile("s_waitcnt lgkmcnt(" #n ")" ::: "memory")
; #define PG8_BAR __builtin_amdgcn_s_barrier()
; #define PG8_SCHED __builtin_amdgcn_sched_barrier(0)
; template <class Epi, class Sched, bool ALIGN_EPI = false, bool SP2 = false>
; __device__ __forceinline__ void gemm_phase(PG8_LAS unsigned char* lds, const Gemm g, const Sched& S, const Epi& E, int wave_s_) {
;     ...
;             PG8_WAIT_V(8); PG8_WAIT_L(0); PG8_BAR; PG8_MMA(1, 0, At, B0); PG8_MMA(1, 1, At, B1); PG8_BAR; PG8_SCHED;
;             PG8_LDB(B0, 1, 0); PG8_LDB(B1, 1, 1); PG8_SCHED; PG8_LDA(At, 1, 0); PG8_STAGE(PG8_SA(0, 1), a2 + hstep, voffA);
;             PG8_WAIT_V(8); PG8_WAIT_L(0); PG8_BAR; PG8_MMA(0, 0, At, B0); PG8_MMA(0, 1, At, B1); PG8_BAR; PG8_SCHED;
	s_setprio 1
	s_waitcnt lgkmcnt(0)
	v_mfma_f32_16x16x32_bf16 v[60:63], v[138:141], v[172:175], 0
	v_mfma_f32_16x16x32_bf16 v[56:59], v[148:151], v[172:175], 0
	v_mfma_f32_16x16x32_bf16 v[52:55], v[138:141], v[180:183], 0
	v_mfma_f32_16x16x32_bf16 v[44:47], v[148:151], v[180:183], 0
	v_mfma_f32_16x16x32_bf16 v[36:39], v[138:141], v[188:191], 0
	v_mfma_f32_16x16x32_bf16 v[28:31], v[148:151], v[188:191], 0
	v_mfma_f32_16x16x32_bf16 v[20:23], v[138:141], v[206:209], 0
	v_mfma_f32_16x16x32_bf16 v[12:15], v[148:151], v[206:209], 0
	v_mfma_f32_16x16x32_bf16 v[60:63], v[144:147], v[176:179], v[60:63]
	v_mfma_f32_16x16x32_bf16 v[56:59], v[152:155], v[176:179], v[56:59]
	v_mfma_f32_16x16x32_bf16 v[52:55], v[144:147], v[184:187], v[52:55]
	v_mfma_f32_16x16x32_bf16 v[44:47], v[152:155], v[184:187], v[44:47]
	v_mfma_f32_16x16x32_bf16 v[36:39], v[144:147], v[192:195], v[36:39]
	v_mfma_f32_16x16x32_bf16 v[28:31], v[152:155], v[192:195], v[28:31]
	v_mfma_f32_16x16x32_bf16 v[20:23], v[144:147], v[210:213], v[20:23]
	v_mfma_f32_16x16x32_bf16 v[12:15], v[152:155], v[210:213], v[12:15]
	s_setprio 0
	s_setprio 1
	v_mfma_f32_16x16x32_bf16 v[48:51], v[156:159], v[172:175], 0
	v_mfma_f32_16x16x32_bf16 v[40:43], v[164:167], v[172:175], 0
	v_mfma_f32_16x16x32_bf16 v[32:35], v[156:159], v[180:183], 0
	v_mfma_f32_16x16x32_bf16 v[24:27], v[164:167], v[180:183], 0
	v_mfma_f32_16x16x32_bf16 v[16:19], v[156:159], v[188:191], 0
	v_mfma_f32_16x16x32_bf16 v[8:11], v[164:167], v[188:191], 0
	v_mfma_f32_16x16x32_bf16 v[4:7], v[156:159], v[206:209], 0
	v_mfma_f32_16x16x32_bf16 v[0:3], v[164:167], v[206:209], 0
	v_mfma_f32_16x16x32_bf16 v[48:51], v[160:163], v[176:179], v[48:51]
	v_mfma_f32_16x16x32_bf16 v[40:43], v[168:171], v[176:179], v[40:43]
	v_mfma_f32_16x16x32_bf16 v[32:35], v[160:163], v[184:187], v[32:35]
	v_mfma_f32_16x16x32_bf16 v[24:27], v[168:171], v[184:187], v[24:27]
	v_mfma_f32_16x16x32_bf16 v[16:19], v[160:163], v[192:195], v[16:19]
	v_mfma_f32_16x16x32_bf16 v[8:11], v[168:171], v[192:195], v[8:11]
	v_mfma_f32_16x16x32_bf16 v[4:7], v[160:163], v[210:213], v[4:7]
	v_mfma_f32_16x16x32_bf16 v[0:3], v[168:171], v[210:213], v[0:3]
	s_setprio 0
	s_barrier
	s_add_i32 s48, 0, 0x18000
	s_add_i32 s49, 0, 0x1c000
	v_add_u32_e32 v152, s48, v142
	v_add_u32_e32 v168, s49, v142
	ds_read_b128 v[138:141], v152
	ds_read_b128 v[144:147], v152 offset:1024
	ds_read_b128 v[148:151], v152 offset:2048
	ds_read_b128 v[152:155], v152 offset:3072
	ds_read_b128 v[156:159], v168
	ds_read_b128 v[160:163], v168 offset:1024
	ds_read_b128 v[164:167], v168 offset:2048
	ds_read_b128 v[168:171], v168 offset:3072
	s_add_u32 s16, s22, 0x18000
	s_addc_u32 s17, s23, 0
	s_mov_b32 m0, s33
	v_lshl_add_u64 v[222:223], s[16:17], 0, v[128:129]
	ds_read_b128 v[172:175], v143 offset:32768
	ds_read_b128 v[176:179], v143 offset:33792
	ds_read_b128 v[180:183], v143 offset:34816
	ds_read_b128 v[184:187], v143 offset:35840
	ds_read_b128 v[188:191], v143 offset:36864
	ds_read_b128 v[192:195], v143 offset:37888
	ds_read_b128 v[206:209], v143 offset:38912
	ds_read_b128 v[210:213], v143 offset:39936
	global_load_lds_dwordx4 v[222:223], off
	v_lshl_add_u64 v[222:223], s[16:17], 0, v[130:131]
	s_mov_b32 m0, s34
	s_nop 0
	global_load_lds_dwordx4 v[222:223], off
	s_mov_b32 m0, s30
	s_nop 0
	global_load_lds_dwordx4 v[218:219], off
	s_mov_b32 m0, s31
	s_nop 0
	global_load_lds_dwordx4 v[220:221], off
	s_waitcnt vmcnt(8)
	s_waitcnt lgkmcnt(0)
	s_barrier
	s_setprio 1
	s_waitcnt lgkmcnt(0)
	v_mfma_f32_16x16x32_bf16 v[124:127], v[138:141], v[172:175], v[124:127]
	v_mfma_f32_16x16x32_bf16 v[120:123], v[148:151], v[172:175], v[120:123]
	v_mfma_f32_16x16x32_bf16 v[116:119], v[138:141], v[180:183], v[116:119]
	v_mfma_f32_16x16x32_bf16 v[108:111], v[148:151], v[180:183], v[108:111]
	v_mfma_f32_16x16x32_bf16 v[100:103], v[138:141], v[188:191], v[100:103]
	v_mfma_f32_16x16x32_bf16 v[92:95], v[148:151], v[188:191], v[92:95]
	v_mfma_f32_16x16x32_bf16 v[84:87], v[138:141], v[206:209], v[84:87]
	v_mfma_f32_16x16x32_bf16 v[76:79], v[148:151], v[206:209], v[76:79]
	v_mfma_f32_16x16x32_bf16 v[124:127], v[144:147], v[176:179], v[124:127]
	v_mfma_f32_16x16x32_bf16 v[120:123], v[152:155], v[176:179], v[120:123]
	v_mfma_f32_16x16x32_bf16 v[116:119], v[144:147], v[184:187], v[116:119]
	v_mfma_f32_16x16x32_bf16 v[108:111], v[152:155], v[184:187], v[108:111]
	v_mfma_f32_16x16x32_bf16 v[100:103], v[144:147], v[192:195], v[100:103]
	v_mfma_f32_16x16x32_bf16 v[92:95], v[152:155], v[192:195], v[92:95]
	v_mfma_f32_16x16x32_bf16 v[84:87], v[144:147], v[210:213], v[84:87]
	v_mfma_f32_16x16x32_bf16 v[76:79], v[152:155], v[210:213], v[76:79]
	s_setprio 0
	s_setprio 1
	v_mfma_f32_16x16x32_bf16 v[112:115], v[156:159], v[172:175], v[112:115]
	v_mfma_f32_16x16x32_bf16 v[104:107], v[164:167], v[172:175], v[104:107]
	v_mfma_f32_16x16x32_bf16 v[96:99], v[156:159], v[180:183], v[96:99]
	v_mfma_f32_16x16x32_bf16 v[88:91], v[164:167], v[180:183], v[88:91]
	v_mfma_f32_16x16x32_bf16 v[80:83], v[156:159], v[188:191], v[80:83]
	v_mfma_f32_16x16x32_bf16 v[72:75], v[164:167], v[188:191], v[72:75]
	v_mfma_f32_16x16x32_bf16 v[68:71], v[156:159], v[206:209], v[68:71]
	v_mfma_f32_16x16x32_bf16 v[64:67], v[164:167], v[206:209], v[64:67]
	v_mfma_f32_16x16x32_bf16 v[112:115], v[160:163], v[176:179], v[112:115]
	v_mfma_f32_16x16x32_bf16 v[104:107], v[168:171], v[176:179], v[104:107]
	v_mfma_f32_16x16x32_bf16 v[96:99], v[160:163], v[184:187], v[96:99]
	v_mfma_f32_16x16x32_bf16 v[88:91], v[168:171], v[184:187], v[88:91]
	v_mfma_f32_16x16x32_bf16 v[80:83], v[160:163], v[192:195], v[80:83]
	v_mfma_f32_16x16x32_bf16 v[72:75], v[168:171], v[192:195], v[72:75]
	v_mfma_f32_16x16x32_bf16 v[68:71], v[160:163], v[210:213], v[68:71]
	v_mfma_f32_16x16x32_bf16 v[64:67], v[168:171], v[210:213], v[64:67]
	s_setprio 0
	s_barrier
; #define PG8_STAGE(bufoff, gbase, voff) do { _Pragma("unroll") for (int _i = 0; _i < 2; ++_i) \
;         __builtin_amdgcn_global_load_lds((const unsigned*)((const char*)(gbase) + (voff)[_i]), (PG8_LAS unsigned*)(lds + (bufoff) + ldsw + _i * 8192), 16, 0, 0); } while (0)
; #define PG8_LDA(dst, b, h) do { _Pragma("unroll") for (int m = 0; m < 4; ++m) _Pragma("unroll") for (int k = 0; k < 2; ++k) dst[m][k] = *(const PG8_LAS bf16x8*)(lds + PG8_SA(b, h) + aoff + m * 2048 + k * 1024); } while (0)
; #define PG8_LDB(dst, b, h) do { _Pragma("unroll") for (int n = 0; n < 2; ++n) _Pragma("unroll") for (int k = 0; k < 2; ++k) dst[n][k] = *(const PG8_LAS bf16x8*)(lds + PG8_SB(b, h) + boff + n * 2048 + k * 1024); } while (0)
; #define PG8_MMA(ai, bj, At, Bt) do { __builtin_amdgcn_s_setprio(1); _Pragma("unroll") for (int m = 0; m < 4; ++m) _Pragma("unroll") for (int n = 0; n < 2; ++n) _Pragma("unroll") for (int k = 0; k < 2; ++k) \
;         acc[ai][bj][m][n] = __builtin_amdgcn_mfma_f32_16x16x32_bf16(Bt[n][k], At[m][k], acc[ai][bj][m][n], 0, 0, 0); __builtin_amdgcn_s_setprio(0); } while (0)
; #define PG8_WAIT_V(n) asm volatile("s_waitcnt vmcnt(" #n ")" ::: "memory")
; #define PG8_BAR __builtin_amdgcn_s_barrier()
; template <class Epi, class Sched, bool ALIGN_EPI = false, bool SP2 = false>
; __device__ __forceinline__ void gemm_phase(PG8_LAS unsigned char* lds, const Gemm g, const Sched& S, const Epi& E, int wave_s_) {
;     ...
;         for (int t = 0; t < nt; t += 2) {
;             const bool last = (t == nt - 2);
;             const char* a1 = cA + (size_t)(t + 1) * kstep;
;             const char* a2 = last ? nA : cA + (size_t)(t + 2) * kstep; const char* b2 = last ? nB : cB + (size_t)(t + 2) * kstep;
;             const char* a3 = a2 + kstep; const char* b3 = b2 + kstep;
;             if (last && has_next) S.a_ready(nxt);
;             if constexpr (SP2) {
;             PG8_LDB(B0, 0, 0); PG8_LDB(B1, 0, 1); PG8_SCHED; PG8_LDA(At, 0, 0); PG8_STAGE(PG8_SA(1, 1), a1 + hstep, voffA);
;             PG8_WAIT_V(8); PG8_WAIT_L(0); PG8_BAR; PG8_MMA(0, 0, At, B0); PG8_MMA(0, 1, At, B1); PG8_BAR; PG8_SCHED;
;     ...
;             PG8_LDA(At, 1, 1); PG8_STAGE(PG8_SB(1, 0), b3, voffB); PG8_STAGE(PG8_SB(1, 1), b3 + hstep, voffB); PG8_STAGE(PG8_SA(1, 0), a3, voffA);
;             PG8_WAIT_V(8); PG8_WAIT_L(0); PG8_BAR; PG8_MMA(1, 0, At, B0); PG8_MMA(1, 1, At, B1); PG8_BAR; PG8_SCHED;
	s_add_i32 s16, s48, s29
	v_lshl_add_u64 v[214:215], v[214:215], 0, s[76:77]
	s_mov_b32 m0, s16
	ds_read_b128 v[172:175], v143 offset:49152
	ds_read_b128 v[176:179], v143 offset:50176
	ds_read_b128 v[180:183], v143 offset:51200
	ds_read_b128 v[184:187], v143 offset:52224
	ds_read_b128 v[188:191], v143 offset:53248
	ds_read_b128 v[192:195], v143 offset:54272
	ds_read_b128 v[206:209], v143 offset:55296
	ds_read_b128 v[210:213], v143 offset:56320
	global_load_lds_dwordx4 v[214:215], off
	s_add_i32 m0, s16, 0x2000
	s_add_u32 s16, s20, 0x18080
	v_lshl_add_u64 v[214:215], v[216:217], 0, s[76:77]
	s_addc_u32 s17, s21, 0
	s_add_i32 s20, s49, s29
	global_load_lds_dwordx4 v[214:215], off
	v_lshl_add_u64 v[214:215], s[16:17], 0, v[196:197]
	s_mov_b32 m0, s20
	s_nop 0
	global_load_lds_dwordx4 v[214:215], off
	v_lshl_add_u64 v[214:215], s[16:17], 0, v[132:133]
	s_add_i32 m0, s20, 0x2000
	s_nop 0
	global_load_lds_dwordx4 v[214:215], off
	v_lshl_add_u64 v[214:215], v[218:219], 0, s[76:77]
	s_mov_b32 m0, s37
	s_nop 0
	global_load_lds_dwordx4 v[214:215], off
	v_lshl_add_u64 v[214:215], v[220:221], 0, s[76:77]
	s_mov_b32 m0, s38
	s_nop 0
	global_load_lds_dwordx4 v[214:215], off
	s_waitcnt vmcnt(6)
	s_waitcnt lgkmcnt(0)
	s_barrier
	s_setprio 1
	s_waitcnt lgkmcnt(0)
	v_mfma_f32_16x16x32_bf16 v[60:63], v[138:141], v[172:175], v[60:63]
	v_mfma_f32_16x16x32_bf16 v[56:59], v[148:151], v[172:175], v[56:59]
	v_mfma_f32_16x16x32_bf16 v[52:55], v[138:141], v[180:183], v[52:55]
	v_mfma_f32_16x16x32_bf16 v[44:47], v[148:151], v[180:183], v[44:47]
	v_mfma_f32_16x16x32_bf16 v[36:39], v[138:141], v[188:191], v[36:39]
	v_mfma_f32_16x16x32_bf16 v[28:31], v[148:151], v[188:191], v[28:31]
	v_mfma_f32_16x16x32_bf16 v[20:23], v[138:141], v[206:209], v[20:23]
	v_mfma_f32_16x16x32_bf16 v[12:15], v[148:151], v[206:209], v[12:15]
	v_mfma_f32_16x16x32_bf16 v[60:63], v[144:147], v[176:179], v[60:63]
	v_mfma_f32_16x16x32_bf16 v[56:59], v[152:155], v[176:179], v[56:59]
	v_mfma_f32_16x16x32_bf16 v[52:55], v[144:147], v[184:187], v[52:55]
	v_mfma_f32_16x16x32_bf16 v[44:47], v[152:155], v[184:187], v[44:47]
	v_mfma_f32_16x16x32_bf16 v[36:39], v[144:147], v[192:195], v[36:39]
	v_mfma_f32_16x16x32_bf16 v[28:31], v[152:155], v[192:195], v[28:31]
	v_mfma_f32_16x16x32_bf16 v[20:23], v[144:147], v[210:213], v[20:23]
	v_mfma_f32_16x16x32_bf16 v[12:15], v[152:155], v[210:213], v[12:15]
	s_setprio 0
	s_setprio 1
	v_mfma_f32_16x16x32_bf16 v[48:51], v[156:159], v[172:175], v[48:51]
	v_mfma_f32_16x16x32_bf16 v[40:43], v[164:167], v[172:175], v[40:43]
	v_mfma_f32_16x16x32_bf16 v[32:35], v[156:159], v[180:183], v[32:35]
	v_mfma_f32_16x16x32_bf16 v[24:27], v[164:167], v[180:183], v[24:27]
	v_mfma_f32_16x16x32_bf16 v[16:19], v[156:159], v[188:191], v[16:19]
	v_mfma_f32_16x16x32_bf16 v[8:11], v[164:167], v[188:191], v[8:11]
	v_mfma_f32_16x16x32_bf16 v[4:7], v[156:159], v[206:209], v[4:7]
	v_mfma_f32_16x16x32_bf16 v[0:3], v[164:167], v[206:209], v[0:3]
	v_mfma_f32_16x16x32_bf16 v[48:51], v[160:163], v[176:179], v[48:51]
	v_mfma_f32_16x16x32_bf16 v[40:43], v[168:171], v[176:179], v[40:43]
	v_mfma_f32_16x16x32_bf16 v[32:35], v[160:163], v[184:187], v[32:35]
	v_mfma_f32_16x16x32_bf16 v[24:27], v[168:171], v[184:187], v[24:27]
	v_mfma_f32_16x16x32_bf16 v[16:19], v[160:163], v[192:195], v[16:19]
	v_mfma_f32_16x16x32_bf16 v[8:11], v[168:171], v[192:195], v[8:11]
	v_mfma_f32_16x16x32_bf16 v[4:7], v[160:163], v[210:213], v[4:7]
	v_mfma_f32_16x16x32_bf16 v[0:3], v[168:171], v[210:213], v[0:3]
	s_setprio 0
	s_barrier
	s_add_i32 s47, s47, 2
	s_add_u32 s45, s45, 0x100
	s_addc_u32 s46, s46, 0
	s_cmp_gt_u32 s47, 3
	s_mov_b64 s[16:17], s[18:19]
	s_cbranch_scc0 .LBB0_1338
	s_branch .Lpeel_exit_4
.LBB0_1338:
	s_add_u32 s18, s16, 0x100
	s_addc_u32 s19, s17, 0
	s_add_i32 s48, 0, 0x10000
	s_cmp_eq_u32 s47, 2
	s_cselect_b32 s23, s7, s19
	s_cselect_b32 s22, s6, s18
	s_cselect_b32 s21, s15, s46
	s_cselect_b32 s20, s14, s45
	s_add_i32 s49, 0, 0x14000
	v_add_u32_e32 v152, s48, v142
	v_add_u32_e32 v168, s49, v142
	ds_read_b128 v[138:141], v152
	ds_read_b128 v[144:147], v152 offset:1024
	ds_read_b128 v[148:151], v152 offset:2048
	ds_read_b128 v[152:155], v152 offset:3072
	ds_read_b128 v[156:159], v168
	ds_read_b128 v[160:163], v168 offset:1024
	ds_read_b128 v[164:167], v168 offset:2048
	ds_read_b128 v[168:171], v168 offset:3072
	v_lshl_add_u64 v[214:215], s[16:17], 0, v[134:135]
	s_add_i32 m0, s30, 0xc000
	ds_read_b128 v[172:175], v143
	ds_read_b128 v[176:179], v143 offset:1024
	ds_read_b128 v[180:183], v143 offset:2048
	ds_read_b128 v[184:187], v143 offset:3072
	ds_read_b128 v[188:191], v143 offset:4096
	ds_read_b128 v[192:195], v143 offset:5120
	ds_read_b128 v[206:209], v143 offset:6144
	ds_read_b128 v[210:213], v143 offset:7168
	global_load_lds_dwordx4 v[214:215], off
	v_lshl_add_u64 v[214:215], s[16:17], 0, v[136:137]
	s_add_i32 m0, s30, 0xe000
	s_nop 0
	global_load_lds_dwordx4 v[214:215], off
	s_waitcnt vmcnt(8)
	s_waitcnt lgkmcnt(0)
	s_barrier
; #define PG8_STAGE(bufoff, gbase, voff) do { _Pragma("unroll") for (int _i = 0; _i < 2; ++_i) \
;         __builtin_amdgcn_global_load_lds((const unsigned*)((const char*)(gbase) + (voff)[_i]), (PG8_LAS unsigned*)(lds + (bufoff) + ldsw + _i * 8192), 16, 0, 0); } while (0)
; #define PG8_LDA(dst, b, h) do { _Pragma("unroll") for (int m = 0; m < 4; ++m) _Pragma("unroll") for (int k = 0; k < 2; ++k) dst[m][k] = *(const PG8_LAS bf16x8*)(lds + PG8_SA(b, h) + aoff + m * 2048 + k * 1024); } while (0)
; #define PG8_MMA(ai, bj, At, Bt) do { __builtin_amdgcn_s_setprio(1); _Pragma("unroll") for (int m = 0; m < 4; ++m) _Pragma("unroll") for (int n = 0; n < 2; ++n) _Pragma("unroll") for (int k = 0; k < 2; ++k) \
;         acc[ai][bj][m][n] = __builtin_amdgcn_mfma_f32_16x16x32_bf16(Bt[n][k], At[m][k], acc[ai][bj][m][n], 0, 0, 0); __builtin_amdgcn_s_setprio(0); } while (0)
; #define PG8_WAIT_V(n) asm volatile("s_waitcnt vmcnt(" #n ")" ::: "memory")
; #define PG8_WAIT_L(n) asm volatile("s_waitcnt lgkmcnt(" #n ")" ::: "memory")
; #define PG8_BAR __builtin_amdgcn_s_barrier()
; #define PG8_SCHED __builtin_amdgcn_sched_barrier(0)
; template <class Epi, class Sched, bool ALIGN_EPI = false, bool SP2 = false>
; __device__ __forceinline__ void gemm_phase(PG8_LAS unsigned char* lds, const Gemm g, const Sched& S, const Epi& E, int wave_s_) {
;     ...
;             PG8_WAIT_V(8); PG8_WAIT_L(0); PG8_BAR; PG8_MMA(0, 0, At, B0); PG8_MMA(0, 1, At, B1); PG8_BAR; PG8_SCHED;
;             PG8_LDA(At, 0, 1); PG8_STAGE(PG8_SB(0, 0), b2, voffB); PG8_STAGE(PG8_SB(0, 1), b2 + hstep, voffB); PG8_STAGE(PG8_SA(0, 0), a2, voffA);
;             PG8_WAIT_V(8); PG8_WAIT_L(0); PG8_BAR; PG8_MMA(1, 0, At, B0); PG8_MMA(1, 1, At, B1); PG8_BAR; PG8_SCHED;
	s_setprio 1
	s_waitcnt lgkmcnt(0)
	v_mfma_f32_16x16x32_bf16 v[124:127], v[138:141], v[172:175], v[124:127]
	v_mfma_f32_16x16x32_bf16 v[120:123], v[148:151], v[172:175], v[120:123]
	v_mfma_f32_16x16x32_bf16 v[116:119], v[138:141], v[180:183], v[116:119]
	v_mfma_f32_16x16x32_bf16 v[108:111], v[148:151], v[180:183], v[108:111]
	v_mfma_f32_16x16x32_bf16 v[100:103], v[138:141], v[188:191], v[100:103]
	v_mfma_f32_16x16x32_bf16 v[92:95], v[148:151], v[188:191], v[92:95]
	v_mfma_f32_16x16x32_bf16 v[84:87], v[138:141], v[206:209], v[84:87]
	v_mfma_f32_16x16x32_bf16 v[76:79], v[148:151], v[206:209], v[76:79]
	v_mfma_f32_16x16x32_bf16 v[124:127], v[144:147], v[176:179], v[124:127]
	v_mfma_f32_16x16x32_bf16 v[120:123], v[152:155], v[176:179], v[120:123]
	v_mfma_f32_16x16x32_bf16 v[116:119], v[144:147], v[184:187], v[116:119]
	v_mfma_f32_16x16x32_bf16 v[108:111], v[152:155], v[184:187], v[108:111]
	v_mfma_f32_16x16x32_bf16 v[100:103], v[144:147], v[192:195], v[100:103]
	v_mfma_f32_16x16x32_bf16 v[92:95], v[152:155], v[192:195], v[92:95]
	v_mfma_f32_16x16x32_bf16 v[84:87], v[144:147], v[210:213], v[84:87]
	v_mfma_f32_16x16x32_bf16 v[76:79], v[152:155], v[210:213], v[76:79]
	s_setprio 0
	s_setprio 1
	v_mfma_f32_16x16x32_bf16 v[112:115], v[156:159], v[172:175], v[112:115]
	v_mfma_f32_16x16x32_bf16 v[104:107], v[164:167], v[172:175], v[104:107]
	v_mfma_f32_16x16x32_bf16 v[96:99], v[156:159], v[180:183], v[96:99]
	v_mfma_f32_16x16x32_bf16 v[88:91], v[164:167], v[180:183], v[88:91]
	v_mfma_f32_16x16x32_bf16 v[80:83], v[156:159], v[188:191], v[80:83]
	v_mfma_f32_16x16x32_bf16 v[72:75], v[164:167], v[188:191], v[72:75]
	v_mfma_f32_16x16x32_bf16 v[68:71], v[156:159], v[206:209], v[68:71]
	v_mfma_f32_16x16x32_bf16 v[64:67], v[164:167], v[206:209], v[64:67]
	v_mfma_f32_16x16x32_bf16 v[112:115], v[160:163], v[176:179], v[112:115]
	v_mfma_f32_16x16x32_bf16 v[104:107], v[168:171], v[176:179], v[104:107]
	v_mfma_f32_16x16x32_bf16 v[96:99], v[160:163], v[184:187], v[96:99]
	v_mfma_f32_16x16x32_bf16 v[88:91], v[168:171], v[184:187], v[88:91]
	v_mfma_f32_16x16x32_bf16 v[80:83], v[160:163], v[192:195], v[80:83]
	v_mfma_f32_16x16x32_bf16 v[72:75], v[168:171], v[192:195], v[72:75]
	v_mfma_f32_16x16x32_bf16 v[68:71], v[160:163], v[210:213], v[68:71]
	v_mfma_f32_16x16x32_bf16 v[64:67], v[168:171], v[210:213], v[64:67]
	s_setprio 0
	s_barrier
	s_add_i32 s16, s48, s29
	v_lshl_add_u64 v[214:215], s[20:21], 0, v[196:197]
	s_mov_b32 m0, s16
	ds_read_b128 v[172:175], v143 offset:16384
	ds_read_b128 v[176:179], v143 offset:17408
	ds_read_b128 v[180:183], v143 offset:18432
	ds_read_b128 v[184:187], v143 offset:19456
	ds_read_b128 v[188:191], v143 offset:20480
	ds_read_b128 v[192:195], v143 offset:21504
	ds_read_b128 v[206:209], v143 offset:22528
	ds_read_b128 v[210:213], v143 offset:23552
	global_load_lds_dwordx4 v[214:215], off
	s_add_i32 m0, s16, 0x2000
	s_add_u32 s16, s20, 0x18000
	v_lshl_add_u64 v[216:217], s[20:21], 0, v[132:133]
	s_addc_u32 s17, s21, 0
	s_add_i32 s48, s49, s29
	global_load_lds_dwordx4 v[216:217], off
	v_lshl_add_u64 v[218:219], s[16:17], 0, v[196:197]
	s_mov_b32 m0, s48
	v_lshl_add_u64 v[220:221], s[22:23], 0, v[130:131]
	global_load_lds_dwordx4 v[218:219], off
	v_lshl_add_u64 v[218:219], s[16:17], 0, v[132:133]
	s_add_i32 m0, s48, 0x2000
	s_nop 0
	global_load_lds_dwordx4 v[218:219], off
	v_lshl_add_u64 v[218:219], s[22:23], 0, v[128:129]
	s_waitcnt vmcnt(6)
	s_waitcnt lgkmcnt(0)
	s_barrier
	s_setprio 1
	s_waitcnt lgkmcnt(0)
	v_mfma_f32_16x16x32_bf16 v[60:63], v[138:141], v[172:175], v[60:63]
	v_mfma_f32_16x16x32_bf16 v[56:59], v[148:151], v[172:175], v[56:59]
	v_mfma_f32_16x16x32_bf16 v[52:55], v[138:141], v[180:183], v[52:55]
	v_mfma_f32_16x16x32_bf16 v[44:47], v[148:151], v[180:183], v[44:47]
	v_mfma_f32_16x16x32_bf16 v[36:39], v[138:141], v[188:191], v[36:39]
	v_mfma_f32_16x16x32_bf16 v[28:31], v[148:151], v[188:191], v[28:31]
	v_mfma_f32_16x16x32_bf16 v[20:23], v[138:141], v[206:209], v[20:23]
	v_mfma_f32_16x16x32_bf16 v[12:15], v[148:151], v[206:209], v[12:15]
	v_mfma_f32_16x16x32_bf16 v[60:63], v[144:147], v[176:179], v[60:63]
	v_mfma_f32_16x16x32_bf16 v[56:59], v[152:155], v[176:179], v[56:59]
	v_mfma_f32_16x16x32_bf16 v[52:55], v[144:147], v[184:187], v[52:55]
	v_mfma_f32_16x16x32_bf16 v[44:47], v[152:155], v[184:187], v[44:47]
	v_mfma_f32_16x16x32_bf16 v[36:39], v[144:147], v[192:195], v[36:39]
	v_mfma_f32_16x16x32_bf16 v[28:31], v[152:155], v[192:195], v[28:31]
	v_mfma_f32_16x16x32_bf16 v[20:23], v[144:147], v[210:213], v[20:23]
	v_mfma_f32_16x16x32_bf16 v[12:15], v[152:155], v[210:213], v[12:15]
	s_setprio 0
	s_setprio 1
	v_mfma_f32_16x16x32_bf16 v[48:51], v[156:159], v[172:175], v[48:51]
	v_mfma_f32_16x16x32_bf16 v[40:43], v[164:167], v[172:175], v[40:43]
	v_mfma_f32_16x16x32_bf16 v[32:35], v[156:159], v[180:183], v[32:35]
	v_mfma_f32_16x16x32_bf16 v[24:27], v[164:167], v[180:183], v[24:27]
	v_mfma_f32_16x16x32_bf16 v[16:19], v[156:159], v[188:191], v[16:19]
	v_mfma_f32_16x16x32_bf16 v[8:11], v[164:167], v[188:191], v[8:11]
	v_mfma_f32_16x16x32_bf16 v[4:7], v[156:159], v[206:209], v[4:7]
	v_mfma_f32_16x16x32_bf16 v[0:3], v[164:167], v[206:209], v[0:3]
	v_mfma_f32_16x16x32_bf16 v[48:51], v[160:163], v[176:179], v[48:51]
	v_mfma_f32_16x16x32_bf16 v[40:43], v[168:171], v[176:179], v[40:43]
	v_mfma_f32_16x16x32_bf16 v[32:35], v[160:163], v[184:187], v[32:35]
	v_mfma_f32_16x16x32_bf16 v[24:27], v[168:171], v[184:187], v[24:27]
	v_mfma_f32_16x16x32_bf16 v[16:19], v[160:163], v[192:195], v[16:19]
	v_mfma_f32_16x16x32_bf16 v[8:11], v[168:171], v[192:195], v[8:11]
	v_mfma_f32_16x16x32_bf16 v[4:7], v[160:163], v[210:213], v[4:7]
	v_mfma_f32_16x16x32_bf16 v[0:3], v[168:171], v[210:213], v[0:3]
	s_setprio 0
	s_barrier
; #define PG8_STAGE(bufoff, gbase, voff) do { _Pragma("unroll") for (int _i = 0; _i < 2; ++_i) \
;         __builtin_amdgcn_global_load_lds((const unsigned*)((const char*)(gbase) + (voff)[_i]), (PG8_LAS unsigned*)(lds + (bufoff) + ldsw + _i * 8192), 16, 0, 0); } while (0)
; #define PG8_LDA(dst, b, h) do { _Pragma("unroll") for (int m = 0; m < 4; ++m) _Pragma("unroll") for (int k = 0; k < 2; ++k) dst[m][k] = *(const PG8_LAS bf16x8*)(lds + PG8_SA(b, h) + aoff + m * 2048 + k * 1024); } while (0)
; #define PG8_LDB(dst, b, h) do { _Pragma("unroll") for (int n = 0; n < 2; ++n) _Pragma("unroll") for (int k = 0; k < 2; ++k) dst[n][k] = *(const PG8_LAS bf16x8*)(lds + PG8_SB(b, h) + boff + n * 2048 + k * 1024); } while (0)
; #define PG8_MMA(ai, bj, At, Bt) do { __builtin_amdgcn_s_setprio(1); _Pragma("unroll") for (int m = 0; m < 4; ++m) _Pragma("unroll") for (int n = 0; n < 2; ++n) _Pragma("unroll") for (int k = 0; k < 2; ++k) \
;         acc[ai][bj][m][n] = __builtin_amdgcn_mfma_f32_16x16x32_bf16(Bt[n][k], At[m][k], acc[ai][bj][m][n], 0, 0, 0); __builtin_amdgcn_s_setprio(0); } while (0)
; #define PG8_WAIT_V(n) asm volatile("s_waitcnt vmcnt(" #n ")" ::: "memory")
; #define PG8_WAIT_L(n) asm volatile("s_waitcnt lgkmcnt(" #n ")" ::: "memory")
; #define PG8_BAR __builtin_amdgcn_s_barrier()
; #define PG8_SCHED __builtin_amdgcn_sched_barrier(0)
; template <class Epi, class Sched, bool ALIGN_EPI = false, bool SP2 = false>
; __device__ __forceinline__ void gemm_phase(PG8_LAS unsigned char* lds, const Gemm g, const Sched& S, const Epi& E, int wave_s_) {
;     ...
;             PG8_LDB(B0, 1, 0); PG8_LDB(B1, 1, 1); PG8_SCHED; PG8_LDA(At, 1, 0); PG8_STAGE(PG8_SA(0, 1), a2 + hstep, voffA);
;             PG8_WAIT_V(8); PG8_WAIT_L(0); PG8_BAR; PG8_MMA(0, 0, At, B0); PG8_MMA(0, 1, At, B1); PG8_BAR; PG8_SCHED;
	s_add_i32 s48, 0, 0x18000
	s_add_i32 s49, 0, 0x1c000
	v_add_u32_e32 v152, s48, v142
	v_add_u32_e32 v168, s49, v142
	ds_read_b128 v[138:141], v152
	ds_read_b128 v[144:147], v152 offset:1024
	ds_read_b128 v[148:151], v152 offset:2048
	ds_read_b128 v[152:155], v152 offset:3072
	ds_read_b128 v[156:159], v168
	ds_read_b128 v[160:163], v168 offset:1024
	ds_read_b128 v[164:167], v168 offset:2048
	ds_read_b128 v[168:171], v168 offset:3072
	s_add_u32 s16, s22, 0x18000
	s_addc_u32 s17, s23, 0
	s_mov_b32 m0, s33
	v_lshl_add_u64 v[222:223], s[16:17], 0, v[128:129]
	ds_read_b128 v[172:175], v143 offset:32768
	ds_read_b128 v[176:179], v143 offset:33792
	ds_read_b128 v[180:183], v143 offset:34816
	ds_read_b128 v[184:187], v143 offset:35840
	ds_read_b128 v[188:191], v143 offset:36864
	ds_read_b128 v[192:195], v143 offset:37888
	ds_read_b128 v[206:209], v143 offset:38912
	ds_read_b128 v[210:213], v143 offset:39936
	global_load_lds_dwordx4 v[222:223], off
	v_lshl_add_u64 v[222:223], s[16:17], 0, v[130:131]
	s_mov_b32 m0, s34
	s_nop 0
	global_load_lds_dwordx4 v[222:223], off
	s_mov_b32 m0, s30
	s_nop 0
	global_load_lds_dwordx4 v[218:219], off
	s_mov_b32 m0, s31
	s_nop 0
	global_load_lds_dwordx4 v[220:221], off
	s_waitcnt vmcnt(8)
	s_waitcnt lgkmcnt(0)
	s_barrier
	s_setprio 1
	s_waitcnt lgkmcnt(0)
	v_mfma_f32_16x16x32_bf16 v[124:127], v[138:141], v[172:175], v[124:127]
	v_mfma_f32_16x16x32_bf16 v[120:123], v[148:151], v[172:175], v[120:123]
	v_mfma_f32_16x16x32_bf16 v[116:119], v[138:141], v[180:183], v[116:119]
	v_mfma_f32_16x16x32_bf16 v[108:111], v[148:151], v[180:183], v[108:111]
	v_mfma_f32_16x16x32_bf16 v[100:103], v[138:141], v[188:191], v[100:103]
	v_mfma_f32_16x16x32_bf16 v[92:95], v[148:151], v[188:191], v[92:95]
	v_mfma_f32_16x16x32_bf16 v[84:87], v[138:141], v[206:209], v[84:87]
	v_mfma_f32_16x16x32_bf16 v[76:79], v[148:151], v[206:209], v[76:79]
	v_mfma_f32_16x16x32_bf16 v[124:127], v[144:147], v[176:179], v[124:127]
	v_mfma_f32_16x16x32_bf16 v[120:123], v[152:155], v[176:179], v[120:123]
	v_mfma_f32_16x16x32_bf16 v[116:119], v[144:147], v[184:187], v[116:119]
	v_mfma_f32_16x16x32_bf16 v[108:111], v[152:155], v[184:187], v[108:111]
	v_mfma_f32_16x16x32_bf16 v[100:103], v[144:147], v[192:195], v[100:103]
	v_mfma_f32_16x16x32_bf16 v[92:95], v[152:155], v[192:195], v[92:95]
	v_mfma_f32_16x16x32_bf16 v[84:87], v[144:147], v[210:213], v[84:87]
	v_mfma_f32_16x16x32_bf16 v[76:79], v[152:155], v[210:213], v[76:79]
	s_setprio 0
	s_setprio 1
	v_mfma_f32_16x16x32_bf16 v[112:115], v[156:159], v[172:175], v[112:115]
	v_mfma_f32_16x16x32_bf16 v[104:107], v[164:167], v[172:175], v[104:107]
	v_mfma_f32_16x16x32_bf16 v[96:99], v[156:159], v[180:183], v[96:99]
	v_mfma_f32_16x16x32_bf16 v[88:91], v[164:167], v[180:183], v[88:91]
	v_mfma_f32_16x16x32_bf16 v[80:83], v[156:159], v[188:191], v[80:83]
	v_mfma_f32_16x16x32_bf16 v[72:75], v[164:167], v[188:191], v[72:75]
	v_mfma_f32_16x16x32_bf16 v[68:71], v[156:159], v[206:209], v[68:71]
	v_mfma_f32_16x16x32_bf16 v[64:67], v[164:167], v[206:209], v[64:67]
	v_mfma_f32_16x16x32_bf16 v[112:115], v[160:163], v[176:179], v[112:115]
	v_mfma_f32_16x16x32_bf16 v[104:107], v[168:171], v[176:179], v[104:107]
	v_mfma_f32_16x16x32_bf16 v[96:99], v[160:163], v[184:187], v[96:99]
	v_mfma_f32_16x16x32_bf16 v[88:91], v[168:171], v[184:187], v[88:91]
	v_mfma_f32_16x16x32_bf16 v[80:83], v[160:163], v[192:195], v[80:83]
	v_mfma_f32_16x16x32_bf16 v[72:75], v[168:171], v[192:195], v[72:75]
	v_mfma_f32_16x16x32_bf16 v[68:71], v[160:163], v[210:213], v[68:71]
	v_mfma_f32_16x16x32_bf16 v[64:67], v[168:171], v[210:213], v[64:67]
	s_setprio 0
	s_barrier
; #define PG8_STAGE(bufoff, gbase, voff) do { _Pragma("unroll") for (int _i = 0; _i < 2; ++_i) \
;         __builtin_amdgcn_global_load_lds((const unsigned*)((const char*)(gbase) + (voff)[_i]), (PG8_LAS unsigned*)(lds + (bufoff) + ldsw + _i * 8192), 16, 0, 0); } while (0)
; #define PG8_LDA(dst, b, h) do { _Pragma("unroll") for (int m = 0; m < 4; ++m) _Pragma("unroll") for (int k = 0; k < 2; ++k) dst[m][k] = *(const PG8_LAS bf16x8*)(lds + PG8_SA(b, h) + aoff + m * 2048 + k * 1024); } while (0)
; #define PG8_MMA(ai, bj, At, Bt) do { __builtin_amdgcn_s_setprio(1); _Pragma("unroll") for (int m = 0; m < 4; ++m) _Pragma("unroll") for (int n = 0; n < 2; ++n) _Pragma("unroll") for (int k = 0; k < 2; ++k) \
;         acc[ai][bj][m][n] = __builtin_amdgcn_mfma_f32_16x16x32_bf16(Bt[n][k], At[m][k], acc[ai][bj][m][n], 0, 0, 0); __builtin_amdgcn_s_setprio(0); } while (0)
; #define PG8_WAIT_V(n) asm volatile("s_waitcnt vmcnt(" #n ")" ::: "memory")
; #define PG8_WAIT_L(n) asm volatile("s_waitcnt lgkmcnt(" #n ")" ::: "memory")
; #define PG8_BAR __builtin_amdgcn_s_barrier()
; #define PG8_SCHED __builtin_amdgcn_sched_barrier(0)
; template <class Epi, class Sched, bool ALIGN_EPI = false, bool SP2 = false>
; __device__ __forceinline__ void gemm_phase(PG8_LAS unsigned char* lds, const Gemm g, const Sched& S, const Epi& E, int wave_s_) {
;     ...
;             PG8_LDA(At, 1, 1); PG8_STAGE(PG8_SB(1, 0), b3, voffB); PG8_STAGE(PG8_SB(1, 1), b3 + hstep, voffB); PG8_STAGE(PG8_SA(1, 0), a3, voffA);
;             PG8_WAIT_V(8); PG8_WAIT_L(0); PG8_BAR; PG8_MMA(1, 0, At, B0); PG8_MMA(1, 1, At, B1); PG8_BAR; PG8_SCHED;
	s_add_i32 s16, s48, s29
	v_lshl_add_u64 v[214:215], v[214:215], 0, s[76:77]
	s_mov_b32 m0, s16
	ds_read_b128 v[172:175], v143 offset:49152
	ds_read_b128 v[176:179], v143 offset:50176
	ds_read_b128 v[180:183], v143 offset:51200
	ds_read_b128 v[184:187], v143 offset:52224
	ds_read_b128 v[188:191], v143 offset:53248
	ds_read_b128 v[192:195], v143 offset:54272
	ds_read_b128 v[206:209], v143 offset:55296
	ds_read_b128 v[210:213], v143 offset:56320
	global_load_lds_dwordx4 v[214:215], off
	s_add_i32 m0, s16, 0x2000
	s_add_u32 s16, s20, 0x18080
	v_lshl_add_u64 v[214:215], v[216:217], 0, s[76:77]
	s_addc_u32 s17, s21, 0
	s_add_i32 s20, s49, s29
	global_load_lds_dwordx4 v[214:215], off
	v_lshl_add_u64 v[214:215], s[16:17], 0, v[196:197]
	s_mov_b32 m0, s20
	s_nop 0
	global_load_lds_dwordx4 v[214:215], off
	v_lshl_add_u64 v[214:215], s[16:17], 0, v[132:133]
	s_add_i32 m0, s20, 0x2000
	s_nop 0
	global_load_lds_dwordx4 v[214:215], off
	v_lshl_add_u64 v[214:215], v[218:219], 0, s[76:77]
	s_mov_b32 m0, s37
	s_nop 0
	global_load_lds_dwordx4 v[214:215], off
	v_lshl_add_u64 v[214:215], v[220:221], 0, s[76:77]
	s_mov_b32 m0, s38
	s_nop 0
	global_load_lds_dwordx4 v[214:215], off
	s_waitcnt vmcnt(6)
	s_waitcnt lgkmcnt(0)
	s_barrier
	s_setprio 1
	s_waitcnt lgkmcnt(0)
	v_mfma_f32_16x16x32_bf16 v[60:63], v[138:141], v[172:175], v[60:63]
	v_mfma_f32_16x16x32_bf16 v[56:59], v[148:151], v[172:175], v[56:59]
	v_mfma_f32_16x16x32_bf16 v[52:55], v[138:141], v[180:183], v[52:55]
	v_mfma_f32_16x16x32_bf16 v[44:47], v[148:151], v[180:183], v[44:47]
	v_mfma_f32_16x16x32_bf16 v[36:39], v[138:141], v[188:191], v[36:39]
	v_mfma_f32_16x16x32_bf16 v[28:31], v[148:151], v[188:191], v[28:31]
	v_mfma_f32_16x16x32_bf16 v[20:23], v[138:141], v[206:209], v[20:23]
	v_mfma_f32_16x16x32_bf16 v[12:15], v[148:151], v[206:209], v[12:15]
	v_mfma_f32_16x16x32_bf16 v[60:63], v[144:147], v[176:179], v[60:63]
	v_mfma_f32_16x16x32_bf16 v[56:59], v[152:155], v[176:179], v[56:59]
	v_mfma_f32_16x16x32_bf16 v[52:55], v[144:147], v[184:187], v[52:55]
	v_mfma_f32_16x16x32_bf16 v[44:47], v[152:155], v[184:187], v[44:47]
	v_mfma_f32_16x16x32_bf16 v[36:39], v[144:147], v[192:195], v[36:39]
	v_mfma_f32_16x16x32_bf16 v[28:31], v[152:155], v[192:195], v[28:31]
	v_mfma_f32_16x16x32_bf16 v[20:23], v[144:147], v[210:213], v[20:23]
	v_mfma_f32_16x16x32_bf16 v[12:15], v[152:155], v[210:213], v[12:15]
	s_setprio 0
	s_setprio 1
	v_mfma_f32_16x16x32_bf16 v[48:51], v[156:159], v[172:175], v[48:51]
	v_mfma_f32_16x16x32_bf16 v[40:43], v[164:167], v[172:175], v[40:43]
	v_mfma_f32_16x16x32_bf16 v[32:35], v[156:159], v[180:183], v[32:35]
	v_mfma_f32_16x16x32_bf16 v[24:27], v[164:167], v[180:183], v[24:27]
	v_mfma_f32_16x16x32_bf16 v[16:19], v[156:159], v[188:191], v[16:19]
	v_mfma_f32_16x16x32_bf16 v[8:11], v[164:167], v[188:191], v[8:11]
	v_mfma_f32_16x16x32_bf16 v[4:7], v[156:159], v[206:209], v[4:7]
	v_mfma_f32_16x16x32_bf16 v[0:3], v[164:167], v[206:209], v[0:3]
	v_mfma_f32_16x16x32_bf16 v[48:51], v[160:163], v[176:179], v[48:51]
	v_mfma_f32_16x16x32_bf16 v[40:43], v[168:171], v[176:179], v[40:43]
	v_mfma_f32_16x16x32_bf16 v[32:35], v[160:163], v[184:187], v[32:35]
	v_mfma_f32_16x16x32_bf16 v[24:27], v[168:171], v[184:187], v[24:27]
	v_mfma_f32_16x16x32_bf16 v[16:19], v[160:163], v[192:195], v[16:19]
	v_mfma_f32_16x16x32_bf16 v[8:11], v[168:171], v[192:195], v[8:11]
	v_mfma_f32_16x16x32_bf16 v[4:7], v[160:163], v[210:213], v[4:7]
	v_mfma_f32_16x16x32_bf16 v[0:3], v[168:171], v[210:213], v[0:3]
	s_setprio 0
	s_barrier
	s_add_i32 s47, s47, 2
	s_add_u32 s45, s45, 0x100
	s_addc_u32 s46, s46, 0
	s_cmp_gt_u32 s47, 3
	s_mov_b64 s[16:17], s[18:19]
	s_cbranch_scc0 .LBB0_1338

;     __device__ __forceinline__ int nt_of(const Unit& u) const { return (u.pm >> 12) ? ktper : kt; }
; #define PG8_STAGE(bufoff, gbase, voff) do { _Pragma("unroll") for (int _i = 0; _i < 2; ++_i) \
;         __builtin_amdgcn_global_load_lds((const unsigned*)((const char*)(gbase) + (voff)[_i]), (PG8_LAS unsigned*)(lds + (bufoff) + ldsw + _i * 8192), 16, 0, 0); } while (0)
; #define PG8_LDA(dst, b, h) do { _Pragma("unroll") for (int m = 0; m < 4; ++m) _Pragma("unroll") for (int k = 0; k < 2; ++k) dst[m][k] = *(const PG8_LAS bf16x8*)(lds + PG8_SA(b, h) + aoff + m * 2048 + k * 1024); } while (0)
; #define PG8_LDB(dst, b, h) do { _Pragma("unroll") for (int n = 0; n < 2; ++n) _Pragma("unroll") for (int k = 0; k < 2; ++k) dst[n][k] = *(const PG8_LAS bf16x8*)(lds + PG8_SB(b, h) + boff + n * 2048 + k * 1024); } while (0)
; #define PG8_WAIT_V(n) asm volatile("s_waitcnt vmcnt(" #n ")" ::: "memory")
; #define PG8_BAR __builtin_amdgcn_s_barrier()
; template <class Epi, class Sched, bool ALIGN_EPI = false, bool SP2 = false>
; __device__ __forceinline__ void gemm_phase(PG8_LAS unsigned char* lds, const Gemm g, const Sched& S, const Epi& E, int wave_s_) {
;     ...
;         const char* nA = has_next ? (const char*)g.A + (size_t)(nxt.pm & 4095) * tstep + (size_t)S.k0_of(nxt) * kstep : cA; const char* nB = has_next ? (const char*)g.Bt + (size_t)nxt.pn * tstep + (size_t)S.k0_of(nxt) * kstep : cB;
;         const int nt = S.nt_of(cur);
;         for (int t = 0; t < nt; t += 2) {
;             const bool last = (t == nt - 2);
;             const char* a1 = cA + (size_t)(t + 1) * kstep;
;             const char* a2 = last ? nA : cA + (size_t)(t + 2) * kstep; const char* b2 = last ? nB : cB + (size_t)(t + 2) * kstep;
;             const char* a3 = a2 + kstep; const char* b3 = b2 + kstep;
;             if (last && has_next) S.a_ready(nxt);
;             if constexpr (SP2) {
;             PG8_LDB(B0, 0, 0); PG8_LDB(B1, 0, 1); PG8_SCHED; PG8_LDA(At, 0, 0); PG8_STAGE(PG8_SA(1, 1), a1 + hstep, voffA);
;             PG8_WAIT_V(8); PG8_WAIT_L(0); PG8_BAR; PG8_MMA(0, 0, At, B0); PG8_MMA(0, 1, At, B1); PG8_BAR; PG8_SCHED;
;             PG8_LDA(At, 0, 1); PG8_STAGE(PG8_SB(0, 0), b2, voffB); PG8_STAGE(PG8_SB(0, 1), b2 + hstep, voffB); PG8_STAGE(PG8_SA(0, 0), a2, voffA);
;             PG8_WAIT_V(8); PG8_WAIT_L(0); PG8_BAR; PG8_MMA(1, 0, At, B0); PG8_MMA(1, 1, At, B1); PG8_BAR; PG8_SCHED;
.LBB0_1357:
	v_mov_b32_e32 v0, 0
	s_mov_b32 s13, 0
	s_mov_b64 s[20:21], -1
	s_mov_b64 s[22:23], 0
	s_add_u32 s30, s18, s13
	s_addc_u32 s31, s19, 0
	s_add_u32 s26, s30, 0x100
	s_addc_u32 s27, s31, 0
	s_and_b64 s[24:25], s[22:23], exec
	s_cselect_b32 s27, s7, s27
	s_cselect_b32 s26, s6, s26
	s_add_u32 s13, s16, s13
	s_addc_u32 s24, s17, 0
	s_add_u32 s13, s13, 0x100
	s_addc_u32 s24, s24, 0
	s_add_i32 s62, 0, 0x10000
	s_and_b64 s[22:23], s[22:23], exec
	s_cselect_b32 s29, s15, s24
	s_cselect_b32 s28, s14, s13
	s_add_i32 s23, 0, 0x14000
	s_add_u32 s34, s30, 0x10080
	s_addc_u32 s35, s31, 0
	s_add_i32 s61, s62, s39
	s_add_i32 m0, s41, 0xc000
	s_add_i32 s64, s41, 0xe000
	s_add_i32 s58, s61, 0x2000
	s_add_u32 s30, s28, 0x10000
	v_add_u32_e32 v150, s62, v136
	v_add_u32_e32 v166, s23, v136
	s_addc_u32 s31, s29, 0
	s_add_i32 s60, s23, s39
	ds_read_b128 v[138:141], v150
	ds_read_b128 v[142:145], v150 offset:1024
	ds_read_b128 v[146:149], v150 offset:2048
	ds_read_b128 v[150:153], v150 offset:3072
	ds_read_b128 v[154:157], v166
	ds_read_b128 v[158:161], v166 offset:1024
	ds_read_b128 v[162:165], v166 offset:2048
	ds_read_b128 v[166:169], v166 offset:3072
	s_add_i32 s59, s60, 0x2000
	s_add_i32 s57, 0, 0x18000
	s_add_i32 s56, 0, 0x1c000
	s_add_u32 s24, s26, 0x10000
	s_addc_u32 s25, s27, 0
	s_add_i32 s55, s57, s39
	s_add_i32 s13, s55, 0x2000
	s_add_u32 s22, s28, 0x10080
	s_addc_u32 s23, s29, 0
	s_add_i32 s63, s56, s39
	s_add_i32 s62, s63, 0x2000
	v_lshl_add_u64 v[194:195], s[34:35], 0, v[134:135]
	ds_read_b128 v[170:173], v137
	ds_read_b128 v[174:177], v137 offset:1024
	ds_read_b128 v[178:181], v137 offset:2048
	ds_read_b128 v[182:185], v137 offset:3072
	ds_read_b128 v[186:189], v137 offset:4096
	ds_read_b128 v[190:193], v137 offset:5120
	ds_read_b128 v[206:209], v137 offset:6144
	ds_read_b128 v[210:213], v137 offset:7168
	global_load_lds_dwordx4 v[194:195], off
	v_lshl_add_u64 v[194:195], s[34:35], 0, v[130:131]
	s_mov_b32 m0, s64
	s_nop 0
	global_load_lds_dwordx4 v[194:195], off
	s_waitcnt vmcnt(8)
	s_waitcnt lgkmcnt(0)
	s_barrier
	s_setprio 1
	s_waitcnt lgkmcnt(0)
	v_mfma_f32_16x16x32_bf16 v[124:127], v[138:141], v[170:173], 0
	v_mfma_f32_16x16x32_bf16 v[120:123], v[146:149], v[170:173], 0
	v_mfma_f32_16x16x32_bf16 v[116:119], v[138:141], v[178:181], 0
	v_mfma_f32_16x16x32_bf16 v[112:115], v[146:149], v[178:181], 0
	v_mfma_f32_16x16x32_bf16 v[108:111], v[138:141], v[186:189], 0
	v_mfma_f32_16x16x32_bf16 v[104:107], v[146:149], v[186:189], 0
	v_mfma_f32_16x16x32_bf16 v[100:103], v[138:141], v[206:209], 0
	v_mfma_f32_16x16x32_bf16 v[96:99], v[146:149], v[206:209], 0
	v_mfma_f32_16x16x32_bf16 v[124:127], v[142:145], v[174:177], v[124:127]
	v_mfma_f32_16x16x32_bf16 v[120:123], v[150:153], v[174:177], v[120:123]
	v_mfma_f32_16x16x32_bf16 v[116:119], v[142:145], v[182:185], v[116:119]
	v_mfma_f32_16x16x32_bf16 v[112:115], v[150:153], v[182:185], v[112:115]
	v_mfma_f32_16x16x32_bf16 v[108:111], v[142:145], v[190:193], v[108:111]
	v_mfma_f32_16x16x32_bf16 v[104:107], v[150:153], v[190:193], v[104:107]
	v_mfma_f32_16x16x32_bf16 v[100:103], v[142:145], v[210:213], v[100:103]
	v_mfma_f32_16x16x32_bf16 v[96:99], v[150:153], v[210:213], v[96:99]
	s_setprio 0
	s_setprio 1
	v_mfma_f32_16x16x32_bf16 v[76:79], v[154:157], v[170:173], 0
	v_mfma_f32_16x16x32_bf16 v[68:71], v[162:165], v[170:173], 0
	v_mfma_f32_16x16x32_bf16 v[60:63], v[154:157], v[178:181], 0
	v_mfma_f32_16x16x32_bf16 v[52:55], v[162:165], v[178:181], 0
	v_mfma_f32_16x16x32_bf16 v[44:47], v[154:157], v[186:189], 0
	v_mfma_f32_16x16x32_bf16 v[40:43], v[162:165], v[186:189], 0
	v_mfma_f32_16x16x32_bf16 v[36:39], v[154:157], v[206:209], 0
	v_mfma_f32_16x16x32_bf16 v[32:35], v[162:165], v[206:209], 0
	v_mfma_f32_16x16x32_bf16 v[76:79], v[158:161], v[174:177], v[76:79]
	v_mfma_f32_16x16x32_bf16 v[68:71], v[166:169], v[174:177], v[68:71]
	v_mfma_f32_16x16x32_bf16 v[60:63], v[158:161], v[182:185], v[60:63]
	v_mfma_f32_16x16x32_bf16 v[52:55], v[166:169], v[182:185], v[52:55]
	v_mfma_f32_16x16x32_bf16 v[44:47], v[158:161], v[190:193], v[44:47]
	v_mfma_f32_16x16x32_bf16 v[40:43], v[166:169], v[190:193], v[40:43]
	v_mfma_f32_16x16x32_bf16 v[36:39], v[158:161], v[210:213], v[36:39]
	v_mfma_f32_16x16x32_bf16 v[32:35], v[166:169], v[210:213], v[32:35]
	s_setprio 0
	s_barrier
	s_mov_b32 m0, s61
	v_lshl_add_u64 v[194:195], s[28:29], 0, v[132:133]
	ds_read_b128 v[170:173], v137 offset:16384
	ds_read_b128 v[174:177], v137 offset:17408
	ds_read_b128 v[178:181], v137 offset:18432
	ds_read_b128 v[182:185], v137 offset:19456
	ds_read_b128 v[186:189], v137 offset:20480
	ds_read_b128 v[190:193], v137 offset:21504
	ds_read_b128 v[206:209], v137 offset:22528
	ds_read_b128 v[210:213], v137 offset:23552
	global_load_lds_dwordx4 v[194:195], off
	v_lshl_add_u64 v[214:215], s[28:29], 0, v[128:129]
	s_mov_b32 m0, s58
	v_lshl_add_u64 v[216:217], s[30:31], 0, v[132:133]
	global_load_lds_dwordx4 v[214:215], off
	s_mov_b32 m0, s60
	v_lshl_add_u64 v[218:219], s[26:27], 0, v[130:131]
	global_load_lds_dwordx4 v[216:217], off
	v_lshl_add_u64 v[216:217], s[30:31], 0, v[128:129]
	s_mov_b32 m0, s59
	s_nop 0
	global_load_lds_dwordx4 v[216:217], off
	v_lshl_add_u64 v[216:217], s[26:27], 0, v[134:135]
	s_waitcnt vmcnt(6)
	s_waitcnt lgkmcnt(0)
	s_barrier
; #define PG8_STAGE(bufoff, gbase, voff) do { _Pragma("unroll") for (int _i = 0; _i < 2; ++_i) \
;         __builtin_amdgcn_global_load_lds((const unsigned*)((const char*)(gbase) + (voff)[_i]), (PG8_LAS unsigned*)(lds + (bufoff) + ldsw + _i * 8192), 16, 0, 0); } while (0)
; #define PG8_LDA(dst, b, h) do { _Pragma("unroll") for (int m = 0; m < 4; ++m) _Pragma("unroll") for (int k = 0; k < 2; ++k) dst[m][k] = *(const PG8_LAS bf16x8*)(lds + PG8_SA(b, h) + aoff + m * 2048 + k * 1024); } while (0)
; #define PG8_LDB(dst, b, h) do { _Pragma("unroll") for (int n = 0; n < 2; ++n) _Pragma("unroll") for (int k = 0; k < 2; ++k) dst[n][k] = *(const PG8_LAS bf16x8*)(lds + PG8_SB(b, h) + boff + n * 2048 + k * 1024); } while (0)
; #define PG8_MMA(ai, bj, At, Bt) do { __builtin_amdgcn_s_setprio(1); _Pragma("unroll") for (int m = 0; m < 4; ++m) _Pragma("unroll") for (int n = 0; n < 2; ++n) _Pragma("unroll") for (int k = 0; k < 2; ++k) \
;         acc[ai][bj][m][n] = __builtin_amdgcn_mfma_f32_16x16x32_bf16(Bt[n][k], At[m][k], acc[ai][bj][m][n], 0, 0, 0); __builtin_amdgcn_s_setprio(0); } while (0)
; #define PG8_WAIT_V(n) asm volatile("s_waitcnt vmcnt(" #n ")" ::: "memory")
; #define PG8_WAIT_L(n) asm volatile("s_waitcnt lgkmcnt(" #n ")" ::: "memory")
; #define PG8_BAR __builtin_amdgcn_s_barrier()
; #define PG8_SCHED __builtin_amdgcn_sched_barrier(0)
; template <class Epi, class Sched, bool ALIGN_EPI = false, bool SP2 = false>
; __device__ __forceinline__ void gemm_phase(PG8_LAS unsigned char* lds, const Gemm g, const Sched& S, const Epi& E, int wave_s_) {
;     ...
;             PG8_WAIT_V(8); PG8_WAIT_L(0); PG8_BAR; PG8_MMA(1, 0, At, B0); PG8_MMA(1, 1, At, B1); PG8_BAR; PG8_SCHED;
;             PG8_LDB(B0, 1, 0); PG8_LDB(B1, 1, 1); PG8_SCHED; PG8_LDA(At, 1, 0); PG8_STAGE(PG8_SA(0, 1), a2 + hstep, voffA);
;             PG8_WAIT_V(8); PG8_WAIT_L(0); PG8_BAR; PG8_MMA(0, 0, At, B0); PG8_MMA(0, 1, At, B1); PG8_BAR; PG8_SCHED;
	s_setprio 1
	s_waitcnt lgkmcnt(0)
	v_mfma_f32_16x16x32_bf16 v[92:95], v[138:141], v[170:173], 0
	v_mfma_f32_16x16x32_bf16 v[88:91], v[146:149], v[170:173], 0
	v_mfma_f32_16x16x32_bf16 v[84:87], v[138:141], v[178:181], 0
	v_mfma_f32_16x16x32_bf16 v[80:83], v[146:149], v[178:181], 0
	v_mfma_f32_16x16x32_bf16 v[72:75], v[138:141], v[186:189], 0
	v_mfma_f32_16x16x32_bf16 v[64:67], v[146:149], v[186:189], 0
	v_mfma_f32_16x16x32_bf16 v[56:59], v[138:141], v[206:209], 0
	v_mfma_f32_16x16x32_bf16 v[48:51], v[146:149], v[206:209], 0
	v_mfma_f32_16x16x32_bf16 v[92:95], v[142:145], v[174:177], v[92:95]
	v_mfma_f32_16x16x32_bf16 v[88:91], v[150:153], v[174:177], v[88:91]
	v_mfma_f32_16x16x32_bf16 v[84:87], v[142:145], v[182:185], v[84:87]
	v_mfma_f32_16x16x32_bf16 v[80:83], v[150:153], v[182:185], v[80:83]
	v_mfma_f32_16x16x32_bf16 v[72:75], v[142:145], v[190:193], v[72:75]
	v_mfma_f32_16x16x32_bf16 v[64:67], v[150:153], v[190:193], v[64:67]
	v_mfma_f32_16x16x32_bf16 v[56:59], v[142:145], v[210:213], v[56:59]
	v_mfma_f32_16x16x32_bf16 v[48:51], v[150:153], v[210:213], v[48:51]
	s_setprio 0
	s_setprio 1
	v_mfma_f32_16x16x32_bf16 v[28:31], v[154:157], v[170:173], 0
	v_mfma_f32_16x16x32_bf16 v[24:27], v[162:165], v[170:173], 0
	v_mfma_f32_16x16x32_bf16 v[20:23], v[154:157], v[178:181], 0
	v_mfma_f32_16x16x32_bf16 v[16:19], v[162:165], v[178:181], 0
	v_mfma_f32_16x16x32_bf16 v[12:15], v[154:157], v[186:189], 0
	v_mfma_f32_16x16x32_bf16 v[8:11], v[162:165], v[186:189], 0
	v_mfma_f32_16x16x32_bf16 v[4:7], v[154:157], v[206:209], 0
	v_mfma_f32_16x16x32_bf16 v[0:3], v[162:165], v[206:209], 0
	v_mfma_f32_16x16x32_bf16 v[28:31], v[158:161], v[174:177], v[28:31]
	v_mfma_f32_16x16x32_bf16 v[24:27], v[166:169], v[174:177], v[24:27]
	v_mfma_f32_16x16x32_bf16 v[20:23], v[158:161], v[182:185], v[20:23]
	v_mfma_f32_16x16x32_bf16 v[16:19], v[166:169], v[182:185], v[16:19]
	v_mfma_f32_16x16x32_bf16 v[12:15], v[158:161], v[190:193], v[12:15]
	v_mfma_f32_16x16x32_bf16 v[8:11], v[166:169], v[190:193], v[8:11]
	v_mfma_f32_16x16x32_bf16 v[4:7], v[158:161], v[210:213], v[4:7]
	v_mfma_f32_16x16x32_bf16 v[0:3], v[166:169], v[210:213], v[0:3]
	s_setprio 0
	s_barrier
	v_add_u32_e32 v150, s57, v136
	v_add_u32_e32 v166, s56, v136
	ds_read_b128 v[138:141], v150
	ds_read_b128 v[142:145], v150 offset:1024
	ds_read_b128 v[146:149], v150 offset:2048
	ds_read_b128 v[150:153], v150 offset:3072
	ds_read_b128 v[154:157], v166
	ds_read_b128 v[158:161], v166 offset:1024
	ds_read_b128 v[162:165], v166 offset:2048
	ds_read_b128 v[166:169], v166 offset:3072
	s_mov_b32 m0, s43
	v_lshl_add_u64 v[220:221], s[24:25], 0, v[134:135]
	ds_read_b128 v[170:173], v137 offset:32768
	ds_read_b128 v[174:177], v137 offset:33792
	ds_read_b128 v[178:181], v137 offset:34816
	ds_read_b128 v[182:185], v137 offset:35840
	ds_read_b128 v[186:189], v137 offset:36864
	ds_read_b128 v[190:193], v137 offset:37888
	ds_read_b128 v[206:209], v137 offset:38912
	ds_read_b128 v[210:213], v137 offset:39936
	global_load_lds_dwordx4 v[220:221], off
	v_lshl_add_u64 v[220:221], s[24:25], 0, v[130:131]
	s_mov_b32 m0, s44
	s_nop 0
	global_load_lds_dwordx4 v[220:221], off
	s_mov_b32 m0, s41
	s_nop 0
	global_load_lds_dwordx4 v[216:217], off
	s_mov_b32 m0, s42
	s_nop 0
	global_load_lds_dwordx4 v[218:219], off
	s_waitcnt vmcnt(8)
	s_waitcnt lgkmcnt(0)
	s_barrier
	s_setprio 1
	s_waitcnt lgkmcnt(0)
	v_mfma_f32_16x16x32_bf16 v[124:127], v[138:141], v[170:173], v[124:127]
	v_mfma_f32_16x16x32_bf16 v[120:123], v[146:149], v[170:173], v[120:123]
	v_mfma_f32_16x16x32_bf16 v[116:119], v[138:141], v[178:181], v[116:119]
	v_mfma_f32_16x16x32_bf16 v[112:115], v[146:149], v[178:181], v[112:115]
	v_mfma_f32_16x16x32_bf16 v[108:111], v[138:141], v[186:189], v[108:111]
	v_mfma_f32_16x16x32_bf16 v[104:107], v[146:149], v[186:189], v[104:107]
	v_mfma_f32_16x16x32_bf16 v[100:103], v[138:141], v[206:209], v[100:103]
	v_mfma_f32_16x16x32_bf16 v[96:99], v[146:149], v[206:209], v[96:99]
	v_mfma_f32_16x16x32_bf16 v[124:127], v[142:145], v[174:177], v[124:127]
	v_mfma_f32_16x16x32_bf16 v[120:123], v[150:153], v[174:177], v[120:123]
	v_mfma_f32_16x16x32_bf16 v[116:119], v[142:145], v[182:185], v[116:119]
	v_mfma_f32_16x16x32_bf16 v[112:115], v[150:153], v[182:185], v[112:115]
	v_mfma_f32_16x16x32_bf16 v[108:111], v[142:145], v[190:193], v[108:111]
	v_mfma_f32_16x16x32_bf16 v[104:107], v[150:153], v[190:193], v[104:107]
	v_mfma_f32_16x16x32_bf16 v[100:103], v[142:145], v[210:213], v[100:103]
	v_mfma_f32_16x16x32_bf16 v[96:99], v[150:153], v[210:213], v[96:99]
	s_setprio 0
	s_setprio 1
	v_mfma_f32_16x16x32_bf16 v[76:79], v[154:157], v[170:173], v[76:79]
	v_mfma_f32_16x16x32_bf16 v[68:71], v[162:165], v[170:173], v[68:71]
	v_mfma_f32_16x16x32_bf16 v[60:63], v[154:157], v[178:181], v[60:63]
	v_mfma_f32_16x16x32_bf16 v[52:55], v[162:165], v[178:181], v[52:55]
	v_mfma_f32_16x16x32_bf16 v[44:47], v[154:157], v[186:189], v[44:47]
	v_mfma_f32_16x16x32_bf16 v[40:43], v[162:165], v[186:189], v[40:43]
	v_mfma_f32_16x16x32_bf16 v[36:39], v[154:157], v[206:209], v[36:39]
	v_mfma_f32_16x16x32_bf16 v[32:35], v[162:165], v[206:209], v[32:35]
	v_mfma_f32_16x16x32_bf16 v[76:79], v[158:161], v[174:177], v[76:79]
	v_mfma_f32_16x16x32_bf16 v[68:71], v[166:169], v[174:177], v[68:71]
	v_mfma_f32_16x16x32_bf16 v[60:63], v[158:161], v[182:185], v[60:63]
	v_mfma_f32_16x16x32_bf16 v[52:55], v[166:169], v[182:185], v[52:55]
	v_mfma_f32_16x16x32_bf16 v[44:47], v[158:161], v[190:193], v[44:47]
	v_mfma_f32_16x16x32_bf16 v[40:43], v[166:169], v[190:193], v[40:43]
	v_mfma_f32_16x16x32_bf16 v[36:39], v[158:161], v[210:213], v[36:39]
	v_mfma_f32_16x16x32_bf16 v[32:35], v[166:169], v[210:213], v[32:35]
	s_setprio 0
	s_barrier
; #define PG8_STAGE(bufoff, gbase, voff) do { _Pragma("unroll") for (int _i = 0; _i < 2; ++_i) \
;         __builtin_amdgcn_global_load_lds((const unsigned*)((const char*)(gbase) + (voff)[_i]), (PG8_LAS unsigned*)(lds + (bufoff) + ldsw + _i * 8192), 16, 0, 0); } while (0)
; #define PG8_LDA(dst, b, h) do { _Pragma("unroll") for (int m = 0; m < 4; ++m) _Pragma("unroll") for (int k = 0; k < 2; ++k) dst[m][k] = *(const PG8_LAS bf16x8*)(lds + PG8_SA(b, h) + aoff + m * 2048 + k * 1024); } while (0)
; #define PG8_LDB(dst, b, h) do { _Pragma("unroll") for (int n = 0; n < 2; ++n) _Pragma("unroll") for (int k = 0; k < 2; ++k) dst[n][k] = *(const PG8_LAS bf16x8*)(lds + PG8_SB(b, h) + boff + n * 2048 + k * 1024); } while (0)
; #define PG8_MMA(ai, bj, At, Bt) do { __builtin_amdgcn_s_setprio(1); _Pragma("unroll") for (int m = 0; m < 4; ++m) _Pragma("unroll") for (int n = 0; n < 2; ++n) _Pragma("unroll") for (int k = 0; k < 2; ++k) \
;         acc[ai][bj][m][n] = __builtin_amdgcn_mfma_f32_16x16x32_bf16(Bt[n][k], At[m][k], acc[ai][bj][m][n], 0, 0, 0); __builtin_amdgcn_s_setprio(0); } while (0)
; #define PG8_WAIT_V(n) asm volatile("s_waitcnt vmcnt(" #n ")" ::: "memory")
; #define PG8_BAR __builtin_amdgcn_s_barrier()
; template <class Epi, class Sched, bool ALIGN_EPI = false, bool SP2 = false>
; __device__ __forceinline__ void gemm_phase(PG8_LAS unsigned char* lds, const Gemm g, const Sched& S, const Epi& E, int wave_s_) {
;     ...
;         for (int t = 0; t < nt; t += 2) {
;             const bool last = (t == nt - 2);
;             const char* a1 = cA + (size_t)(t + 1) * kstep;
;             const char* a2 = last ? nA : cA + (size_t)(t + 2) * kstep; const char* b2 = last ? nB : cB + (size_t)(t + 2) * kstep;
;             const char* a3 = a2 + kstep; const char* b3 = b2 + kstep;
;             if (last && has_next) S.a_ready(nxt);
;             if constexpr (SP2) {
;             PG8_LDB(B0, 0, 0); PG8_LDB(B1, 0, 1); PG8_SCHED; PG8_LDA(At, 0, 0); PG8_STAGE(PG8_SA(1, 1), a1 + hstep, voffA);
;             PG8_WAIT_V(8); PG8_WAIT_L(0); PG8_BAR; PG8_MMA(0, 0, At, B0); PG8_MMA(0, 1, At, B1); PG8_BAR; PG8_SCHED;
;     ...
;             PG8_LDA(At, 1, 1); PG8_STAGE(PG8_SB(1, 0), b3, voffB); PG8_STAGE(PG8_SB(1, 1), b3 + hstep, voffB); PG8_STAGE(PG8_SA(1, 0), a3, voffA);
;             PG8_WAIT_V(8); PG8_WAIT_L(0); PG8_BAR; PG8_MMA(1, 0, At, B0); PG8_MMA(1, 1, At, B1); PG8_BAR; PG8_SCHED;
	s_mov_b32 m0, s55
	v_lshl_add_u64 v[194:195], v[194:195], 0, s[76:77]
	ds_read_b128 v[170:173], v137 offset:49152
	ds_read_b128 v[174:177], v137 offset:50176
	ds_read_b128 v[178:181], v137 offset:51200
	ds_read_b128 v[182:185], v137 offset:52224
	ds_read_b128 v[186:189], v137 offset:53248
	ds_read_b128 v[190:193], v137 offset:54272
	ds_read_b128 v[206:209], v137 offset:55296
	ds_read_b128 v[210:213], v137 offset:56320
	global_load_lds_dwordx4 v[194:195], off
	v_lshl_add_u64 v[194:195], v[214:215], 0, s[76:77]
	s_mov_b32 m0, s13
	s_nop 0
	global_load_lds_dwordx4 v[194:195], off
	v_lshl_add_u64 v[194:195], s[22:23], 0, v[132:133]
	s_mov_b32 m0, s63
	s_nop 0
	global_load_lds_dwordx4 v[194:195], off
	v_lshl_add_u64 v[194:195], s[22:23], 0, v[128:129]
	s_mov_b32 m0, s62
	s_nop 0
	global_load_lds_dwordx4 v[194:195], off
	v_lshl_add_u64 v[194:195], v[216:217], 0, s[76:77]
	s_mov_b32 m0, s46
	s_nop 0
	global_load_lds_dwordx4 v[194:195], off
	v_lshl_add_u64 v[194:195], v[218:219], 0, s[76:77]
	s_mov_b32 m0, s47
	s_nop 0
	global_load_lds_dwordx4 v[194:195], off
	s_waitcnt vmcnt(6)
	s_waitcnt lgkmcnt(0)
	s_barrier
	s_setprio 1
	s_waitcnt lgkmcnt(0)
	v_mfma_f32_16x16x32_bf16 v[92:95], v[138:141], v[170:173], v[92:95]
	v_mfma_f32_16x16x32_bf16 v[88:91], v[146:149], v[170:173], v[88:91]
	v_mfma_f32_16x16x32_bf16 v[84:87], v[138:141], v[178:181], v[84:87]
	v_mfma_f32_16x16x32_bf16 v[80:83], v[146:149], v[178:181], v[80:83]
	v_mfma_f32_16x16x32_bf16 v[72:75], v[138:141], v[186:189], v[72:75]
	v_mfma_f32_16x16x32_bf16 v[64:67], v[146:149], v[186:189], v[64:67]
	v_mfma_f32_16x16x32_bf16 v[56:59], v[138:141], v[206:209], v[56:59]
	v_mfma_f32_16x16x32_bf16 v[48:51], v[146:149], v[206:209], v[48:51]
	v_mfma_f32_16x16x32_bf16 v[92:95], v[142:145], v[174:177], v[92:95]
	v_mfma_f32_16x16x32_bf16 v[88:91], v[150:153], v[174:177], v[88:91]
	v_mfma_f32_16x16x32_bf16 v[84:87], v[142:145], v[182:185], v[84:87]
	v_mfma_f32_16x16x32_bf16 v[80:83], v[150:153], v[182:185], v[80:83]
	v_mfma_f32_16x16x32_bf16 v[72:75], v[142:145], v[190:193], v[72:75]
	v_mfma_f32_16x16x32_bf16 v[64:67], v[150:153], v[190:193], v[64:67]
	v_mfma_f32_16x16x32_bf16 v[56:59], v[142:145], v[210:213], v[56:59]
	v_mfma_f32_16x16x32_bf16 v[48:51], v[150:153], v[210:213], v[48:51]
	s_setprio 0
	s_setprio 1
	v_mfma_f32_16x16x32_bf16 v[28:31], v[154:157], v[170:173], v[28:31]
	v_mfma_f32_16x16x32_bf16 v[24:27], v[162:165], v[170:173], v[24:27]
	v_mfma_f32_16x16x32_bf16 v[20:23], v[154:157], v[178:181], v[20:23]
	v_mfma_f32_16x16x32_bf16 v[16:19], v[162:165], v[178:181], v[16:19]
	v_mfma_f32_16x16x32_bf16 v[12:15], v[154:157], v[186:189], v[12:15]
	v_mfma_f32_16x16x32_bf16 v[8:11], v[162:165], v[186:189], v[8:11]
	v_mfma_f32_16x16x32_bf16 v[4:7], v[154:157], v[206:209], v[4:7]
	v_mfma_f32_16x16x32_bf16 v[0:3], v[162:165], v[206:209], v[0:3]
	v_mfma_f32_16x16x32_bf16 v[28:31], v[158:161], v[174:177], v[28:31]
	v_mfma_f32_16x16x32_bf16 v[24:27], v[166:169], v[174:177], v[24:27]
	v_mfma_f32_16x16x32_bf16 v[20:23], v[158:161], v[182:185], v[20:23]
	v_mfma_f32_16x16x32_bf16 v[16:19], v[166:169], v[182:185], v[16:19]
	v_mfma_f32_16x16x32_bf16 v[12:15], v[158:161], v[190:193], v[12:15]
	v_mfma_f32_16x16x32_bf16 v[8:11], v[166:169], v[190:193], v[8:11]
	v_mfma_f32_16x16x32_bf16 v[4:7], v[158:161], v[210:213], v[4:7]
	v_mfma_f32_16x16x32_bf16 v[0:3], v[166:169], v[210:213], v[0:3]
	s_setprio 0
	s_barrier
	s_movk_i32 s13, 0x100
	s_andn2_b64 vcc, exec, s[20:21]
	s_mov_b64 s[22:23], -1
	s_mov_b64 s[20:21], 0
	s_cbranch_vccz .LBB0_1358
	s_branch .Lpeel_exit_5
.LBB0_1358:
	s_add_u32 s30, s18, s13
	s_addc_u32 s31, s19, 0
	s_add_u32 s26, s30, 0x100
	s_addc_u32 s27, s31, 0
	s_and_b64 s[24:25], s[22:23], exec
	s_cselect_b32 s27, s7, s27
	s_cselect_b32 s26, s6, s26
	s_add_u32 s13, s16, s13
	s_addc_u32 s24, s17, 0
	s_add_u32 s13, s13, 0x100
	s_addc_u32 s24, s24, 0
	s_add_i32 s62, 0, 0x10000
	s_and_b64 s[22:23], s[22:23], exec
	s_cselect_b32 s29, s15, s24
	s_cselect_b32 s28, s14, s13
	s_add_i32 s23, 0, 0x14000
	s_add_u32 s34, s30, 0x10080
	s_addc_u32 s35, s31, 0
	s_add_i32 s61, s62, s39
	s_add_i32 m0, s41, 0xc000
	s_add_i32 s64, s41, 0xe000
	s_add_i32 s58, s61, 0x2000
	s_add_u32 s30, s28, 0x10000
	v_add_u32_e32 v150, s62, v136
	v_add_u32_e32 v166, s23, v136
	s_addc_u32 s31, s29, 0
	s_add_i32 s60, s23, s39
	ds_read_b128 v[138:141], v150
	ds_read_b128 v[142:145], v150 offset:1024
	ds_read_b128 v[146:149], v150 offset:2048
	ds_read_b128 v[150:153], v150 offset:3072
	ds_read_b128 v[154:157], v166
	ds_read_b128 v[158:161], v166 offset:1024
	ds_read_b128 v[162:165], v166 offset:2048
	ds_read_b128 v[166:169], v166 offset:3072
	s_add_i32 s59, s60, 0x2000
	s_add_i32 s57, 0, 0x18000
	s_add_i32 s56, 0, 0x1c000
	s_add_u32 s24, s26, 0x10000
	s_addc_u32 s25, s27, 0
	s_add_i32 s55, s57, s39
	s_add_i32 s13, s55, 0x2000
	s_add_u32 s22, s28, 0x10080
	s_addc_u32 s23, s29, 0
	s_add_i32 s63, s56, s39
	s_add_i32 s62, s63, 0x2000
	v_lshl_add_u64 v[194:195], s[34:35], 0, v[134:135]
	ds_read_b128 v[170:173], v137
	ds_read_b128 v[174:177], v137 offset:1024
	ds_read_b128 v[178:181], v137 offset:2048
	ds_read_b128 v[182:185], v137 offset:3072
	ds_read_b128 v[186:189], v137 offset:4096
	ds_read_b128 v[190:193], v137 offset:5120
	ds_read_b128 v[206:209], v137 offset:6144
	ds_read_b128 v[210:213], v137 offset:7168
	global_load_lds_dwordx4 v[194:195], off
	v_lshl_add_u64 v[194:195], s[34:35], 0, v[130:131]
	s_mov_b32 m0, s64
	s_nop 0
	global_load_lds_dwordx4 v[194:195], off
	s_waitcnt vmcnt(8)
	s_waitcnt lgkmcnt(0)
	s_barrier
; #define PG8_STAGE(bufoff, gbase, voff) do { _Pragma("unroll") for (int _i = 0; _i < 2; ++_i) \
;         __builtin_amdgcn_global_load_lds((const unsigned*)((const char*)(gbase) + (voff)[_i]), (PG8_LAS unsigned*)(lds + (bufoff) + ldsw + _i * 8192), 16, 0, 0); } while (0)
; #define PG8_LDA(dst, b, h) do { _Pragma("unroll") for (int m = 0; m < 4; ++m) _Pragma("unroll") for (int k = 0; k < 2; ++k) dst[m][k] = *(const PG8_LAS bf16x8*)(lds + PG8_SA(b, h) + aoff + m * 2048 + k * 1024); } while (0)
; #define PG8_LDB(dst, b, h) do { _Pragma("unroll") for (int n = 0; n < 2; ++n) _Pragma("unroll") for (int k = 0; k < 2; ++k) dst[n][k] = *(const PG8_LAS bf16x8*)(lds + PG8_SB(b, h) + boff + n * 2048 + k * 1024); } while (0)
; #define PG8_MMA(ai, bj, At, Bt) do { __builtin_amdgcn_s_setprio(1); _Pragma("unroll") for (int m = 0; m < 4; ++m) _Pragma("unroll") for (int n = 0; n < 2; ++n) _Pragma("unroll") for (int k = 0; k < 2; ++k) \
;         acc[ai][bj][m][n] = __builtin_amdgcn_mfma_f32_16x16x32_bf16(Bt[n][k], At[m][k], acc[ai][bj][m][n], 0, 0, 0); __builtin_amdgcn_s_setprio(0); } while (0)
; #define PG8_WAIT_V(n) asm volatile("s_waitcnt vmcnt(" #n ")" ::: "memory")
; #define PG8_WAIT_L(n) asm volatile("s_waitcnt lgkmcnt(" #n ")" ::: "memory")
; #define PG8_BAR __builtin_amdgcn_s_barrier()
; #define PG8_SCHED __builtin_amdgcn_sched_barrier(0)
; template <class Epi, class Sched, bool ALIGN_EPI = false, bool SP2 = false>
; __device__ __forceinline__ void gemm_phase(PG8_LAS unsigned char* lds, const Gemm g, const Sched& S, const Epi& E, int wave_s_) {
;     ...
;             PG8_WAIT_V(8); PG8_WAIT_L(0); PG8_BAR; PG8_MMA(0, 0, At, B0); PG8_MMA(0, 1, At, B1); PG8_BAR; PG8_SCHED;
;             PG8_LDA(At, 0, 1); PG8_STAGE(PG8_SB(0, 0), b2, voffB); PG8_STAGE(PG8_SB(0, 1), b2 + hstep, voffB); PG8_STAGE(PG8_SA(0, 0), a2, voffA);
;             PG8_WAIT_V(8); PG8_WAIT_L(0); PG8_BAR; PG8_MMA(1, 0, At, B0); PG8_MMA(1, 1, At, B1); PG8_BAR; PG8_SCHED;
;             PG8_LDB(B0, 1, 0); PG8_LDB(B1, 1, 1); PG8_SCHED; PG8_LDA(At, 1, 0); PG8_STAGE(PG8_SA(0, 1), a2 + hstep, voffA);
;             PG8_WAIT_V(8); PG8_WAIT_L(0); PG8_BAR; PG8_MMA(0, 0, At, B0); PG8_MMA(0, 1, At, B1); PG8_BAR; PG8_SCHED;
	s_setprio 1
	s_waitcnt lgkmcnt(0)
	v_mfma_f32_16x16x32_bf16 v[124:127], v[138:141], v[170:173], v[124:127]
	v_mfma_f32_16x16x32_bf16 v[120:123], v[146:149], v[170:173], v[120:123]
	v_mfma_f32_16x16x32_bf16 v[116:119], v[138:141], v[178:181], v[116:119]
	v_mfma_f32_16x16x32_bf16 v[112:115], v[146:149], v[178:181], v[112:115]
	v_mfma_f32_16x16x32_bf16 v[108:111], v[138:141], v[186:189], v[108:111]
	v_mfma_f32_16x16x32_bf16 v[104:107], v[146:149], v[186:189], v[104:107]
	v_mfma_f32_16x16x32_bf16 v[100:103], v[138:141], v[206:209], v[100:103]
	v_mfma_f32_16x16x32_bf16 v[96:99], v[146:149], v[206:209], v[96:99]
	v_mfma_f32_16x16x32_bf16 v[124:127], v[142:145], v[174:177], v[124:127]
	v_mfma_f32_16x16x32_bf16 v[120:123], v[150:153], v[174:177], v[120:123]
	v_mfma_f32_16x16x32_bf16 v[116:119], v[142:145], v[182:185], v[116:119]
	v_mfma_f32_16x16x32_bf16 v[112:115], v[150:153], v[182:185], v[112:115]
	v_mfma_f32_16x16x32_bf16 v[108:111], v[142:145], v[190:193], v[108:111]
	v_mfma_f32_16x16x32_bf16 v[104:107], v[150:153], v[190:193], v[104:107]
	v_mfma_f32_16x16x32_bf16 v[100:103], v[142:145], v[210:213], v[100:103]
	v_mfma_f32_16x16x32_bf16 v[96:99], v[150:153], v[210:213], v[96:99]
	s_setprio 0
	s_setprio 1
	v_mfma_f32_16x16x32_bf16 v[76:79], v[154:157], v[170:173], v[76:79]
	v_mfma_f32_16x16x32_bf16 v[68:71], v[162:165], v[170:173], v[68:71]
	v_mfma_f32_16x16x32_bf16 v[60:63], v[154:157], v[178:181], v[60:63]
	v_mfma_f32_16x16x32_bf16 v[52:55], v[162:165], v[178:181], v[52:55]
	v_mfma_f32_16x16x32_bf16 v[44:47], v[154:157], v[186:189], v[44:47]
	v_mfma_f32_16x16x32_bf16 v[40:43], v[162:165], v[186:189], v[40:43]
	v_mfma_f32_16x16x32_bf16 v[36:39], v[154:157], v[206:209], v[36:39]
	v_mfma_f32_16x16x32_bf16 v[32:35], v[162:165], v[206:209], v[32:35]
	v_mfma_f32_16x16x32_bf16 v[76:79], v[158:161], v[174:177], v[76:79]
	v_mfma_f32_16x16x32_bf16 v[68:71], v[166:169], v[174:177], v[68:71]
	v_mfma_f32_16x16x32_bf16 v[60:63], v[158:161], v[182:185], v[60:63]
	v_mfma_f32_16x16x32_bf16 v[52:55], v[166:169], v[182:185], v[52:55]
	v_mfma_f32_16x16x32_bf16 v[44:47], v[158:161], v[190:193], v[44:47]
	v_mfma_f32_16x16x32_bf16 v[40:43], v[166:169], v[190:193], v[40:43]
	v_mfma_f32_16x16x32_bf16 v[36:39], v[158:161], v[210:213], v[36:39]
	v_mfma_f32_16x16x32_bf16 v[32:35], v[166:169], v[210:213], v[32:35]
	s_setprio 0
	s_barrier
	s_mov_b32 m0, s61
	v_lshl_add_u64 v[194:195], s[28:29], 0, v[132:133]
	ds_read_b128 v[170:173], v137 offset:16384
	ds_read_b128 v[174:177], v137 offset:17408
	ds_read_b128 v[178:181], v137 offset:18432
	ds_read_b128 v[182:185], v137 offset:19456
	ds_read_b128 v[186:189], v137 offset:20480
	ds_read_b128 v[190:193], v137 offset:21504
	ds_read_b128 v[206:209], v137 offset:22528
	ds_read_b128 v[210:213], v137 offset:23552
	global_load_lds_dwordx4 v[194:195], off
	v_lshl_add_u64 v[214:215], s[28:29], 0, v[128:129]
	s_mov_b32 m0, s58
	v_lshl_add_u64 v[216:217], s[30:31], 0, v[132:133]
	global_load_lds_dwordx4 v[214:215], off
	s_mov_b32 m0, s60
	v_lshl_add_u64 v[218:219], s[26:27], 0, v[130:131]
	global_load_lds_dwordx4 v[216:217], off
	v_lshl_add_u64 v[216:217], s[30:31], 0, v[128:129]
	s_mov_b32 m0, s59
	s_nop 0
	global_load_lds_dwordx4 v[216:217], off
	v_lshl_add_u64 v[216:217], s[26:27], 0, v[134:135]
	s_waitcnt vmcnt(6)
	s_waitcnt lgkmcnt(0)
	s_barrier
	s_setprio 1
	s_waitcnt lgkmcnt(0)
	v_mfma_f32_16x16x32_bf16 v[92:95], v[138:141], v[170:173], v[92:95]
	v_mfma_f32_16x16x32_bf16 v[88:91], v[146:149], v[170:173], v[88:91]
	v_mfma_f32_16x16x32_bf16 v[84:87], v[138:141], v[178:181], v[84:87]
	v_mfma_f32_16x16x32_bf16 v[80:83], v[146:149], v[178:181], v[80:83]
	v_mfma_f32_16x16x32_bf16 v[72:75], v[138:141], v[186:189], v[72:75]
	v_mfma_f32_16x16x32_bf16 v[64:67], v[146:149], v[186:189], v[64:67]
	v_mfma_f32_16x16x32_bf16 v[56:59], v[138:141], v[206:209], v[56:59]
	v_mfma_f32_16x16x32_bf16 v[48:51], v[146:149], v[206:209], v[48:51]
	v_mfma_f32_16x16x32_bf16 v[92:95], v[142:145], v[174:177], v[92:95]
	v_mfma_f32_16x16x32_bf16 v[88:91], v[150:153], v[174:177], v[88:91]
	v_mfma_f32_16x16x32_bf16 v[84:87], v[142:145], v[182:185], v[84:87]
	v_mfma_f32_16x16x32_bf16 v[80:83], v[150:153], v[182:185], v[80:83]
	v_mfma_f32_16x16x32_bf16 v[72:75], v[142:145], v[190:193], v[72:75]
	v_mfma_f32_16x16x32_bf16 v[64:67], v[150:153], v[190:193], v[64:67]
	v_mfma_f32_16x16x32_bf16 v[56:59], v[142:145], v[210:213], v[56:59]
	v_mfma_f32_16x16x32_bf16 v[48:51], v[150:153], v[210:213], v[48:51]
	s_setprio 0
	s_setprio 1
	v_mfma_f32_16x16x32_bf16 v[28:31], v[154:157], v[170:173], v[28:31]
	v_mfma_f32_16x16x32_bf16 v[24:27], v[162:165], v[170:173], v[24:27]
	v_mfma_f32_16x16x32_bf16 v[20:23], v[154:157], v[178:181], v[20:23]
	v_mfma_f32_16x16x32_bf16 v[16:19], v[162:165], v[178:181], v[16:19]
	v_mfma_f32_16x16x32_bf16 v[12:15], v[154:157], v[186:189], v[12:15]
	v_mfma_f32_16x16x32_bf16 v[8:11], v[162:165], v[186:189], v[8:11]
	v_mfma_f32_16x16x32_bf16 v[4:7], v[154:157], v[206:209], v[4:7]
	v_mfma_f32_16x16x32_bf16 v[0:3], v[162:165], v[206:209], v[0:3]
	v_mfma_f32_16x16x32_bf16 v[28:31], v[158:161], v[174:177], v[28:31]
	v_mfma_f32_16x16x32_bf16 v[24:27], v[166:169], v[174:177], v[24:27]
	v_mfma_f32_16x16x32_bf16 v[20:23], v[158:161], v[182:185], v[20:23]
	v_mfma_f32_16x16x32_bf16 v[16:19], v[166:169], v[182:185], v[16:19]
	v_mfma_f32_16x16x32_bf16 v[12:15], v[158:161], v[190:193], v[12:15]
	v_mfma_f32_16x16x32_bf16 v[8:11], v[166:169], v[190:193], v[8:11]
	v_mfma_f32_16x16x32_bf16 v[4:7], v[158:161], v[210:213], v[4:7]
	v_mfma_f32_16x16x32_bf16 v[0:3], v[166:169], v[210:213], v[0:3]
	s_setprio 0
	s_barrier
; #define PG8_STAGE(bufoff, gbase, voff) do { _Pragma("unroll") for (int _i = 0; _i < 2; ++_i) \
;         __builtin_amdgcn_global_load_lds((const unsigned*)((const char*)(gbase) + (voff)[_i]), (PG8_LAS unsigned*)(lds + (bufoff) + ldsw + _i * 8192), 16, 0, 0); } while (0)
; #define PG8_LDA(dst, b, h) do { _Pragma("unroll") for (int m = 0; m < 4; ++m) _Pragma("unroll") for (int k = 0; k < 2; ++k) dst[m][k] = *(const PG8_LAS bf16x8*)(lds + PG8_SA(b, h) + aoff + m * 2048 + k * 1024); } while (0)
; #define PG8_LDB(dst, b, h) do { _Pragma("unroll") for (int n = 0; n < 2; ++n) _Pragma("unroll") for (int k = 0; k < 2; ++k) dst[n][k] = *(const PG8_LAS bf16x8*)(lds + PG8_SB(b, h) + boff + n * 2048 + k * 1024); } while (0)
; #define PG8_MMA(ai, bj, At, Bt) do { __builtin_amdgcn_s_setprio(1); _Pragma("unroll") for (int m = 0; m < 4; ++m) _Pragma("unroll") for (int n = 0; n < 2; ++n) _Pragma("unroll") for (int k = 0; k < 2; ++k) \
;         acc[ai][bj][m][n] = __builtin_amdgcn_mfma_f32_16x16x32_bf16(Bt[n][k], At[m][k], acc[ai][bj][m][n], 0, 0, 0); __builtin_amdgcn_s_setprio(0); } while (0)
; #define PG8_WAIT_V(n) asm volatile("s_waitcnt vmcnt(" #n ")" ::: "memory")
; #define PG8_WAIT_L(n) asm volatile("s_waitcnt lgkmcnt(" #n ")" ::: "memory")
; #define PG8_BAR __builtin_amdgcn_s_barrier()
; #define PG8_SCHED __builtin_amdgcn_sched_barrier(0)
; template <class Epi, class Sched, bool ALIGN_EPI = false, bool SP2 = false>
; __device__ __forceinline__ void gemm_phase(PG8_LAS unsigned char* lds, const Gemm g, const Sched& S, const Epi& E, int wave_s_) {
;     ...
;         for (int t = 0; t < nt; t += 2) {
;             const bool last = (t == nt - 2);
;             const char* a1 = cA + (size_t)(t + 1) * kstep;
;             const char* a2 = last ? nA : cA + (size_t)(t + 2) * kstep; const char* b2 = last ? nB : cB + (size_t)(t + 2) * kstep;
;     ...
;             PG8_LDB(B0, 1, 0); PG8_LDB(B1, 1, 1); PG8_SCHED; PG8_LDA(At, 1, 0); PG8_STAGE(PG8_SA(0, 1), a2 + hstep, voffA);
;             PG8_WAIT_V(8); PG8_WAIT_L(0); PG8_BAR; PG8_MMA(0, 0, At, B0); PG8_MMA(0, 1, At, B1); PG8_BAR; PG8_SCHED;
;             PG8_LDA(At, 1, 1); PG8_STAGE(PG8_SB(1, 0), b3, voffB); PG8_STAGE(PG8_SB(1, 1), b3 + hstep, voffB); PG8_STAGE(PG8_SA(1, 0), a3, voffA);
;             PG8_WAIT_V(8); PG8_WAIT_L(0); PG8_BAR; PG8_MMA(1, 0, At, B0); PG8_MMA(1, 1, At, B1); PG8_BAR; PG8_SCHED;
	v_add_u32_e32 v150, s57, v136
	v_add_u32_e32 v166, s56, v136
	ds_read_b128 v[138:141], v150
	ds_read_b128 v[142:145], v150 offset:1024
	ds_read_b128 v[146:149], v150 offset:2048
	ds_read_b128 v[150:153], v150 offset:3072
	ds_read_b128 v[154:157], v166
	ds_read_b128 v[158:161], v166 offset:1024
	ds_read_b128 v[162:165], v166 offset:2048
	ds_read_b128 v[166:169], v166 offset:3072
	s_mov_b32 m0, s43
	v_lshl_add_u64 v[220:221], s[24:25], 0, v[134:135]
	ds_read_b128 v[170:173], v137 offset:32768
	ds_read_b128 v[174:177], v137 offset:33792
	ds_read_b128 v[178:181], v137 offset:34816
	ds_read_b128 v[182:185], v137 offset:35840
	ds_read_b128 v[186:189], v137 offset:36864
	ds_read_b128 v[190:193], v137 offset:37888
	ds_read_b128 v[206:209], v137 offset:38912
	ds_read_b128 v[210:213], v137 offset:39936
	global_load_lds_dwordx4 v[220:221], off
	v_lshl_add_u64 v[220:221], s[24:25], 0, v[130:131]
	s_mov_b32 m0, s44
	s_nop 0
	global_load_lds_dwordx4 v[220:221], off
	s_mov_b32 m0, s41
	s_nop 0
	global_load_lds_dwordx4 v[216:217], off
	s_mov_b32 m0, s42
	s_nop 0
	global_load_lds_dwordx4 v[218:219], off
	s_waitcnt vmcnt(8)
	s_waitcnt lgkmcnt(0)
	s_barrier
	s_setprio 1
	s_waitcnt lgkmcnt(0)
	v_mfma_f32_16x16x32_bf16 v[124:127], v[138:141], v[170:173], v[124:127]
	v_mfma_f32_16x16x32_bf16 v[120:123], v[146:149], v[170:173], v[120:123]
	v_mfma_f32_16x16x32_bf16 v[116:119], v[138:141], v[178:181], v[116:119]
	v_mfma_f32_16x16x32_bf16 v[112:115], v[146:149], v[178:181], v[112:115]
	v_mfma_f32_16x16x32_bf16 v[108:111], v[138:141], v[186:189], v[108:111]
	v_mfma_f32_16x16x32_bf16 v[104:107], v[146:149], v[186:189], v[104:107]
	v_mfma_f32_16x16x32_bf16 v[100:103], v[138:141], v[206:209], v[100:103]
	v_mfma_f32_16x16x32_bf16 v[96:99], v[146:149], v[206:209], v[96:99]
	v_mfma_f32_16x16x32_bf16 v[124:127], v[142:145], v[174:177], v[124:127]
	v_mfma_f32_16x16x32_bf16 v[120:123], v[150:153], v[174:177], v[120:123]
	v_mfma_f32_16x16x32_bf16 v[116:119], v[142:145], v[182:185], v[116:119]
	v_mfma_f32_16x16x32_bf16 v[112:115], v[150:153], v[182:185], v[112:115]
	v_mfma_f32_16x16x32_bf16 v[108:111], v[142:145], v[190:193], v[108:111]
	v_mfma_f32_16x16x32_bf16 v[104:107], v[150:153], v[190:193], v[104:107]
	v_mfma_f32_16x16x32_bf16 v[100:103], v[142:145], v[210:213], v[100:103]
	v_mfma_f32_16x16x32_bf16 v[96:99], v[150:153], v[210:213], v[96:99]
	s_setprio 0
	s_setprio 1
	v_mfma_f32_16x16x32_bf16 v[76:79], v[154:157], v[170:173], v[76:79]
	v_mfma_f32_16x16x32_bf16 v[68:71], v[162:165], v[170:173], v[68:71]
	v_mfma_f32_16x16x32_bf16 v[60:63], v[154:157], v[178:181], v[60:63]
	v_mfma_f32_16x16x32_bf16 v[52:55], v[162:165], v[178:181], v[52:55]
	v_mfma_f32_16x16x32_bf16 v[44:47], v[154:157], v[186:189], v[44:47]
	v_mfma_f32_16x16x32_bf16 v[40:43], v[162:165], v[186:189], v[40:43]
	v_mfma_f32_16x16x32_bf16 v[36:39], v[154:157], v[206:209], v[36:39]
	v_mfma_f32_16x16x32_bf16 v[32:35], v[162:165], v[206:209], v[32:35]
	v_mfma_f32_16x16x32_bf16 v[76:79], v[158:161], v[174:177], v[76:79]
	v_mfma_f32_16x16x32_bf16 v[68:71], v[166:169], v[174:177], v[68:71]
	v_mfma_f32_16x16x32_bf16 v[60:63], v[158:161], v[182:185], v[60:63]
	v_mfma_f32_16x16x32_bf16 v[52:55], v[166:169], v[182:185], v[52:55]
	v_mfma_f32_16x16x32_bf16 v[44:47], v[158:161], v[190:193], v[44:47]
	v_mfma_f32_16x16x32_bf16 v[40:43], v[166:169], v[190:193], v[40:43]
	v_mfma_f32_16x16x32_bf16 v[36:39], v[158:161], v[210:213], v[36:39]
	v_mfma_f32_16x16x32_bf16 v[32:35], v[166:169], v[210:213], v[32:35]
	s_setprio 0
	s_barrier
	s_mov_b32 m0, s55
	v_lshl_add_u64 v[194:195], v[194:195], 0, s[76:77]
	ds_read_b128 v[170:173], v137 offset:49152
	ds_read_b128 v[174:177], v137 offset:50176
	ds_read_b128 v[178:181], v137 offset:51200
	ds_read_b128 v[182:185], v137 offset:52224
	ds_read_b128 v[186:189], v137 offset:53248
	ds_read_b128 v[190:193], v137 offset:54272
	ds_read_b128 v[206:209], v137 offset:55296
	ds_read_b128 v[210:213], v137 offset:56320
	global_load_lds_dwordx4 v[194:195], off
	v_lshl_add_u64 v[194:195], v[214:215], 0, s[76:77]
	s_mov_b32 m0, s13
	s_nop 0
	global_load_lds_dwordx4 v[194:195], off
	v_lshl_add_u64 v[194:195], s[22:23], 0, v[132:133]
	s_mov_b32 m0, s63
	s_nop 0
	global_load_lds_dwordx4 v[194:195], off
	v_lshl_add_u64 v[194:195], s[22:23], 0, v[128:129]
	s_mov_b32 m0, s62
	s_nop 0
	global_load_lds_dwordx4 v[194:195], off
	v_lshl_add_u64 v[194:195], v[216:217], 0, s[76:77]
	s_mov_b32 m0, s46
	s_nop 0
	global_load_lds_dwordx4 v[194:195], off
	v_lshl_add_u64 v[194:195], v[218:219], 0, s[76:77]
	s_mov_b32 m0, s47
	s_nop 0
	global_load_lds_dwordx4 v[194:195], off
	s_waitcnt vmcnt(6)
	s_waitcnt lgkmcnt(0)
	s_barrier
	s_setprio 1
	s_waitcnt lgkmcnt(0)
	v_mfma_f32_16x16x32_bf16 v[92:95], v[138:141], v[170:173], v[92:95]
	v_mfma_f32_16x16x32_bf16 v[88:91], v[146:149], v[170:173], v[88:91]
	v_mfma_f32_16x16x32_bf16 v[84:87], v[138:141], v[178:181], v[84:87]
	v_mfma_f32_16x16x32_bf16 v[80:83], v[146:149], v[178:181], v[80:83]
	v_mfma_f32_16x16x32_bf16 v[72:75], v[138:141], v[186:189], v[72:75]
	v_mfma_f32_16x16x32_bf16 v[64:67], v[146:149], v[186:189], v[64:67]
	v_mfma_f32_16x16x32_bf16 v[56:59], v[138:141], v[206:209], v[56:59]
	v_mfma_f32_16x16x32_bf16 v[48:51], v[146:149], v[206:209], v[48:51]
	v_mfma_f32_16x16x32_bf16 v[92:95], v[142:145], v[174:177], v[92:95]
	v_mfma_f32_16x16x32_bf16 v[88:91], v[150:153], v[174:177], v[88:91]
	v_mfma_f32_16x16x32_bf16 v[84:87], v[142:145], v[182:185], v[84:87]
	v_mfma_f32_16x16x32_bf16 v[80:83], v[150:153], v[182:185], v[80:83]
	v_mfma_f32_16x16x32_bf16 v[72:75], v[142:145], v[190:193], v[72:75]
	v_mfma_f32_16x16x32_bf16 v[64:67], v[150:153], v[190:193], v[64:67]
	v_mfma_f32_16x16x32_bf16 v[56:59], v[142:145], v[210:213], v[56:59]
	v_mfma_f32_16x16x32_bf16 v[48:51], v[150:153], v[210:213], v[48:51]
	s_setprio 0
	s_setprio 1
	v_mfma_f32_16x16x32_bf16 v[28:31], v[154:157], v[170:173], v[28:31]
	v_mfma_f32_16x16x32_bf16 v[24:27], v[162:165], v[170:173], v[24:27]
	v_mfma_f32_16x16x32_bf16 v[20:23], v[154:157], v[178:181], v[20:23]
	v_mfma_f32_16x16x32_bf16 v[16:19], v[162:165], v[178:181], v[16:19]
	v_mfma_f32_16x16x32_bf16 v[12:15], v[154:157], v[186:189], v[12:15]
	v_mfma_f32_16x16x32_bf16 v[8:11], v[162:165], v[186:189], v[8:11]
	v_mfma_f32_16x16x32_bf16 v[4:7], v[154:157], v[206:209], v[4:7]
	v_mfma_f32_16x16x32_bf16 v[0:3], v[162:165], v[206:209], v[0:3]
	v_mfma_f32_16x16x32_bf16 v[28:31], v[158:161], v[174:177], v[28:31]
	v_mfma_f32_16x16x32_bf16 v[24:27], v[166:169], v[174:177], v[24:27]
	v_mfma_f32_16x16x32_bf16 v[20:23], v[158:161], v[182:185], v[20:23]
	v_mfma_f32_16x16x32_bf16 v[16:19], v[166:169], v[182:185], v[16:19]
	v_mfma_f32_16x16x32_bf16 v[12:15], v[158:161], v[190:193], v[12:15]
	v_mfma_f32_16x16x32_bf16 v[8:11], v[166:169], v[190:193], v[8:11]
	v_mfma_f32_16x16x32_bf16 v[4:7], v[158:161], v[210:213], v[4:7]
	v_mfma_f32_16x16x32_bf16 v[0:3], v[166:169], v[210:213], v[0:3]
	s_setprio 0
	s_barrier
	s_movk_i32 s13, 0x100
	s_andn2_b64 vcc, exec, s[20:21]
	s_mov_b64 s[22:23], -1
	s_mov_b64 s[20:21], 0
	s_cbranch_vccz .LBB0_1358

;     __device__ __forceinline__ int nt_of(const Unit& u) const { return (u.pm >> 12) ? ktper : kt; }
; #define PG8_STAGE(bufoff, gbase, voff) do { _Pragma("unroll") for (int _i = 0; _i < 2; ++_i) \
;         __builtin_amdgcn_global_load_lds((const unsigned*)((const char*)(gbase) + (voff)[_i]), (PG8_LAS unsigned*)(lds + (bufoff) + ldsw + _i * 8192), 16, 0, 0); } while (0)
; #define PG8_LDA(dst, b, h) do { _Pragma("unroll") for (int m = 0; m < 4; ++m) _Pragma("unroll") for (int k = 0; k < 2; ++k) dst[m][k] = *(const PG8_LAS bf16x8*)(lds + PG8_SA(b, h) + aoff + m * 2048 + k * 1024); } while (0)
; #define PG8_LDB(dst, b, h) do { _Pragma("unroll") for (int n = 0; n < 2; ++n) _Pragma("unroll") for (int k = 0; k < 2; ++k) dst[n][k] = *(const PG8_LAS bf16x8*)(lds + PG8_SB(b, h) + boff + n * 2048 + k * 1024); } while (0)
; #define PG8_WAIT_V(n) asm volatile("s_waitcnt vmcnt(" #n ")" ::: "memory")
; template <class Epi, class Sched, bool ALIGN_EPI = false, bool SP2 = false>
; __device__ __forceinline__ void gemm_phase(PG8_LAS unsigned char* lds, const Gemm g, const Sched& S, const Epi& E, int wave_s_) {
;     ...
;         const bool has_next = S.next(ui + 1, nxt);
;         const char* nA = has_next ? (const char*)g.A + (size_t)(nxt.pm & 4095) * tstep + (size_t)S.k0_of(nxt) * kstep : cA; const char* nB = has_next ? (const char*)g.Bt + (size_t)nxt.pn * tstep + (size_t)S.k0_of(nxt) * kstep : cB;
;         const int nt = S.nt_of(cur);
;         for (int t = 0; t < nt; t += 2) {
;             const bool last = (t == nt - 2);
;             const char* a1 = cA + (size_t)(t + 1) * kstep;
;             const char* a2 = last ? nA : cA + (size_t)(t + 2) * kstep; const char* b2 = last ? nB : cB + (size_t)(t + 2) * kstep;
;             const char* a3 = a2 + kstep; const char* b3 = b2 + kstep;
;             if (last && has_next) S.a_ready(nxt);
;             if constexpr (SP2) {
;             PG8_LDB(B0, 0, 0); PG8_LDB(B1, 0, 1); PG8_SCHED; PG8_LDA(At, 0, 0); PG8_STAGE(PG8_SA(1, 1), a1 + hstep, voffA);
;             PG8_WAIT_V(8); PG8_WAIT_L(0); PG8_BAR; PG8_MMA(0, 0, At, B0); PG8_MMA(0, 1, At, B1); PG8_BAR; PG8_SCHED;
;             PG8_LDA(At, 0, 1); PG8_STAGE(PG8_SB(0, 0), b2, voffB); PG8_STAGE(PG8_SB(0, 1), b2 + hstep, voffB); PG8_STAGE(PG8_SA(0, 0), a2, voffA);
;             PG8_WAIT_V(8); PG8_WAIT_L(0); PG8_BAR; PG8_MMA(1, 0, At, B0); PG8_MMA(1, 1, At, B1); PG8_BAR; PG8_SCHED;
.LBB0_1580:
	s_cmpk_gt_u32 s54, 0xfff
	s_cselect_b64 s[26:27], -1, 0
	s_cmpk_lt_u32 s54, 0x1000
	s_cselect_b64 s[6:7], -1, 0
	s_and_b64 s[30:31], s[6:7], exec
	s_cselect_b32 s9, 16, 4
	s_add_i32 s21, s9, -2
	s_add_u32 s55, s28, 0x100
	v_mov_b32_e32 v0, 0
	s_addc_u32 s56, s29, 0
	s_mov_b32 s30, 0
	v_mov_b32_e32 v1, v0
	v_mov_b64_e32 v[2:3], 0
	v_mov_b64_e32 v[4:5], 0
	v_mov_b64_e32 v[6:7], 0
	v_mov_b64_e32 v[12:13], 0
	v_mov_b64_e32 v[14:15], 0
	v_mov_b64_e32 v[20:21], 0
	v_mov_b64_e32 v[22:23], 0
	v_mov_b64_e32 v[32:33], 0
	v_mov_b64_e32 v[34:35], 0
	v_mov_b64_e32 v[36:37], 0
	v_mov_b64_e32 v[38:39], 0
	v_mov_b64_e32 v[44:45], 0
	v_mov_b64_e32 v[46:47], 0
	v_mov_b64_e32 v[52:53], 0
	v_mov_b64_e32 v[54:55], 0
	v_mov_b64_e32 v[8:9], 0
	v_mov_b64_e32 v[10:11], 0
	v_mov_b64_e32 v[16:17], 0
	v_mov_b64_e32 v[18:19], 0
	v_mov_b64_e32 v[24:25], 0
	v_mov_b64_e32 v[26:27], 0
	v_mov_b64_e32 v[28:29], 0
	v_mov_b64_e32 v[30:31], 0
	v_mov_b64_e32 v[40:41], 0
	v_mov_b64_e32 v[42:43], 0
	v_mov_b64_e32 v[48:49], 0
	v_mov_b64_e32 v[50:51], 0
	v_mov_b64_e32 v[56:57], 0
	v_mov_b64_e32 v[58:59], 0
	v_mov_b64_e32 v[60:61], 0
	v_mov_b64_e32 v[62:63], 0
	v_mov_b64_e32 v[64:65], 0
	v_mov_b64_e32 v[66:67], 0
	v_mov_b64_e32 v[68:69], 0
	v_mov_b64_e32 v[70:71], 0
	v_mov_b64_e32 v[76:77], 0
	v_mov_b64_e32 v[78:79], 0
	v_mov_b64_e32 v[84:85], 0
	v_mov_b64_e32 v[86:87], 0
	s_waitcnt vmcnt(0)
	s_add_i32 s57, s30, 2
	s_add_u32 s28, s10, 0x100
	s_addc_u32 s29, s11, 0
	s_add_i32 s58, 0, 0x10000
	s_cmp_eq_u32 s21, s30
	s_cselect_b32 s35, s23, s29
	s_cselect_b32 s34, s22, s28
	s_cselect_b32 s31, s25, s56
	s_cselect_b32 s30, s24, s55
	s_add_i32 s59, 0, 0x14000
	v_add_u32_e32 v100, s58, v224
	v_add_u32_e32 v120, s59, v224
	ds_read_b128 v[88:91], v100
	ds_read_b128 v[92:95], v100 offset:1024
	ds_read_b128 v[96:99], v100 offset:2048
	ds_read_b128 v[100:103], v100 offset:3072
	ds_read_b128 v[108:111], v120
	ds_read_b128 v[112:115], v120 offset:1024
	ds_read_b128 v[116:119], v120 offset:2048
	ds_read_b128 v[120:123], v120 offset:3072
	v_lshl_add_u64 v[198:199], s[10:11], 0, v[206:207]
	s_add_i32 m0, s40, 0xc000
	ds_read_b128 v[160:163], v225
	ds_read_b128 v[164:167], v225 offset:1024
	ds_read_b128 v[168:171], v225 offset:2048
	ds_read_b128 v[172:175], v225 offset:3072
	ds_read_b128 v[176:179], v225 offset:4096
	ds_read_b128 v[180:183], v225 offset:5120
	ds_read_b128 v[184:187], v225 offset:6144
	ds_read_b128 v[188:191], v225 offset:7168
	global_load_lds_dwordx4 v[198:199], off
	v_lshl_add_u64 v[198:199], s[10:11], 0, v[194:195]
	s_add_i32 m0, s40, 0xe000
	s_nop 0
	global_load_lds_dwordx4 v[198:199], off
	s_waitcnt vmcnt(8)
	s_waitcnt lgkmcnt(0)
	s_barrier
	s_setprio 1
	s_waitcnt lgkmcnt(0)
	v_mfma_f32_16x16x32_bf16 v[156:159], v[88:91], v[160:163], 0
	v_mfma_f32_16x16x32_bf16 v[152:155], v[96:99], v[160:163], 0
	v_mfma_f32_16x16x32_bf16 v[144:147], v[88:91], v[168:171], 0
	v_mfma_f32_16x16x32_bf16 v[136:139], v[96:99], v[168:171], 0
	v_mfma_f32_16x16x32_bf16 v[124:127], v[88:91], v[176:179], 0
	v_mfma_f32_16x16x32_bf16 v[104:107], v[96:99], v[176:179], 0
	v_mfma_f32_16x16x32_bf16 v[80:83], v[88:91], v[184:187], 0
	v_mfma_f32_16x16x32_bf16 v[72:75], v[96:99], v[184:187], 0
	v_mfma_f32_16x16x32_bf16 v[156:159], v[92:95], v[164:167], v[156:159]
	v_mfma_f32_16x16x32_bf16 v[152:155], v[100:103], v[164:167], v[152:155]
	v_mfma_f32_16x16x32_bf16 v[144:147], v[92:95], v[172:175], v[144:147]
	v_mfma_f32_16x16x32_bf16 v[136:139], v[100:103], v[172:175], v[136:139]
	v_mfma_f32_16x16x32_bf16 v[124:127], v[92:95], v[180:183], v[124:127]
	v_mfma_f32_16x16x32_bf16 v[104:107], v[100:103], v[180:183], v[104:107]
	v_mfma_f32_16x16x32_bf16 v[80:83], v[92:95], v[188:191], v[80:83]
	v_mfma_f32_16x16x32_bf16 v[72:75], v[100:103], v[188:191], v[72:75]
	s_setprio 0
	s_setprio 1
	v_mfma_f32_16x16x32_bf16 v[148:151], v[108:111], v[160:163], 0
	v_mfma_f32_16x16x32_bf16 v[140:143], v[116:119], v[160:163], 0
	v_mfma_f32_16x16x32_bf16 v[132:135], v[108:111], v[168:171], 0
	v_mfma_f32_16x16x32_bf16 v[128:131], v[116:119], v[168:171], 0
	v_mfma_f32_16x16x32_bf16 v[84:87], v[108:111], v[176:179], 0
	v_mfma_f32_16x16x32_bf16 v[76:79], v[116:119], v[176:179], 0
	v_mfma_f32_16x16x32_bf16 v[68:71], v[108:111], v[184:187], 0
	v_mfma_f32_16x16x32_bf16 v[64:67], v[116:119], v[184:187], 0
	v_mfma_f32_16x16x32_bf16 v[148:151], v[112:115], v[164:167], v[148:151]
	v_mfma_f32_16x16x32_bf16 v[140:143], v[120:123], v[164:167], v[140:143]
	v_mfma_f32_16x16x32_bf16 v[132:135], v[112:115], v[172:175], v[132:135]
	v_mfma_f32_16x16x32_bf16 v[128:131], v[120:123], v[172:175], v[128:131]
	v_mfma_f32_16x16x32_bf16 v[84:87], v[112:115], v[180:183], v[84:87]
	v_mfma_f32_16x16x32_bf16 v[76:79], v[120:123], v[180:183], v[76:79]
	v_mfma_f32_16x16x32_bf16 v[68:71], v[112:115], v[188:191], v[68:71]
	v_mfma_f32_16x16x32_bf16 v[64:67], v[120:123], v[188:191], v[64:67]
	s_setprio 0
	s_barrier
	s_add_i32 s10, s58, s39
	v_lshl_add_u64 v[198:199], s[30:31], 0, v[196:197]
	s_mov_b32 m0, s10
	ds_read_b128 v[160:163], v225 offset:16384
	ds_read_b128 v[164:167], v225 offset:17408
	ds_read_b128 v[168:171], v225 offset:18432
	ds_read_b128 v[172:175], v225 offset:19456
	ds_read_b128 v[176:179], v225 offset:20480
	ds_read_b128 v[180:183], v225 offset:21504
	ds_read_b128 v[184:187], v225 offset:22528
	ds_read_b128 v[188:191], v225 offset:23552
	global_load_lds_dwordx4 v[198:199], off
	s_add_i32 m0, s10, 0x2000
	s_add_u32 s10, s30, 0x40000
	v_lshl_add_u64 v[204:205], s[30:31], 0, v[192:193]
	s_addc_u32 s11, s31, 0
	s_add_i32 s58, s59, s39
	global_load_lds_dwordx4 v[204:205], off
	v_lshl_add_u64 v[208:209], s[10:11], 0, v[196:197]
	s_mov_b32 m0, s58
	v_lshl_add_u64 v[210:211], s[34:35], 0, v[192:193]
	global_load_lds_dwordx4 v[208:209], off
	v_lshl_add_u64 v[208:209], s[10:11], 0, v[192:193]
	s_add_i32 m0, s58, 0x2000
	s_nop 0
	global_load_lds_dwordx4 v[208:209], off
	v_lshl_add_u64 v[208:209], s[34:35], 0, v[196:197]
	s_waitcnt vmcnt(6)
	s_waitcnt lgkmcnt(0)
	s_barrier
; #define PG8_STAGE(bufoff, gbase, voff) do { _Pragma("unroll") for (int _i = 0; _i < 2; ++_i) \
;         __builtin_amdgcn_global_load_lds((const unsigned*)((const char*)(gbase) + (voff)[_i]), (PG8_LAS unsigned*)(lds + (bufoff) + ldsw + _i * 8192), 16, 0, 0); } while (0)
; #define PG8_LDA(dst, b, h) do { _Pragma("unroll") for (int m = 0; m < 4; ++m) _Pragma("unroll") for (int k = 0; k < 2; ++k) dst[m][k] = *(const PG8_LAS bf16x8*)(lds + PG8_SA(b, h) + aoff + m * 2048 + k * 1024); } while (0)
; #define PG8_LDB(dst, b, h) do { _Pragma("unroll") for (int n = 0; n < 2; ++n) _Pragma("unroll") for (int k = 0; k < 2; ++k) dst[n][k] = *(const PG8_LAS bf16x8*)(lds + PG8_SB(b, h) + boff + n * 2048 + k * 1024); } while (0)
; #define PG8_MMA(ai, bj, At, Bt) do { __builtin_amdgcn_s_setprio(1); _Pragma("unroll") for (int m = 0; m < 4; ++m) _Pragma("unroll") for (int n = 0; n < 2; ++n) _Pragma("unroll") for (int k = 0; k < 2; ++k) \
;         acc[ai][bj][m][n] = __builtin_amdgcn_mfma_f32_16x16x32_bf16(Bt[n][k], At[m][k], acc[ai][bj][m][n], 0, 0, 0); __builtin_amdgcn_s_setprio(0); } while (0)
; #define PG8_WAIT_V(n) asm volatile("s_waitcnt vmcnt(" #n ")" ::: "memory")
; #define PG8_WAIT_L(n) asm volatile("s_waitcnt lgkmcnt(" #n ")" ::: "memory")
; #define PG8_BAR __builtin_amdgcn_s_barrier()
; #define PG8_SCHED __builtin_amdgcn_sched_barrier(0)
; template <class Epi, class Sched, bool ALIGN_EPI = false, bool SP2 = false>
; __device__ __forceinline__ void gemm_phase(PG8_LAS unsigned char* lds, const Gemm g, const Sched& S, const Epi& E, int wave_s_) {
;     ...
;             PG8_WAIT_V(8); PG8_WAIT_L(0); PG8_BAR; PG8_MMA(1, 0, At, B0); PG8_MMA(1, 1, At, B1); PG8_BAR; PG8_SCHED;
;             PG8_LDB(B0, 1, 0); PG8_LDB(B1, 1, 1); PG8_SCHED; PG8_LDA(At, 1, 0); PG8_STAGE(PG8_SA(0, 1), a2 + hstep, voffA);
;             PG8_WAIT_V(8); PG8_WAIT_L(0); PG8_BAR; PG8_MMA(0, 0, At, B0); PG8_MMA(0, 1, At, B1); PG8_BAR; PG8_SCHED;
	s_setprio 1
	s_waitcnt lgkmcnt(0)
	v_mfma_f32_16x16x32_bf16 v[60:63], v[88:91], v[160:163], 0
	v_mfma_f32_16x16x32_bf16 v[56:59], v[96:99], v[160:163], 0
	v_mfma_f32_16x16x32_bf16 v[48:51], v[88:91], v[168:171], 0
	v_mfma_f32_16x16x32_bf16 v[40:43], v[96:99], v[168:171], 0
	v_mfma_f32_16x16x32_bf16 v[28:31], v[88:91], v[176:179], 0
	v_mfma_f32_16x16x32_bf16 v[24:27], v[96:99], v[176:179], 0
	v_mfma_f32_16x16x32_bf16 v[16:19], v[88:91], v[184:187], 0
	v_mfma_f32_16x16x32_bf16 v[8:11], v[96:99], v[184:187], 0
	v_mfma_f32_16x16x32_bf16 v[60:63], v[92:95], v[164:167], v[60:63]
	v_mfma_f32_16x16x32_bf16 v[56:59], v[100:103], v[164:167], v[56:59]
	v_mfma_f32_16x16x32_bf16 v[48:51], v[92:95], v[172:175], v[48:51]
	v_mfma_f32_16x16x32_bf16 v[40:43], v[100:103], v[172:175], v[40:43]
	v_mfma_f32_16x16x32_bf16 v[28:31], v[92:95], v[180:183], v[28:31]
	v_mfma_f32_16x16x32_bf16 v[24:27], v[100:103], v[180:183], v[24:27]
	v_mfma_f32_16x16x32_bf16 v[16:19], v[92:95], v[188:191], v[16:19]
	v_mfma_f32_16x16x32_bf16 v[8:11], v[100:103], v[188:191], v[8:11]
	s_setprio 0
	s_setprio 1
	v_mfma_f32_16x16x32_bf16 v[52:55], v[108:111], v[160:163], 0
	v_mfma_f32_16x16x32_bf16 v[44:47], v[116:119], v[160:163], 0
	v_mfma_f32_16x16x32_bf16 v[36:39], v[108:111], v[168:171], 0
	v_mfma_f32_16x16x32_bf16 v[32:35], v[116:119], v[168:171], 0
	v_mfma_f32_16x16x32_bf16 v[20:23], v[108:111], v[176:179], 0
	v_mfma_f32_16x16x32_bf16 v[12:15], v[116:119], v[176:179], 0
	v_mfma_f32_16x16x32_bf16 v[4:7], v[108:111], v[184:187], 0
	v_mfma_f32_16x16x32_bf16 v[0:3], v[116:119], v[184:187], 0
	v_mfma_f32_16x16x32_bf16 v[52:55], v[112:115], v[164:167], v[52:55]
	v_mfma_f32_16x16x32_bf16 v[44:47], v[120:123], v[164:167], v[44:47]
	v_mfma_f32_16x16x32_bf16 v[36:39], v[112:115], v[172:175], v[36:39]
	v_mfma_f32_16x16x32_bf16 v[32:35], v[120:123], v[172:175], v[32:35]
	v_mfma_f32_16x16x32_bf16 v[20:23], v[112:115], v[180:183], v[20:23]
	v_mfma_f32_16x16x32_bf16 v[12:15], v[120:123], v[180:183], v[12:15]
	v_mfma_f32_16x16x32_bf16 v[4:7], v[112:115], v[188:191], v[4:7]
	v_mfma_f32_16x16x32_bf16 v[0:3], v[120:123], v[188:191], v[0:3]
	s_setprio 0
	s_barrier
	s_add_i32 s58, 0, 0x18000
	s_add_i32 s59, 0, 0x1c000
	v_add_u32_e32 v100, s58, v224
	v_add_u32_e32 v120, s59, v224
	ds_read_b128 v[88:91], v100
	ds_read_b128 v[92:95], v100 offset:1024
	ds_read_b128 v[96:99], v100 offset:2048
	ds_read_b128 v[100:103], v100 offset:3072
	ds_read_b128 v[108:111], v120
	ds_read_b128 v[112:115], v120 offset:1024
	ds_read_b128 v[116:119], v120 offset:2048
	ds_read_b128 v[120:123], v120 offset:3072
	s_add_u32 s10, s34, 0x40000
	s_addc_u32 s11, s35, 0
	s_mov_b32 m0, s42
	v_lshl_add_u64 v[212:213], s[10:11], 0, v[196:197]
	ds_read_b128 v[160:163], v225 offset:32768
	ds_read_b128 v[164:167], v225 offset:33792
	ds_read_b128 v[168:171], v225 offset:34816
	ds_read_b128 v[172:175], v225 offset:35840
	ds_read_b128 v[176:179], v225 offset:36864
	ds_read_b128 v[180:183], v225 offset:37888
	ds_read_b128 v[184:187], v225 offset:38912
	ds_read_b128 v[188:191], v225 offset:39936
	global_load_lds_dwordx4 v[212:213], off
	v_lshl_add_u64 v[212:213], s[10:11], 0, v[192:193]
	s_mov_b32 m0, s43
	s_nop 0
	global_load_lds_dwordx4 v[212:213], off
	s_mov_b32 m0, s40
	s_nop 0
	global_load_lds_dwordx4 v[208:209], off
	s_mov_b32 m0, s41
	s_nop 0
	global_load_lds_dwordx4 v[210:211], off
	s_waitcnt vmcnt(8)
	s_waitcnt lgkmcnt(0)
	s_barrier
	s_setprio 1
	s_waitcnt lgkmcnt(0)
	v_mfma_f32_16x16x32_bf16 v[156:159], v[88:91], v[160:163], v[156:159]
	v_mfma_f32_16x16x32_bf16 v[152:155], v[96:99], v[160:163], v[152:155]
	v_mfma_f32_16x16x32_bf16 v[144:147], v[88:91], v[168:171], v[144:147]
	v_mfma_f32_16x16x32_bf16 v[136:139], v[96:99], v[168:171], v[136:139]
	v_mfma_f32_16x16x32_bf16 v[124:127], v[88:91], v[176:179], v[124:127]
	v_mfma_f32_16x16x32_bf16 v[104:107], v[96:99], v[176:179], v[104:107]
	v_mfma_f32_16x16x32_bf16 v[80:83], v[88:91], v[184:187], v[80:83]
	v_mfma_f32_16x16x32_bf16 v[72:75], v[96:99], v[184:187], v[72:75]
	v_mfma_f32_16x16x32_bf16 v[156:159], v[92:95], v[164:167], v[156:159]
	v_mfma_f32_16x16x32_bf16 v[152:155], v[100:103], v[164:167], v[152:155]
	v_mfma_f32_16x16x32_bf16 v[144:147], v[92:95], v[172:175], v[144:147]
	v_mfma_f32_16x16x32_bf16 v[136:139], v[100:103], v[172:175], v[136:139]
	v_mfma_f32_16x16x32_bf16 v[124:127], v[92:95], v[180:183], v[124:127]
	v_mfma_f32_16x16x32_bf16 v[104:107], v[100:103], v[180:183], v[104:107]
	v_mfma_f32_16x16x32_bf16 v[80:83], v[92:95], v[188:191], v[80:83]
	v_mfma_f32_16x16x32_bf16 v[72:75], v[100:103], v[188:191], v[72:75]
	s_setprio 0
	s_setprio 1
	v_mfma_f32_16x16x32_bf16 v[148:151], v[108:111], v[160:163], v[148:151]
	v_mfma_f32_16x16x32_bf16 v[140:143], v[116:119], v[160:163], v[140:143]
	v_mfma_f32_16x16x32_bf16 v[132:135], v[108:111], v[168:171], v[132:135]
	v_mfma_f32_16x16x32_bf16 v[128:131], v[116:119], v[168:171], v[128:131]
	v_mfma_f32_16x16x32_bf16 v[84:87], v[108:111], v[176:179], v[84:87]
	v_mfma_f32_16x16x32_bf16 v[76:79], v[116:119], v[176:179], v[76:79]
	v_mfma_f32_16x16x32_bf16 v[68:71], v[108:111], v[184:187], v[68:71]
	v_mfma_f32_16x16x32_bf16 v[64:67], v[116:119], v[184:187], v[64:67]
	v_mfma_f32_16x16x32_bf16 v[148:151], v[112:115], v[164:167], v[148:151]
	v_mfma_f32_16x16x32_bf16 v[140:143], v[120:123], v[164:167], v[140:143]
	v_mfma_f32_16x16x32_bf16 v[132:135], v[112:115], v[172:175], v[132:135]
	v_mfma_f32_16x16x32_bf16 v[128:131], v[120:123], v[172:175], v[128:131]
	v_mfma_f32_16x16x32_bf16 v[84:87], v[112:115], v[180:183], v[84:87]
	v_mfma_f32_16x16x32_bf16 v[76:79], v[120:123], v[180:183], v[76:79]
	v_mfma_f32_16x16x32_bf16 v[68:71], v[112:115], v[188:191], v[68:71]
	v_mfma_f32_16x16x32_bf16 v[64:67], v[120:123], v[188:191], v[64:67]
	s_setprio 0
	s_barrier
; #define PG8_STAGE(bufoff, gbase, voff) do { _Pragma("unroll") for (int _i = 0; _i < 2; ++_i) \
;         __builtin_amdgcn_global_load_lds((const unsigned*)((const char*)(gbase) + (voff)[_i]), (PG8_LAS unsigned*)(lds + (bufoff) + ldsw + _i * 8192), 16, 0, 0); } while (0)
; #define PG8_LDA(dst, b, h) do { _Pragma("unroll") for (int m = 0; m < 4; ++m) _Pragma("unroll") for (int k = 0; k < 2; ++k) dst[m][k] = *(const PG8_LAS bf16x8*)(lds + PG8_SA(b, h) + aoff + m * 2048 + k * 1024); } while (0)
; #define PG8_LDB(dst, b, h) do { _Pragma("unroll") for (int n = 0; n < 2; ++n) _Pragma("unroll") for (int k = 0; k < 2; ++k) dst[n][k] = *(const PG8_LAS bf16x8*)(lds + PG8_SB(b, h) + boff + n * 2048 + k * 1024); } while (0)
; #define PG8_MMA(ai, bj, At, Bt) do { __builtin_amdgcn_s_setprio(1); _Pragma("unroll") for (int m = 0; m < 4; ++m) _Pragma("unroll") for (int n = 0; n < 2; ++n) _Pragma("unroll") for (int k = 0; k < 2; ++k) \
;         acc[ai][bj][m][n] = __builtin_amdgcn_mfma_f32_16x16x32_bf16(Bt[n][k], At[m][k], acc[ai][bj][m][n], 0, 0, 0); __builtin_amdgcn_s_setprio(0); } while (0)
; #define PG8_BAR __builtin_amdgcn_s_barrier()
; template <class Epi, class Sched, bool ALIGN_EPI = false, bool SP2 = false>
; __device__ __forceinline__ void gemm_phase(PG8_LAS unsigned char* lds, const Gemm g, const Sched& S, const Epi& E, int wave_s_) {
;     ...
;             PG8_LDB(B0, 0, 0); PG8_LDB(B1, 0, 1); PG8_SCHED; PG8_LDA(At, 0, 0); PG8_STAGE(PG8_SA(1, 1), a1 + hstep, voffA);
;             PG8_WAIT_V(8); PG8_WAIT_L(0); PG8_BAR; PG8_MMA(0, 0, At, B0); PG8_MMA(0, 1, At, B1); PG8_BAR; PG8_SCHED;
;             PG8_LDA(At, 0, 1); PG8_STAGE(PG8_SB(0, 0), b2, voffB); PG8_STAGE(PG8_SB(0, 1), b2 + hstep, voffB); PG8_STAGE(PG8_SA(0, 0), a2, voffA);
;             PG8_WAIT_V(8); PG8_WAIT_L(0); PG8_BAR; PG8_MMA(1, 0, At, B0); PG8_MMA(1, 1, At, B1); PG8_BAR; PG8_SCHED;
;             PG8_LDB(B0, 1, 0); PG8_LDB(B1, 1, 1); PG8_SCHED; PG8_LDA(At, 1, 0); PG8_STAGE(PG8_SA(0, 1), a2 + hstep, voffA);
;             PG8_WAIT_V(8); PG8_WAIT_L(0); PG8_BAR; PG8_MMA(0, 0, At, B0); PG8_MMA(0, 1, At, B1); PG8_BAR; PG8_SCHED;
;             PG8_LDA(At, 1, 1); PG8_STAGE(PG8_SB(1, 0), b3, voffB); PG8_STAGE(PG8_SB(1, 1), b3 + hstep, voffB); PG8_STAGE(PG8_SA(1, 0), a3, voffA);
;             PG8_WAIT_V(8); PG8_WAIT_L(0); PG8_BAR; PG8_MMA(1, 0, At, B0); PG8_MMA(1, 1, At, B1); PG8_BAR; PG8_SCHED;
	s_add_i32 s10, s58, s39
	v_lshl_add_u64 v[198:199], v[198:199], 0, s[76:77]
	s_mov_b32 m0, s10
	ds_read_b128 v[160:163], v225 offset:49152
	ds_read_b128 v[164:167], v225 offset:50176
	ds_read_b128 v[168:171], v225 offset:51200
	ds_read_b128 v[172:175], v225 offset:52224
	ds_read_b128 v[176:179], v225 offset:53248
	ds_read_b128 v[180:183], v225 offset:54272
	ds_read_b128 v[184:187], v225 offset:55296
	ds_read_b128 v[188:191], v225 offset:56320
	global_load_lds_dwordx4 v[198:199], off
	s_add_i32 m0, s10, 0x2000
	s_add_u32 s10, s30, 0x40080
	v_lshl_add_u64 v[198:199], v[204:205], 0, s[76:77]
	s_addc_u32 s11, s31, 0
	s_add_i32 s30, s59, s39
	global_load_lds_dwordx4 v[198:199], off
	v_lshl_add_u64 v[198:199], s[10:11], 0, v[196:197]
	s_mov_b32 m0, s30
	s_nop 0
	global_load_lds_dwordx4 v[198:199], off
	v_lshl_add_u64 v[198:199], s[10:11], 0, v[192:193]
	s_add_i32 m0, s30, 0x2000
	s_nop 0
	global_load_lds_dwordx4 v[198:199], off
	v_lshl_add_u64 v[198:199], v[208:209], 0, s[76:77]
	s_mov_b32 m0, s46
	s_nop 0
	global_load_lds_dwordx4 v[198:199], off
	v_lshl_add_u64 v[198:199], v[210:211], 0, s[76:77]
	s_mov_b32 m0, s47
	s_nop 0
	global_load_lds_dwordx4 v[198:199], off
	s_waitcnt vmcnt(6)
	s_waitcnt lgkmcnt(0)
	s_barrier
	s_setprio 1
	s_waitcnt lgkmcnt(0)
	v_mfma_f32_16x16x32_bf16 v[60:63], v[88:91], v[160:163], v[60:63]
	v_mfma_f32_16x16x32_bf16 v[56:59], v[96:99], v[160:163], v[56:59]
	v_mfma_f32_16x16x32_bf16 v[48:51], v[88:91], v[168:171], v[48:51]
	v_mfma_f32_16x16x32_bf16 v[40:43], v[96:99], v[168:171], v[40:43]
	v_mfma_f32_16x16x32_bf16 v[28:31], v[88:91], v[176:179], v[28:31]
	v_mfma_f32_16x16x32_bf16 v[24:27], v[96:99], v[176:179], v[24:27]
	v_mfma_f32_16x16x32_bf16 v[16:19], v[88:91], v[184:187], v[16:19]
	v_mfma_f32_16x16x32_bf16 v[8:11], v[96:99], v[184:187], v[8:11]
	v_mfma_f32_16x16x32_bf16 v[60:63], v[92:95], v[164:167], v[60:63]
	v_mfma_f32_16x16x32_bf16 v[56:59], v[100:103], v[164:167], v[56:59]
	v_mfma_f32_16x16x32_bf16 v[48:51], v[92:95], v[172:175], v[48:51]
	v_mfma_f32_16x16x32_bf16 v[40:43], v[100:103], v[172:175], v[40:43]
	v_mfma_f32_16x16x32_bf16 v[28:31], v[92:95], v[180:183], v[28:31]
	v_mfma_f32_16x16x32_bf16 v[24:27], v[100:103], v[180:183], v[24:27]
	v_mfma_f32_16x16x32_bf16 v[16:19], v[92:95], v[188:191], v[16:19]
	v_mfma_f32_16x16x32_bf16 v[8:11], v[100:103], v[188:191], v[8:11]
	s_setprio 0
	s_setprio 1
	v_mfma_f32_16x16x32_bf16 v[52:55], v[108:111], v[160:163], v[52:55]
	v_mfma_f32_16x16x32_bf16 v[44:47], v[116:119], v[160:163], v[44:47]
	v_mfma_f32_16x16x32_bf16 v[36:39], v[108:111], v[168:171], v[36:39]
	v_mfma_f32_16x16x32_bf16 v[32:35], v[116:119], v[168:171], v[32:35]
	v_mfma_f32_16x16x32_bf16 v[20:23], v[108:111], v[176:179], v[20:23]
	v_mfma_f32_16x16x32_bf16 v[12:15], v[116:119], v[176:179], v[12:15]
	v_mfma_f32_16x16x32_bf16 v[4:7], v[108:111], v[184:187], v[4:7]
	v_mfma_f32_16x16x32_bf16 v[0:3], v[116:119], v[184:187], v[0:3]
	v_mfma_f32_16x16x32_bf16 v[52:55], v[112:115], v[164:167], v[52:55]
	v_mfma_f32_16x16x32_bf16 v[44:47], v[120:123], v[164:167], v[44:47]
	v_mfma_f32_16x16x32_bf16 v[36:39], v[112:115], v[172:175], v[36:39]
	v_mfma_f32_16x16x32_bf16 v[32:35], v[120:123], v[172:175], v[32:35]
	v_mfma_f32_16x16x32_bf16 v[20:23], v[112:115], v[180:183], v[20:23]
	v_mfma_f32_16x16x32_bf16 v[12:15], v[120:123], v[180:183], v[12:15]
	v_mfma_f32_16x16x32_bf16 v[4:7], v[112:115], v[188:191], v[4:7]
	v_mfma_f32_16x16x32_bf16 v[0:3], v[120:123], v[188:191], v[0:3]
	s_setprio 0
	s_barrier
	s_add_u32 s55, s55, 0x100
	s_addc_u32 s56, s56, 0
	s_cmp_ge_u32 s57, s9
	s_mov_b64 s[10:11], s[28:29]
	s_mov_b32 s30, s57
	s_cbranch_scc0 .LBB0_1581
	s_branch .Lpeel_exit_6
.LBB0_1581:
	s_add_i32 s57, s30, 2
	s_add_u32 s28, s10, 0x100
	s_addc_u32 s29, s11, 0
	s_add_i32 s58, 0, 0x10000
	s_cmp_eq_u32 s21, s30
	s_cselect_b32 s35, s23, s29
	s_cselect_b32 s34, s22, s28
	s_cselect_b32 s31, s25, s56
	s_cselect_b32 s30, s24, s55
	s_add_i32 s59, 0, 0x14000
	v_add_u32_e32 v100, s58, v224
	v_add_u32_e32 v120, s59, v224
	ds_read_b128 v[88:91], v100
	ds_read_b128 v[92:95], v100 offset:1024
	ds_read_b128 v[96:99], v100 offset:2048
	ds_read_b128 v[100:103], v100 offset:3072
	ds_read_b128 v[108:111], v120
	ds_read_b128 v[112:115], v120 offset:1024
	ds_read_b128 v[116:119], v120 offset:2048
	ds_read_b128 v[120:123], v120 offset:3072
	v_lshl_add_u64 v[198:199], s[10:11], 0, v[206:207]
	s_add_i32 m0, s40, 0xc000
	ds_read_b128 v[160:163], v225
	ds_read_b128 v[164:167], v225 offset:1024
	ds_read_b128 v[168:171], v225 offset:2048
	ds_read_b128 v[172:175], v225 offset:3072
	ds_read_b128 v[176:179], v225 offset:4096
	ds_read_b128 v[180:183], v225 offset:5120
	ds_read_b128 v[184:187], v225 offset:6144
	ds_read_b128 v[188:191], v225 offset:7168
	global_load_lds_dwordx4 v[198:199], off
	v_lshl_add_u64 v[198:199], s[10:11], 0, v[194:195]
	s_add_i32 m0, s40, 0xe000
	s_nop 0
	global_load_lds_dwordx4 v[198:199], off
	s_waitcnt vmcnt(8)
	s_waitcnt lgkmcnt(0)
	s_barrier
; #define PG8_STAGE(bufoff, gbase, voff) do { _Pragma("unroll") for (int _i = 0; _i < 2; ++_i) \
;         __builtin_amdgcn_global_load_lds((const unsigned*)((const char*)(gbase) + (voff)[_i]), (PG8_LAS unsigned*)(lds + (bufoff) + ldsw + _i * 8192), 16, 0, 0); } while (0)
; #define PG8_LDA(dst, b, h) do { _Pragma("unroll") for (int m = 0; m < 4; ++m) _Pragma("unroll") for (int k = 0; k < 2; ++k) dst[m][k] = *(const PG8_LAS bf16x8*)(lds + PG8_SA(b, h) + aoff + m * 2048 + k * 1024); } while (0)
; #define PG8_MMA(ai, bj, At, Bt) do { __builtin_amdgcn_s_setprio(1); _Pragma("unroll") for (int m = 0; m < 4; ++m) _Pragma("unroll") for (int n = 0; n < 2; ++n) _Pragma("unroll") for (int k = 0; k < 2; ++k) \
;         acc[ai][bj][m][n] = __builtin_amdgcn_mfma_f32_16x16x32_bf16(Bt[n][k], At[m][k], acc[ai][bj][m][n], 0, 0, 0); __builtin_amdgcn_s_setprio(0); } while (0)
; #define PG8_WAIT_V(n) asm volatile("s_waitcnt vmcnt(" #n ")" ::: "memory")
; #define PG8_WAIT_L(n) asm volatile("s_waitcnt lgkmcnt(" #n ")" ::: "memory")
; #define PG8_BAR __builtin_amdgcn_s_barrier()
; #define PG8_SCHED __builtin_amdgcn_sched_barrier(0)
; template <class Epi, class Sched, bool ALIGN_EPI = false, bool SP2 = false>
; __device__ __forceinline__ void gemm_phase(PG8_LAS unsigned char* lds, const Gemm g, const Sched& S, const Epi& E, int wave_s_) {
;     ...
;             PG8_WAIT_V(8); PG8_WAIT_L(0); PG8_BAR; PG8_MMA(0, 0, At, B0); PG8_MMA(0, 1, At, B1); PG8_BAR; PG8_SCHED;
;             PG8_LDA(At, 0, 1); PG8_STAGE(PG8_SB(0, 0), b2, voffB); PG8_STAGE(PG8_SB(0, 1), b2 + hstep, voffB); PG8_STAGE(PG8_SA(0, 0), a2, voffA);
;             PG8_WAIT_V(8); PG8_WAIT_L(0); PG8_BAR; PG8_MMA(1, 0, At, B0); PG8_MMA(1, 1, At, B1); PG8_BAR; PG8_SCHED;
	s_setprio 1
	s_waitcnt lgkmcnt(0)
	v_mfma_f32_16x16x32_bf16 v[156:159], v[88:91], v[160:163], v[156:159]
	v_mfma_f32_16x16x32_bf16 v[152:155], v[96:99], v[160:163], v[152:155]
	v_mfma_f32_16x16x32_bf16 v[144:147], v[88:91], v[168:171], v[144:147]
	v_mfma_f32_16x16x32_bf16 v[136:139], v[96:99], v[168:171], v[136:139]
	v_mfma_f32_16x16x32_bf16 v[124:127], v[88:91], v[176:179], v[124:127]
	v_mfma_f32_16x16x32_bf16 v[104:107], v[96:99], v[176:179], v[104:107]
	v_mfma_f32_16x16x32_bf16 v[80:83], v[88:91], v[184:187], v[80:83]
	v_mfma_f32_16x16x32_bf16 v[72:75], v[96:99], v[184:187], v[72:75]
	v_mfma_f32_16x16x32_bf16 v[156:159], v[92:95], v[164:167], v[156:159]
	v_mfma_f32_16x16x32_bf16 v[152:155], v[100:103], v[164:167], v[152:155]
	v_mfma_f32_16x16x32_bf16 v[144:147], v[92:95], v[172:175], v[144:147]
	v_mfma_f32_16x16x32_bf16 v[136:139], v[100:103], v[172:175], v[136:139]
	v_mfma_f32_16x16x32_bf16 v[124:127], v[92:95], v[180:183], v[124:127]
	v_mfma_f32_16x16x32_bf16 v[104:107], v[100:103], v[180:183], v[104:107]
	v_mfma_f32_16x16x32_bf16 v[80:83], v[92:95], v[188:191], v[80:83]
	v_mfma_f32_16x16x32_bf16 v[72:75], v[100:103], v[188:191], v[72:75]
	s_setprio 0
	s_setprio 1
	v_mfma_f32_16x16x32_bf16 v[148:151], v[108:111], v[160:163], v[148:151]
	v_mfma_f32_16x16x32_bf16 v[140:143], v[116:119], v[160:163], v[140:143]
	v_mfma_f32_16x16x32_bf16 v[132:135], v[108:111], v[168:171], v[132:135]
	v_mfma_f32_16x16x32_bf16 v[128:131], v[116:119], v[168:171], v[128:131]
	v_mfma_f32_16x16x32_bf16 v[84:87], v[108:111], v[176:179], v[84:87]
	v_mfma_f32_16x16x32_bf16 v[76:79], v[116:119], v[176:179], v[76:79]
	v_mfma_f32_16x16x32_bf16 v[68:71], v[108:111], v[184:187], v[68:71]
	v_mfma_f32_16x16x32_bf16 v[64:67], v[116:119], v[184:187], v[64:67]
	v_mfma_f32_16x16x32_bf16 v[148:151], v[112:115], v[164:167], v[148:151]
	v_mfma_f32_16x16x32_bf16 v[140:143], v[120:123], v[164:167], v[140:143]
	v_mfma_f32_16x16x32_bf16 v[132:135], v[112:115], v[172:175], v[132:135]
	v_mfma_f32_16x16x32_bf16 v[128:131], v[120:123], v[172:175], v[128:131]
	v_mfma_f32_16x16x32_bf16 v[84:87], v[112:115], v[180:183], v[84:87]
	v_mfma_f32_16x16x32_bf16 v[76:79], v[120:123], v[180:183], v[76:79]
	v_mfma_f32_16x16x32_bf16 v[68:71], v[112:115], v[188:191], v[68:71]
	v_mfma_f32_16x16x32_bf16 v[64:67], v[120:123], v[188:191], v[64:67]
	s_setprio 0
	s_barrier
	s_add_i32 s10, s58, s39
	v_lshl_add_u64 v[198:199], s[30:31], 0, v[196:197]
	s_mov_b32 m0, s10
	ds_read_b128 v[160:163], v225 offset:16384
	ds_read_b128 v[164:167], v225 offset:17408
	ds_read_b128 v[168:171], v225 offset:18432
	ds_read_b128 v[172:175], v225 offset:19456
	ds_read_b128 v[176:179], v225 offset:20480
	ds_read_b128 v[180:183], v225 offset:21504
	ds_read_b128 v[184:187], v225 offset:22528
	ds_read_b128 v[188:191], v225 offset:23552
	global_load_lds_dwordx4 v[198:199], off
	s_add_i32 m0, s10, 0x2000
	s_add_u32 s10, s30, 0x40000
	v_lshl_add_u64 v[204:205], s[30:31], 0, v[192:193]
	s_addc_u32 s11, s31, 0
	s_add_i32 s58, s59, s39
	global_load_lds_dwordx4 v[204:205], off
	v_lshl_add_u64 v[208:209], s[10:11], 0, v[196:197]
	s_mov_b32 m0, s58
	v_lshl_add_u64 v[210:211], s[34:35], 0, v[192:193]
	global_load_lds_dwordx4 v[208:209], off
	v_lshl_add_u64 v[208:209], s[10:11], 0, v[192:193]
	s_add_i32 m0, s58, 0x2000
	s_nop 0
	global_load_lds_dwordx4 v[208:209], off
	v_lshl_add_u64 v[208:209], s[34:35], 0, v[196:197]
	s_waitcnt vmcnt(6)
	s_waitcnt lgkmcnt(0)
	s_barrier
	s_setprio 1
	s_waitcnt lgkmcnt(0)
	v_mfma_f32_16x16x32_bf16 v[60:63], v[88:91], v[160:163], v[60:63]
	v_mfma_f32_16x16x32_bf16 v[56:59], v[96:99], v[160:163], v[56:59]
	v_mfma_f32_16x16x32_bf16 v[48:51], v[88:91], v[168:171], v[48:51]
	v_mfma_f32_16x16x32_bf16 v[40:43], v[96:99], v[168:171], v[40:43]
	v_mfma_f32_16x16x32_bf16 v[28:31], v[88:91], v[176:179], v[28:31]
	v_mfma_f32_16x16x32_bf16 v[24:27], v[96:99], v[176:179], v[24:27]
	v_mfma_f32_16x16x32_bf16 v[16:19], v[88:91], v[184:187], v[16:19]
	v_mfma_f32_16x16x32_bf16 v[8:11], v[96:99], v[184:187], v[8:11]
	v_mfma_f32_16x16x32_bf16 v[60:63], v[92:95], v[164:167], v[60:63]
	v_mfma_f32_16x16x32_bf16 v[56:59], v[100:103], v[164:167], v[56:59]
	v_mfma_f32_16x16x32_bf16 v[48:51], v[92:95], v[172:175], v[48:51]
	v_mfma_f32_16x16x32_bf16 v[40:43], v[100:103], v[172:175], v[40:43]
	v_mfma_f32_16x16x32_bf16 v[28:31], v[92:95], v[180:183], v[28:31]
	v_mfma_f32_16x16x32_bf16 v[24:27], v[100:103], v[180:183], v[24:27]
	v_mfma_f32_16x16x32_bf16 v[16:19], v[92:95], v[188:191], v[16:19]
	v_mfma_f32_16x16x32_bf16 v[8:11], v[100:103], v[188:191], v[8:11]
	s_setprio 0
	s_setprio 1
	v_mfma_f32_16x16x32_bf16 v[52:55], v[108:111], v[160:163], v[52:55]
	v_mfma_f32_16x16x32_bf16 v[44:47], v[116:119], v[160:163], v[44:47]
	v_mfma_f32_16x16x32_bf16 v[36:39], v[108:111], v[168:171], v[36:39]
	v_mfma_f32_16x16x32_bf16 v[32:35], v[116:119], v[168:171], v[32:35]
	v_mfma_f32_16x16x32_bf16 v[20:23], v[108:111], v[176:179], v[20:23]
	v_mfma_f32_16x16x32_bf16 v[12:15], v[116:119], v[176:179], v[12:15]
	v_mfma_f32_16x16x32_bf16 v[4:7], v[108:111], v[184:187], v[4:7]
	v_mfma_f32_16x16x32_bf16 v[0:3], v[116:119], v[184:187], v[0:3]
	v_mfma_f32_16x16x32_bf16 v[52:55], v[112:115], v[164:167], v[52:55]
	v_mfma_f32_16x16x32_bf16 v[44:47], v[120:123], v[164:167], v[44:47]
	v_mfma_f32_16x16x32_bf16 v[36:39], v[112:115], v[172:175], v[36:39]
	v_mfma_f32_16x16x32_bf16 v[32:35], v[120:123], v[172:175], v[32:35]
	v_mfma_f32_16x16x32_bf16 v[20:23], v[112:115], v[180:183], v[20:23]
	v_mfma_f32_16x16x32_bf16 v[12:15], v[120:123], v[180:183], v[12:15]
	v_mfma_f32_16x16x32_bf16 v[4:7], v[112:115], v[188:191], v[4:7]
	v_mfma_f32_16x16x32_bf16 v[0:3], v[120:123], v[188:191], v[0:3]
	s_setprio 0
	s_barrier
; #define PG8_STAGE(bufoff, gbase, voff) do { _Pragma("unroll") for (int _i = 0; _i < 2; ++_i) \
;         __builtin_amdgcn_global_load_lds((const unsigned*)((const char*)(gbase) + (voff)[_i]), (PG8_LAS unsigned*)(lds + (bufoff) + ldsw + _i * 8192), 16, 0, 0); } while (0)
; #define PG8_LDA(dst, b, h) do { _Pragma("unroll") for (int m = 0; m < 4; ++m) _Pragma("unroll") for (int k = 0; k < 2; ++k) dst[m][k] = *(const PG8_LAS bf16x8*)(lds + PG8_SA(b, h) + aoff + m * 2048 + k * 1024); } while (0)
; #define PG8_LDB(dst, b, h) do { _Pragma("unroll") for (int n = 0; n < 2; ++n) _Pragma("unroll") for (int k = 0; k < 2; ++k) dst[n][k] = *(const PG8_LAS bf16x8*)(lds + PG8_SB(b, h) + boff + n * 2048 + k * 1024); } while (0)
; #define PG8_MMA(ai, bj, At, Bt) do { __builtin_amdgcn_s_setprio(1); _Pragma("unroll") for (int m = 0; m < 4; ++m) _Pragma("unroll") for (int n = 0; n < 2; ++n) _Pragma("unroll") for (int k = 0; k < 2; ++k) \
;         acc[ai][bj][m][n] = __builtin_amdgcn_mfma_f32_16x16x32_bf16(Bt[n][k], At[m][k], acc[ai][bj][m][n], 0, 0, 0); __builtin_amdgcn_s_setprio(0); } while (0)
; #define PG8_WAIT_V(n) asm volatile("s_waitcnt vmcnt(" #n ")" ::: "memory")
; #define PG8_WAIT_L(n) asm volatile("s_waitcnt lgkmcnt(" #n ")" ::: "memory")
; #define PG8_BAR __builtin_amdgcn_s_barrier()
; #define PG8_SCHED __builtin_amdgcn_sched_barrier(0)
; template <class Epi, class Sched, bool ALIGN_EPI = false, bool SP2 = false>
; __device__ __forceinline__ void gemm_phase(PG8_LAS unsigned char* lds, const Gemm g, const Sched& S, const Epi& E, int wave_s_) {
;     ...
;             PG8_LDB(B0, 1, 0); PG8_LDB(B1, 1, 1); PG8_SCHED; PG8_LDA(At, 1, 0); PG8_STAGE(PG8_SA(0, 1), a2 + hstep, voffA);
;             PG8_WAIT_V(8); PG8_WAIT_L(0); PG8_BAR; PG8_MMA(0, 0, At, B0); PG8_MMA(0, 1, At, B1); PG8_BAR; PG8_SCHED;
	s_add_i32 s58, 0, 0x18000
	s_add_i32 s59, 0, 0x1c000
	v_add_u32_e32 v100, s58, v224
	v_add_u32_e32 v120, s59, v224
	ds_read_b128 v[88:91], v100
	ds_read_b128 v[92:95], v100 offset:1024
	ds_read_b128 v[96:99], v100 offset:2048
	ds_read_b128 v[100:103], v100 offset:3072
	ds_read_b128 v[108:111], v120
	ds_read_b128 v[112:115], v120 offset:1024
	ds_read_b128 v[116:119], v120 offset:2048
	ds_read_b128 v[120:123], v120 offset:3072
	s_add_u32 s10, s34, 0x40000
	s_addc_u32 s11, s35, 0
	s_mov_b32 m0, s42
	v_lshl_add_u64 v[212:213], s[10:11], 0, v[196:197]
	ds_read_b128 v[160:163], v225 offset:32768
	ds_read_b128 v[164:167], v225 offset:33792
	ds_read_b128 v[168:171], v225 offset:34816
	ds_read_b128 v[172:175], v225 offset:35840
	ds_read_b128 v[176:179], v225 offset:36864
	ds_read_b128 v[180:183], v225 offset:37888
	ds_read_b128 v[184:187], v225 offset:38912
	ds_read_b128 v[188:191], v225 offset:39936
	global_load_lds_dwordx4 v[212:213], off
	v_lshl_add_u64 v[212:213], s[10:11], 0, v[192:193]
	s_mov_b32 m0, s43
	s_nop 0
	global_load_lds_dwordx4 v[212:213], off
	s_mov_b32 m0, s40
	s_nop 0
	global_load_lds_dwordx4 v[208:209], off
	s_mov_b32 m0, s41
	s_nop 0
	global_load_lds_dwordx4 v[210:211], off
	s_waitcnt vmcnt(8)
	s_waitcnt lgkmcnt(0)
	s_barrier
	s_setprio 1
	s_waitcnt lgkmcnt(0)
	v_mfma_f32_16x16x32_bf16 v[156:159], v[88:91], v[160:163], v[156:159]
	v_mfma_f32_16x16x32_bf16 v[152:155], v[96:99], v[160:163], v[152:155]
	v_mfma_f32_16x16x32_bf16 v[144:147], v[88:91], v[168:171], v[144:147]
	v_mfma_f32_16x16x32_bf16 v[136:139], v[96:99], v[168:171], v[136:139]
	v_mfma_f32_16x16x32_bf16 v[124:127], v[88:91], v[176:179], v[124:127]
	v_mfma_f32_16x16x32_bf16 v[104:107], v[96:99], v[176:179], v[104:107]
	v_mfma_f32_16x16x32_bf16 v[80:83], v[88:91], v[184:187], v[80:83]
	v_mfma_f32_16x16x32_bf16 v[72:75], v[96:99], v[184:187], v[72:75]
	v_mfma_f32_16x16x32_bf16 v[156:159], v[92:95], v[164:167], v[156:159]
	v_mfma_f32_16x16x32_bf16 v[152:155], v[100:103], v[164:167], v[152:155]
	v_mfma_f32_16x16x32_bf16 v[144:147], v[92:95], v[172:175], v[144:147]
	v_mfma_f32_16x16x32_bf16 v[136:139], v[100:103], v[172:175], v[136:139]
	v_mfma_f32_16x16x32_bf16 v[124:127], v[92:95], v[180:183], v[124:127]
	v_mfma_f32_16x16x32_bf16 v[104:107], v[100:103], v[180:183], v[104:107]
	v_mfma_f32_16x16x32_bf16 v[80:83], v[92:95], v[188:191], v[80:83]
	v_mfma_f32_16x16x32_bf16 v[72:75], v[100:103], v[188:191], v[72:75]
	s_setprio 0
	s_setprio 1
	v_mfma_f32_16x16x32_bf16 v[148:151], v[108:111], v[160:163], v[148:151]
	v_mfma_f32_16x16x32_bf16 v[140:143], v[116:119], v[160:163], v[140:143]
	v_mfma_f32_16x16x32_bf16 v[132:135], v[108:111], v[168:171], v[132:135]
	v_mfma_f32_16x16x32_bf16 v[128:131], v[116:119], v[168:171], v[128:131]
	v_mfma_f32_16x16x32_bf16 v[84:87], v[108:111], v[176:179], v[84:87]
	v_mfma_f32_16x16x32_bf16 v[76:79], v[116:119], v[176:179], v[76:79]
	v_mfma_f32_16x16x32_bf16 v[68:71], v[108:111], v[184:187], v[68:71]
	v_mfma_f32_16x16x32_bf16 v[64:67], v[116:119], v[184:187], v[64:67]
	v_mfma_f32_16x16x32_bf16 v[148:151], v[112:115], v[164:167], v[148:151]
	v_mfma_f32_16x16x32_bf16 v[140:143], v[120:123], v[164:167], v[140:143]
	v_mfma_f32_16x16x32_bf16 v[132:135], v[112:115], v[172:175], v[132:135]
	v_mfma_f32_16x16x32_bf16 v[128:131], v[120:123], v[172:175], v[128:131]
	v_mfma_f32_16x16x32_bf16 v[84:87], v[112:115], v[180:183], v[84:87]
	v_mfma_f32_16x16x32_bf16 v[76:79], v[120:123], v[180:183], v[76:79]
	v_mfma_f32_16x16x32_bf16 v[68:71], v[112:115], v[188:191], v[68:71]
	v_mfma_f32_16x16x32_bf16 v[64:67], v[120:123], v[188:191], v[64:67]
	s_setprio 0
	s_barrier
; #define PG8_STAGE(bufoff, gbase, voff) do { _Pragma("unroll") for (int _i = 0; _i < 2; ++_i) \
;         __builtin_amdgcn_global_load_lds((const unsigned*)((const char*)(gbase) + (voff)[_i]), (PG8_LAS unsigned*)(lds + (bufoff) + ldsw + _i * 8192), 16, 0, 0); } while (0)
; #define PG8_LDA(dst, b, h) do { _Pragma("unroll") for (int m = 0; m < 4; ++m) _Pragma("unroll") for (int k = 0; k < 2; ++k) dst[m][k] = *(const PG8_LAS bf16x8*)(lds + PG8_SA(b, h) + aoff + m * 2048 + k * 1024); } while (0)
; #define PG8_MMA(ai, bj, At, Bt) do { __builtin_amdgcn_s_setprio(1); _Pragma("unroll") for (int m = 0; m < 4; ++m) _Pragma("unroll") for (int n = 0; n < 2; ++n) _Pragma("unroll") for (int k = 0; k < 2; ++k) \
;         acc[ai][bj][m][n] = __builtin_amdgcn_mfma_f32_16x16x32_bf16(Bt[n][k], At[m][k], acc[ai][bj][m][n], 0, 0, 0); __builtin_amdgcn_s_setprio(0); } while (0)
; #define PG8_WAIT_V(n) asm volatile("s_waitcnt vmcnt(" #n ")" ::: "memory")
; #define PG8_WAIT_L(n) asm volatile("s_waitcnt lgkmcnt(" #n ")" ::: "memory")
; #define PG8_BAR __builtin_amdgcn_s_barrier()
; #define PG8_SCHED __builtin_amdgcn_sched_barrier(0)
; template <class Epi, class Sched, bool ALIGN_EPI = false, bool SP2 = false>
; __device__ __forceinline__ void gemm_phase(PG8_LAS unsigned char* lds, const Gemm g, const Sched& S, const Epi& E, int wave_s_) {
;     ...
;         for (int t = 0; t < nt; t += 2) {
;             const bool last = (t == nt - 2);
;             const char* a1 = cA + (size_t)(t + 1) * kstep;
;             const char* a2 = last ? nA : cA + (size_t)(t + 2) * kstep; const char* b2 = last ? nB : cB + (size_t)(t + 2) * kstep;
;     ...
;             PG8_LDA(At, 1, 1); PG8_STAGE(PG8_SB(1, 0), b3, voffB); PG8_STAGE(PG8_SB(1, 1), b3 + hstep, voffB); PG8_STAGE(PG8_SA(1, 0), a3, voffA);
;             PG8_WAIT_V(8); PG8_WAIT_L(0); PG8_BAR; PG8_MMA(1, 0, At, B0); PG8_MMA(1, 1, At, B1); PG8_BAR; PG8_SCHED;
	s_add_i32 s10, s58, s39
	v_lshl_add_u64 v[198:199], v[198:199], 0, s[76:77]
	s_mov_b32 m0, s10
	ds_read_b128 v[160:163], v225 offset:49152
	ds_read_b128 v[164:167], v225 offset:50176
	ds_read_b128 v[168:171], v225 offset:51200
	ds_read_b128 v[172:175], v225 offset:52224
	ds_read_b128 v[176:179], v225 offset:53248
	ds_read_b128 v[180:183], v225 offset:54272
	ds_read_b128 v[184:187], v225 offset:55296
	ds_read_b128 v[188:191], v225 offset:56320
	global_load_lds_dwordx4 v[198:199], off
	s_add_i32 m0, s10, 0x2000
	s_add_u32 s10, s30, 0x40080
	v_lshl_add_u64 v[198:199], v[204:205], 0, s[76:77]
	s_addc_u32 s11, s31, 0
	s_add_i32 s30, s59, s39
	global_load_lds_dwordx4 v[198:199], off
	v_lshl_add_u64 v[198:199], s[10:11], 0, v[196:197]
	s_mov_b32 m0, s30
	s_nop 0
	global_load_lds_dwordx4 v[198:199], off
	v_lshl_add_u64 v[198:199], s[10:11], 0, v[192:193]
	s_add_i32 m0, s30, 0x2000
	s_nop 0
	global_load_lds_dwordx4 v[198:199], off
	v_lshl_add_u64 v[198:199], v[208:209], 0, s[76:77]
	s_mov_b32 m0, s46
	s_nop 0
	global_load_lds_dwordx4 v[198:199], off
	v_lshl_add_u64 v[198:199], v[210:211], 0, s[76:77]
	s_mov_b32 m0, s47
	s_nop 0
	global_load_lds_dwordx4 v[198:199], off
	s_waitcnt vmcnt(6)
	s_waitcnt lgkmcnt(0)
	s_barrier
	s_setprio 1
	s_waitcnt lgkmcnt(0)
	v_mfma_f32_16x16x32_bf16 v[60:63], v[88:91], v[160:163], v[60:63]
	v_mfma_f32_16x16x32_bf16 v[56:59], v[96:99], v[160:163], v[56:59]
	v_mfma_f32_16x16x32_bf16 v[48:51], v[88:91], v[168:171], v[48:51]
	v_mfma_f32_16x16x32_bf16 v[40:43], v[96:99], v[168:171], v[40:43]
	v_mfma_f32_16x16x32_bf16 v[28:31], v[88:91], v[176:179], v[28:31]
	v_mfma_f32_16x16x32_bf16 v[24:27], v[96:99], v[176:179], v[24:27]
	v_mfma_f32_16x16x32_bf16 v[16:19], v[88:91], v[184:187], v[16:19]
	v_mfma_f32_16x16x32_bf16 v[8:11], v[96:99], v[184:187], v[8:11]
	v_mfma_f32_16x16x32_bf16 v[60:63], v[92:95], v[164:167], v[60:63]
	v_mfma_f32_16x16x32_bf16 v[56:59], v[100:103], v[164:167], v[56:59]
	v_mfma_f32_16x16x32_bf16 v[48:51], v[92:95], v[172:175], v[48:51]
	v_mfma_f32_16x16x32_bf16 v[40:43], v[100:103], v[172:175], v[40:43]
	v_mfma_f32_16x16x32_bf16 v[28:31], v[92:95], v[180:183], v[28:31]
	v_mfma_f32_16x16x32_bf16 v[24:27], v[100:103], v[180:183], v[24:27]
	v_mfma_f32_16x16x32_bf16 v[16:19], v[92:95], v[188:191], v[16:19]
	v_mfma_f32_16x16x32_bf16 v[8:11], v[100:103], v[188:191], v[8:11]
	s_setprio 0
	s_setprio 1
	v_mfma_f32_16x16x32_bf16 v[52:55], v[108:111], v[160:163], v[52:55]
	v_mfma_f32_16x16x32_bf16 v[44:47], v[116:119], v[160:163], v[44:47]
	v_mfma_f32_16x16x32_bf16 v[36:39], v[108:111], v[168:171], v[36:39]
	v_mfma_f32_16x16x32_bf16 v[32:35], v[116:119], v[168:171], v[32:35]
	v_mfma_f32_16x16x32_bf16 v[20:23], v[108:111], v[176:179], v[20:23]
	v_mfma_f32_16x16x32_bf16 v[12:15], v[116:119], v[176:179], v[12:15]
	v_mfma_f32_16x16x32_bf16 v[4:7], v[108:111], v[184:187], v[4:7]
	v_mfma_f32_16x16x32_bf16 v[0:3], v[116:119], v[184:187], v[0:3]
	v_mfma_f32_16x16x32_bf16 v[52:55], v[112:115], v[164:167], v[52:55]
	v_mfma_f32_16x16x32_bf16 v[44:47], v[120:123], v[164:167], v[44:47]
	v_mfma_f32_16x16x32_bf16 v[36:39], v[112:115], v[172:175], v[36:39]
	v_mfma_f32_16x16x32_bf16 v[32:35], v[120:123], v[172:175], v[32:35]
	v_mfma_f32_16x16x32_bf16 v[20:23], v[112:115], v[180:183], v[20:23]
	v_mfma_f32_16x16x32_bf16 v[12:15], v[120:123], v[180:183], v[12:15]
	v_mfma_f32_16x16x32_bf16 v[4:7], v[112:115], v[188:191], v[4:7]
	v_mfma_f32_16x16x32_bf16 v[0:3], v[120:123], v[188:191], v[0:3]
	s_setprio 0
	s_barrier
	s_add_u32 s55, s55, 0x100
	s_addc_u32 s56, s56, 0
	s_cmp_ge_u32 s57, s9
	s_mov_b64 s[10:11], s[28:29]
	s_mov_b32 s30, s57
	s_cbranch_scc0 .LBB0_1581

;     __device__ __forceinline__ int nt_of(const Unit& u) const { return (u.pm >> 12) ? ktper : kt; }
; #define PG8_STAGE(bufoff, gbase, voff) do { _Pragma("unroll") for (int _i = 0; _i < 2; ++_i) \
;         __builtin_amdgcn_global_load_lds((const unsigned*)((const char*)(gbase) + (voff)[_i]), (PG8_LAS unsigned*)(lds + (bufoff) + ldsw + _i * 8192), 16, 0, 0); } while (0)
; #define PG8_LDA(dst, b, h) do { _Pragma("unroll") for (int m = 0; m < 4; ++m) _Pragma("unroll") for (int k = 0; k < 2; ++k) dst[m][k] = *(const PG8_LAS bf16x8*)(lds + PG8_SA(b, h) + aoff + m * 2048 + k * 1024); } while (0)
; #define PG8_LDB(dst, b, h) do { _Pragma("unroll") for (int n = 0; n < 2; ++n) _Pragma("unroll") for (int k = 0; k < 2; ++k) dst[n][k] = *(const PG8_LAS bf16x8*)(lds + PG8_SB(b, h) + boff + n * 2048 + k * 1024); } while (0)
; #define PG8_WAIT_V(n) asm volatile("s_waitcnt vmcnt(" #n ")" ::: "memory")
; template <class Epi, class Sched, bool ALIGN_EPI = false, bool SP2 = false>
; __device__ __forceinline__ void gemm_phase(PG8_LAS unsigned char* lds, const Gemm g, const Sched& S, const Epi& E, int wave_s_) {
;     ...
;         const bool has_next = S.next(ui + 1, nxt);
;         const char* nA = has_next ? (const char*)g.A + (size_t)(nxt.pm & 4095) * tstep + (size_t)S.k0_of(nxt) * kstep : cA; const char* nB = has_next ? (const char*)g.Bt + (size_t)nxt.pn * tstep + (size_t)S.k0_of(nxt) * kstep : cB;
;         const int nt = S.nt_of(cur);
;         for (int t = 0; t < nt; t += 2) {
;             const bool last = (t == nt - 2);
;             const char* a1 = cA + (size_t)(t + 1) * kstep;
;             const char* a2 = last ? nA : cA + (size_t)(t + 2) * kstep; const char* b2 = last ? nB : cB + (size_t)(t + 2) * kstep;
;             const char* a3 = a2 + kstep; const char* b3 = b2 + kstep;
;             if (last && has_next) S.a_ready(nxt);
;             if constexpr (SP2) {
;             PG8_LDB(B0, 0, 0); PG8_LDB(B1, 0, 1); PG8_SCHED; PG8_LDA(At, 0, 0); PG8_STAGE(PG8_SA(1, 1), a1 + hstep, voffA);
;             PG8_WAIT_V(8); PG8_WAIT_L(0); PG8_BAR; PG8_MMA(0, 0, At, B0); PG8_MMA(0, 1, At, B1); PG8_BAR; PG8_SCHED;
;             PG8_LDA(At, 0, 1); PG8_STAGE(PG8_SB(0, 0), b2, voffB); PG8_STAGE(PG8_SB(0, 1), b2 + hstep, voffB); PG8_STAGE(PG8_SA(0, 0), a2, voffA);
;             PG8_WAIT_V(8); PG8_WAIT_L(0); PG8_BAR; PG8_MMA(1, 0, At, B0); PG8_MMA(1, 1, At, B1); PG8_BAR; PG8_SCHED;
.LBB0_1819:
	s_add_u32 s15, s18, 0x100
	s_addc_u32 s45, s19, 0
	s_add_u32 s18, s20, 0x40080
	v_mov_b32_e32 v0, 0
	s_addc_u32 s19, s21, 0
	s_mov_b32 s46, -2
	s_add_u32 s20, s18, 0xfffc0080
	s_addc_u32 s21, s19, -1
	s_add_i32 s47, 0, 0x10000
	s_cmp_eq_u32 s46, 12
	s_cselect_b32 s23, s7, s21
	s_cselect_b32 s22, s6, s20
	s_cselect_b32 s21, s17, s45
	s_cselect_b32 s20, s16, s15
	s_add_i32 s50, 0, 0x14000
	v_add_u32_e32 v152, s47, v138
	v_add_u32_e32 v168, s50, v138
	ds_read_b128 v[140:143], v152
	ds_read_b128 v[144:147], v152 offset:1024
	ds_read_b128 v[148:151], v152 offset:2048
	ds_read_b128 v[152:155], v152 offset:3072
	ds_read_b128 v[156:159], v168
	ds_read_b128 v[160:163], v168 offset:1024
	ds_read_b128 v[164:167], v168 offset:2048
	ds_read_b128 v[168:171], v168 offset:3072
	v_lshl_add_u64 v[198:199], s[18:19], 0, v[136:137]
	s_add_i32 m0, s31, 0xc000
	ds_read_b128 v[172:175], v139
	ds_read_b128 v[176:179], v139 offset:1024
	ds_read_b128 v[180:183], v139 offset:2048
	ds_read_b128 v[184:187], v139 offset:3072
	ds_read_b128 v[188:191], v139 offset:4096
	ds_read_b128 v[192:195], v139 offset:5120
	ds_read_b128 v[206:209], v139 offset:6144
	ds_read_b128 v[210:213], v139 offset:7168
	global_load_lds_dwordx4 v[198:199], off
	v_lshl_add_u64 v[198:199], s[18:19], 0, v[134:135]
	s_add_i32 m0, s31, 0xe000
	s_nop 0
	global_load_lds_dwordx4 v[198:199], off
	s_waitcnt vmcnt(8)
	s_waitcnt lgkmcnt(0)
	s_barrier
	s_setprio 1
	s_waitcnt lgkmcnt(0)
	v_mfma_f32_16x16x32_bf16 v[124:127], v[140:143], v[172:175], 0
	v_mfma_f32_16x16x32_bf16 v[116:119], v[148:151], v[172:175], 0
	v_mfma_f32_16x16x32_bf16 v[108:111], v[140:143], v[180:183], 0
	v_mfma_f32_16x16x32_bf16 v[100:103], v[148:151], v[180:183], 0
	v_mfma_f32_16x16x32_bf16 v[92:95], v[140:143], v[188:191], 0
	v_mfma_f32_16x16x32_bf16 v[84:87], v[148:151], v[188:191], 0
	v_mfma_f32_16x16x32_bf16 v[76:79], v[140:143], v[206:209], 0
	v_mfma_f32_16x16x32_bf16 v[68:71], v[148:151], v[206:209], 0
	v_mfma_f32_16x16x32_bf16 v[124:127], v[144:147], v[176:179], v[124:127]
	v_mfma_f32_16x16x32_bf16 v[116:119], v[152:155], v[176:179], v[116:119]
	v_mfma_f32_16x16x32_bf16 v[108:111], v[144:147], v[184:187], v[108:111]
	v_mfma_f32_16x16x32_bf16 v[100:103], v[152:155], v[184:187], v[100:103]
	v_mfma_f32_16x16x32_bf16 v[92:95], v[144:147], v[192:195], v[92:95]
	v_mfma_f32_16x16x32_bf16 v[84:87], v[152:155], v[192:195], v[84:87]
	v_mfma_f32_16x16x32_bf16 v[76:79], v[144:147], v[210:213], v[76:79]
	v_mfma_f32_16x16x32_bf16 v[68:71], v[152:155], v[210:213], v[68:71]
	s_setprio 0
	s_setprio 1
	v_mfma_f32_16x16x32_bf16 v[120:123], v[156:159], v[172:175], 0
	v_mfma_f32_16x16x32_bf16 v[112:115], v[164:167], v[172:175], 0
	v_mfma_f32_16x16x32_bf16 v[104:107], v[156:159], v[180:183], 0
	v_mfma_f32_16x16x32_bf16 v[96:99], v[164:167], v[180:183], 0
	v_mfma_f32_16x16x32_bf16 v[88:91], v[156:159], v[188:191], 0
	v_mfma_f32_16x16x32_bf16 v[80:83], v[164:167], v[188:191], 0
	v_mfma_f32_16x16x32_bf16 v[72:75], v[156:159], v[206:209], 0
	v_mfma_f32_16x16x32_bf16 v[64:67], v[164:167], v[206:209], 0
	v_mfma_f32_16x16x32_bf16 v[120:123], v[160:163], v[176:179], v[120:123]
	v_mfma_f32_16x16x32_bf16 v[112:115], v[168:171], v[176:179], v[112:115]
	v_mfma_f32_16x16x32_bf16 v[104:107], v[160:163], v[184:187], v[104:107]
	v_mfma_f32_16x16x32_bf16 v[96:99], v[168:171], v[184:187], v[96:99]
	v_mfma_f32_16x16x32_bf16 v[88:91], v[160:163], v[192:195], v[88:91]
	v_mfma_f32_16x16x32_bf16 v[80:83], v[168:171], v[192:195], v[80:83]
	v_mfma_f32_16x16x32_bf16 v[72:75], v[160:163], v[210:213], v[72:75]
	v_mfma_f32_16x16x32_bf16 v[64:67], v[168:171], v[210:213], v[64:67]
	s_setprio 0
	s_barrier
	s_add_i32 s47, s47, s30
	v_lshl_add_u64 v[198:199], s[20:21], 0, v[196:197]
	s_mov_b32 m0, s47
	ds_read_b128 v[172:175], v139 offset:16384
	ds_read_b128 v[176:179], v139 offset:17408
	ds_read_b128 v[180:183], v139 offset:18432
	ds_read_b128 v[184:187], v139 offset:19456
	ds_read_b128 v[188:191], v139 offset:20480
	ds_read_b128 v[192:195], v139 offset:21504
	ds_read_b128 v[206:209], v139 offset:22528
	ds_read_b128 v[210:213], v139 offset:23552
	global_load_lds_dwordx4 v[198:199], off
	s_add_i32 m0, s47, 0x2000
	s_add_u32 s48, s20, 0x40000
	v_lshl_add_u64 v[204:205], s[20:21], 0, v[132:133]
	s_addc_u32 s49, s21, 0
	s_add_i32 s47, s50, s30
	global_load_lds_dwordx4 v[204:205], off
	v_lshl_add_u64 v[214:215], s[48:49], 0, v[196:197]
	s_mov_b32 m0, s47
	v_lshl_add_u64 v[216:217], s[22:23], 0, v[130:131]
	global_load_lds_dwordx4 v[214:215], off
	v_lshl_add_u64 v[214:215], s[48:49], 0, v[132:133]
	s_add_i32 m0, s47, 0x2000
	s_nop 0
	global_load_lds_dwordx4 v[214:215], off
	v_lshl_add_u64 v[214:215], s[22:23], 0, v[128:129]
	s_waitcnt vmcnt(6)
	s_waitcnt lgkmcnt(0)
	s_barrier
; #define PG8_STAGE(bufoff, gbase, voff) do { _Pragma("unroll") for (int _i = 0; _i < 2; ++_i) \
;         __builtin_amdgcn_global_load_lds((const unsigned*)((const char*)(gbase) + (voff)[_i]), (PG8_LAS unsigned*)(lds + (bufoff) + ldsw + _i * 8192), 16, 0, 0); } while (0)
; #define PG8_LDA(dst, b, h) do { _Pragma("unroll") for (int m = 0; m < 4; ++m) _Pragma("unroll") for (int k = 0; k < 2; ++k) dst[m][k] = *(const PG8_LAS bf16x8*)(lds + PG8_SA(b, h) + aoff + m * 2048 + k * 1024); } while (0)
; #define PG8_LDB(dst, b, h) do { _Pragma("unroll") for (int n = 0; n < 2; ++n) _Pragma("unroll") for (int k = 0; k < 2; ++k) dst[n][k] = *(const PG8_LAS bf16x8*)(lds + PG8_SB(b, h) + boff + n * 2048 + k * 1024); } while (0)
; #define PG8_MMA(ai, bj, At, Bt) do { __builtin_amdgcn_s_setprio(1); _Pragma("unroll") for (int m = 0; m < 4; ++m) _Pragma("unroll") for (int n = 0; n < 2; ++n) _Pragma("unroll") for (int k = 0; k < 2; ++k) \
;         acc[ai][bj][m][n] = __builtin_amdgcn_mfma_f32_16x16x32_bf16(Bt[n][k], At[m][k], acc[ai][bj][m][n], 0, 0, 0); __builtin_amdgcn_s_setprio(0); } while (0)
; #define PG8_WAIT_V(n) asm volatile("s_waitcnt vmcnt(" #n ")" ::: "memory")
; #define PG8_WAIT_L(n) asm volatile("s_waitcnt lgkmcnt(" #n ")" ::: "memory")
; #define PG8_BAR __builtin_amdgcn_s_barrier()
; #define PG8_SCHED __builtin_amdgcn_sched_barrier(0)
; template <class Epi, class Sched, bool ALIGN_EPI = false, bool SP2 = false>
; __device__ __forceinline__ void gemm_phase(PG8_LAS unsigned char* lds, const Gemm g, const Sched& S, const Epi& E, int wave_s_) {
;     ...
;             PG8_WAIT_V(8); PG8_WAIT_L(0); PG8_BAR; PG8_MMA(1, 0, At, B0); PG8_MMA(1, 1, At, B1); PG8_BAR; PG8_SCHED;
;             PG8_LDB(B0, 1, 0); PG8_LDB(B1, 1, 1); PG8_SCHED; PG8_LDA(At, 1, 0); PG8_STAGE(PG8_SA(0, 1), a2 + hstep, voffA);
;             PG8_WAIT_V(8); PG8_WAIT_L(0); PG8_BAR; PG8_MMA(0, 0, At, B0); PG8_MMA(0, 1, At, B1); PG8_BAR; PG8_SCHED;
	s_setprio 1
	s_waitcnt lgkmcnt(0)
	v_mfma_f32_16x16x32_bf16 v[60:63], v[140:143], v[172:175], 0
	v_mfma_f32_16x16x32_bf16 v[52:55], v[148:151], v[172:175], 0
	v_mfma_f32_16x16x32_bf16 v[44:47], v[140:143], v[180:183], 0
	v_mfma_f32_16x16x32_bf16 v[36:39], v[148:151], v[180:183], 0
	v_mfma_f32_16x16x32_bf16 v[28:31], v[140:143], v[188:191], 0
	v_mfma_f32_16x16x32_bf16 v[20:23], v[148:151], v[188:191], 0
	v_mfma_f32_16x16x32_bf16 v[12:15], v[140:143], v[206:209], 0
	v_mfma_f32_16x16x32_bf16 v[4:7], v[148:151], v[206:209], 0
	v_mfma_f32_16x16x32_bf16 v[60:63], v[144:147], v[176:179], v[60:63]
	v_mfma_f32_16x16x32_bf16 v[52:55], v[152:155], v[176:179], v[52:55]
	v_mfma_f32_16x16x32_bf16 v[44:47], v[144:147], v[184:187], v[44:47]
	v_mfma_f32_16x16x32_bf16 v[36:39], v[152:155], v[184:187], v[36:39]
	v_mfma_f32_16x16x32_bf16 v[28:31], v[144:147], v[192:195], v[28:31]
	v_mfma_f32_16x16x32_bf16 v[20:23], v[152:155], v[192:195], v[20:23]
	v_mfma_f32_16x16x32_bf16 v[12:15], v[144:147], v[210:213], v[12:15]
	v_mfma_f32_16x16x32_bf16 v[4:7], v[152:155], v[210:213], v[4:7]
	s_setprio 0
	s_setprio 1
	v_mfma_f32_16x16x32_bf16 v[56:59], v[156:159], v[172:175], 0
	v_mfma_f32_16x16x32_bf16 v[48:51], v[164:167], v[172:175], 0
	v_mfma_f32_16x16x32_bf16 v[40:43], v[156:159], v[180:183], 0
	v_mfma_f32_16x16x32_bf16 v[32:35], v[164:167], v[180:183], 0
	v_mfma_f32_16x16x32_bf16 v[24:27], v[156:159], v[188:191], 0
	v_mfma_f32_16x16x32_bf16 v[16:19], v[164:167], v[188:191], 0
	v_mfma_f32_16x16x32_bf16 v[8:11], v[156:159], v[206:209], 0
	v_mfma_f32_16x16x32_bf16 v[0:3], v[164:167], v[206:209], 0
	v_mfma_f32_16x16x32_bf16 v[56:59], v[160:163], v[176:179], v[56:59]
	v_mfma_f32_16x16x32_bf16 v[48:51], v[168:171], v[176:179], v[48:51]
	v_mfma_f32_16x16x32_bf16 v[40:43], v[160:163], v[184:187], v[40:43]
	v_mfma_f32_16x16x32_bf16 v[32:35], v[168:171], v[184:187], v[32:35]
	v_mfma_f32_16x16x32_bf16 v[24:27], v[160:163], v[192:195], v[24:27]
	v_mfma_f32_16x16x32_bf16 v[16:19], v[168:171], v[192:195], v[16:19]
	v_mfma_f32_16x16x32_bf16 v[8:11], v[160:163], v[210:213], v[8:11]
	v_mfma_f32_16x16x32_bf16 v[0:3], v[168:171], v[210:213], v[0:3]
	s_setprio 0
	s_barrier
	s_add_i32 s47, 0, 0x18000
	s_add_i32 s48, 0, 0x1c000
	v_add_u32_e32 v152, s47, v138
	v_add_u32_e32 v168, s48, v138
	ds_read_b128 v[140:143], v152
	ds_read_b128 v[144:147], v152 offset:1024
	ds_read_b128 v[148:151], v152 offset:2048
	ds_read_b128 v[152:155], v152 offset:3072
	ds_read_b128 v[156:159], v168
	ds_read_b128 v[160:163], v168 offset:1024
	ds_read_b128 v[164:167], v168 offset:2048
	ds_read_b128 v[168:171], v168 offset:3072
	s_add_u32 s22, s22, 0x40000
	s_addc_u32 s23, s23, 0
	s_mov_b32 m0, s34
	v_lshl_add_u64 v[218:219], s[22:23], 0, v[128:129]
	ds_read_b128 v[172:175], v139 offset:32768
	ds_read_b128 v[176:179], v139 offset:33792
	ds_read_b128 v[180:183], v139 offset:34816
	ds_read_b128 v[184:187], v139 offset:35840
	ds_read_b128 v[188:191], v139 offset:36864
	ds_read_b128 v[192:195], v139 offset:37888
	ds_read_b128 v[206:209], v139 offset:38912
	ds_read_b128 v[210:213], v139 offset:39936
	global_load_lds_dwordx4 v[218:219], off
	v_lshl_add_u64 v[218:219], s[22:23], 0, v[130:131]
	s_mov_b32 m0, s35
	s_nop 0
	global_load_lds_dwordx4 v[218:219], off
	s_mov_b32 m0, s31
	s_nop 0
	global_load_lds_dwordx4 v[214:215], off
	s_mov_b32 m0, s33
	s_nop 0
	global_load_lds_dwordx4 v[216:217], off
	s_waitcnt vmcnt(8)
	s_waitcnt lgkmcnt(0)
	s_barrier
	s_setprio 1
	s_waitcnt lgkmcnt(0)
	v_mfma_f32_16x16x32_bf16 v[124:127], v[140:143], v[172:175], v[124:127]
	v_mfma_f32_16x16x32_bf16 v[116:119], v[148:151], v[172:175], v[116:119]
	v_mfma_f32_16x16x32_bf16 v[108:111], v[140:143], v[180:183], v[108:111]
	v_mfma_f32_16x16x32_bf16 v[100:103], v[148:151], v[180:183], v[100:103]
	v_mfma_f32_16x16x32_bf16 v[92:95], v[140:143], v[188:191], v[92:95]
	v_mfma_f32_16x16x32_bf16 v[84:87], v[148:151], v[188:191], v[84:87]
	v_mfma_f32_16x16x32_bf16 v[76:79], v[140:143], v[206:209], v[76:79]
	v_mfma_f32_16x16x32_bf16 v[68:71], v[148:151], v[206:209], v[68:71]
	v_mfma_f32_16x16x32_bf16 v[124:127], v[144:147], v[176:179], v[124:127]
	v_mfma_f32_16x16x32_bf16 v[116:119], v[152:155], v[176:179], v[116:119]
	v_mfma_f32_16x16x32_bf16 v[108:111], v[144:147], v[184:187], v[108:111]
	v_mfma_f32_16x16x32_bf16 v[100:103], v[152:155], v[184:187], v[100:103]
	v_mfma_f32_16x16x32_bf16 v[92:95], v[144:147], v[192:195], v[92:95]
	v_mfma_f32_16x16x32_bf16 v[84:87], v[152:155], v[192:195], v[84:87]
	v_mfma_f32_16x16x32_bf16 v[76:79], v[144:147], v[210:213], v[76:79]
	v_mfma_f32_16x16x32_bf16 v[68:71], v[152:155], v[210:213], v[68:71]
	s_setprio 0
	s_setprio 1
	v_mfma_f32_16x16x32_bf16 v[120:123], v[156:159], v[172:175], v[120:123]
	v_mfma_f32_16x16x32_bf16 v[112:115], v[164:167], v[172:175], v[112:115]
	v_mfma_f32_16x16x32_bf16 v[104:107], v[156:159], v[180:183], v[104:107]
	v_mfma_f32_16x16x32_bf16 v[96:99], v[164:167], v[180:183], v[96:99]
	v_mfma_f32_16x16x32_bf16 v[88:91], v[156:159], v[188:191], v[88:91]
	v_mfma_f32_16x16x32_bf16 v[80:83], v[164:167], v[188:191], v[80:83]
	v_mfma_f32_16x16x32_bf16 v[72:75], v[156:159], v[206:209], v[72:75]
	v_mfma_f32_16x16x32_bf16 v[64:67], v[164:167], v[206:209], v[64:67]
	v_mfma_f32_16x16x32_bf16 v[120:123], v[160:163], v[176:179], v[120:123]
	v_mfma_f32_16x16x32_bf16 v[112:115], v[168:171], v[176:179], v[112:115]
	v_mfma_f32_16x16x32_bf16 v[104:107], v[160:163], v[184:187], v[104:107]
	v_mfma_f32_16x16x32_bf16 v[96:99], v[168:171], v[184:187], v[96:99]
	v_mfma_f32_16x16x32_bf16 v[88:91], v[160:163], v[192:195], v[88:91]
	v_mfma_f32_16x16x32_bf16 v[80:83], v[168:171], v[192:195], v[80:83]
	v_mfma_f32_16x16x32_bf16 v[72:75], v[160:163], v[210:213], v[72:75]
	v_mfma_f32_16x16x32_bf16 v[64:67], v[168:171], v[210:213], v[64:67]
	s_setprio 0
	s_barrier
; #define PG8_STAGE(bufoff, gbase, voff) do { _Pragma("unroll") for (int _i = 0; _i < 2; ++_i) \
;         __builtin_amdgcn_global_load_lds((const unsigned*)((const char*)(gbase) + (voff)[_i]), (PG8_LAS unsigned*)(lds + (bufoff) + ldsw + _i * 8192), 16, 0, 0); } while (0)
; #define PG8_LDA(dst, b, h) do { _Pragma("unroll") for (int m = 0; m < 4; ++m) _Pragma("unroll") for (int k = 0; k < 2; ++k) dst[m][k] = *(const PG8_LAS bf16x8*)(lds + PG8_SA(b, h) + aoff + m * 2048 + k * 1024); } while (0)
; #define PG8_LDB(dst, b, h) do { _Pragma("unroll") for (int n = 0; n < 2; ++n) _Pragma("unroll") for (int k = 0; k < 2; ++k) dst[n][k] = *(const PG8_LAS bf16x8*)(lds + PG8_SB(b, h) + boff + n * 2048 + k * 1024); } while (0)
; #define PG8_MMA(ai, bj, At, Bt) do { __builtin_amdgcn_s_setprio(1); _Pragma("unroll") for (int m = 0; m < 4; ++m) _Pragma("unroll") for (int n = 0; n < 2; ++n) _Pragma("unroll") for (int k = 0; k < 2; ++k) \
;         acc[ai][bj][m][n] = __builtin_amdgcn_mfma_f32_16x16x32_bf16(Bt[n][k], At[m][k], acc[ai][bj][m][n], 0, 0, 0); __builtin_amdgcn_s_setprio(0); } while (0)
; #define PG8_BAR __builtin_amdgcn_s_barrier()
; template <class Epi, class Sched, bool ALIGN_EPI = false, bool SP2 = false>
; __device__ __forceinline__ void gemm_phase(PG8_LAS unsigned char* lds, const Gemm g, const Sched& S, const Epi& E, int wave_s_) {
;     ...
;             PG8_LDB(B0, 0, 0); PG8_LDB(B1, 0, 1); PG8_SCHED; PG8_LDA(At, 0, 0); PG8_STAGE(PG8_SA(1, 1), a1 + hstep, voffA);
;             PG8_WAIT_V(8); PG8_WAIT_L(0); PG8_BAR; PG8_MMA(0, 0, At, B0); PG8_MMA(0, 1, At, B1); PG8_BAR; PG8_SCHED;
;             PG8_LDA(At, 0, 1); PG8_STAGE(PG8_SB(0, 0), b2, voffB); PG8_STAGE(PG8_SB(0, 1), b2 + hstep, voffB); PG8_STAGE(PG8_SA(0, 0), a2, voffA);
;             PG8_WAIT_V(8); PG8_WAIT_L(0); PG8_BAR; PG8_MMA(1, 0, At, B0); PG8_MMA(1, 1, At, B1); PG8_BAR; PG8_SCHED;
;             PG8_LDB(B0, 1, 0); PG8_LDB(B1, 1, 1); PG8_SCHED; PG8_LDA(At, 1, 0); PG8_STAGE(PG8_SA(0, 1), a2 + hstep, voffA);
;             PG8_WAIT_V(8); PG8_WAIT_L(0); PG8_BAR; PG8_MMA(0, 0, At, B0); PG8_MMA(0, 1, At, B1); PG8_BAR; PG8_SCHED;
;             PG8_LDA(At, 1, 1); PG8_STAGE(PG8_SB(1, 0), b3, voffB); PG8_STAGE(PG8_SB(1, 1), b3 + hstep, voffB); PG8_STAGE(PG8_SA(1, 0), a3, voffA);
;             PG8_WAIT_V(8); PG8_WAIT_L(0); PG8_BAR; PG8_MMA(1, 0, At, B0); PG8_MMA(1, 1, At, B1); PG8_BAR; PG8_SCHED;
	s_add_i32 s22, s47, s30
	v_lshl_add_u64 v[198:199], v[198:199], 0, s[76:77]
	s_mov_b32 m0, s22
	ds_read_b128 v[172:175], v139 offset:49152
	ds_read_b128 v[176:179], v139 offset:50176
	ds_read_b128 v[180:183], v139 offset:51200
	ds_read_b128 v[184:187], v139 offset:52224
	ds_read_b128 v[188:191], v139 offset:53248
	ds_read_b128 v[192:195], v139 offset:54272
	ds_read_b128 v[206:209], v139 offset:55296
	ds_read_b128 v[210:213], v139 offset:56320
	global_load_lds_dwordx4 v[198:199], off
	s_add_i32 m0, s22, 0x2000
	s_add_u32 s20, s20, 0x40080
	v_lshl_add_u64 v[198:199], v[204:205], 0, s[76:77]
	s_addc_u32 s21, s21, 0
	s_add_i32 s22, s48, s30
	global_load_lds_dwordx4 v[198:199], off
	v_lshl_add_u64 v[198:199], s[20:21], 0, v[196:197]
	s_mov_b32 m0, s22
	s_nop 0
	global_load_lds_dwordx4 v[198:199], off
	v_lshl_add_u64 v[198:199], s[20:21], 0, v[132:133]
	s_add_i32 m0, s22, 0x2000
	s_nop 0
	global_load_lds_dwordx4 v[198:199], off
	v_lshl_add_u64 v[198:199], v[214:215], 0, s[76:77]
	s_mov_b32 m0, s38
	s_nop 0
	global_load_lds_dwordx4 v[198:199], off
	v_lshl_add_u64 v[198:199], v[216:217], 0, s[76:77]
	s_mov_b32 m0, s39
	s_nop 0
	global_load_lds_dwordx4 v[198:199], off
	s_waitcnt vmcnt(6)
	s_waitcnt lgkmcnt(0)
	s_barrier
	s_setprio 1
	s_waitcnt lgkmcnt(0)
	v_mfma_f32_16x16x32_bf16 v[60:63], v[140:143], v[172:175], v[60:63]
	v_mfma_f32_16x16x32_bf16 v[52:55], v[148:151], v[172:175], v[52:55]
	v_mfma_f32_16x16x32_bf16 v[44:47], v[140:143], v[180:183], v[44:47]
	v_mfma_f32_16x16x32_bf16 v[36:39], v[148:151], v[180:183], v[36:39]
	v_mfma_f32_16x16x32_bf16 v[28:31], v[140:143], v[188:191], v[28:31]
	v_mfma_f32_16x16x32_bf16 v[20:23], v[148:151], v[188:191], v[20:23]
	v_mfma_f32_16x16x32_bf16 v[12:15], v[140:143], v[206:209], v[12:15]
	v_mfma_f32_16x16x32_bf16 v[4:7], v[148:151], v[206:209], v[4:7]
	v_mfma_f32_16x16x32_bf16 v[60:63], v[144:147], v[176:179], v[60:63]
	v_mfma_f32_16x16x32_bf16 v[52:55], v[152:155], v[176:179], v[52:55]
	v_mfma_f32_16x16x32_bf16 v[44:47], v[144:147], v[184:187], v[44:47]
	v_mfma_f32_16x16x32_bf16 v[36:39], v[152:155], v[184:187], v[36:39]
	v_mfma_f32_16x16x32_bf16 v[28:31], v[144:147], v[192:195], v[28:31]
	v_mfma_f32_16x16x32_bf16 v[20:23], v[152:155], v[192:195], v[20:23]
	v_mfma_f32_16x16x32_bf16 v[12:15], v[144:147], v[210:213], v[12:15]
	v_mfma_f32_16x16x32_bf16 v[4:7], v[152:155], v[210:213], v[4:7]
	s_setprio 0
	s_setprio 1
	v_mfma_f32_16x16x32_bf16 v[56:59], v[156:159], v[172:175], v[56:59]
	v_mfma_f32_16x16x32_bf16 v[48:51], v[164:167], v[172:175], v[48:51]
	v_mfma_f32_16x16x32_bf16 v[40:43], v[156:159], v[180:183], v[40:43]
	v_mfma_f32_16x16x32_bf16 v[32:35], v[164:167], v[180:183], v[32:35]
	v_mfma_f32_16x16x32_bf16 v[24:27], v[156:159], v[188:191], v[24:27]
	v_mfma_f32_16x16x32_bf16 v[16:19], v[164:167], v[188:191], v[16:19]
	v_mfma_f32_16x16x32_bf16 v[8:11], v[156:159], v[206:209], v[8:11]
	v_mfma_f32_16x16x32_bf16 v[0:3], v[164:167], v[206:209], v[0:3]
	v_mfma_f32_16x16x32_bf16 v[56:59], v[160:163], v[176:179], v[56:59]
	v_mfma_f32_16x16x32_bf16 v[48:51], v[168:171], v[176:179], v[48:51]
	v_mfma_f32_16x16x32_bf16 v[40:43], v[160:163], v[184:187], v[40:43]
	v_mfma_f32_16x16x32_bf16 v[32:35], v[168:171], v[184:187], v[32:35]
	v_mfma_f32_16x16x32_bf16 v[24:27], v[160:163], v[192:195], v[24:27]
	v_mfma_f32_16x16x32_bf16 v[16:19], v[168:171], v[192:195], v[16:19]
	v_mfma_f32_16x16x32_bf16 v[8:11], v[160:163], v[210:213], v[8:11]
	v_mfma_f32_16x16x32_bf16 v[0:3], v[168:171], v[210:213], v[0:3]
	s_setprio 0
	s_barrier
	s_add_i32 s46, s46, 2
	s_add_u32 s15, s15, 0x100
	s_addc_u32 s45, s45, 0
	s_add_u32 s18, s18, 0x100
	s_addc_u32 s19, s19, 0
	s_cmp_gt_u32 s46, 13
	s_cbranch_scc0 .LBB0_1820
	s_branch .Lpeel_exit_7
.LBB0_1820:
	s_add_u32 s20, s18, 0xfffc0080
	s_addc_u32 s21, s19, -1
	s_add_i32 s47, 0, 0x10000
	s_cmp_eq_u32 s46, 12
	s_cselect_b32 s23, s7, s21
	s_cselect_b32 s22, s6, s20
	s_cselect_b32 s21, s17, s45
	s_cselect_b32 s20, s16, s15
	s_add_i32 s50, 0, 0x14000
	v_add_u32_e32 v152, s47, v138
	v_add_u32_e32 v168, s50, v138
	ds_read_b128 v[140:143], v152
	ds_read_b128 v[144:147], v152 offset:1024
	ds_read_b128 v[148:151], v152 offset:2048
	ds_read_b128 v[152:155], v152 offset:3072
	ds_read_b128 v[156:159], v168
	ds_read_b128 v[160:163], v168 offset:1024
	ds_read_b128 v[164:167], v168 offset:2048
	ds_read_b128 v[168:171], v168 offset:3072
	v_lshl_add_u64 v[198:199], s[18:19], 0, v[136:137]
	s_add_i32 m0, s31, 0xc000
	ds_read_b128 v[172:175], v139
	ds_read_b128 v[176:179], v139 offset:1024
	ds_read_b128 v[180:183], v139 offset:2048
	ds_read_b128 v[184:187], v139 offset:3072
	ds_read_b128 v[188:191], v139 offset:4096
	ds_read_b128 v[192:195], v139 offset:5120
	ds_read_b128 v[206:209], v139 offset:6144
	ds_read_b128 v[210:213], v139 offset:7168
	global_load_lds_dwordx4 v[198:199], off
	v_lshl_add_u64 v[198:199], s[18:19], 0, v[134:135]
	s_add_i32 m0, s31, 0xe000
	s_nop 0
	global_load_lds_dwordx4 v[198:199], off
	s_waitcnt vmcnt(8)
	s_waitcnt lgkmcnt(0)
	s_barrier
; #define PG8_STAGE(bufoff, gbase, voff) do { _Pragma("unroll") for (int _i = 0; _i < 2; ++_i) \
;         __builtin_amdgcn_global_load_lds((const unsigned*)((const char*)(gbase) + (voff)[_i]), (PG8_LAS unsigned*)(lds + (bufoff) + ldsw + _i * 8192), 16, 0, 0); } while (0)
; #define PG8_LDA(dst, b, h) do { _Pragma("unroll") for (int m = 0; m < 4; ++m) _Pragma("unroll") for (int k = 0; k < 2; ++k) dst[m][k] = *(const PG8_LAS bf16x8*)(lds + PG8_SA(b, h) + aoff + m * 2048 + k * 1024); } while (0)
; #define PG8_MMA(ai, bj, At, Bt) do { __builtin_amdgcn_s_setprio(1); _Pragma("unroll") for (int m = 0; m < 4; ++m) _Pragma("unroll") for (int n = 0; n < 2; ++n) _Pragma("unroll") for (int k = 0; k < 2; ++k) \
;         acc[ai][bj][m][n] = __builtin_amdgcn_mfma_f32_16x16x32_bf16(Bt[n][k], At[m][k], acc[ai][bj][m][n], 0, 0, 0); __builtin_amdgcn_s_setprio(0); } while (0)
; #define PG8_WAIT_V(n) asm volatile("s_waitcnt vmcnt(" #n ")" ::: "memory")
; #define PG8_WAIT_L(n) asm volatile("s_waitcnt lgkmcnt(" #n ")" ::: "memory")
; #define PG8_BAR __builtin_amdgcn_s_barrier()
; #define PG8_SCHED __builtin_amdgcn_sched_barrier(0)
; template <class Epi, class Sched, bool ALIGN_EPI = false, bool SP2 = false>
; __device__ __forceinline__ void gemm_phase(PG8_LAS unsigned char* lds, const Gemm g, const Sched& S, const Epi& E, int wave_s_) {
;     ...
;             PG8_WAIT_V(8); PG8_WAIT_L(0); PG8_BAR; PG8_MMA(0, 0, At, B0); PG8_MMA(0, 1, At, B1); PG8_BAR; PG8_SCHED;
;             PG8_LDA(At, 0, 1); PG8_STAGE(PG8_SB(0, 0), b2, voffB); PG8_STAGE(PG8_SB(0, 1), b2 + hstep, voffB); PG8_STAGE(PG8_SA(0, 0), a2, voffA);
;             PG8_WAIT_V(8); PG8_WAIT_L(0); PG8_BAR; PG8_MMA(1, 0, At, B0); PG8_MMA(1, 1, At, B1); PG8_BAR; PG8_SCHED;
	s_setprio 1
	s_waitcnt lgkmcnt(0)
	v_mfma_f32_16x16x32_bf16 v[124:127], v[140:143], v[172:175], v[124:127]
	v_mfma_f32_16x16x32_bf16 v[116:119], v[148:151], v[172:175], v[116:119]
	v_mfma_f32_16x16x32_bf16 v[108:111], v[140:143], v[180:183], v[108:111]
	v_mfma_f32_16x16x32_bf16 v[100:103], v[148:151], v[180:183], v[100:103]
	v_mfma_f32_16x16x32_bf16 v[92:95], v[140:143], v[188:191], v[92:95]
	v_mfma_f32_16x16x32_bf16 v[84:87], v[148:151], v[188:191], v[84:87]
	v_mfma_f32_16x16x32_bf16 v[76:79], v[140:143], v[206:209], v[76:79]
	v_mfma_f32_16x16x32_bf16 v[68:71], v[148:151], v[206:209], v[68:71]
	v_mfma_f32_16x16x32_bf16 v[124:127], v[144:147], v[176:179], v[124:127]
	v_mfma_f32_16x16x32_bf16 v[116:119], v[152:155], v[176:179], v[116:119]
	v_mfma_f32_16x16x32_bf16 v[108:111], v[144:147], v[184:187], v[108:111]
	v_mfma_f32_16x16x32_bf16 v[100:103], v[152:155], v[184:187], v[100:103]
	v_mfma_f32_16x16x32_bf16 v[92:95], v[144:147], v[192:195], v[92:95]
	v_mfma_f32_16x16x32_bf16 v[84:87], v[152:155], v[192:195], v[84:87]
	v_mfma_f32_16x16x32_bf16 v[76:79], v[144:147], v[210:213], v[76:79]
	v_mfma_f32_16x16x32_bf16 v[68:71], v[152:155], v[210:213], v[68:71]
	s_setprio 0
	s_setprio 1
	v_mfma_f32_16x16x32_bf16 v[120:123], v[156:159], v[172:175], v[120:123]
	v_mfma_f32_16x16x32_bf16 v[112:115], v[164:167], v[172:175], v[112:115]
	v_mfma_f32_16x16x32_bf16 v[104:107], v[156:159], v[180:183], v[104:107]
	v_mfma_f32_16x16x32_bf16 v[96:99], v[164:167], v[180:183], v[96:99]
	v_mfma_f32_16x16x32_bf16 v[88:91], v[156:159], v[188:191], v[88:91]
	v_mfma_f32_16x16x32_bf16 v[80:83], v[164:167], v[188:191], v[80:83]
	v_mfma_f32_16x16x32_bf16 v[72:75], v[156:159], v[206:209], v[72:75]
	v_mfma_f32_16x16x32_bf16 v[64:67], v[164:167], v[206:209], v[64:67]
	v_mfma_f32_16x16x32_bf16 v[120:123], v[160:163], v[176:179], v[120:123]
	v_mfma_f32_16x16x32_bf16 v[112:115], v[168:171], v[176:179], v[112:115]
	v_mfma_f32_16x16x32_bf16 v[104:107], v[160:163], v[184:187], v[104:107]
	v_mfma_f32_16x16x32_bf16 v[96:99], v[168:171], v[184:187], v[96:99]
	v_mfma_f32_16x16x32_bf16 v[88:91], v[160:163], v[192:195], v[88:91]
	v_mfma_f32_16x16x32_bf16 v[80:83], v[168:171], v[192:195], v[80:83]
	v_mfma_f32_16x16x32_bf16 v[72:75], v[160:163], v[210:213], v[72:75]
	v_mfma_f32_16x16x32_bf16 v[64:67], v[168:171], v[210:213], v[64:67]
	s_setprio 0
	s_barrier
	s_add_i32 s47, s47, s30
	v_lshl_add_u64 v[198:199], s[20:21], 0, v[196:197]
	s_mov_b32 m0, s47
	ds_read_b128 v[172:175], v139 offset:16384
	ds_read_b128 v[176:179], v139 offset:17408
	ds_read_b128 v[180:183], v139 offset:18432
	ds_read_b128 v[184:187], v139 offset:19456
	ds_read_b128 v[188:191], v139 offset:20480
	ds_read_b128 v[192:195], v139 offset:21504
	ds_read_b128 v[206:209], v139 offset:22528
	ds_read_b128 v[210:213], v139 offset:23552
	global_load_lds_dwordx4 v[198:199], off
	s_add_i32 m0, s47, 0x2000
	s_add_u32 s48, s20, 0x40000
	v_lshl_add_u64 v[204:205], s[20:21], 0, v[132:133]
	s_addc_u32 s49, s21, 0
	s_add_i32 s47, s50, s30
	global_load_lds_dwordx4 v[204:205], off
	v_lshl_add_u64 v[214:215], s[48:49], 0, v[196:197]
	s_mov_b32 m0, s47
	v_lshl_add_u64 v[216:217], s[22:23], 0, v[130:131]
	global_load_lds_dwordx4 v[214:215], off
	v_lshl_add_u64 v[214:215], s[48:49], 0, v[132:133]
	s_add_i32 m0, s47, 0x2000
	s_nop 0
	global_load_lds_dwordx4 v[214:215], off
	v_lshl_add_u64 v[214:215], s[22:23], 0, v[128:129]
	s_waitcnt vmcnt(6)
	s_waitcnt lgkmcnt(0)
	s_barrier
	s_setprio 1
	s_waitcnt lgkmcnt(0)
	v_mfma_f32_16x16x32_bf16 v[60:63], v[140:143], v[172:175], v[60:63]
	v_mfma_f32_16x16x32_bf16 v[52:55], v[148:151], v[172:175], v[52:55]
	v_mfma_f32_16x16x32_bf16 v[44:47], v[140:143], v[180:183], v[44:47]
	v_mfma_f32_16x16x32_bf16 v[36:39], v[148:151], v[180:183], v[36:39]
	v_mfma_f32_16x16x32_bf16 v[28:31], v[140:143], v[188:191], v[28:31]
	v_mfma_f32_16x16x32_bf16 v[20:23], v[148:151], v[188:191], v[20:23]
	v_mfma_f32_16x16x32_bf16 v[12:15], v[140:143], v[206:209], v[12:15]
	v_mfma_f32_16x16x32_bf16 v[4:7], v[148:151], v[206:209], v[4:7]
	v_mfma_f32_16x16x32_bf16 v[60:63], v[144:147], v[176:179], v[60:63]
	v_mfma_f32_16x16x32_bf16 v[52:55], v[152:155], v[176:179], v[52:55]
	v_mfma_f32_16x16x32_bf16 v[44:47], v[144:147], v[184:187], v[44:47]
	v_mfma_f32_16x16x32_bf16 v[36:39], v[152:155], v[184:187], v[36:39]
	v_mfma_f32_16x16x32_bf16 v[28:31], v[144:147], v[192:195], v[28:31]
	v_mfma_f32_16x16x32_bf16 v[20:23], v[152:155], v[192:195], v[20:23]
	v_mfma_f32_16x16x32_bf16 v[12:15], v[144:147], v[210:213], v[12:15]
	v_mfma_f32_16x16x32_bf16 v[4:7], v[152:155], v[210:213], v[4:7]
	s_setprio 0
	s_setprio 1
	v_mfma_f32_16x16x32_bf16 v[56:59], v[156:159], v[172:175], v[56:59]
	v_mfma_f32_16x16x32_bf16 v[48:51], v[164:167], v[172:175], v[48:51]
	v_mfma_f32_16x16x32_bf16 v[40:43], v[156:159], v[180:183], v[40:43]
	v_mfma_f32_16x16x32_bf16 v[32:35], v[164:167], v[180:183], v[32:35]
	v_mfma_f32_16x16x32_bf16 v[24:27], v[156:159], v[188:191], v[24:27]
	v_mfma_f32_16x16x32_bf16 v[16:19], v[164:167], v[188:191], v[16:19]
	v_mfma_f32_16x16x32_bf16 v[8:11], v[156:159], v[206:209], v[8:11]
	v_mfma_f32_16x16x32_bf16 v[0:3], v[164:167], v[206:209], v[0:3]
	v_mfma_f32_16x16x32_bf16 v[56:59], v[160:163], v[176:179], v[56:59]
	v_mfma_f32_16x16x32_bf16 v[48:51], v[168:171], v[176:179], v[48:51]
	v_mfma_f32_16x16x32_bf16 v[40:43], v[160:163], v[184:187], v[40:43]
	v_mfma_f32_16x16x32_bf16 v[32:35], v[168:171], v[184:187], v[32:35]
	v_mfma_f32_16x16x32_bf16 v[24:27], v[160:163], v[192:195], v[24:27]
	v_mfma_f32_16x16x32_bf16 v[16:19], v[168:171], v[192:195], v[16:19]
	v_mfma_f32_16x16x32_bf16 v[8:11], v[160:163], v[210:213], v[8:11]
	v_mfma_f32_16x16x32_bf16 v[0:3], v[168:171], v[210:213], v[0:3]
	s_setprio 0
	s_barrier
; #define PG8_STAGE(bufoff, gbase, voff) do { _Pragma("unroll") for (int _i = 0; _i < 2; ++_i) \
;         __builtin_amdgcn_global_load_lds((const unsigned*)((const char*)(gbase) + (voff)[_i]), (PG8_LAS unsigned*)(lds + (bufoff) + ldsw + _i * 8192), 16, 0, 0); } while (0)
; #define PG8_LDA(dst, b, h) do { _Pragma("unroll") for (int m = 0; m < 4; ++m) _Pragma("unroll") for (int k = 0; k < 2; ++k) dst[m][k] = *(const PG8_LAS bf16x8*)(lds + PG8_SA(b, h) + aoff + m * 2048 + k * 1024); } while (0)
; #define PG8_LDB(dst, b, h) do { _Pragma("unroll") for (int n = 0; n < 2; ++n) _Pragma("unroll") for (int k = 0; k < 2; ++k) dst[n][k] = *(const PG8_LAS bf16x8*)(lds + PG8_SB(b, h) + boff + n * 2048 + k * 1024); } while (0)
; #define PG8_MMA(ai, bj, At, Bt) do { __builtin_amdgcn_s_setprio(1); _Pragma("unroll") for (int m = 0; m < 4; ++m) _Pragma("unroll") for (int n = 0; n < 2; ++n) _Pragma("unroll") for (int k = 0; k < 2; ++k) \
;         acc[ai][bj][m][n] = __builtin_amdgcn_mfma_f32_16x16x32_bf16(Bt[n][k], At[m][k], acc[ai][bj][m][n], 0, 0, 0); __builtin_amdgcn_s_setprio(0); } while (0)
; #define PG8_WAIT_V(n) asm volatile("s_waitcnt vmcnt(" #n ")" ::: "memory")
; #define PG8_WAIT_L(n) asm volatile("s_waitcnt lgkmcnt(" #n ")" ::: "memory")
; #define PG8_BAR __builtin_amdgcn_s_barrier()
; #define PG8_SCHED __builtin_amdgcn_sched_barrier(0)
; template <class Epi, class Sched, bool ALIGN_EPI = false, bool SP2 = false>
; __device__ __forceinline__ void gemm_phase(PG8_LAS unsigned char* lds, const Gemm g, const Sched& S, const Epi& E, int wave_s_) {
;     ...
;             PG8_LDB(B0, 1, 0); PG8_LDB(B1, 1, 1); PG8_SCHED; PG8_LDA(At, 1, 0); PG8_STAGE(PG8_SA(0, 1), a2 + hstep, voffA);
;             PG8_WAIT_V(8); PG8_WAIT_L(0); PG8_BAR; PG8_MMA(0, 0, At, B0); PG8_MMA(0, 1, At, B1); PG8_BAR; PG8_SCHED;
	s_add_i32 s47, 0, 0x18000
	s_add_i32 s48, 0, 0x1c000
	v_add_u32_e32 v152, s47, v138
	v_add_u32_e32 v168, s48, v138
	ds_read_b128 v[140:143], v152
	ds_read_b128 v[144:147], v152 offset:1024
	ds_read_b128 v[148:151], v152 offset:2048
	ds_read_b128 v[152:155], v152 offset:3072
	ds_read_b128 v[156:159], v168
	ds_read_b128 v[160:163], v168 offset:1024
	ds_read_b128 v[164:167], v168 offset:2048
	ds_read_b128 v[168:171], v168 offset:3072
	s_add_u32 s22, s22, 0x40000
	s_addc_u32 s23, s23, 0
	s_mov_b32 m0, s34
	v_lshl_add_u64 v[218:219], s[22:23], 0, v[128:129]
	ds_read_b128 v[172:175], v139 offset:32768
	ds_read_b128 v[176:179], v139 offset:33792
	ds_read_b128 v[180:183], v139 offset:34816
	ds_read_b128 v[184:187], v139 offset:35840
	ds_read_b128 v[188:191], v139 offset:36864
	ds_read_b128 v[192:195], v139 offset:37888
	ds_read_b128 v[206:209], v139 offset:38912
	ds_read_b128 v[210:213], v139 offset:39936
	global_load_lds_dwordx4 v[218:219], off
	v_lshl_add_u64 v[218:219], s[22:23], 0, v[130:131]
	s_mov_b32 m0, s35
	s_nop 0
	global_load_lds_dwordx4 v[218:219], off
	s_mov_b32 m0, s31
	s_nop 0
	global_load_lds_dwordx4 v[214:215], off
	s_mov_b32 m0, s33
	s_nop 0
	global_load_lds_dwordx4 v[216:217], off
	s_waitcnt vmcnt(8)
	s_waitcnt lgkmcnt(0)
	s_barrier
	s_setprio 1
	s_waitcnt lgkmcnt(0)
	v_mfma_f32_16x16x32_bf16 v[124:127], v[140:143], v[172:175], v[124:127]
	v_mfma_f32_16x16x32_bf16 v[116:119], v[148:151], v[172:175], v[116:119]
	v_mfma_f32_16x16x32_bf16 v[108:111], v[140:143], v[180:183], v[108:111]
	v_mfma_f32_16x16x32_bf16 v[100:103], v[148:151], v[180:183], v[100:103]
	v_mfma_f32_16x16x32_bf16 v[92:95], v[140:143], v[188:191], v[92:95]
	v_mfma_f32_16x16x32_bf16 v[84:87], v[148:151], v[188:191], v[84:87]
	v_mfma_f32_16x16x32_bf16 v[76:79], v[140:143], v[206:209], v[76:79]
	v_mfma_f32_16x16x32_bf16 v[68:71], v[148:151], v[206:209], v[68:71]
	v_mfma_f32_16x16x32_bf16 v[124:127], v[144:147], v[176:179], v[124:127]
	v_mfma_f32_16x16x32_bf16 v[116:119], v[152:155], v[176:179], v[116:119]
	v_mfma_f32_16x16x32_bf16 v[108:111], v[144:147], v[184:187], v[108:111]
	v_mfma_f32_16x16x32_bf16 v[100:103], v[152:155], v[184:187], v[100:103]
	v_mfma_f32_16x16x32_bf16 v[92:95], v[144:147], v[192:195], v[92:95]
	v_mfma_f32_16x16x32_bf16 v[84:87], v[152:155], v[192:195], v[84:87]
	v_mfma_f32_16x16x32_bf16 v[76:79], v[144:147], v[210:213], v[76:79]
	v_mfma_f32_16x16x32_bf16 v[68:71], v[152:155], v[210:213], v[68:71]
	s_setprio 0
	s_setprio 1
	v_mfma_f32_16x16x32_bf16 v[120:123], v[156:159], v[172:175], v[120:123]
	v_mfma_f32_16x16x32_bf16 v[112:115], v[164:167], v[172:175], v[112:115]
	v_mfma_f32_16x16x32_bf16 v[104:107], v[156:159], v[180:183], v[104:107]
	v_mfma_f32_16x16x32_bf16 v[96:99], v[164:167], v[180:183], v[96:99]
	v_mfma_f32_16x16x32_bf16 v[88:91], v[156:159], v[188:191], v[88:91]
	v_mfma_f32_16x16x32_bf16 v[80:83], v[164:167], v[188:191], v[80:83]
	v_mfma_f32_16x16x32_bf16 v[72:75], v[156:159], v[206:209], v[72:75]
	v_mfma_f32_16x16x32_bf16 v[64:67], v[164:167], v[206:209], v[64:67]
	v_mfma_f32_16x16x32_bf16 v[120:123], v[160:163], v[176:179], v[120:123]
	v_mfma_f32_16x16x32_bf16 v[112:115], v[168:171], v[176:179], v[112:115]
	v_mfma_f32_16x16x32_bf16 v[104:107], v[160:163], v[184:187], v[104:107]
	v_mfma_f32_16x16x32_bf16 v[96:99], v[168:171], v[184:187], v[96:99]
	v_mfma_f32_16x16x32_bf16 v[88:91], v[160:163], v[192:195], v[88:91]
	v_mfma_f32_16x16x32_bf16 v[80:83], v[168:171], v[192:195], v[80:83]
	v_mfma_f32_16x16x32_bf16 v[72:75], v[160:163], v[210:213], v[72:75]
	v_mfma_f32_16x16x32_bf16 v[64:67], v[168:171], v[210:213], v[64:67]
	s_setprio 0
	s_barrier
; #define PG8_STAGE(bufoff, gbase, voff) do { _Pragma("unroll") for (int _i = 0; _i < 2; ++_i) \
;         __builtin_amdgcn_global_load_lds((const unsigned*)((const char*)(gbase) + (voff)[_i]), (PG8_LAS unsigned*)(lds + (bufoff) + ldsw + _i * 8192), 16, 0, 0); } while (0)
; #define PG8_LDA(dst, b, h) do { _Pragma("unroll") for (int m = 0; m < 4; ++m) _Pragma("unroll") for (int k = 0; k < 2; ++k) dst[m][k] = *(const PG8_LAS bf16x8*)(lds + PG8_SA(b, h) + aoff + m * 2048 + k * 1024); } while (0)
; #define PG8_MMA(ai, bj, At, Bt) do { __builtin_amdgcn_s_setprio(1); _Pragma("unroll") for (int m = 0; m < 4; ++m) _Pragma("unroll") for (int n = 0; n < 2; ++n) _Pragma("unroll") for (int k = 0; k < 2; ++k) \
;         acc[ai][bj][m][n] = __builtin_amdgcn_mfma_f32_16x16x32_bf16(Bt[n][k], At[m][k], acc[ai][bj][m][n], 0, 0, 0); __builtin_amdgcn_s_setprio(0); } while (0)
; #define PG8_WAIT_V(n) asm volatile("s_waitcnt vmcnt(" #n ")" ::: "memory")
; #define PG8_WAIT_L(n) asm volatile("s_waitcnt lgkmcnt(" #n ")" ::: "memory")
; #define PG8_BAR __builtin_amdgcn_s_barrier()
; #define PG8_SCHED __builtin_amdgcn_sched_barrier(0)
; template <class Epi, class Sched, bool ALIGN_EPI = false, bool SP2 = false>
; __device__ __forceinline__ void gemm_phase(PG8_LAS unsigned char* lds, const Gemm g, const Sched& S, const Epi& E, int wave_s_) {
;     ...
;         for (int t = 0; t < nt; t += 2) {
;             const bool last = (t == nt - 2);
;             const char* a1 = cA + (size_t)(t + 1) * kstep;
;             const char* a2 = last ? nA : cA + (size_t)(t + 2) * kstep; const char* b2 = last ? nB : cB + (size_t)(t + 2) * kstep;
;     ...
;             PG8_LDA(At, 1, 1); PG8_STAGE(PG8_SB(1, 0), b3, voffB); PG8_STAGE(PG8_SB(1, 1), b3 + hstep, voffB); PG8_STAGE(PG8_SA(1, 0), a3, voffA);
;             PG8_WAIT_V(8); PG8_WAIT_L(0); PG8_BAR; PG8_MMA(1, 0, At, B0); PG8_MMA(1, 1, At, B1); PG8_BAR; PG8_SCHED;
	s_add_i32 s22, s47, s30
	v_lshl_add_u64 v[198:199], v[198:199], 0, s[76:77]
	s_mov_b32 m0, s22
	ds_read_b128 v[172:175], v139 offset:49152
	ds_read_b128 v[176:179], v139 offset:50176
	ds_read_b128 v[180:183], v139 offset:51200
	ds_read_b128 v[184:187], v139 offset:52224
	ds_read_b128 v[188:191], v139 offset:53248
	ds_read_b128 v[192:195], v139 offset:54272
	ds_read_b128 v[206:209], v139 offset:55296
	ds_read_b128 v[210:213], v139 offset:56320
	global_load_lds_dwordx4 v[198:199], off
	s_add_i32 m0, s22, 0x2000
	s_add_u32 s20, s20, 0x40080
	v_lshl_add_u64 v[198:199], v[204:205], 0, s[76:77]
	s_addc_u32 s21, s21, 0
	s_add_i32 s22, s48, s30
	global_load_lds_dwordx4 v[198:199], off
	v_lshl_add_u64 v[198:199], s[20:21], 0, v[196:197]
	s_mov_b32 m0, s22
	s_nop 0
	global_load_lds_dwordx4 v[198:199], off
	v_lshl_add_u64 v[198:199], s[20:21], 0, v[132:133]
	s_add_i32 m0, s22, 0x2000
	s_nop 0
	global_load_lds_dwordx4 v[198:199], off
	v_lshl_add_u64 v[198:199], v[214:215], 0, s[76:77]
	s_mov_b32 m0, s38
	s_nop 0
	global_load_lds_dwordx4 v[198:199], off
	v_lshl_add_u64 v[198:199], v[216:217], 0, s[76:77]
	s_mov_b32 m0, s39
	s_nop 0
	global_load_lds_dwordx4 v[198:199], off
	s_waitcnt vmcnt(6)
	s_waitcnt lgkmcnt(0)
	s_barrier
	s_setprio 1
	s_waitcnt lgkmcnt(0)
	v_mfma_f32_16x16x32_bf16 v[60:63], v[140:143], v[172:175], v[60:63]
	v_mfma_f32_16x16x32_bf16 v[52:55], v[148:151], v[172:175], v[52:55]
	v_mfma_f32_16x16x32_bf16 v[44:47], v[140:143], v[180:183], v[44:47]
	v_mfma_f32_16x16x32_bf16 v[36:39], v[148:151], v[180:183], v[36:39]
	v_mfma_f32_16x16x32_bf16 v[28:31], v[140:143], v[188:191], v[28:31]
	v_mfma_f32_16x16x32_bf16 v[20:23], v[148:151], v[188:191], v[20:23]
	v_mfma_f32_16x16x32_bf16 v[12:15], v[140:143], v[206:209], v[12:15]
	v_mfma_f32_16x16x32_bf16 v[4:7], v[148:151], v[206:209], v[4:7]
	v_mfma_f32_16x16x32_bf16 v[60:63], v[144:147], v[176:179], v[60:63]
	v_mfma_f32_16x16x32_bf16 v[52:55], v[152:155], v[176:179], v[52:55]
	v_mfma_f32_16x16x32_bf16 v[44:47], v[144:147], v[184:187], v[44:47]
	v_mfma_f32_16x16x32_bf16 v[36:39], v[152:155], v[184:187], v[36:39]
	v_mfma_f32_16x16x32_bf16 v[28:31], v[144:147], v[192:195], v[28:31]
	v_mfma_f32_16x16x32_bf16 v[20:23], v[152:155], v[192:195], v[20:23]
	v_mfma_f32_16x16x32_bf16 v[12:15], v[144:147], v[210:213], v[12:15]
	v_mfma_f32_16x16x32_bf16 v[4:7], v[152:155], v[210:213], v[4:7]
	s_setprio 0
	s_setprio 1
	v_mfma_f32_16x16x32_bf16 v[56:59], v[156:159], v[172:175], v[56:59]
	v_mfma_f32_16x16x32_bf16 v[48:51], v[164:167], v[172:175], v[48:51]
	v_mfma_f32_16x16x32_bf16 v[40:43], v[156:159], v[180:183], v[40:43]
	v_mfma_f32_16x16x32_bf16 v[32:35], v[164:167], v[180:183], v[32:35]
	v_mfma_f32_16x16x32_bf16 v[24:27], v[156:159], v[188:191], v[24:27]
	v_mfma_f32_16x16x32_bf16 v[16:19], v[164:167], v[188:191], v[16:19]
	v_mfma_f32_16x16x32_bf16 v[8:11], v[156:159], v[206:209], v[8:11]
	v_mfma_f32_16x16x32_bf16 v[0:3], v[164:167], v[206:209], v[0:3]
	v_mfma_f32_16x16x32_bf16 v[56:59], v[160:163], v[176:179], v[56:59]
	v_mfma_f32_16x16x32_bf16 v[48:51], v[168:171], v[176:179], v[48:51]
	v_mfma_f32_16x16x32_bf16 v[40:43], v[160:163], v[184:187], v[40:43]
	v_mfma_f32_16x16x32_bf16 v[32:35], v[168:171], v[184:187], v[32:35]
	v_mfma_f32_16x16x32_bf16 v[24:27], v[160:163], v[192:195], v[24:27]
	v_mfma_f32_16x16x32_bf16 v[16:19], v[168:171], v[192:195], v[16:19]
	v_mfma_f32_16x16x32_bf16 v[8:11], v[160:163], v[210:213], v[8:11]
	v_mfma_f32_16x16x32_bf16 v[0:3], v[168:171], v[210:213], v[0:3]
	s_setprio 0
	s_barrier
	s_add_i32 s46, s46, 2
	s_add_u32 s15, s15, 0x100
	s_addc_u32 s45, s45, 0
	s_add_u32 s18, s18, 0x100
	s_addc_u32 s19, s19, 0
	s_cmp_gt_u32 s46, 13
	s_cbranch_scc0 .LBB0_1820

;     __device__ __forceinline__ int nt_of(const Unit& u) const { return (u.pm >> 12) ? ktper : kt; }
; #define PG8_STAGE(bufoff, gbase, voff) do { _Pragma("unroll") for (int _i = 0; _i < 2; ++_i) \
;         __builtin_amdgcn_global_load_lds((const unsigned*)((const char*)(gbase) + (voff)[_i]), (PG8_LAS unsigned*)(lds + (bufoff) + ldsw + _i * 8192), 16, 0, 0); } while (0)
; #define PG8_LDA(dst, b, h) do { _Pragma("unroll") for (int m = 0; m < 4; ++m) _Pragma("unroll") for (int k = 0; k < 2; ++k) dst[m][k] = *(const PG8_LAS bf16x8*)(lds + PG8_SA(b, h) + aoff + m * 2048 + k * 1024); } while (0)
; #define PG8_LDB(dst, b, h) do { _Pragma("unroll") for (int n = 0; n < 2; ++n) _Pragma("unroll") for (int k = 0; k < 2; ++k) dst[n][k] = *(const PG8_LAS bf16x8*)(lds + PG8_SB(b, h) + boff + n * 2048 + k * 1024); } while (0)
; #define PG8_WAIT_V(n) asm volatile("s_waitcnt vmcnt(" #n ")" ::: "memory")
; template <class Epi, class Sched, bool ALIGN_EPI = false, bool SP2 = false>
; __device__ __forceinline__ void gemm_phase(PG8_LAS unsigned char* lds, const Gemm g, const Sched& S, const Epi& E, int wave_s_) {
;     ...
;         const bool has_next = S.next(ui + 1, nxt);
;         const char* nA = has_next ? (const char*)g.A + (size_t)(nxt.pm & 4095) * tstep + (size_t)S.k0_of(nxt) * kstep : cA; const char* nB = has_next ? (const char*)g.Bt + (size_t)nxt.pn * tstep + (size_t)S.k0_of(nxt) * kstep : cB;
;         const int nt = S.nt_of(cur);
;         for (int t = 0; t < nt; t += 2) {
;             const bool last = (t == nt - 2);
;             const char* a1 = cA + (size_t)(t + 1) * kstep;
;             const char* a2 = last ? nA : cA + (size_t)(t + 2) * kstep; const char* b2 = last ? nB : cB + (size_t)(t + 2) * kstep;
;             const char* a3 = a2 + kstep; const char* b3 = b2 + kstep;
;             if (last && has_next) S.a_ready(nxt);
;             if constexpr (SP2) {
;             PG8_LDB(B0, 0, 0); PG8_LDB(B1, 0, 1); PG8_SCHED; PG8_LDA(At, 0, 0); PG8_STAGE(PG8_SA(1, 1), a1 + hstep, voffA);
;             PG8_WAIT_V(8); PG8_WAIT_L(0); PG8_BAR; PG8_MMA(0, 0, At, B0); PG8_MMA(0, 1, At, B1); PG8_BAR; PG8_SCHED;
;             PG8_LDA(At, 0, 1); PG8_STAGE(PG8_SB(0, 0), b2, voffB); PG8_STAGE(PG8_SB(0, 1), b2 + hstep, voffB); PG8_STAGE(PG8_SA(0, 0), a2, voffA);
;             PG8_WAIT_V(8); PG8_WAIT_L(0); PG8_BAR; PG8_MMA(1, 0, At, B0); PG8_MMA(1, 1, At, B1); PG8_BAR; PG8_SCHED;
.LBB0_1907:
	s_cmpk_gt_u32 s51, 0xfff
	s_cselect_b64 s[24:25], -1, 0
	s_cmpk_lt_u32 s51, 0x1000
	s_cselect_b64 s[6:7], -1, 0
	s_and_b64 s[26:27], s[6:7], exec
	s_cselect_b32 s53, 44, 4
	s_add_i32 s54, s53, -2
	s_add_u32 s55, s10, 0x100
	v_mov_b32_e32 v0, 0
	s_addc_u32 s56, s11, 0
	s_mov_b32 s26, 0
	s_add_i32 s57, s26, 2
	s_add_u32 s10, s8, 0x100
	s_addc_u32 s11, s9, 0
	s_add_i32 s58, 0, 0x10000
	s_cmp_eq_u32 s54, s26
	s_cselect_b32 s29, s21, s11
	s_cselect_b32 s28, s20, s10
	s_cselect_b32 s27, s23, s56
	s_cselect_b32 s26, s22, s55
	s_add_i32 s59, 0, 0x14000
	v_add_u32_e32 v100, s58, v224
	v_add_u32_e32 v120, s59, v224
	ds_read_b128 v[76:79], v100
	ds_read_b128 v[84:87], v100 offset:1024
	ds_read_b128 v[92:95], v100 offset:2048
	ds_read_b128 v[100:103], v100 offset:3072
	ds_read_b128 v[104:107], v120
	ds_read_b128 v[108:111], v120 offset:1024
	ds_read_b128 v[112:115], v120 offset:2048
	ds_read_b128 v[120:123], v120 offset:3072
	v_lshl_add_u64 v[198:199], s[8:9], 0, v[206:207]
	s_add_i32 m0, s36, 0xc000
	ds_read_b128 v[160:163], v225
	ds_read_b128 v[164:167], v225 offset:1024
	ds_read_b128 v[168:171], v225 offset:2048
	ds_read_b128 v[172:175], v225 offset:3072
	ds_read_b128 v[176:179], v225 offset:4096
	ds_read_b128 v[180:183], v225 offset:5120
	ds_read_b128 v[184:187], v225 offset:6144
	ds_read_b128 v[188:191], v225 offset:7168
	global_load_lds_dwordx4 v[198:199], off
	v_lshl_add_u64 v[198:199], s[8:9], 0, v[194:195]
	s_add_i32 m0, s36, 0xe000
	s_nop 0
	global_load_lds_dwordx4 v[198:199], off
	s_waitcnt vmcnt(8)
	s_waitcnt lgkmcnt(0)
	s_barrier
	s_setprio 1
	s_waitcnt lgkmcnt(0)
	v_mfma_f32_16x16x32_bf16 v[156:159], v[76:79], v[160:163], 0
	v_mfma_f32_16x16x32_bf16 v[152:155], v[92:95], v[160:163], 0
	v_mfma_f32_16x16x32_bf16 v[144:147], v[76:79], v[168:171], 0
	v_mfma_f32_16x16x32_bf16 v[136:139], v[92:95], v[168:171], 0
	v_mfma_f32_16x16x32_bf16 v[124:127], v[76:79], v[176:179], 0
	v_mfma_f32_16x16x32_bf16 v[116:119], v[92:95], v[176:179], 0
	v_mfma_f32_16x16x32_bf16 v[88:91], v[76:79], v[184:187], 0
	v_mfma_f32_16x16x32_bf16 v[72:75], v[92:95], v[184:187], 0
	v_mfma_f32_16x16x32_bf16 v[156:159], v[84:87], v[164:167], v[156:159]
	v_mfma_f32_16x16x32_bf16 v[152:155], v[100:103], v[164:167], v[152:155]
	v_mfma_f32_16x16x32_bf16 v[144:147], v[84:87], v[172:175], v[144:147]
	v_mfma_f32_16x16x32_bf16 v[136:139], v[100:103], v[172:175], v[136:139]
	v_mfma_f32_16x16x32_bf16 v[124:127], v[84:87], v[180:183], v[124:127]
	v_mfma_f32_16x16x32_bf16 v[116:119], v[100:103], v[180:183], v[116:119]
	v_mfma_f32_16x16x32_bf16 v[88:91], v[84:87], v[188:191], v[88:91]
	v_mfma_f32_16x16x32_bf16 v[72:75], v[100:103], v[188:191], v[72:75]
	s_setprio 0
	s_setprio 1
	v_mfma_f32_16x16x32_bf16 v[148:151], v[104:107], v[160:163], 0
	v_mfma_f32_16x16x32_bf16 v[140:143], v[112:115], v[160:163], 0
	v_mfma_f32_16x16x32_bf16 v[132:135], v[104:107], v[168:171], 0
	v_mfma_f32_16x16x32_bf16 v[128:131], v[112:115], v[168:171], 0
	v_mfma_f32_16x16x32_bf16 v[96:99], v[104:107], v[176:179], 0
	v_mfma_f32_16x16x32_bf16 v[80:83], v[112:115], v[176:179], 0
	v_mfma_f32_16x16x32_bf16 v[68:71], v[104:107], v[184:187], 0
	v_mfma_f32_16x16x32_bf16 v[64:67], v[112:115], v[184:187], 0
	v_mfma_f32_16x16x32_bf16 v[148:151], v[108:111], v[164:167], v[148:151]
	v_mfma_f32_16x16x32_bf16 v[140:143], v[120:123], v[164:167], v[140:143]
	v_mfma_f32_16x16x32_bf16 v[132:135], v[108:111], v[172:175], v[132:135]
	v_mfma_f32_16x16x32_bf16 v[128:131], v[120:123], v[172:175], v[128:131]
	v_mfma_f32_16x16x32_bf16 v[96:99], v[108:111], v[180:183], v[96:99]
	v_mfma_f32_16x16x32_bf16 v[80:83], v[120:123], v[180:183], v[80:83]
	v_mfma_f32_16x16x32_bf16 v[68:71], v[108:111], v[188:191], v[68:71]
	v_mfma_f32_16x16x32_bf16 v[64:67], v[120:123], v[188:191], v[64:67]
	s_setprio 0
	s_barrier
	s_add_i32 s8, s58, s35
	v_lshl_add_u64 v[198:199], s[26:27], 0, v[196:197]
	s_mov_b32 m0, s8
	ds_read_b128 v[160:163], v225 offset:16384
	ds_read_b128 v[164:167], v225 offset:17408
	ds_read_b128 v[168:171], v225 offset:18432
	ds_read_b128 v[172:175], v225 offset:19456
	ds_read_b128 v[176:179], v225 offset:20480
	ds_read_b128 v[180:183], v225 offset:21504
	ds_read_b128 v[184:187], v225 offset:22528
	ds_read_b128 v[188:191], v225 offset:23552
	global_load_lds_dwordx4 v[198:199], off
	s_add_i32 m0, s8, 0x2000
	s_add_u32 s8, s26, 0xb0000
	v_lshl_add_u64 v[204:205], s[26:27], 0, v[192:193]
	s_addc_u32 s9, s27, 0
	s_add_i32 s58, s59, s35
	global_load_lds_dwordx4 v[204:205], off
	v_lshl_add_u64 v[208:209], s[8:9], 0, v[196:197]
	s_mov_b32 m0, s58
	v_lshl_add_u64 v[210:211], s[28:29], 0, v[192:193]
	global_load_lds_dwordx4 v[208:209], off
	v_lshl_add_u64 v[208:209], s[8:9], 0, v[192:193]
	s_add_i32 m0, s58, 0x2000
	s_nop 0
	global_load_lds_dwordx4 v[208:209], off
	v_lshl_add_u64 v[208:209], s[28:29], 0, v[196:197]
	s_waitcnt vmcnt(6)
	s_waitcnt lgkmcnt(0)
	s_barrier
; #define PG8_STAGE(bufoff, gbase, voff) do { _Pragma("unroll") for (int _i = 0; _i < 2; ++_i) \
;         __builtin_amdgcn_global_load_lds((const unsigned*)((const char*)(gbase) + (voff)[_i]), (PG8_LAS unsigned*)(lds + (bufoff) + ldsw + _i * 8192), 16, 0, 0); } while (0)
; #define PG8_LDA(dst, b, h) do { _Pragma("unroll") for (int m = 0; m < 4; ++m) _Pragma("unroll") for (int k = 0; k < 2; ++k) dst[m][k] = *(const PG8_LAS bf16x8*)(lds + PG8_SA(b, h) + aoff + m * 2048 + k * 1024); } while (0)
; #define PG8_LDB(dst, b, h) do { _Pragma("unroll") for (int n = 0; n < 2; ++n) _Pragma("unroll") for (int k = 0; k < 2; ++k) dst[n][k] = *(const PG8_LAS bf16x8*)(lds + PG8_SB(b, h) + boff + n * 2048 + k * 1024); } while (0)
; #define PG8_MMA(ai, bj, At, Bt) do { __builtin_amdgcn_s_setprio(1); _Pragma("unroll") for (int m = 0; m < 4; ++m) _Pragma("unroll") for (int n = 0; n < 2; ++n) _Pragma("unroll") for (int k = 0; k < 2; ++k) \
;         acc[ai][bj][m][n] = __builtin_amdgcn_mfma_f32_16x16x32_bf16(Bt[n][k], At[m][k], acc[ai][bj][m][n], 0, 0, 0); __builtin_amdgcn_s_setprio(0); } while (0)
; #define PG8_WAIT_V(n) asm volatile("s_waitcnt vmcnt(" #n ")" ::: "memory")
; #define PG8_WAIT_L(n) asm volatile("s_waitcnt lgkmcnt(" #n ")" ::: "memory")
; #define PG8_BAR __builtin_amdgcn_s_barrier()
; #define PG8_SCHED __builtin_amdgcn_sched_barrier(0)
; template <class Epi, class Sched, bool ALIGN_EPI = false, bool SP2 = false>
; __device__ __forceinline__ void gemm_phase(PG8_LAS unsigned char* lds, const Gemm g, const Sched& S, const Epi& E, int wave_s_) {
;     ...
;             PG8_WAIT_V(8); PG8_WAIT_L(0); PG8_BAR; PG8_MMA(1, 0, At, B0); PG8_MMA(1, 1, At, B1); PG8_BAR; PG8_SCHED;
;             PG8_LDB(B0, 1, 0); PG8_LDB(B1, 1, 1); PG8_SCHED; PG8_LDA(At, 1, 0); PG8_STAGE(PG8_SA(0, 1), a2 + hstep, voffA);
;             PG8_WAIT_V(8); PG8_WAIT_L(0); PG8_BAR; PG8_MMA(0, 0, At, B0); PG8_MMA(0, 1, At, B1); PG8_BAR; PG8_SCHED;
	s_setprio 1
	s_waitcnt lgkmcnt(0)
	v_mfma_f32_16x16x32_bf16 v[60:63], v[76:79], v[160:163], 0
	v_mfma_f32_16x16x32_bf16 v[56:59], v[92:95], v[160:163], 0
	v_mfma_f32_16x16x32_bf16 v[48:51], v[76:79], v[168:171], 0
	v_mfma_f32_16x16x32_bf16 v[40:43], v[92:95], v[168:171], 0
	v_mfma_f32_16x16x32_bf16 v[28:31], v[76:79], v[176:179], 0
	v_mfma_f32_16x16x32_bf16 v[24:27], v[92:95], v[176:179], 0
	v_mfma_f32_16x16x32_bf16 v[16:19], v[76:79], v[184:187], 0
	v_mfma_f32_16x16x32_bf16 v[8:11], v[92:95], v[184:187], 0
	v_mfma_f32_16x16x32_bf16 v[60:63], v[84:87], v[164:167], v[60:63]
	v_mfma_f32_16x16x32_bf16 v[56:59], v[100:103], v[164:167], v[56:59]
	v_mfma_f32_16x16x32_bf16 v[48:51], v[84:87], v[172:175], v[48:51]
	v_mfma_f32_16x16x32_bf16 v[40:43], v[100:103], v[172:175], v[40:43]
	v_mfma_f32_16x16x32_bf16 v[28:31], v[84:87], v[180:183], v[28:31]
	v_mfma_f32_16x16x32_bf16 v[24:27], v[100:103], v[180:183], v[24:27]
	v_mfma_f32_16x16x32_bf16 v[16:19], v[84:87], v[188:191], v[16:19]
	v_mfma_f32_16x16x32_bf16 v[8:11], v[100:103], v[188:191], v[8:11]
	s_setprio 0
	s_setprio 1
	v_mfma_f32_16x16x32_bf16 v[52:55], v[104:107], v[160:163], 0
	v_mfma_f32_16x16x32_bf16 v[44:47], v[112:115], v[160:163], 0
	v_mfma_f32_16x16x32_bf16 v[36:39], v[104:107], v[168:171], 0
	v_mfma_f32_16x16x32_bf16 v[32:35], v[112:115], v[168:171], 0
	v_mfma_f32_16x16x32_bf16 v[20:23], v[104:107], v[176:179], 0
	v_mfma_f32_16x16x32_bf16 v[12:15], v[112:115], v[176:179], 0
	v_mfma_f32_16x16x32_bf16 v[4:7], v[104:107], v[184:187], 0
	v_mfma_f32_16x16x32_bf16 v[0:3], v[112:115], v[184:187], 0
	v_mfma_f32_16x16x32_bf16 v[52:55], v[108:111], v[164:167], v[52:55]
	v_mfma_f32_16x16x32_bf16 v[44:47], v[120:123], v[164:167], v[44:47]
	v_mfma_f32_16x16x32_bf16 v[36:39], v[108:111], v[172:175], v[36:39]
	v_mfma_f32_16x16x32_bf16 v[32:35], v[120:123], v[172:175], v[32:35]
	v_mfma_f32_16x16x32_bf16 v[20:23], v[108:111], v[180:183], v[20:23]
	v_mfma_f32_16x16x32_bf16 v[12:15], v[120:123], v[180:183], v[12:15]
	v_mfma_f32_16x16x32_bf16 v[4:7], v[108:111], v[188:191], v[4:7]
	v_mfma_f32_16x16x32_bf16 v[0:3], v[120:123], v[188:191], v[0:3]
	s_setprio 0
	s_barrier
	s_add_i32 s58, 0, 0x18000
	s_add_i32 s59, 0, 0x1c000
	v_add_u32_e32 v100, s58, v224
	v_add_u32_e32 v120, s59, v224
	ds_read_b128 v[76:79], v100
	ds_read_b128 v[84:87], v100 offset:1024
	ds_read_b128 v[92:95], v100 offset:2048
	ds_read_b128 v[100:103], v100 offset:3072
	ds_read_b128 v[104:107], v120
	ds_read_b128 v[108:111], v120 offset:1024
	ds_read_b128 v[112:115], v120 offset:2048
	ds_read_b128 v[120:123], v120 offset:3072
	s_add_u32 s8, s28, 0xb0000
	s_addc_u32 s9, s29, 0
	s_mov_b32 m0, s38
	v_lshl_add_u64 v[212:213], s[8:9], 0, v[196:197]
	ds_read_b128 v[160:163], v225 offset:32768
	ds_read_b128 v[164:167], v225 offset:33792
	ds_read_b128 v[168:171], v225 offset:34816
	ds_read_b128 v[172:175], v225 offset:35840
	ds_read_b128 v[176:179], v225 offset:36864
	ds_read_b128 v[180:183], v225 offset:37888
	ds_read_b128 v[184:187], v225 offset:38912
	ds_read_b128 v[188:191], v225 offset:39936
	global_load_lds_dwordx4 v[212:213], off
	v_lshl_add_u64 v[212:213], s[8:9], 0, v[192:193]
	s_mov_b32 m0, s39
	s_nop 0
	global_load_lds_dwordx4 v[212:213], off
	s_mov_b32 m0, s36
	s_nop 0
	global_load_lds_dwordx4 v[208:209], off
	s_mov_b32 m0, s37
	s_nop 0
	global_load_lds_dwordx4 v[210:211], off
	s_waitcnt vmcnt(8)
	s_waitcnt lgkmcnt(0)
	s_barrier
	s_setprio 1
	s_waitcnt lgkmcnt(0)
	v_mfma_f32_16x16x32_bf16 v[156:159], v[76:79], v[160:163], v[156:159]
	v_mfma_f32_16x16x32_bf16 v[152:155], v[92:95], v[160:163], v[152:155]
	v_mfma_f32_16x16x32_bf16 v[144:147], v[76:79], v[168:171], v[144:147]
	v_mfma_f32_16x16x32_bf16 v[136:139], v[92:95], v[168:171], v[136:139]
	v_mfma_f32_16x16x32_bf16 v[124:127], v[76:79], v[176:179], v[124:127]
	v_mfma_f32_16x16x32_bf16 v[116:119], v[92:95], v[176:179], v[116:119]
	v_mfma_f32_16x16x32_bf16 v[88:91], v[76:79], v[184:187], v[88:91]
	v_mfma_f32_16x16x32_bf16 v[72:75], v[92:95], v[184:187], v[72:75]
	v_mfma_f32_16x16x32_bf16 v[156:159], v[84:87], v[164:167], v[156:159]
	v_mfma_f32_16x16x32_bf16 v[152:155], v[100:103], v[164:167], v[152:155]
	v_mfma_f32_16x16x32_bf16 v[144:147], v[84:87], v[172:175], v[144:147]
	v_mfma_f32_16x16x32_bf16 v[136:139], v[100:103], v[172:175], v[136:139]
	v_mfma_f32_16x16x32_bf16 v[124:127], v[84:87], v[180:183], v[124:127]
	v_mfma_f32_16x16x32_bf16 v[116:119], v[100:103], v[180:183], v[116:119]
	v_mfma_f32_16x16x32_bf16 v[88:91], v[84:87], v[188:191], v[88:91]
	v_mfma_f32_16x16x32_bf16 v[72:75], v[100:103], v[188:191], v[72:75]
	s_setprio 0
	s_setprio 1
	v_mfma_f32_16x16x32_bf16 v[148:151], v[104:107], v[160:163], v[148:151]
	v_mfma_f32_16x16x32_bf16 v[140:143], v[112:115], v[160:163], v[140:143]
	v_mfma_f32_16x16x32_bf16 v[132:135], v[104:107], v[168:171], v[132:135]
	v_mfma_f32_16x16x32_bf16 v[128:131], v[112:115], v[168:171], v[128:131]
	v_mfma_f32_16x16x32_bf16 v[96:99], v[104:107], v[176:179], v[96:99]
	v_mfma_f32_16x16x32_bf16 v[80:83], v[112:115], v[176:179], v[80:83]
	v_mfma_f32_16x16x32_bf16 v[68:71], v[104:107], v[184:187], v[68:71]
	v_mfma_f32_16x16x32_bf16 v[64:67], v[112:115], v[184:187], v[64:67]
	v_mfma_f32_16x16x32_bf16 v[148:151], v[108:111], v[164:167], v[148:151]
	v_mfma_f32_16x16x32_bf16 v[140:143], v[120:123], v[164:167], v[140:143]
	v_mfma_f32_16x16x32_bf16 v[132:135], v[108:111], v[172:175], v[132:135]
	v_mfma_f32_16x16x32_bf16 v[128:131], v[120:123], v[172:175], v[128:131]
	v_mfma_f32_16x16x32_bf16 v[96:99], v[108:111], v[180:183], v[96:99]
	v_mfma_f32_16x16x32_bf16 v[80:83], v[120:123], v[180:183], v[80:83]
	v_mfma_f32_16x16x32_bf16 v[68:71], v[108:111], v[188:191], v[68:71]
	v_mfma_f32_16x16x32_bf16 v[64:67], v[120:123], v[188:191], v[64:67]
	s_setprio 0
	s_barrier
; #define PG8_STAGE(bufoff, gbase, voff) do { _Pragma("unroll") for (int _i = 0; _i < 2; ++_i) \
;         __builtin_amdgcn_global_load_lds((const unsigned*)((const char*)(gbase) + (voff)[_i]), (PG8_LAS unsigned*)(lds + (bufoff) + ldsw + _i * 8192), 16, 0, 0); } while (0)
; #define PG8_LDA(dst, b, h) do { _Pragma("unroll") for (int m = 0; m < 4; ++m) _Pragma("unroll") for (int k = 0; k < 2; ++k) dst[m][k] = *(const PG8_LAS bf16x8*)(lds + PG8_SA(b, h) + aoff + m * 2048 + k * 1024); } while (0)
; #define PG8_LDB(dst, b, h) do { _Pragma("unroll") for (int n = 0; n < 2; ++n) _Pragma("unroll") for (int k = 0; k < 2; ++k) dst[n][k] = *(const PG8_LAS bf16x8*)(lds + PG8_SB(b, h) + boff + n * 2048 + k * 1024); } while (0)
; #define PG8_MMA(ai, bj, At, Bt) do { __builtin_amdgcn_s_setprio(1); _Pragma("unroll") for (int m = 0; m < 4; ++m) _Pragma("unroll") for (int n = 0; n < 2; ++n) _Pragma("unroll") for (int k = 0; k < 2; ++k) \
;         acc[ai][bj][m][n] = __builtin_amdgcn_mfma_f32_16x16x32_bf16(Bt[n][k], At[m][k], acc[ai][bj][m][n], 0, 0, 0); __builtin_amdgcn_s_setprio(0); } while (0)
; #define PG8_BAR __builtin_amdgcn_s_barrier()
; template <class Epi, class Sched, bool ALIGN_EPI = false, bool SP2 = false>
; __device__ __forceinline__ void gemm_phase(PG8_LAS unsigned char* lds, const Gemm g, const Sched& S, const Epi& E, int wave_s_) {
;     ...
;             PG8_LDB(B0, 0, 0); PG8_LDB(B1, 0, 1); PG8_SCHED; PG8_LDA(At, 0, 0); PG8_STAGE(PG8_SA(1, 1), a1 + hstep, voffA);
;             PG8_WAIT_V(8); PG8_WAIT_L(0); PG8_BAR; PG8_MMA(0, 0, At, B0); PG8_MMA(0, 1, At, B1); PG8_BAR; PG8_SCHED;
;             PG8_LDA(At, 0, 1); PG8_STAGE(PG8_SB(0, 0), b2, voffB); PG8_STAGE(PG8_SB(0, 1), b2 + hstep, voffB); PG8_STAGE(PG8_SA(0, 0), a2, voffA);
;             PG8_WAIT_V(8); PG8_WAIT_L(0); PG8_BAR; PG8_MMA(1, 0, At, B0); PG8_MMA(1, 1, At, B1); PG8_BAR; PG8_SCHED;
;             PG8_LDB(B0, 1, 0); PG8_LDB(B1, 1, 1); PG8_SCHED; PG8_LDA(At, 1, 0); PG8_STAGE(PG8_SA(0, 1), a2 + hstep, voffA);
;             PG8_WAIT_V(8); PG8_WAIT_L(0); PG8_BAR; PG8_MMA(0, 0, At, B0); PG8_MMA(0, 1, At, B1); PG8_BAR; PG8_SCHED;
;             PG8_LDA(At, 1, 1); PG8_STAGE(PG8_SB(1, 0), b3, voffB); PG8_STAGE(PG8_SB(1, 1), b3 + hstep, voffB); PG8_STAGE(PG8_SA(1, 0), a3, voffA);
;             PG8_WAIT_V(8); PG8_WAIT_L(0); PG8_BAR; PG8_MMA(1, 0, At, B0); PG8_MMA(1, 1, At, B1); PG8_BAR; PG8_SCHED;
	s_add_i32 s8, s58, s35
	v_lshl_add_u64 v[198:199], v[198:199], 0, s[76:77]
	s_mov_b32 m0, s8
	ds_read_b128 v[160:163], v225 offset:49152
	ds_read_b128 v[164:167], v225 offset:50176
	ds_read_b128 v[168:171], v225 offset:51200
	ds_read_b128 v[172:175], v225 offset:52224
	ds_read_b128 v[176:179], v225 offset:53248
	ds_read_b128 v[180:183], v225 offset:54272
	ds_read_b128 v[184:187], v225 offset:55296
	ds_read_b128 v[188:191], v225 offset:56320
	global_load_lds_dwordx4 v[198:199], off
	s_add_i32 m0, s8, 0x2000
	s_add_u32 s8, s26, 0xb0080
	v_lshl_add_u64 v[198:199], v[204:205], 0, s[76:77]
	s_addc_u32 s9, s27, 0
	s_add_i32 s26, s59, s35
	global_load_lds_dwordx4 v[198:199], off
	v_lshl_add_u64 v[198:199], s[8:9], 0, v[196:197]
	s_mov_b32 m0, s26
	s_nop 0
	global_load_lds_dwordx4 v[198:199], off
	v_lshl_add_u64 v[198:199], s[8:9], 0, v[192:193]
	s_add_i32 m0, s26, 0x2000
	s_nop 0
	global_load_lds_dwordx4 v[198:199], off
	v_lshl_add_u64 v[198:199], v[208:209], 0, s[76:77]
	s_mov_b32 m0, s42
	s_nop 0
	global_load_lds_dwordx4 v[198:199], off
	v_lshl_add_u64 v[198:199], v[210:211], 0, s[76:77]
	s_mov_b32 m0, s43
	s_nop 0
	global_load_lds_dwordx4 v[198:199], off
	s_waitcnt vmcnt(6)
	s_waitcnt lgkmcnt(0)
	s_barrier
	s_setprio 1
	s_waitcnt lgkmcnt(0)
	v_mfma_f32_16x16x32_bf16 v[60:63], v[76:79], v[160:163], v[60:63]
	v_mfma_f32_16x16x32_bf16 v[56:59], v[92:95], v[160:163], v[56:59]
	v_mfma_f32_16x16x32_bf16 v[48:51], v[76:79], v[168:171], v[48:51]
	v_mfma_f32_16x16x32_bf16 v[40:43], v[92:95], v[168:171], v[40:43]
	v_mfma_f32_16x16x32_bf16 v[28:31], v[76:79], v[176:179], v[28:31]
	v_mfma_f32_16x16x32_bf16 v[24:27], v[92:95], v[176:179], v[24:27]
	v_mfma_f32_16x16x32_bf16 v[16:19], v[76:79], v[184:187], v[16:19]
	v_mfma_f32_16x16x32_bf16 v[8:11], v[92:95], v[184:187], v[8:11]
	v_mfma_f32_16x16x32_bf16 v[60:63], v[84:87], v[164:167], v[60:63]
	v_mfma_f32_16x16x32_bf16 v[56:59], v[100:103], v[164:167], v[56:59]
	v_mfma_f32_16x16x32_bf16 v[48:51], v[84:87], v[172:175], v[48:51]
	v_mfma_f32_16x16x32_bf16 v[40:43], v[100:103], v[172:175], v[40:43]
	v_mfma_f32_16x16x32_bf16 v[28:31], v[84:87], v[180:183], v[28:31]
	v_mfma_f32_16x16x32_bf16 v[24:27], v[100:103], v[180:183], v[24:27]
	v_mfma_f32_16x16x32_bf16 v[16:19], v[84:87], v[188:191], v[16:19]
	v_mfma_f32_16x16x32_bf16 v[8:11], v[100:103], v[188:191], v[8:11]
	s_setprio 0
	s_setprio 1
	v_mfma_f32_16x16x32_bf16 v[52:55], v[104:107], v[160:163], v[52:55]
	v_mfma_f32_16x16x32_bf16 v[44:47], v[112:115], v[160:163], v[44:47]
	v_mfma_f32_16x16x32_bf16 v[36:39], v[104:107], v[168:171], v[36:39]
	v_mfma_f32_16x16x32_bf16 v[32:35], v[112:115], v[168:171], v[32:35]
	v_mfma_f32_16x16x32_bf16 v[20:23], v[104:107], v[176:179], v[20:23]
	v_mfma_f32_16x16x32_bf16 v[12:15], v[112:115], v[176:179], v[12:15]
	v_mfma_f32_16x16x32_bf16 v[4:7], v[104:107], v[184:187], v[4:7]
	v_mfma_f32_16x16x32_bf16 v[0:3], v[112:115], v[184:187], v[0:3]
	v_mfma_f32_16x16x32_bf16 v[52:55], v[108:111], v[164:167], v[52:55]
	v_mfma_f32_16x16x32_bf16 v[44:47], v[120:123], v[164:167], v[44:47]
	v_mfma_f32_16x16x32_bf16 v[36:39], v[108:111], v[172:175], v[36:39]
	v_mfma_f32_16x16x32_bf16 v[32:35], v[120:123], v[172:175], v[32:35]
	v_mfma_f32_16x16x32_bf16 v[20:23], v[108:111], v[180:183], v[20:23]
	v_mfma_f32_16x16x32_bf16 v[12:15], v[120:123], v[180:183], v[12:15]
	v_mfma_f32_16x16x32_bf16 v[4:7], v[108:111], v[188:191], v[4:7]
	v_mfma_f32_16x16x32_bf16 v[0:3], v[120:123], v[188:191], v[0:3]
	s_setprio 0
	s_barrier
	s_add_u32 s55, s55, 0x100
	s_addc_u32 s56, s56, 0
	s_cmp_ge_u32 s57, s53
	s_mov_b64 s[8:9], s[10:11]
	s_mov_b32 s26, s57
	s_cbranch_scc0 .LBB0_1908
	s_branch .Lpeel_exit_8
.LBB0_1908:
	s_add_i32 s57, s26, 2
	s_add_u32 s10, s8, 0x100
	s_addc_u32 s11, s9, 0
	s_add_i32 s58, 0, 0x10000
	s_cmp_eq_u32 s54, s26
	s_cselect_b32 s29, s21, s11
	s_cselect_b32 s28, s20, s10
	s_cselect_b32 s27, s23, s56
	s_cselect_b32 s26, s22, s55
	s_add_i32 s59, 0, 0x14000
	v_add_u32_e32 v100, s58, v224
	v_add_u32_e32 v120, s59, v224
	ds_read_b128 v[76:79], v100
	ds_read_b128 v[84:87], v100 offset:1024
	ds_read_b128 v[92:95], v100 offset:2048
	ds_read_b128 v[100:103], v100 offset:3072
	ds_read_b128 v[104:107], v120
	ds_read_b128 v[108:111], v120 offset:1024
	ds_read_b128 v[112:115], v120 offset:2048
	ds_read_b128 v[120:123], v120 offset:3072
	v_lshl_add_u64 v[198:199], s[8:9], 0, v[206:207]
	s_add_i32 m0, s36, 0xc000
	ds_read_b128 v[160:163], v225
	ds_read_b128 v[164:167], v225 offset:1024
	ds_read_b128 v[168:171], v225 offset:2048
	ds_read_b128 v[172:175], v225 offset:3072
	ds_read_b128 v[176:179], v225 offset:4096
	ds_read_b128 v[180:183], v225 offset:5120
	ds_read_b128 v[184:187], v225 offset:6144
	ds_read_b128 v[188:191], v225 offset:7168
	global_load_lds_dwordx4 v[198:199], off
	v_lshl_add_u64 v[198:199], s[8:9], 0, v[194:195]
	s_add_i32 m0, s36, 0xe000
	s_nop 0
	global_load_lds_dwordx4 v[198:199], off
	s_waitcnt vmcnt(8)
	s_waitcnt lgkmcnt(0)
	s_barrier
; #define PG8_STAGE(bufoff, gbase, voff) do { _Pragma("unroll") for (int _i = 0; _i < 2; ++_i) \
;         __builtin_amdgcn_global_load_lds((const unsigned*)((const char*)(gbase) + (voff)[_i]), (PG8_LAS unsigned*)(lds + (bufoff) + ldsw + _i * 8192), 16, 0, 0); } while (0)
; #define PG8_LDA(dst, b, h) do { _Pragma("unroll") for (int m = 0; m < 4; ++m) _Pragma("unroll") for (int k = 0; k < 2; ++k) dst[m][k] = *(const PG8_LAS bf16x8*)(lds + PG8_SA(b, h) + aoff + m * 2048 + k * 1024); } while (0)
; #define PG8_MMA(ai, bj, At, Bt) do { __builtin_amdgcn_s_setprio(1); _Pragma("unroll") for (int m = 0; m < 4; ++m) _Pragma("unroll") for (int n = 0; n < 2; ++n) _Pragma("unroll") for (int k = 0; k < 2; ++k) \
;         acc[ai][bj][m][n] = __builtin_amdgcn_mfma_f32_16x16x32_bf16(Bt[n][k], At[m][k], acc[ai][bj][m][n], 0, 0, 0); __builtin_amdgcn_s_setprio(0); } while (0)
; #define PG8_WAIT_V(n) asm volatile("s_waitcnt vmcnt(" #n ")" ::: "memory")
; #define PG8_WAIT_L(n) asm volatile("s_waitcnt lgkmcnt(" #n ")" ::: "memory")
; #define PG8_BAR __builtin_amdgcn_s_barrier()
; #define PG8_SCHED __builtin_amdgcn_sched_barrier(0)
; template <class Epi, class Sched, bool ALIGN_EPI = false, bool SP2 = false>
; __device__ __forceinline__ void gemm_phase(PG8_LAS unsigned char* lds, const Gemm g, const Sched& S, const Epi& E, int wave_s_) {
;     ...
;             PG8_WAIT_V(8); PG8_WAIT_L(0); PG8_BAR; PG8_MMA(0, 0, At, B0); PG8_MMA(0, 1, At, B1); PG8_BAR; PG8_SCHED;
;             PG8_LDA(At, 0, 1); PG8_STAGE(PG8_SB(0, 0), b2, voffB); PG8_STAGE(PG8_SB(0, 1), b2 + hstep, voffB); PG8_STAGE(PG8_SA(0, 0), a2, voffA);
;             PG8_WAIT_V(8); PG8_WAIT_L(0); PG8_BAR; PG8_MMA(1, 0, At, B0); PG8_MMA(1, 1, At, B1); PG8_BAR; PG8_SCHED;
	s_setprio 1
	s_waitcnt lgkmcnt(0)
	v_mfma_f32_16x16x32_bf16 v[156:159], v[76:79], v[160:163], v[156:159]
	v_mfma_f32_16x16x32_bf16 v[152:155], v[92:95], v[160:163], v[152:155]
	v_mfma_f32_16x16x32_bf16 v[144:147], v[76:79], v[168:171], v[144:147]
	v_mfma_f32_16x16x32_bf16 v[136:139], v[92:95], v[168:171], v[136:139]
	v_mfma_f32_16x16x32_bf16 v[124:127], v[76:79], v[176:179], v[124:127]
	v_mfma_f32_16x16x32_bf16 v[116:119], v[92:95], v[176:179], v[116:119]
	v_mfma_f32_16x16x32_bf16 v[88:91], v[76:79], v[184:187], v[88:91]
	v_mfma_f32_16x16x32_bf16 v[72:75], v[92:95], v[184:187], v[72:75]
	v_mfma_f32_16x16x32_bf16 v[156:159], v[84:87], v[164:167], v[156:159]
	v_mfma_f32_16x16x32_bf16 v[152:155], v[100:103], v[164:167], v[152:155]
	v_mfma_f32_16x16x32_bf16 v[144:147], v[84:87], v[172:175], v[144:147]
	v_mfma_f32_16x16x32_bf16 v[136:139], v[100:103], v[172:175], v[136:139]
	v_mfma_f32_16x16x32_bf16 v[124:127], v[84:87], v[180:183], v[124:127]
	v_mfma_f32_16x16x32_bf16 v[116:119], v[100:103], v[180:183], v[116:119]
	v_mfma_f32_16x16x32_bf16 v[88:91], v[84:87], v[188:191], v[88:91]
	v_mfma_f32_16x16x32_bf16 v[72:75], v[100:103], v[188:191], v[72:75]
	s_setprio 0
	s_setprio 1
	v_mfma_f32_16x16x32_bf16 v[148:151], v[104:107], v[160:163], v[148:151]
	v_mfma_f32_16x16x32_bf16 v[140:143], v[112:115], v[160:163], v[140:143]
	v_mfma_f32_16x16x32_bf16 v[132:135], v[104:107], v[168:171], v[132:135]
	v_mfma_f32_16x16x32_bf16 v[128:131], v[112:115], v[168:171], v[128:131]
	v_mfma_f32_16x16x32_bf16 v[96:99], v[104:107], v[176:179], v[96:99]
	v_mfma_f32_16x16x32_bf16 v[80:83], v[112:115], v[176:179], v[80:83]
	v_mfma_f32_16x16x32_bf16 v[68:71], v[104:107], v[184:187], v[68:71]
	v_mfma_f32_16x16x32_bf16 v[64:67], v[112:115], v[184:187], v[64:67]
	v_mfma_f32_16x16x32_bf16 v[148:151], v[108:111], v[164:167], v[148:151]
	v_mfma_f32_16x16x32_bf16 v[140:143], v[120:123], v[164:167], v[140:143]
	v_mfma_f32_16x16x32_bf16 v[132:135], v[108:111], v[172:175], v[132:135]
	v_mfma_f32_16x16x32_bf16 v[128:131], v[120:123], v[172:175], v[128:131]
	v_mfma_f32_16x16x32_bf16 v[96:99], v[108:111], v[180:183], v[96:99]
	v_mfma_f32_16x16x32_bf16 v[80:83], v[120:123], v[180:183], v[80:83]
	v_mfma_f32_16x16x32_bf16 v[68:71], v[108:111], v[188:191], v[68:71]
	v_mfma_f32_16x16x32_bf16 v[64:67], v[120:123], v[188:191], v[64:67]
	s_setprio 0
	s_barrier
	s_add_i32 s8, s58, s35
	v_lshl_add_u64 v[198:199], s[26:27], 0, v[196:197]
	s_mov_b32 m0, s8
	ds_read_b128 v[160:163], v225 offset:16384
	ds_read_b128 v[164:167], v225 offset:17408
	ds_read_b128 v[168:171], v225 offset:18432
	ds_read_b128 v[172:175], v225 offset:19456
	ds_read_b128 v[176:179], v225 offset:20480
	ds_read_b128 v[180:183], v225 offset:21504
	ds_read_b128 v[184:187], v225 offset:22528
	ds_read_b128 v[188:191], v225 offset:23552
	global_load_lds_dwordx4 v[198:199], off
	s_add_i32 m0, s8, 0x2000
	s_add_u32 s8, s26, 0xb0000
	v_lshl_add_u64 v[204:205], s[26:27], 0, v[192:193]
	s_addc_u32 s9, s27, 0
	s_add_i32 s58, s59, s35
	global_load_lds_dwordx4 v[204:205], off
	v_lshl_add_u64 v[208:209], s[8:9], 0, v[196:197]
	s_mov_b32 m0, s58
	v_lshl_add_u64 v[210:211], s[28:29], 0, v[192:193]
	global_load_lds_dwordx4 v[208:209], off
	v_lshl_add_u64 v[208:209], s[8:9], 0, v[192:193]
	s_add_i32 m0, s58, 0x2000
	s_nop 0
	global_load_lds_dwordx4 v[208:209], off
	v_lshl_add_u64 v[208:209], s[28:29], 0, v[196:197]
	s_waitcnt vmcnt(6)
	s_waitcnt lgkmcnt(0)
	s_barrier
	s_setprio 1
	s_waitcnt lgkmcnt(0)
	v_mfma_f32_16x16x32_bf16 v[60:63], v[76:79], v[160:163], v[60:63]
	v_mfma_f32_16x16x32_bf16 v[56:59], v[92:95], v[160:163], v[56:59]
	v_mfma_f32_16x16x32_bf16 v[48:51], v[76:79], v[168:171], v[48:51]
	v_mfma_f32_16x16x32_bf16 v[40:43], v[92:95], v[168:171], v[40:43]
	v_mfma_f32_16x16x32_bf16 v[28:31], v[76:79], v[176:179], v[28:31]
	v_mfma_f32_16x16x32_bf16 v[24:27], v[92:95], v[176:179], v[24:27]
	v_mfma_f32_16x16x32_bf16 v[16:19], v[76:79], v[184:187], v[16:19]
	v_mfma_f32_16x16x32_bf16 v[8:11], v[92:95], v[184:187], v[8:11]
	v_mfma_f32_16x16x32_bf16 v[60:63], v[84:87], v[164:167], v[60:63]
	v_mfma_f32_16x16x32_bf16 v[56:59], v[100:103], v[164:167], v[56:59]
	v_mfma_f32_16x16x32_bf16 v[48:51], v[84:87], v[172:175], v[48:51]
	v_mfma_f32_16x16x32_bf16 v[40:43], v[100:103], v[172:175], v[40:43]
	v_mfma_f32_16x16x32_bf16 v[28:31], v[84:87], v[180:183], v[28:31]
	v_mfma_f32_16x16x32_bf16 v[24:27], v[100:103], v[180:183], v[24:27]
	v_mfma_f32_16x16x32_bf16 v[16:19], v[84:87], v[188:191], v[16:19]
	v_mfma_f32_16x16x32_bf16 v[8:11], v[100:103], v[188:191], v[8:11]
	s_setprio 0
	s_setprio 1
	v_mfma_f32_16x16x32_bf16 v[52:55], v[104:107], v[160:163], v[52:55]
	v_mfma_f32_16x16x32_bf16 v[44:47], v[112:115], v[160:163], v[44:47]
	v_mfma_f32_16x16x32_bf16 v[36:39], v[104:107], v[168:171], v[36:39]
	v_mfma_f32_16x16x32_bf16 v[32:35], v[112:115], v[168:171], v[32:35]
	v_mfma_f32_16x16x32_bf16 v[20:23], v[104:107], v[176:179], v[20:23]
	v_mfma_f32_16x16x32_bf16 v[12:15], v[112:115], v[176:179], v[12:15]
	v_mfma_f32_16x16x32_bf16 v[4:7], v[104:107], v[184:187], v[4:7]
	v_mfma_f32_16x16x32_bf16 v[0:3], v[112:115], v[184:187], v[0:3]
	v_mfma_f32_16x16x32_bf16 v[52:55], v[108:111], v[164:167], v[52:55]
	v_mfma_f32_16x16x32_bf16 v[44:47], v[120:123], v[164:167], v[44:47]
	v_mfma_f32_16x16x32_bf16 v[36:39], v[108:111], v[172:175], v[36:39]
	v_mfma_f32_16x16x32_bf16 v[32:35], v[120:123], v[172:175], v[32:35]
	v_mfma_f32_16x16x32_bf16 v[20:23], v[108:111], v[180:183], v[20:23]
	v_mfma_f32_16x16x32_bf16 v[12:15], v[120:123], v[180:183], v[12:15]
	v_mfma_f32_16x16x32_bf16 v[4:7], v[108:111], v[188:191], v[4:7]
	v_mfma_f32_16x16x32_bf16 v[0:3], v[120:123], v[188:191], v[0:3]
	s_setprio 0
	s_barrier
; #define PG8_STAGE(bufoff, gbase, voff) do { _Pragma("unroll") for (int _i = 0; _i < 2; ++_i) \
;         __builtin_amdgcn_global_load_lds((const unsigned*)((const char*)(gbase) + (voff)[_i]), (PG8_LAS unsigned*)(lds + (bufoff) + ldsw + _i * 8192), 16, 0, 0); } while (0)
; #define PG8_LDA(dst, b, h) do { _Pragma("unroll") for (int m = 0; m < 4; ++m) _Pragma("unroll") for (int k = 0; k < 2; ++k) dst[m][k] = *(const PG8_LAS bf16x8*)(lds + PG8_SA(b, h) + aoff + m * 2048 + k * 1024); } while (0)
; #define PG8_LDB(dst, b, h) do { _Pragma("unroll") for (int n = 0; n < 2; ++n) _Pragma("unroll") for (int k = 0; k < 2; ++k) dst[n][k] = *(const PG8_LAS bf16x8*)(lds + PG8_SB(b, h) + boff + n * 2048 + k * 1024); } while (0)
; #define PG8_MMA(ai, bj, At, Bt) do { __builtin_amdgcn_s_setprio(1); _Pragma("unroll") for (int m = 0; m < 4; ++m) _Pragma("unroll") for (int n = 0; n < 2; ++n) _Pragma("unroll") for (int k = 0; k < 2; ++k) \
;         acc[ai][bj][m][n] = __builtin_amdgcn_mfma_f32_16x16x32_bf16(Bt[n][k], At[m][k], acc[ai][bj][m][n], 0, 0, 0); __builtin_amdgcn_s_setprio(0); } while (0)
; #define PG8_WAIT_V(n) asm volatile("s_waitcnt vmcnt(" #n ")" ::: "memory")
; #define PG8_WAIT_L(n) asm volatile("s_waitcnt lgkmcnt(" #n ")" ::: "memory")
; #define PG8_BAR __builtin_amdgcn_s_barrier()
; #define PG8_SCHED __builtin_amdgcn_sched_barrier(0)
; template <class Epi, class Sched, bool ALIGN_EPI = false, bool SP2 = false>
; __device__ __forceinline__ void gemm_phase(PG8_LAS unsigned char* lds, const Gemm g, const Sched& S, const Epi& E, int wave_s_) {
;     ...
;             PG8_LDB(B0, 1, 0); PG8_LDB(B1, 1, 1); PG8_SCHED; PG8_LDA(At, 1, 0); PG8_STAGE(PG8_SA(0, 1), a2 + hstep, voffA);
;             PG8_WAIT_V(8); PG8_WAIT_L(0); PG8_BAR; PG8_MMA(0, 0, At, B0); PG8_MMA(0, 1, At, B1); PG8_BAR; PG8_SCHED;
	s_add_i32 s58, 0, 0x18000
	s_add_i32 s59, 0, 0x1c000
	v_add_u32_e32 v100, s58, v224
	v_add_u32_e32 v120, s59, v224
	ds_read_b128 v[76:79], v100
	ds_read_b128 v[84:87], v100 offset:1024
	ds_read_b128 v[92:95], v100 offset:2048
	ds_read_b128 v[100:103], v100 offset:3072
	ds_read_b128 v[104:107], v120
	ds_read_b128 v[108:111], v120 offset:1024
	ds_read_b128 v[112:115], v120 offset:2048
	ds_read_b128 v[120:123], v120 offset:3072
	s_add_u32 s8, s28, 0xb0000
	s_addc_u32 s9, s29, 0
	s_mov_b32 m0, s38
	v_lshl_add_u64 v[212:213], s[8:9], 0, v[196:197]
	ds_read_b128 v[160:163], v225 offset:32768
	ds_read_b128 v[164:167], v225 offset:33792
	ds_read_b128 v[168:171], v225 offset:34816
	ds_read_b128 v[172:175], v225 offset:35840
	ds_read_b128 v[176:179], v225 offset:36864
	ds_read_b128 v[180:183], v225 offset:37888
	ds_read_b128 v[184:187], v225 offset:38912
	ds_read_b128 v[188:191], v225 offset:39936
	global_load_lds_dwordx4 v[212:213], off
	v_lshl_add_u64 v[212:213], s[8:9], 0, v[192:193]
	s_mov_b32 m0, s39
	s_nop 0
	global_load_lds_dwordx4 v[212:213], off
	s_mov_b32 m0, s36
	s_nop 0
	global_load_lds_dwordx4 v[208:209], off
	s_mov_b32 m0, s37
	s_nop 0
	global_load_lds_dwordx4 v[210:211], off
	s_waitcnt vmcnt(8)
	s_waitcnt lgkmcnt(0)
	s_barrier
	s_setprio 1
	s_waitcnt lgkmcnt(0)
	v_mfma_f32_16x16x32_bf16 v[156:159], v[76:79], v[160:163], v[156:159]
	v_mfma_f32_16x16x32_bf16 v[152:155], v[92:95], v[160:163], v[152:155]
	v_mfma_f32_16x16x32_bf16 v[144:147], v[76:79], v[168:171], v[144:147]
	v_mfma_f32_16x16x32_bf16 v[136:139], v[92:95], v[168:171], v[136:139]
	v_mfma_f32_16x16x32_bf16 v[124:127], v[76:79], v[176:179], v[124:127]
	v_mfma_f32_16x16x32_bf16 v[116:119], v[92:95], v[176:179], v[116:119]
	v_mfma_f32_16x16x32_bf16 v[88:91], v[76:79], v[184:187], v[88:91]
	v_mfma_f32_16x16x32_bf16 v[72:75], v[92:95], v[184:187], v[72:75]
	v_mfma_f32_16x16x32_bf16 v[156:159], v[84:87], v[164:167], v[156:159]
	v_mfma_f32_16x16x32_bf16 v[152:155], v[100:103], v[164:167], v[152:155]
	v_mfma_f32_16x16x32_bf16 v[144:147], v[84:87], v[172:175], v[144:147]
	v_mfma_f32_16x16x32_bf16 v[136:139], v[100:103], v[172:175], v[136:139]
	v_mfma_f32_16x16x32_bf16 v[124:127], v[84:87], v[180:183], v[124:127]
	v_mfma_f32_16x16x32_bf16 v[116:119], v[100:103], v[180:183], v[116:119]
	v_mfma_f32_16x16x32_bf16 v[88:91], v[84:87], v[188:191], v[88:91]
	v_mfma_f32_16x16x32_bf16 v[72:75], v[100:103], v[188:191], v[72:75]
	s_setprio 0
	s_setprio 1
	v_mfma_f32_16x16x32_bf16 v[148:151], v[104:107], v[160:163], v[148:151]
	v_mfma_f32_16x16x32_bf16 v[140:143], v[112:115], v[160:163], v[140:143]
	v_mfma_f32_16x16x32_bf16 v[132:135], v[104:107], v[168:171], v[132:135]
	v_mfma_f32_16x16x32_bf16 v[128:131], v[112:115], v[168:171], v[128:131]
	v_mfma_f32_16x16x32_bf16 v[96:99], v[104:107], v[176:179], v[96:99]
	v_mfma_f32_16x16x32_bf16 v[80:83], v[112:115], v[176:179], v[80:83]
	v_mfma_f32_16x16x32_bf16 v[68:71], v[104:107], v[184:187], v[68:71]
	v_mfma_f32_16x16x32_bf16 v[64:67], v[112:115], v[184:187], v[64:67]
	v_mfma_f32_16x16x32_bf16 v[148:151], v[108:111], v[164:167], v[148:151]
	v_mfma_f32_16x16x32_bf16 v[140:143], v[120:123], v[164:167], v[140:143]
	v_mfma_f32_16x16x32_bf16 v[132:135], v[108:111], v[172:175], v[132:135]
	v_mfma_f32_16x16x32_bf16 v[128:131], v[120:123], v[172:175], v[128:131]
	v_mfma_f32_16x16x32_bf16 v[96:99], v[108:111], v[180:183], v[96:99]
	v_mfma_f32_16x16x32_bf16 v[80:83], v[120:123], v[180:183], v[80:83]
	v_mfma_f32_16x16x32_bf16 v[68:71], v[108:111], v[188:191], v[68:71]
	v_mfma_f32_16x16x32_bf16 v[64:67], v[120:123], v[188:191], v[64:67]
	s_setprio 0
	s_barrier
; #define PG8_STAGE(bufoff, gbase, voff) do { _Pragma("unroll") for (int _i = 0; _i < 2; ++_i) \
;         __builtin_amdgcn_global_load_lds((const unsigned*)((const char*)(gbase) + (voff)[_i]), (PG8_LAS unsigned*)(lds + (bufoff) + ldsw + _i * 8192), 16, 0, 0); } while (0)
; #define PG8_LDA(dst, b, h) do { _Pragma("unroll") for (int m = 0; m < 4; ++m) _Pragma("unroll") for (int k = 0; k < 2; ++k) dst[m][k] = *(const PG8_LAS bf16x8*)(lds + PG8_SA(b, h) + aoff + m * 2048 + k * 1024); } while (0)
; #define PG8_MMA(ai, bj, At, Bt) do { __builtin_amdgcn_s_setprio(1); _Pragma("unroll") for (int m = 0; m < 4; ++m) _Pragma("unroll") for (int n = 0; n < 2; ++n) _Pragma("unroll") for (int k = 0; k < 2; ++k) \
;         acc[ai][bj][m][n] = __builtin_amdgcn_mfma_f32_16x16x32_bf16(Bt[n][k], At[m][k], acc[ai][bj][m][n], 0, 0, 0); __builtin_amdgcn_s_setprio(0); } while (0)
; #define PG8_WAIT_V(n) asm volatile("s_waitcnt vmcnt(" #n ")" ::: "memory")
; #define PG8_WAIT_L(n) asm volatile("s_waitcnt lgkmcnt(" #n ")" ::: "memory")
; #define PG8_BAR __builtin_amdgcn_s_barrier()
; #define PG8_SCHED __builtin_amdgcn_sched_barrier(0)
; template <class Epi, class Sched, bool ALIGN_EPI = false, bool SP2 = false>
; __device__ __forceinline__ void gemm_phase(PG8_LAS unsigned char* lds, const Gemm g, const Sched& S, const Epi& E, int wave_s_) {
;     ...
;         for (int t = 0; t < nt; t += 2) {
;             const bool last = (t == nt - 2);
;             const char* a1 = cA + (size_t)(t + 1) * kstep;
;             const char* a2 = last ? nA : cA + (size_t)(t + 2) * kstep; const char* b2 = last ? nB : cB + (size_t)(t + 2) * kstep;
;     ...
;             PG8_LDA(At, 1, 1); PG8_STAGE(PG8_SB(1, 0), b3, voffB); PG8_STAGE(PG8_SB(1, 1), b3 + hstep, voffB); PG8_STAGE(PG8_SA(1, 0), a3, voffA);
;             PG8_WAIT_V(8); PG8_WAIT_L(0); PG8_BAR; PG8_MMA(1, 0, At, B0); PG8_MMA(1, 1, At, B1); PG8_BAR; PG8_SCHED;
	s_add_i32 s8, s58, s35
	v_lshl_add_u64 v[198:199], v[198:199], 0, s[76:77]
	s_mov_b32 m0, s8
	ds_read_b128 v[160:163], v225 offset:49152
	ds_read_b128 v[164:167], v225 offset:50176
	ds_read_b128 v[168:171], v225 offset:51200
	ds_read_b128 v[172:175], v225 offset:52224
	ds_read_b128 v[176:179], v225 offset:53248
	ds_read_b128 v[180:183], v225 offset:54272
	ds_read_b128 v[184:187], v225 offset:55296
	ds_read_b128 v[188:191], v225 offset:56320
	global_load_lds_dwordx4 v[198:199], off
	s_add_i32 m0, s8, 0x2000
	s_add_u32 s8, s26, 0xb0080
	v_lshl_add_u64 v[198:199], v[204:205], 0, s[76:77]
	s_addc_u32 s9, s27, 0
	s_add_i32 s26, s59, s35
	global_load_lds_dwordx4 v[198:199], off
	v_lshl_add_u64 v[198:199], s[8:9], 0, v[196:197]
	s_mov_b32 m0, s26
	s_nop 0
	global_load_lds_dwordx4 v[198:199], off
	v_lshl_add_u64 v[198:199], s[8:9], 0, v[192:193]
	s_add_i32 m0, s26, 0x2000
	s_nop 0
	global_load_lds_dwordx4 v[198:199], off
	v_lshl_add_u64 v[198:199], v[208:209], 0, s[76:77]
	s_mov_b32 m0, s42
	s_nop 0
	global_load_lds_dwordx4 v[198:199], off
	v_lshl_add_u64 v[198:199], v[210:211], 0, s[76:77]
	s_mov_b32 m0, s43
	s_nop 0
	global_load_lds_dwordx4 v[198:199], off
	s_waitcnt vmcnt(6)
	s_waitcnt lgkmcnt(0)
	s_barrier
	s_setprio 1
	s_waitcnt lgkmcnt(0)
	v_mfma_f32_16x16x32_bf16 v[60:63], v[76:79], v[160:163], v[60:63]
	v_mfma_f32_16x16x32_bf16 v[56:59], v[92:95], v[160:163], v[56:59]
	v_mfma_f32_16x16x32_bf16 v[48:51], v[76:79], v[168:171], v[48:51]
	v_mfma_f32_16x16x32_bf16 v[40:43], v[92:95], v[168:171], v[40:43]
	v_mfma_f32_16x16x32_bf16 v[28:31], v[76:79], v[176:179], v[28:31]
	v_mfma_f32_16x16x32_bf16 v[24:27], v[92:95], v[176:179], v[24:27]
	v_mfma_f32_16x16x32_bf16 v[16:19], v[76:79], v[184:187], v[16:19]
	v_mfma_f32_16x16x32_bf16 v[8:11], v[92:95], v[184:187], v[8:11]
	v_mfma_f32_16x16x32_bf16 v[60:63], v[84:87], v[164:167], v[60:63]
	v_mfma_f32_16x16x32_bf16 v[56:59], v[100:103], v[164:167], v[56:59]
	v_mfma_f32_16x16x32_bf16 v[48:51], v[84:87], v[172:175], v[48:51]
	v_mfma_f32_16x16x32_bf16 v[40:43], v[100:103], v[172:175], v[40:43]
	v_mfma_f32_16x16x32_bf16 v[28:31], v[84:87], v[180:183], v[28:31]
	v_mfma_f32_16x16x32_bf16 v[24:27], v[100:103], v[180:183], v[24:27]
	v_mfma_f32_16x16x32_bf16 v[16:19], v[84:87], v[188:191], v[16:19]
	v_mfma_f32_16x16x32_bf16 v[8:11], v[100:103], v[188:191], v[8:11]
	s_setprio 0
	s_setprio 1
	v_mfma_f32_16x16x32_bf16 v[52:55], v[104:107], v[160:163], v[52:55]
	v_mfma_f32_16x16x32_bf16 v[44:47], v[112:115], v[160:163], v[44:47]
	v_mfma_f32_16x16x32_bf16 v[36:39], v[104:107], v[168:171], v[36:39]
	v_mfma_f32_16x16x32_bf16 v[32:35], v[112:115], v[168:171], v[32:35]
	v_mfma_f32_16x16x32_bf16 v[20:23], v[104:107], v[176:179], v[20:23]
	v_mfma_f32_16x16x32_bf16 v[12:15], v[112:115], v[176:179], v[12:15]
	v_mfma_f32_16x16x32_bf16 v[4:7], v[104:107], v[184:187], v[4:7]
	v_mfma_f32_16x16x32_bf16 v[0:3], v[112:115], v[184:187], v[0:3]
	v_mfma_f32_16x16x32_bf16 v[52:55], v[108:111], v[164:167], v[52:55]
	v_mfma_f32_16x16x32_bf16 v[44:47], v[120:123], v[164:167], v[44:47]
	v_mfma_f32_16x16x32_bf16 v[36:39], v[108:111], v[172:175], v[36:39]
	v_mfma_f32_16x16x32_bf16 v[32:35], v[120:123], v[172:175], v[32:35]
	v_mfma_f32_16x16x32_bf16 v[20:23], v[108:111], v[180:183], v[20:23]
	v_mfma_f32_16x16x32_bf16 v[12:15], v[120:123], v[180:183], v[12:15]
	v_mfma_f32_16x16x32_bf16 v[4:7], v[108:111], v[188:191], v[4:7]
	v_mfma_f32_16x16x32_bf16 v[0:3], v[120:123], v[188:191], v[0:3]
	s_setprio 0
	s_barrier
	s_add_u32 s55, s55, 0x100
	s_addc_u32 s56, s56, 0
	s_cmp_ge_u32 s57, s53
	s_mov_b64 s[8:9], s[10:11]
	s_mov_b32 s26, s57
	s_cbranch_scc0 .LBB0_1908
